# GEMM load segments: LDS-DMA issue moved ahead of the ds_read burst (in-loop segments, 66 sites); on top of v022
# speedup vs baseline: 1.0543x; 1.0543x over previous
.LBB0_183:
	s_ashr_i32 s13, s12, 31
	s_lshl_b64 s[24:25], s[12:13], 19
	s_add_u32 s24, s80, s24
	s_addc_u32 s25, s81, s25
	s_and_b64 s[30:31], s[4:5], exec
	s_cselect_b32 s13, s25, s45
	s_cselect_b32 s66, s24, s44
	s_ashr_i32 s11, s10, 31
	s_lshl_b64 s[30:31], s[10:11], 19
	s_add_u32 s30, s52, s30
	s_addc_u32 s31, s53, s31
	s_and_b64 s[48:49], s[4:5], exec
	s_cselect_b32 s11, s31, s47
	s_cselect_b32 s67, s30, s46
	s_add_u32 s44, s44, 0x40080
	s_addc_u32 s45, s45, 0
	s_add_u32 s68, s46, 0x100
	s_addc_u32 s69, s47, 0
	s_mov_b32 s70, -2
	s_add_u32 s18, s44, 0xfffc0080
	s_addc_u32 s19, s45, -1
	s_cmp_eq_u32 s70, 12
	s_cselect_b32 s49, s13, s19
	s_cselect_b32 s48, s66, s18
	s_cselect_b32 s47, s11, s69
	s_cselect_b32 s46, s67, s68
	v_lshl_add_u64 v[178:179], s[44:45], 0, v[132:133]
	s_add_i32 m0, s37, 0xc000
	s_nop 0
	global_load_lds_dwordx4 v[178:179], off
	v_lshl_add_u64 v[178:179], s[44:45], 0, v[134:135]
	s_add_i32 m0, s37, 0xe000
	s_nop 0
	global_load_lds_dwordx4 v[178:179], off
	ds_read_b128 v[140:143], v147
	ds_read_b128 v[150:153], v147 offset:1024
	ds_read_b128 v[154:157], v147 offset:2048
	ds_read_b128 v[158:161], v147 offset:3072
	ds_read_b128 v[162:165], v148
	ds_read_b128 v[166:169], v148 offset:1024
	ds_read_b128 v[170:173], v148 offset:2048
	ds_read_b128 v[174:177], v148 offset:3072
	ds_read_b128 v[184:187], v149
	ds_read_b128 v[188:191], v149 offset:1024
	ds_read_b128 v[192:195], v149 offset:2048
	ds_read_b128 v[196:199], v149 offset:3072
	ds_read_b128 v[200:203], v149 offset:4096
	ds_read_b128 v[204:207], v149 offset:5120
	ds_read_b128 v[208:211], v149 offset:6144
	ds_read_b128 v[212:215], v149 offset:7168
	s_waitcnt vmcnt(8)
	s_waitcnt lgkmcnt(0)
	s_barrier
	s_setprio 1
	s_waitcnt lgkmcnt(0)
	v_mfma_f32_16x16x32_bf16 v[124:127], v[140:143], v[184:187], 0
	v_mfma_f32_16x16x32_bf16 v[124:127], v[150:153], v[188:191], v[124:127]
	v_mfma_f32_16x16x32_bf16 v[120:123], v[154:157], v[184:187], 0
	v_mfma_f32_16x16x32_bf16 v[120:123], v[158:161], v[188:191], v[120:123]
	v_mfma_f32_16x16x32_bf16 v[108:111], v[140:143], v[192:195], 0
	v_mfma_f32_16x16x32_bf16 v[108:111], v[150:153], v[196:199], v[108:111]
	v_mfma_f32_16x16x32_bf16 v[104:107], v[154:157], v[192:195], 0
	v_mfma_f32_16x16x32_bf16 v[104:107], v[158:161], v[196:199], v[104:107]
	v_mfma_f32_16x16x32_bf16 v[92:95], v[140:143], v[200:203], 0
	v_mfma_f32_16x16x32_bf16 v[92:95], v[150:153], v[204:207], v[92:95]
	v_mfma_f32_16x16x32_bf16 v[88:91], v[154:157], v[200:203], 0
	v_mfma_f32_16x16x32_bf16 v[88:91], v[158:161], v[204:207], v[88:91]
	v_mfma_f32_16x16x32_bf16 v[76:79], v[140:143], v[208:211], 0
	v_mfma_f32_16x16x32_bf16 v[76:79], v[150:153], v[212:215], v[76:79]
	v_mfma_f32_16x16x32_bf16 v[72:75], v[154:157], v[208:211], 0
	v_mfma_f32_16x16x32_bf16 v[72:75], v[158:161], v[212:215], v[72:75]
	v_mfma_f32_16x16x32_bf16 v[116:119], v[162:165], v[184:187], 0
	v_mfma_f32_16x16x32_bf16 v[116:119], v[166:169], v[188:191], v[116:119]
	v_mfma_f32_16x16x32_bf16 v[112:115], v[170:173], v[184:187], 0
	v_mfma_f32_16x16x32_bf16 v[112:115], v[174:177], v[188:191], v[112:115]
	v_mfma_f32_16x16x32_bf16 v[100:103], v[162:165], v[192:195], 0
	v_mfma_f32_16x16x32_bf16 v[100:103], v[166:169], v[196:199], v[100:103]
	v_mfma_f32_16x16x32_bf16 v[96:99], v[170:173], v[192:195], 0
	v_mfma_f32_16x16x32_bf16 v[96:99], v[174:177], v[196:199], v[96:99]
	v_mfma_f32_16x16x32_bf16 v[84:87], v[162:165], v[200:203], 0
	v_mfma_f32_16x16x32_bf16 v[84:87], v[166:169], v[204:207], v[84:87]
	v_mfma_f32_16x16x32_bf16 v[80:83], v[170:173], v[200:203], 0
	v_mfma_f32_16x16x32_bf16 v[80:83], v[174:177], v[204:207], v[80:83]
	v_mfma_f32_16x16x32_bf16 v[68:71], v[162:165], v[208:211], 0
	v_mfma_f32_16x16x32_bf16 v[68:71], v[166:169], v[212:215], v[68:71]
	v_mfma_f32_16x16x32_bf16 v[64:67], v[170:173], v[208:211], 0
	v_mfma_f32_16x16x32_bf16 v[64:67], v[174:177], v[212:215], v[64:67]
	s_setprio 0
	s_barrier
	s_add_i32 s18, s62, s54
	v_lshl_add_u64 v[178:179], s[46:47], 0, v[130:131]
	s_mov_b32 m0, s18
	s_nop 0
	global_load_lds_dwordx4 v[178:179], off
	s_add_i32 m0, s18, 0x2000
	s_add_u32 s72, s46, 0x40000
	v_lshl_add_u64 v[216:217], s[46:47], 0, v[128:129]
	s_addc_u32 s73, s47, 0
	s_add_i32 s18, s63, s54
	global_load_lds_dwordx4 v[216:217], off
	v_lshl_add_u64 v[218:219], s[72:73], 0, v[130:131]
	s_mov_b32 m0, s18
	v_lshl_add_u64 v[220:221], s[48:49], 0, v[128:129]
	global_load_lds_dwordx4 v[218:219], off
	v_lshl_add_u64 v[218:219], s[72:73], 0, v[128:129]
	s_add_i32 m0, s18, 0x2000
	s_nop 0
	global_load_lds_dwordx4 v[218:219], off
	v_lshl_add_u64 v[218:219], s[48:49], 0, v[130:131]
	s_mov_b32 m0, s37
	s_nop 0
	global_load_lds_dwordx4 v[218:219], off
	s_mov_b32 m0, s56
	s_nop 0
	global_load_lds_dwordx4 v[220:221], off
	ds_read_b128 v[184:187], v149 offset:16384
	ds_read_b128 v[188:191], v149 offset:17408
	ds_read_b128 v[192:195], v149 offset:18432
	ds_read_b128 v[196:199], v149 offset:19456
	ds_read_b128 v[200:203], v149 offset:20480
	ds_read_b128 v[204:207], v149 offset:21504
	ds_read_b128 v[208:211], v149 offset:22528
	ds_read_b128 v[212:215], v149 offset:23552
	s_waitcnt vmcnt(8)
	s_waitcnt lgkmcnt(0)
	s_barrier
	s_setprio 1
	s_waitcnt lgkmcnt(0)
	v_mfma_f32_16x16x32_bf16 v[60:63], v[140:143], v[184:187], 0
	v_mfma_f32_16x16x32_bf16 v[60:63], v[150:153], v[188:191], v[60:63]
	v_mfma_f32_16x16x32_bf16 v[56:59], v[154:157], v[184:187], 0
	v_mfma_f32_16x16x32_bf16 v[56:59], v[158:161], v[188:191], v[56:59]
	v_mfma_f32_16x16x32_bf16 v[44:47], v[140:143], v[192:195], 0
	v_mfma_f32_16x16x32_bf16 v[44:47], v[150:153], v[196:199], v[44:47]
	v_mfma_f32_16x16x32_bf16 v[40:43], v[154:157], v[192:195], 0
	v_mfma_f32_16x16x32_bf16 v[40:43], v[158:161], v[196:199], v[40:43]
	v_mfma_f32_16x16x32_bf16 v[28:31], v[140:143], v[200:203], 0
	v_mfma_f32_16x16x32_bf16 v[28:31], v[150:153], v[204:207], v[28:31]
	v_mfma_f32_16x16x32_bf16 v[24:27], v[154:157], v[200:203], 0
	v_mfma_f32_16x16x32_bf16 v[24:27], v[158:161], v[204:207], v[24:27]
	v_mfma_f32_16x16x32_bf16 v[12:15], v[140:143], v[208:211], 0
	v_mfma_f32_16x16x32_bf16 v[12:15], v[150:153], v[212:215], v[12:15]
	v_mfma_f32_16x16x32_bf16 v[8:11], v[154:157], v[208:211], 0
	v_mfma_f32_16x16x32_bf16 v[8:11], v[158:161], v[212:215], v[8:11]
	v_mfma_f32_16x16x32_bf16 v[52:55], v[162:165], v[184:187], 0
	v_mfma_f32_16x16x32_bf16 v[52:55], v[166:169], v[188:191], v[52:55]
	v_mfma_f32_16x16x32_bf16 v[48:51], v[170:173], v[184:187], 0
	v_mfma_f32_16x16x32_bf16 v[48:51], v[174:177], v[188:191], v[48:51]
	v_mfma_f32_16x16x32_bf16 v[36:39], v[162:165], v[192:195], 0
	v_mfma_f32_16x16x32_bf16 v[36:39], v[166:169], v[196:199], v[36:39]
	v_mfma_f32_16x16x32_bf16 v[32:35], v[170:173], v[192:195], 0
	v_mfma_f32_16x16x32_bf16 v[32:35], v[174:177], v[196:199], v[32:35]
	v_mfma_f32_16x16x32_bf16 v[20:23], v[162:165], v[200:203], 0
	v_mfma_f32_16x16x32_bf16 v[20:23], v[166:169], v[204:207], v[20:23]
	v_mfma_f32_16x16x32_bf16 v[16:19], v[170:173], v[200:203], 0
	v_mfma_f32_16x16x32_bf16 v[16:19], v[174:177], v[204:207], v[16:19]
	v_mfma_f32_16x16x32_bf16 v[4:7], v[162:165], v[208:211], 0
	v_mfma_f32_16x16x32_bf16 v[4:7], v[166:169], v[212:215], v[4:7]
	v_mfma_f32_16x16x32_bf16 v[0:3], v[170:173], v[208:211], 0
	v_mfma_f32_16x16x32_bf16 v[0:3], v[174:177], v[212:215], v[0:3]
	s_setprio 0
	s_barrier
	s_branch .Lmid_gemm0
.LBB0_184:
	s_add_u32 s18, s44, 0xfffc0080
	s_addc_u32 s19, s45, -1
	s_cmp_eq_u32 s70, 12
	s_cselect_b32 s49, s13, s19
	s_cselect_b32 s48, s66, s18
	s_cselect_b32 s47, s11, s69
	s_cselect_b32 s46, s67, s68
	v_lshl_add_u64 v[178:179], s[44:45], 0, v[132:133]
	s_add_i32 m0, s37, 0xc000
	s_nop 0
	global_load_lds_dwordx4 v[178:179], off
	v_lshl_add_u64 v[178:179], s[44:45], 0, v[134:135]
	s_add_i32 m0, s37, 0xe000
	s_nop 0
	global_load_lds_dwordx4 v[178:179], off
	ds_read_b128 v[140:143], v147
	ds_read_b128 v[150:153], v147 offset:1024
	ds_read_b128 v[154:157], v147 offset:2048
	ds_read_b128 v[158:161], v147 offset:3072
	ds_read_b128 v[162:165], v148
	ds_read_b128 v[166:169], v148 offset:1024
	ds_read_b128 v[170:173], v148 offset:2048
	ds_read_b128 v[174:177], v148 offset:3072
	ds_read_b128 v[184:187], v149
	ds_read_b128 v[188:191], v149 offset:1024
	ds_read_b128 v[192:195], v149 offset:2048
	ds_read_b128 v[196:199], v149 offset:3072
	ds_read_b128 v[200:203], v149 offset:4096
	ds_read_b128 v[204:207], v149 offset:5120
	ds_read_b128 v[208:211], v149 offset:6144
	ds_read_b128 v[212:215], v149 offset:7168
	s_waitcnt vmcnt(8)
	s_waitcnt lgkmcnt(0)
	s_barrier
	s_setprio 1
	s_waitcnt lgkmcnt(0)
	v_mfma_f32_16x16x32_bf16 v[124:127], v[140:143], v[184:187], v[124:127]
	v_mfma_f32_16x16x32_bf16 v[124:127], v[150:153], v[188:191], v[124:127]
	v_mfma_f32_16x16x32_bf16 v[120:123], v[154:157], v[184:187], v[120:123]
	v_mfma_f32_16x16x32_bf16 v[120:123], v[158:161], v[188:191], v[120:123]
	v_mfma_f32_16x16x32_bf16 v[108:111], v[140:143], v[192:195], v[108:111]
	v_mfma_f32_16x16x32_bf16 v[108:111], v[150:153], v[196:199], v[108:111]
	v_mfma_f32_16x16x32_bf16 v[104:107], v[154:157], v[192:195], v[104:107]
	v_mfma_f32_16x16x32_bf16 v[104:107], v[158:161], v[196:199], v[104:107]
	v_mfma_f32_16x16x32_bf16 v[92:95], v[140:143], v[200:203], v[92:95]
	v_mfma_f32_16x16x32_bf16 v[92:95], v[150:153], v[204:207], v[92:95]
	v_mfma_f32_16x16x32_bf16 v[88:91], v[154:157], v[200:203], v[88:91]
	v_mfma_f32_16x16x32_bf16 v[88:91], v[158:161], v[204:207], v[88:91]
	v_mfma_f32_16x16x32_bf16 v[76:79], v[140:143], v[208:211], v[76:79]
	v_mfma_f32_16x16x32_bf16 v[76:79], v[150:153], v[212:215], v[76:79]
	v_mfma_f32_16x16x32_bf16 v[72:75], v[154:157], v[208:211], v[72:75]
	v_mfma_f32_16x16x32_bf16 v[72:75], v[158:161], v[212:215], v[72:75]
	v_mfma_f32_16x16x32_bf16 v[116:119], v[162:165], v[184:187], v[116:119]
	v_mfma_f32_16x16x32_bf16 v[116:119], v[166:169], v[188:191], v[116:119]
	v_mfma_f32_16x16x32_bf16 v[112:115], v[170:173], v[184:187], v[112:115]
	v_mfma_f32_16x16x32_bf16 v[112:115], v[174:177], v[188:191], v[112:115]
	v_mfma_f32_16x16x32_bf16 v[100:103], v[162:165], v[192:195], v[100:103]
	v_mfma_f32_16x16x32_bf16 v[100:103], v[166:169], v[196:199], v[100:103]
	v_mfma_f32_16x16x32_bf16 v[96:99], v[170:173], v[192:195], v[96:99]
	v_mfma_f32_16x16x32_bf16 v[96:99], v[174:177], v[196:199], v[96:99]
	v_mfma_f32_16x16x32_bf16 v[84:87], v[162:165], v[200:203], v[84:87]
	v_mfma_f32_16x16x32_bf16 v[84:87], v[166:169], v[204:207], v[84:87]
	v_mfma_f32_16x16x32_bf16 v[80:83], v[170:173], v[200:203], v[80:83]
	v_mfma_f32_16x16x32_bf16 v[80:83], v[174:177], v[204:207], v[80:83]
	v_mfma_f32_16x16x32_bf16 v[68:71], v[162:165], v[208:211], v[68:71]
	v_mfma_f32_16x16x32_bf16 v[68:71], v[166:169], v[212:215], v[68:71]
	v_mfma_f32_16x16x32_bf16 v[64:67], v[170:173], v[208:211], v[64:67]
	v_mfma_f32_16x16x32_bf16 v[64:67], v[174:177], v[212:215], v[64:67]
	s_setprio 0
	s_barrier
	s_add_i32 s18, s62, s54
	v_lshl_add_u64 v[178:179], s[46:47], 0, v[130:131]
	s_mov_b32 m0, s18
	s_nop 0
	global_load_lds_dwordx4 v[178:179], off
	s_add_i32 m0, s18, 0x2000
	s_add_u32 s72, s46, 0x40000
	v_lshl_add_u64 v[216:217], s[46:47], 0, v[128:129]
	s_addc_u32 s73, s47, 0
	s_add_i32 s18, s63, s54
	global_load_lds_dwordx4 v[216:217], off
	v_lshl_add_u64 v[218:219], s[72:73], 0, v[130:131]
	s_mov_b32 m0, s18
	v_lshl_add_u64 v[220:221], s[48:49], 0, v[128:129]
	global_load_lds_dwordx4 v[218:219], off
	v_lshl_add_u64 v[218:219], s[72:73], 0, v[128:129]
	s_add_i32 m0, s18, 0x2000
	s_nop 0
	global_load_lds_dwordx4 v[218:219], off
	v_lshl_add_u64 v[218:219], s[48:49], 0, v[130:131]
	s_mov_b32 m0, s37
	s_nop 0
	global_load_lds_dwordx4 v[218:219], off
	s_mov_b32 m0, s56
	s_nop 0
	global_load_lds_dwordx4 v[220:221], off
	ds_read_b128 v[184:187], v149 offset:16384
	ds_read_b128 v[188:191], v149 offset:17408
	ds_read_b128 v[192:195], v149 offset:18432
	ds_read_b128 v[196:199], v149 offset:19456
	ds_read_b128 v[200:203], v149 offset:20480
	ds_read_b128 v[204:207], v149 offset:21504
	ds_read_b128 v[208:211], v149 offset:22528
	ds_read_b128 v[212:215], v149 offset:23552
	s_waitcnt vmcnt(8)
	s_waitcnt lgkmcnt(0)
	s_barrier
	s_setprio 1
	s_waitcnt lgkmcnt(0)
	v_mfma_f32_16x16x32_bf16 v[60:63], v[140:143], v[184:187], v[60:63]
	v_mfma_f32_16x16x32_bf16 v[60:63], v[150:153], v[188:191], v[60:63]
	v_mfma_f32_16x16x32_bf16 v[56:59], v[154:157], v[184:187], v[56:59]
	v_mfma_f32_16x16x32_bf16 v[56:59], v[158:161], v[188:191], v[56:59]
	v_mfma_f32_16x16x32_bf16 v[44:47], v[140:143], v[192:195], v[44:47]
	v_mfma_f32_16x16x32_bf16 v[44:47], v[150:153], v[196:199], v[44:47]
	v_mfma_f32_16x16x32_bf16 v[40:43], v[154:157], v[192:195], v[40:43]
	v_mfma_f32_16x16x32_bf16 v[40:43], v[158:161], v[196:199], v[40:43]
	v_mfma_f32_16x16x32_bf16 v[28:31], v[140:143], v[200:203], v[28:31]
	v_mfma_f32_16x16x32_bf16 v[28:31], v[150:153], v[204:207], v[28:31]
	v_mfma_f32_16x16x32_bf16 v[24:27], v[154:157], v[200:203], v[24:27]
	v_mfma_f32_16x16x32_bf16 v[24:27], v[158:161], v[204:207], v[24:27]
	v_mfma_f32_16x16x32_bf16 v[12:15], v[140:143], v[208:211], v[12:15]
	v_mfma_f32_16x16x32_bf16 v[12:15], v[150:153], v[212:215], v[12:15]
	v_mfma_f32_16x16x32_bf16 v[8:11], v[154:157], v[208:211], v[8:11]
	v_mfma_f32_16x16x32_bf16 v[8:11], v[158:161], v[212:215], v[8:11]
	v_mfma_f32_16x16x32_bf16 v[52:55], v[162:165], v[184:187], v[52:55]
	v_mfma_f32_16x16x32_bf16 v[52:55], v[166:169], v[188:191], v[52:55]
	v_mfma_f32_16x16x32_bf16 v[48:51], v[170:173], v[184:187], v[48:51]
	v_mfma_f32_16x16x32_bf16 v[48:51], v[174:177], v[188:191], v[48:51]
	v_mfma_f32_16x16x32_bf16 v[36:39], v[162:165], v[192:195], v[36:39]
	v_mfma_f32_16x16x32_bf16 v[36:39], v[166:169], v[196:199], v[36:39]
	v_mfma_f32_16x16x32_bf16 v[32:35], v[170:173], v[192:195], v[32:35]
	v_mfma_f32_16x16x32_bf16 v[32:35], v[174:177], v[196:199], v[32:35]
	v_mfma_f32_16x16x32_bf16 v[20:23], v[162:165], v[200:203], v[20:23]
	v_mfma_f32_16x16x32_bf16 v[20:23], v[166:169], v[204:207], v[20:23]
	v_mfma_f32_16x16x32_bf16 v[16:19], v[170:173], v[200:203], v[16:19]
	v_mfma_f32_16x16x32_bf16 v[16:19], v[174:177], v[204:207], v[16:19]
	v_mfma_f32_16x16x32_bf16 v[4:7], v[162:165], v[208:211], v[4:7]
	v_mfma_f32_16x16x32_bf16 v[4:7], v[166:169], v[212:215], v[4:7]
	v_mfma_f32_16x16x32_bf16 v[0:3], v[170:173], v[208:211], v[0:3]
	v_mfma_f32_16x16x32_bf16 v[0:3], v[174:177], v[212:215], v[0:3]
	s_setprio 0
	s_barrier
.Lmid_gemm0:
	s_add_i32 s18, 0, 0x18000
	s_add_i32 s19, 0, 0x1c000
	v_add_u32_e32 v158, s18, v145
	v_add_u32_e32 v174, s19, v145
	s_add_u32 s48, s48, 0x40000
	s_addc_u32 s49, s49, 0
	s_mov_b32 m0, s57
	v_lshl_add_u64 v[222:223], s[48:49], 0, v[130:131]
	global_load_lds_dwordx4 v[222:223], off
	v_lshl_add_u64 v[222:223], s[48:49], 0, v[128:129]
	s_mov_b32 m0, s58
	s_nop 0
	global_load_lds_dwordx4 v[222:223], off
	ds_read_b128 v[140:143], v158
	ds_read_b128 v[150:153], v158 offset:1024
	ds_read_b128 v[154:157], v158 offset:2048
	ds_read_b128 v[158:161], v158 offset:3072
	ds_read_b128 v[162:165], v174
	ds_read_b128 v[166:169], v174 offset:1024
	ds_read_b128 v[170:173], v174 offset:2048
	ds_read_b128 v[174:177], v174 offset:3072
	ds_read_b128 v[184:187], v149 offset:32768
	ds_read_b128 v[188:191], v149 offset:33792
	ds_read_b128 v[192:195], v149 offset:34816
	ds_read_b128 v[196:199], v149 offset:35840
	ds_read_b128 v[200:203], v149 offset:36864
	ds_read_b128 v[204:207], v149 offset:37888
	ds_read_b128 v[208:211], v149 offset:38912
	ds_read_b128 v[212:215], v149 offset:39936
	s_waitcnt vmcnt(8)
	s_waitcnt lgkmcnt(0)
	s_barrier
	s_setprio 1
	s_waitcnt lgkmcnt(0)
	v_mfma_f32_16x16x32_bf16 v[124:127], v[140:143], v[184:187], v[124:127]
	v_mfma_f32_16x16x32_bf16 v[124:127], v[150:153], v[188:191], v[124:127]
	v_mfma_f32_16x16x32_bf16 v[120:123], v[154:157], v[184:187], v[120:123]
	v_mfma_f32_16x16x32_bf16 v[120:123], v[158:161], v[188:191], v[120:123]
	v_mfma_f32_16x16x32_bf16 v[108:111], v[140:143], v[192:195], v[108:111]
	v_mfma_f32_16x16x32_bf16 v[108:111], v[150:153], v[196:199], v[108:111]
	v_mfma_f32_16x16x32_bf16 v[104:107], v[154:157], v[192:195], v[104:107]
	v_mfma_f32_16x16x32_bf16 v[104:107], v[158:161], v[196:199], v[104:107]
	v_mfma_f32_16x16x32_bf16 v[92:95], v[140:143], v[200:203], v[92:95]
	v_mfma_f32_16x16x32_bf16 v[92:95], v[150:153], v[204:207], v[92:95]
	v_mfma_f32_16x16x32_bf16 v[88:91], v[154:157], v[200:203], v[88:91]
	v_mfma_f32_16x16x32_bf16 v[88:91], v[158:161], v[204:207], v[88:91]
	v_mfma_f32_16x16x32_bf16 v[76:79], v[140:143], v[208:211], v[76:79]
	v_mfma_f32_16x16x32_bf16 v[76:79], v[150:153], v[212:215], v[76:79]
	v_mfma_f32_16x16x32_bf16 v[72:75], v[154:157], v[208:211], v[72:75]
	v_mfma_f32_16x16x32_bf16 v[72:75], v[158:161], v[212:215], v[72:75]
	v_mfma_f32_16x16x32_bf16 v[116:119], v[162:165], v[184:187], v[116:119]
	v_mfma_f32_16x16x32_bf16 v[116:119], v[166:169], v[188:191], v[116:119]
	v_mfma_f32_16x16x32_bf16 v[112:115], v[170:173], v[184:187], v[112:115]
	v_mfma_f32_16x16x32_bf16 v[112:115], v[174:177], v[188:191], v[112:115]
	v_mfma_f32_16x16x32_bf16 v[100:103], v[162:165], v[192:195], v[100:103]
	v_mfma_f32_16x16x32_bf16 v[100:103], v[166:169], v[196:199], v[100:103]
	v_mfma_f32_16x16x32_bf16 v[96:99], v[170:173], v[192:195], v[96:99]
	v_mfma_f32_16x16x32_bf16 v[96:99], v[174:177], v[196:199], v[96:99]
	v_mfma_f32_16x16x32_bf16 v[84:87], v[162:165], v[200:203], v[84:87]
	v_mfma_f32_16x16x32_bf16 v[84:87], v[166:169], v[204:207], v[84:87]
	v_mfma_f32_16x16x32_bf16 v[80:83], v[170:173], v[200:203], v[80:83]
	v_mfma_f32_16x16x32_bf16 v[80:83], v[174:177], v[204:207], v[80:83]
	v_mfma_f32_16x16x32_bf16 v[68:71], v[162:165], v[208:211], v[68:71]
	v_mfma_f32_16x16x32_bf16 v[68:71], v[166:169], v[212:215], v[68:71]
	v_mfma_f32_16x16x32_bf16 v[64:67], v[170:173], v[208:211], v[64:67]
	v_mfma_f32_16x16x32_bf16 v[64:67], v[174:177], v[212:215], v[64:67]
	s_setprio 0
	s_barrier
	s_add_i32 s18, s18, s54
	v_lshl_add_u64 v[178:179], v[178:179], 0, s[6:7]
	s_mov_b32 m0, s18
	s_nop 0
	global_load_lds_dwordx4 v[178:179], off
	s_add_i32 m0, s18, 0x2000
	s_add_u32 s46, s46, 0x40080
	v_lshl_add_u64 v[178:179], v[216:217], 0, s[6:7]
	s_addc_u32 s47, s47, 0
	s_add_i32 s18, s19, s54
	global_load_lds_dwordx4 v[178:179], off
	v_lshl_add_u64 v[178:179], s[46:47], 0, v[130:131]
	s_mov_b32 m0, s18
	s_nop 0
	global_load_lds_dwordx4 v[178:179], off
	v_lshl_add_u64 v[178:179], s[46:47], 0, v[128:129]
	s_add_i32 m0, s18, 0x2000
	s_nop 0
	global_load_lds_dwordx4 v[178:179], off
	v_lshl_add_u64 v[178:179], v[218:219], 0, s[6:7]
	s_mov_b32 m0, s60
	s_nop 0
	global_load_lds_dwordx4 v[178:179], off
	v_lshl_add_u64 v[178:179], v[220:221], 0, s[6:7]
	s_mov_b32 m0, s61
	s_nop 0
	global_load_lds_dwordx4 v[178:179], off
	ds_read_b128 v[184:187], v149 offset:49152
	ds_read_b128 v[188:191], v149 offset:50176
	ds_read_b128 v[192:195], v149 offset:51200
	ds_read_b128 v[196:199], v149 offset:52224
	ds_read_b128 v[200:203], v149 offset:53248
	ds_read_b128 v[204:207], v149 offset:54272
	ds_read_b128 v[208:211], v149 offset:55296
	ds_read_b128 v[212:215], v149 offset:56320
	s_waitcnt vmcnt(8)
	s_waitcnt lgkmcnt(0)
	s_barrier
	s_setprio 1
	s_waitcnt lgkmcnt(0)
	v_mfma_f32_16x16x32_bf16 v[60:63], v[140:143], v[184:187], v[60:63]
	v_mfma_f32_16x16x32_bf16 v[60:63], v[150:153], v[188:191], v[60:63]
	v_mfma_f32_16x16x32_bf16 v[56:59], v[154:157], v[184:187], v[56:59]
	v_mfma_f32_16x16x32_bf16 v[56:59], v[158:161], v[188:191], v[56:59]
	v_mfma_f32_16x16x32_bf16 v[44:47], v[140:143], v[192:195], v[44:47]
	v_mfma_f32_16x16x32_bf16 v[44:47], v[150:153], v[196:199], v[44:47]
	v_mfma_f32_16x16x32_bf16 v[40:43], v[154:157], v[192:195], v[40:43]
	v_mfma_f32_16x16x32_bf16 v[40:43], v[158:161], v[196:199], v[40:43]
	v_mfma_f32_16x16x32_bf16 v[28:31], v[140:143], v[200:203], v[28:31]
	v_mfma_f32_16x16x32_bf16 v[28:31], v[150:153], v[204:207], v[28:31]
	v_mfma_f32_16x16x32_bf16 v[24:27], v[154:157], v[200:203], v[24:27]
	v_mfma_f32_16x16x32_bf16 v[24:27], v[158:161], v[204:207], v[24:27]
	v_mfma_f32_16x16x32_bf16 v[12:15], v[140:143], v[208:211], v[12:15]
	v_mfma_f32_16x16x32_bf16 v[12:15], v[150:153], v[212:215], v[12:15]
	v_mfma_f32_16x16x32_bf16 v[8:11], v[154:157], v[208:211], v[8:11]
	v_mfma_f32_16x16x32_bf16 v[8:11], v[158:161], v[212:215], v[8:11]
	v_mfma_f32_16x16x32_bf16 v[52:55], v[162:165], v[184:187], v[52:55]
	v_mfma_f32_16x16x32_bf16 v[52:55], v[166:169], v[188:191], v[52:55]
	v_mfma_f32_16x16x32_bf16 v[48:51], v[170:173], v[184:187], v[48:51]
	v_mfma_f32_16x16x32_bf16 v[48:51], v[174:177], v[188:191], v[48:51]
	v_mfma_f32_16x16x32_bf16 v[36:39], v[162:165], v[192:195], v[36:39]
	v_mfma_f32_16x16x32_bf16 v[36:39], v[166:169], v[196:199], v[36:39]
	v_mfma_f32_16x16x32_bf16 v[32:35], v[170:173], v[192:195], v[32:35]
	v_mfma_f32_16x16x32_bf16 v[32:35], v[174:177], v[196:199], v[32:35]
	v_mfma_f32_16x16x32_bf16 v[20:23], v[162:165], v[200:203], v[20:23]
	v_mfma_f32_16x16x32_bf16 v[20:23], v[166:169], v[204:207], v[20:23]
	v_mfma_f32_16x16x32_bf16 v[16:19], v[170:173], v[200:203], v[16:19]
	v_mfma_f32_16x16x32_bf16 v[16:19], v[174:177], v[204:207], v[16:19]
	v_mfma_f32_16x16x32_bf16 v[4:7], v[162:165], v[208:211], v[4:7]
	v_mfma_f32_16x16x32_bf16 v[4:7], v[166:169], v[212:215], v[4:7]
	v_mfma_f32_16x16x32_bf16 v[0:3], v[170:173], v[208:211], v[0:3]
	v_mfma_f32_16x16x32_bf16 v[0:3], v[174:177], v[212:215], v[0:3]
	s_setprio 0
	s_barrier
	s_add_i32 s70, s70, 2
	s_add_u32 s44, s44, 0x100
	s_addc_u32 s45, s45, 0
	s_add_u32 s68, s68, 0x100
	s_addc_u32 s69, s69, 0
	s_cmp_gt_u32 s70, 13
	s_cbranch_scc0 .LBB0_184
	s_and_b64 vcc, exec, s[8:9]
	s_cbranch_vccz .LBB0_187
	s_barrier

.LBB0_263:
	s_add_u32 s84, s54, 0x100
	s_addc_u32 s85, s55, 0
	s_mov_b32 s86, -2
	ds_read_b128 v[152:155], v149
	ds_read_b128 v[156:159], v149 offset:1024
	ds_read_b128 v[160:163], v149 offset:2048
	ds_read_b128 v[164:167], v149 offset:3072
	ds_read_b128 v[168:171], v150
	ds_read_b128 v[172:175], v150 offset:1024
	ds_read_b128 v[176:179], v150 offset:2048
	ds_read_b128 v[184:187], v150 offset:3072
	s_add_u32 s54, s52, 0x100
	s_addc_u32 s55, s53, 0
	s_cmp_eq_u32 s86, 40
	s_cselect_b32 s59, s7, s55
	s_cselect_b32 s58, s6, s54
	s_cselect_b32 s57, s49, s85
	s_cselect_b32 s56, s48, s84
	v_lshl_add_u64 v[144:145], s[52:53], 0, v[136:137]
	s_add_i32 m0, s63, 0xc000
	ds_read_b128 v[188:191], v151
	ds_read_b128 v[192:195], v151 offset:1024
	ds_read_b128 v[196:199], v151 offset:2048
	ds_read_b128 v[200:203], v151 offset:3072
	ds_read_b128 v[204:207], v151 offset:4096
	ds_read_b128 v[208:211], v151 offset:5120
	ds_read_b128 v[212:215], v151 offset:6144
	ds_read_b128 v[216:219], v151 offset:7168
	global_load_lds_dwordx4 v[144:145], off
	v_lshl_add_u64 v[144:145], s[52:53], 0, v[138:139]
	s_add_i32 m0, s63, 0xe000
	s_nop 0
	global_load_lds_dwordx4 v[144:145], off
	s_waitcnt vmcnt(8)
	s_waitcnt lgkmcnt(0)
	s_barrier
	s_setprio 1
	s_waitcnt lgkmcnt(0)
	v_mfma_f32_16x16x32_bf16 v[124:127], v[152:155], v[188:191], 0
	v_mfma_f32_16x16x32_bf16 v[124:127], v[156:159], v[192:195], v[124:127]
	v_mfma_f32_16x16x32_bf16 v[120:123], v[160:163], v[188:191], 0
	v_mfma_f32_16x16x32_bf16 v[120:123], v[164:167], v[192:195], v[120:123]
	v_mfma_f32_16x16x32_bf16 v[116:119], v[152:155], v[196:199], 0
	v_mfma_f32_16x16x32_bf16 v[116:119], v[156:159], v[200:203], v[116:119]
	v_mfma_f32_16x16x32_bf16 v[108:111], v[160:163], v[196:199], 0
	v_mfma_f32_16x16x32_bf16 v[108:111], v[164:167], v[200:203], v[108:111]
	v_mfma_f32_16x16x32_bf16 v[100:103], v[152:155], v[204:207], 0
	v_mfma_f32_16x16x32_bf16 v[100:103], v[156:159], v[208:211], v[100:103]
	v_mfma_f32_16x16x32_bf16 v[92:95], v[160:163], v[204:207], 0
	v_mfma_f32_16x16x32_bf16 v[92:95], v[164:167], v[208:211], v[92:95]
	v_mfma_f32_16x16x32_bf16 v[84:87], v[152:155], v[212:215], 0
	v_mfma_f32_16x16x32_bf16 v[84:87], v[156:159], v[216:219], v[84:87]
	v_mfma_f32_16x16x32_bf16 v[76:79], v[160:163], v[212:215], 0
	v_mfma_f32_16x16x32_bf16 v[76:79], v[164:167], v[216:219], v[76:79]
	v_mfma_f32_16x16x32_bf16 v[112:115], v[168:171], v[188:191], 0
	v_mfma_f32_16x16x32_bf16 v[112:115], v[172:175], v[192:195], v[112:115]
	v_mfma_f32_16x16x32_bf16 v[104:107], v[176:179], v[188:191], 0
	v_mfma_f32_16x16x32_bf16 v[104:107], v[184:187], v[192:195], v[104:107]
	v_mfma_f32_16x16x32_bf16 v[96:99], v[168:171], v[196:199], 0
	v_mfma_f32_16x16x32_bf16 v[96:99], v[172:175], v[200:203], v[96:99]
	v_mfma_f32_16x16x32_bf16 v[88:91], v[176:179], v[196:199], 0
	v_mfma_f32_16x16x32_bf16 v[88:91], v[184:187], v[200:203], v[88:91]
	v_mfma_f32_16x16x32_bf16 v[80:83], v[168:171], v[204:207], 0
	v_mfma_f32_16x16x32_bf16 v[80:83], v[172:175], v[208:211], v[80:83]
	v_mfma_f32_16x16x32_bf16 v[72:75], v[176:179], v[204:207], 0
	v_mfma_f32_16x16x32_bf16 v[72:75], v[184:187], v[208:211], v[72:75]
	v_mfma_f32_16x16x32_bf16 v[68:71], v[168:171], v[212:215], 0
	v_mfma_f32_16x16x32_bf16 v[68:71], v[172:175], v[216:219], v[68:71]
	v_mfma_f32_16x16x32_bf16 v[64:67], v[176:179], v[212:215], 0
	v_mfma_f32_16x16x32_bf16 v[64:67], v[184:187], v[216:219], v[64:67]
	s_setprio 0
	s_barrier
	s_add_i32 s18, s70, s62
	v_lshl_add_u64 v[144:145], s[56:57], 0, v[130:131]
	s_mov_b32 m0, s18
	s_nop 0
	global_load_lds_dwordx4 v[144:145], off
	s_add_i32 m0, s18, 0x2000
	s_add_u32 s52, s56, 0xb0000
	v_lshl_add_u64 v[220:221], s[56:57], 0, v[134:135]
	s_addc_u32 s53, s57, 0
	s_add_i32 s18, s71, s62
	global_load_lds_dwordx4 v[220:221], off
	v_lshl_add_u64 v[222:223], s[52:53], 0, v[130:131]
	s_mov_b32 m0, s18
	v_lshl_add_u64 v[224:225], s[58:59], 0, v[132:133]
	global_load_lds_dwordx4 v[222:223], off
	v_lshl_add_u64 v[222:223], s[52:53], 0, v[134:135]
	s_add_i32 m0, s18, 0x2000
	s_nop 0
	global_load_lds_dwordx4 v[222:223], off
	v_lshl_add_u64 v[222:223], s[58:59], 0, v[128:129]
	s_mov_b32 m0, s63
	s_nop 0
	global_load_lds_dwordx4 v[222:223], off
	s_mov_b32 m0, s64
	s_nop 0
	global_load_lds_dwordx4 v[224:225], off
	ds_read_b128 v[188:191], v151 offset:16384
	ds_read_b128 v[192:195], v151 offset:17408
	ds_read_b128 v[196:199], v151 offset:18432
	ds_read_b128 v[200:203], v151 offset:19456
	ds_read_b128 v[204:207], v151 offset:20480
	ds_read_b128 v[208:211], v151 offset:21504
	ds_read_b128 v[212:215], v151 offset:22528
	ds_read_b128 v[216:219], v151 offset:23552
	s_waitcnt vmcnt(8)
	s_waitcnt lgkmcnt(0)
	s_barrier
	s_setprio 1
	s_waitcnt lgkmcnt(0)
	v_mfma_f32_16x16x32_bf16 v[60:63], v[152:155], v[188:191], 0
	v_mfma_f32_16x16x32_bf16 v[60:63], v[156:159], v[192:195], v[60:63]
	v_mfma_f32_16x16x32_bf16 v[56:59], v[160:163], v[188:191], 0
	v_mfma_f32_16x16x32_bf16 v[56:59], v[164:167], v[192:195], v[56:59]
	v_mfma_f32_16x16x32_bf16 v[52:55], v[152:155], v[196:199], 0
	v_mfma_f32_16x16x32_bf16 v[52:55], v[156:159], v[200:203], v[52:55]
	v_mfma_f32_16x16x32_bf16 v[44:47], v[160:163], v[196:199], 0
	v_mfma_f32_16x16x32_bf16 v[44:47], v[164:167], v[200:203], v[44:47]
	v_mfma_f32_16x16x32_bf16 v[36:39], v[152:155], v[204:207], 0
	v_mfma_f32_16x16x32_bf16 v[36:39], v[156:159], v[208:211], v[36:39]
	v_mfma_f32_16x16x32_bf16 v[28:31], v[160:163], v[204:207], 0
	v_mfma_f32_16x16x32_bf16 v[28:31], v[164:167], v[208:211], v[28:31]
	v_mfma_f32_16x16x32_bf16 v[20:23], v[152:155], v[212:215], 0
	v_mfma_f32_16x16x32_bf16 v[20:23], v[156:159], v[216:219], v[20:23]
	v_mfma_f32_16x16x32_bf16 v[12:15], v[160:163], v[212:215], 0
	v_mfma_f32_16x16x32_bf16 v[12:15], v[164:167], v[216:219], v[12:15]
	v_mfma_f32_16x16x32_bf16 v[48:51], v[168:171], v[188:191], 0
	v_mfma_f32_16x16x32_bf16 v[48:51], v[172:175], v[192:195], v[48:51]
	v_mfma_f32_16x16x32_bf16 v[40:43], v[176:179], v[188:191], 0
	v_mfma_f32_16x16x32_bf16 v[40:43], v[184:187], v[192:195], v[40:43]
	v_mfma_f32_16x16x32_bf16 v[32:35], v[168:171], v[196:199], 0
	v_mfma_f32_16x16x32_bf16 v[32:35], v[172:175], v[200:203], v[32:35]
	v_mfma_f32_16x16x32_bf16 v[24:27], v[176:179], v[196:199], 0
	v_mfma_f32_16x16x32_bf16 v[24:27], v[184:187], v[200:203], v[24:27]
	v_mfma_f32_16x16x32_bf16 v[16:19], v[168:171], v[204:207], 0
	v_mfma_f32_16x16x32_bf16 v[16:19], v[172:175], v[208:211], v[16:19]
	v_mfma_f32_16x16x32_bf16 v[8:11], v[176:179], v[204:207], 0
	v_mfma_f32_16x16x32_bf16 v[8:11], v[184:187], v[208:211], v[8:11]
	v_mfma_f32_16x16x32_bf16 v[4:7], v[168:171], v[212:215], 0
	v_mfma_f32_16x16x32_bf16 v[4:7], v[172:175], v[216:219], v[4:7]
	v_mfma_f32_16x16x32_bf16 v[0:3], v[176:179], v[212:215], 0
	v_mfma_f32_16x16x32_bf16 v[0:3], v[184:187], v[216:219], v[0:3]
	s_setprio 0
	s_barrier
	s_branch .Lmid_gemm1
.LBB0_264:
	s_add_u32 s54, s52, 0x100
	s_addc_u32 s55, s53, 0
	s_cmp_eq_u32 s86, 40
	s_cselect_b32 s59, s7, s55
	s_cselect_b32 s58, s6, s54
	s_cselect_b32 s57, s49, s85
	s_cselect_b32 s56, s48, s84
	v_lshl_add_u64 v[144:145], s[52:53], 0, v[136:137]
	s_add_i32 m0, s63, 0xc000
	s_nop 0
	global_load_lds_dwordx4 v[144:145], off
	v_lshl_add_u64 v[144:145], s[52:53], 0, v[138:139]
	s_add_i32 m0, s63, 0xe000
	s_nop 0
	global_load_lds_dwordx4 v[144:145], off
	ds_read_b128 v[152:155], v149
	ds_read_b128 v[156:159], v149 offset:1024
	ds_read_b128 v[160:163], v149 offset:2048
	ds_read_b128 v[164:167], v149 offset:3072
	ds_read_b128 v[168:171], v150
	ds_read_b128 v[172:175], v150 offset:1024
	ds_read_b128 v[176:179], v150 offset:2048
	ds_read_b128 v[184:187], v150 offset:3072
	ds_read_b128 v[188:191], v151
	ds_read_b128 v[192:195], v151 offset:1024
	ds_read_b128 v[196:199], v151 offset:2048
	ds_read_b128 v[200:203], v151 offset:3072
	ds_read_b128 v[204:207], v151 offset:4096
	ds_read_b128 v[208:211], v151 offset:5120
	ds_read_b128 v[212:215], v151 offset:6144
	ds_read_b128 v[216:219], v151 offset:7168
	s_waitcnt vmcnt(8)
	s_waitcnt lgkmcnt(0)
	s_barrier
	s_setprio 1
	s_waitcnt lgkmcnt(0)
	v_mfma_f32_16x16x32_bf16 v[124:127], v[152:155], v[188:191], v[124:127]
	v_mfma_f32_16x16x32_bf16 v[124:127], v[156:159], v[192:195], v[124:127]
	v_mfma_f32_16x16x32_bf16 v[120:123], v[160:163], v[188:191], v[120:123]
	v_mfma_f32_16x16x32_bf16 v[120:123], v[164:167], v[192:195], v[120:123]
	v_mfma_f32_16x16x32_bf16 v[116:119], v[152:155], v[196:199], v[116:119]
	v_mfma_f32_16x16x32_bf16 v[116:119], v[156:159], v[200:203], v[116:119]
	v_mfma_f32_16x16x32_bf16 v[108:111], v[160:163], v[196:199], v[108:111]
	v_mfma_f32_16x16x32_bf16 v[108:111], v[164:167], v[200:203], v[108:111]
	v_mfma_f32_16x16x32_bf16 v[100:103], v[152:155], v[204:207], v[100:103]
	v_mfma_f32_16x16x32_bf16 v[100:103], v[156:159], v[208:211], v[100:103]
	v_mfma_f32_16x16x32_bf16 v[92:95], v[160:163], v[204:207], v[92:95]
	v_mfma_f32_16x16x32_bf16 v[92:95], v[164:167], v[208:211], v[92:95]
	v_mfma_f32_16x16x32_bf16 v[84:87], v[152:155], v[212:215], v[84:87]
	v_mfma_f32_16x16x32_bf16 v[84:87], v[156:159], v[216:219], v[84:87]
	v_mfma_f32_16x16x32_bf16 v[76:79], v[160:163], v[212:215], v[76:79]
	v_mfma_f32_16x16x32_bf16 v[76:79], v[164:167], v[216:219], v[76:79]
	v_mfma_f32_16x16x32_bf16 v[112:115], v[168:171], v[188:191], v[112:115]
	v_mfma_f32_16x16x32_bf16 v[112:115], v[172:175], v[192:195], v[112:115]
	v_mfma_f32_16x16x32_bf16 v[104:107], v[176:179], v[188:191], v[104:107]
	v_mfma_f32_16x16x32_bf16 v[104:107], v[184:187], v[192:195], v[104:107]
	v_mfma_f32_16x16x32_bf16 v[96:99], v[168:171], v[196:199], v[96:99]
	v_mfma_f32_16x16x32_bf16 v[96:99], v[172:175], v[200:203], v[96:99]
	v_mfma_f32_16x16x32_bf16 v[88:91], v[176:179], v[196:199], v[88:91]
	v_mfma_f32_16x16x32_bf16 v[88:91], v[184:187], v[200:203], v[88:91]
	v_mfma_f32_16x16x32_bf16 v[80:83], v[168:171], v[204:207], v[80:83]
	v_mfma_f32_16x16x32_bf16 v[80:83], v[172:175], v[208:211], v[80:83]
	v_mfma_f32_16x16x32_bf16 v[72:75], v[176:179], v[204:207], v[72:75]
	v_mfma_f32_16x16x32_bf16 v[72:75], v[184:187], v[208:211], v[72:75]
	v_mfma_f32_16x16x32_bf16 v[68:71], v[168:171], v[212:215], v[68:71]
	v_mfma_f32_16x16x32_bf16 v[68:71], v[172:175], v[216:219], v[68:71]
	v_mfma_f32_16x16x32_bf16 v[64:67], v[176:179], v[212:215], v[64:67]
	v_mfma_f32_16x16x32_bf16 v[64:67], v[184:187], v[216:219], v[64:67]
	s_setprio 0
	s_barrier
	s_add_i32 s18, s70, s62
	v_lshl_add_u64 v[144:145], s[56:57], 0, v[130:131]
	s_mov_b32 m0, s18
	s_nop 0
	global_load_lds_dwordx4 v[144:145], off
	s_add_i32 m0, s18, 0x2000
	s_add_u32 s52, s56, 0xb0000
	v_lshl_add_u64 v[220:221], s[56:57], 0, v[134:135]
	s_addc_u32 s53, s57, 0
	s_add_i32 s18, s71, s62
	global_load_lds_dwordx4 v[220:221], off
	v_lshl_add_u64 v[222:223], s[52:53], 0, v[130:131]
	s_mov_b32 m0, s18
	v_lshl_add_u64 v[224:225], s[58:59], 0, v[132:133]
	global_load_lds_dwordx4 v[222:223], off
	v_lshl_add_u64 v[222:223], s[52:53], 0, v[134:135]
	s_add_i32 m0, s18, 0x2000
	s_nop 0
	global_load_lds_dwordx4 v[222:223], off
	v_lshl_add_u64 v[222:223], s[58:59], 0, v[128:129]
	s_mov_b32 m0, s63
	s_nop 0
	global_load_lds_dwordx4 v[222:223], off
	s_mov_b32 m0, s64
	s_nop 0
	global_load_lds_dwordx4 v[224:225], off
	ds_read_b128 v[188:191], v151 offset:16384
	ds_read_b128 v[192:195], v151 offset:17408
	ds_read_b128 v[196:199], v151 offset:18432
	ds_read_b128 v[200:203], v151 offset:19456
	ds_read_b128 v[204:207], v151 offset:20480
	ds_read_b128 v[208:211], v151 offset:21504
	ds_read_b128 v[212:215], v151 offset:22528
	ds_read_b128 v[216:219], v151 offset:23552
	s_waitcnt vmcnt(8)
	s_waitcnt lgkmcnt(0)
	s_barrier
	s_setprio 1
	s_waitcnt lgkmcnt(0)
	v_mfma_f32_16x16x32_bf16 v[60:63], v[152:155], v[188:191], v[60:63]
	v_mfma_f32_16x16x32_bf16 v[60:63], v[156:159], v[192:195], v[60:63]
	v_mfma_f32_16x16x32_bf16 v[56:59], v[160:163], v[188:191], v[56:59]
	v_mfma_f32_16x16x32_bf16 v[56:59], v[164:167], v[192:195], v[56:59]
	v_mfma_f32_16x16x32_bf16 v[52:55], v[152:155], v[196:199], v[52:55]
	v_mfma_f32_16x16x32_bf16 v[52:55], v[156:159], v[200:203], v[52:55]
	v_mfma_f32_16x16x32_bf16 v[44:47], v[160:163], v[196:199], v[44:47]
	v_mfma_f32_16x16x32_bf16 v[44:47], v[164:167], v[200:203], v[44:47]
	v_mfma_f32_16x16x32_bf16 v[36:39], v[152:155], v[204:207], v[36:39]
	v_mfma_f32_16x16x32_bf16 v[36:39], v[156:159], v[208:211], v[36:39]
	v_mfma_f32_16x16x32_bf16 v[28:31], v[160:163], v[204:207], v[28:31]
	v_mfma_f32_16x16x32_bf16 v[28:31], v[164:167], v[208:211], v[28:31]
	v_mfma_f32_16x16x32_bf16 v[20:23], v[152:155], v[212:215], v[20:23]
	v_mfma_f32_16x16x32_bf16 v[20:23], v[156:159], v[216:219], v[20:23]
	v_mfma_f32_16x16x32_bf16 v[12:15], v[160:163], v[212:215], v[12:15]
	v_mfma_f32_16x16x32_bf16 v[12:15], v[164:167], v[216:219], v[12:15]
	v_mfma_f32_16x16x32_bf16 v[48:51], v[168:171], v[188:191], v[48:51]
	v_mfma_f32_16x16x32_bf16 v[48:51], v[172:175], v[192:195], v[48:51]
	v_mfma_f32_16x16x32_bf16 v[40:43], v[176:179], v[188:191], v[40:43]
	v_mfma_f32_16x16x32_bf16 v[40:43], v[184:187], v[192:195], v[40:43]
	v_mfma_f32_16x16x32_bf16 v[32:35], v[168:171], v[196:199], v[32:35]
	v_mfma_f32_16x16x32_bf16 v[32:35], v[172:175], v[200:203], v[32:35]
	v_mfma_f32_16x16x32_bf16 v[24:27], v[176:179], v[196:199], v[24:27]
	v_mfma_f32_16x16x32_bf16 v[24:27], v[184:187], v[200:203], v[24:27]
	v_mfma_f32_16x16x32_bf16 v[16:19], v[168:171], v[204:207], v[16:19]
	v_mfma_f32_16x16x32_bf16 v[16:19], v[172:175], v[208:211], v[16:19]
	v_mfma_f32_16x16x32_bf16 v[8:11], v[176:179], v[204:207], v[8:11]
	v_mfma_f32_16x16x32_bf16 v[8:11], v[184:187], v[208:211], v[8:11]
	v_mfma_f32_16x16x32_bf16 v[4:7], v[168:171], v[212:215], v[4:7]
	v_mfma_f32_16x16x32_bf16 v[4:7], v[172:175], v[216:219], v[4:7]
	v_mfma_f32_16x16x32_bf16 v[0:3], v[176:179], v[212:215], v[0:3]
	v_mfma_f32_16x16x32_bf16 v[0:3], v[184:187], v[216:219], v[0:3]
	s_setprio 0
	s_barrier
.Lmid_gemm1:
	s_add_i32 s18, 0, 0x18000
	s_add_i32 s19, 0, 0x1c000
	v_add_u32_e32 v164, s18, v147
	v_add_u32_e32 v181, s19, v147
	s_add_u32 s52, s58, 0xb0000
	s_addc_u32 s53, s59, 0
	s_mov_b32 m0, s65
	v_lshl_add_u64 v[226:227], s[52:53], 0, v[128:129]
	global_load_lds_dwordx4 v[226:227], off
	v_lshl_add_u64 v[226:227], s[52:53], 0, v[132:133]
	s_mov_b32 m0, s66
	s_nop 0
	global_load_lds_dwordx4 v[226:227], off
	ds_read_b128 v[152:155], v164
	ds_read_b128 v[156:159], v164 offset:1024
	ds_read_b128 v[160:163], v164 offset:2048
	ds_read_b128 v[164:167], v164 offset:3072
	ds_read_b128 v[168:171], v181
	ds_read_b128 v[172:175], v181 offset:1024
	ds_read_b128 v[176:179], v181 offset:2048
	ds_read_b128 v[184:187], v181 offset:3072
	ds_read_b128 v[188:191], v151 offset:32768
	ds_read_b128 v[192:195], v151 offset:33792
	ds_read_b128 v[196:199], v151 offset:34816
	ds_read_b128 v[200:203], v151 offset:35840
	ds_read_b128 v[204:207], v151 offset:36864
	ds_read_b128 v[208:211], v151 offset:37888
	ds_read_b128 v[212:215], v151 offset:38912
	ds_read_b128 v[216:219], v151 offset:39936
	s_waitcnt vmcnt(8)
	s_waitcnt lgkmcnt(0)
	s_barrier
	s_setprio 1
	s_waitcnt lgkmcnt(0)
	v_mfma_f32_16x16x32_bf16 v[124:127], v[152:155], v[188:191], v[124:127]
	v_mfma_f32_16x16x32_bf16 v[124:127], v[156:159], v[192:195], v[124:127]
	v_mfma_f32_16x16x32_bf16 v[120:123], v[160:163], v[188:191], v[120:123]
	v_mfma_f32_16x16x32_bf16 v[120:123], v[164:167], v[192:195], v[120:123]
	v_mfma_f32_16x16x32_bf16 v[116:119], v[152:155], v[196:199], v[116:119]
	v_mfma_f32_16x16x32_bf16 v[116:119], v[156:159], v[200:203], v[116:119]
	v_mfma_f32_16x16x32_bf16 v[108:111], v[160:163], v[196:199], v[108:111]
	v_mfma_f32_16x16x32_bf16 v[108:111], v[164:167], v[200:203], v[108:111]
	v_mfma_f32_16x16x32_bf16 v[100:103], v[152:155], v[204:207], v[100:103]
	v_mfma_f32_16x16x32_bf16 v[100:103], v[156:159], v[208:211], v[100:103]
	v_mfma_f32_16x16x32_bf16 v[92:95], v[160:163], v[204:207], v[92:95]
	v_mfma_f32_16x16x32_bf16 v[92:95], v[164:167], v[208:211], v[92:95]
	v_mfma_f32_16x16x32_bf16 v[84:87], v[152:155], v[212:215], v[84:87]
	v_mfma_f32_16x16x32_bf16 v[84:87], v[156:159], v[216:219], v[84:87]
	v_mfma_f32_16x16x32_bf16 v[76:79], v[160:163], v[212:215], v[76:79]
	v_mfma_f32_16x16x32_bf16 v[76:79], v[164:167], v[216:219], v[76:79]
	v_mfma_f32_16x16x32_bf16 v[112:115], v[168:171], v[188:191], v[112:115]
	v_mfma_f32_16x16x32_bf16 v[112:115], v[172:175], v[192:195], v[112:115]
	v_mfma_f32_16x16x32_bf16 v[104:107], v[176:179], v[188:191], v[104:107]
	v_mfma_f32_16x16x32_bf16 v[104:107], v[184:187], v[192:195], v[104:107]
	v_mfma_f32_16x16x32_bf16 v[96:99], v[168:171], v[196:199], v[96:99]
	v_mfma_f32_16x16x32_bf16 v[96:99], v[172:175], v[200:203], v[96:99]
	v_mfma_f32_16x16x32_bf16 v[88:91], v[176:179], v[196:199], v[88:91]
	v_mfma_f32_16x16x32_bf16 v[88:91], v[184:187], v[200:203], v[88:91]
	v_mfma_f32_16x16x32_bf16 v[80:83], v[168:171], v[204:207], v[80:83]
	v_mfma_f32_16x16x32_bf16 v[80:83], v[172:175], v[208:211], v[80:83]
	v_mfma_f32_16x16x32_bf16 v[72:75], v[176:179], v[204:207], v[72:75]
	v_mfma_f32_16x16x32_bf16 v[72:75], v[184:187], v[208:211], v[72:75]
	v_mfma_f32_16x16x32_bf16 v[68:71], v[168:171], v[212:215], v[68:71]
	v_mfma_f32_16x16x32_bf16 v[68:71], v[172:175], v[216:219], v[68:71]
	v_mfma_f32_16x16x32_bf16 v[64:67], v[176:179], v[212:215], v[64:67]
	v_mfma_f32_16x16x32_bf16 v[64:67], v[184:187], v[216:219], v[64:67]
	s_setprio 0
	s_barrier
	s_add_i32 s18, s18, s62
	v_lshl_add_u64 v[144:145], v[144:145], 0, s[8:9]
	s_mov_b32 m0, s18
	s_nop 0
	global_load_lds_dwordx4 v[144:145], off
	s_add_i32 m0, s18, 0x2000
	s_add_u32 s52, s56, 0xb0080
	v_lshl_add_u64 v[144:145], v[220:221], 0, s[8:9]
	s_addc_u32 s53, s57, 0
	s_add_i32 s18, s19, s62
	global_load_lds_dwordx4 v[144:145], off
	v_lshl_add_u64 v[144:145], s[52:53], 0, v[130:131]
	s_mov_b32 m0, s18
	s_nop 0
	global_load_lds_dwordx4 v[144:145], off
	v_lshl_add_u64 v[144:145], s[52:53], 0, v[134:135]
	s_add_i32 m0, s18, 0x2000
	s_nop 0
	global_load_lds_dwordx4 v[144:145], off
	v_lshl_add_u64 v[144:145], v[222:223], 0, s[8:9]
	s_mov_b32 m0, s68
	s_nop 0
	global_load_lds_dwordx4 v[144:145], off
	v_lshl_add_u64 v[144:145], v[224:225], 0, s[8:9]
	s_mov_b32 m0, s69
	s_nop 0
	global_load_lds_dwordx4 v[144:145], off
	ds_read_b128 v[188:191], v151 offset:49152
	ds_read_b128 v[192:195], v151 offset:50176
	ds_read_b128 v[196:199], v151 offset:51200
	ds_read_b128 v[200:203], v151 offset:52224
	ds_read_b128 v[204:207], v151 offset:53248
	ds_read_b128 v[208:211], v151 offset:54272
	ds_read_b128 v[212:215], v151 offset:55296
	ds_read_b128 v[216:219], v151 offset:56320
	s_waitcnt vmcnt(8)
	s_waitcnt lgkmcnt(0)
	s_barrier
	s_setprio 1
	s_waitcnt lgkmcnt(0)
	v_mfma_f32_16x16x32_bf16 v[60:63], v[152:155], v[188:191], v[60:63]
	v_mfma_f32_16x16x32_bf16 v[60:63], v[156:159], v[192:195], v[60:63]
	v_mfma_f32_16x16x32_bf16 v[56:59], v[160:163], v[188:191], v[56:59]
	v_mfma_f32_16x16x32_bf16 v[56:59], v[164:167], v[192:195], v[56:59]
	v_mfma_f32_16x16x32_bf16 v[52:55], v[152:155], v[196:199], v[52:55]
	v_mfma_f32_16x16x32_bf16 v[52:55], v[156:159], v[200:203], v[52:55]
	v_mfma_f32_16x16x32_bf16 v[44:47], v[160:163], v[196:199], v[44:47]
	v_mfma_f32_16x16x32_bf16 v[44:47], v[164:167], v[200:203], v[44:47]
	v_mfma_f32_16x16x32_bf16 v[36:39], v[152:155], v[204:207], v[36:39]
	v_mfma_f32_16x16x32_bf16 v[36:39], v[156:159], v[208:211], v[36:39]
	v_mfma_f32_16x16x32_bf16 v[28:31], v[160:163], v[204:207], v[28:31]
	v_mfma_f32_16x16x32_bf16 v[28:31], v[164:167], v[208:211], v[28:31]
	v_mfma_f32_16x16x32_bf16 v[20:23], v[152:155], v[212:215], v[20:23]
	v_mfma_f32_16x16x32_bf16 v[20:23], v[156:159], v[216:219], v[20:23]
	v_mfma_f32_16x16x32_bf16 v[12:15], v[160:163], v[212:215], v[12:15]
	v_mfma_f32_16x16x32_bf16 v[12:15], v[164:167], v[216:219], v[12:15]
	v_mfma_f32_16x16x32_bf16 v[48:51], v[168:171], v[188:191], v[48:51]
	v_mfma_f32_16x16x32_bf16 v[48:51], v[172:175], v[192:195], v[48:51]
	v_mfma_f32_16x16x32_bf16 v[40:43], v[176:179], v[188:191], v[40:43]
	v_mfma_f32_16x16x32_bf16 v[40:43], v[184:187], v[192:195], v[40:43]
	v_mfma_f32_16x16x32_bf16 v[32:35], v[168:171], v[196:199], v[32:35]
	v_mfma_f32_16x16x32_bf16 v[32:35], v[172:175], v[200:203], v[32:35]
	v_mfma_f32_16x16x32_bf16 v[24:27], v[176:179], v[196:199], v[24:27]
	v_mfma_f32_16x16x32_bf16 v[24:27], v[184:187], v[200:203], v[24:27]
	v_mfma_f32_16x16x32_bf16 v[16:19], v[168:171], v[204:207], v[16:19]
	v_mfma_f32_16x16x32_bf16 v[16:19], v[172:175], v[208:211], v[16:19]
	v_mfma_f32_16x16x32_bf16 v[8:11], v[176:179], v[204:207], v[8:11]
	v_mfma_f32_16x16x32_bf16 v[8:11], v[184:187], v[208:211], v[8:11]
	v_mfma_f32_16x16x32_bf16 v[4:7], v[168:171], v[212:215], v[4:7]
	v_mfma_f32_16x16x32_bf16 v[4:7], v[172:175], v[216:219], v[4:7]
	v_mfma_f32_16x16x32_bf16 v[0:3], v[176:179], v[212:215], v[0:3]
	v_mfma_f32_16x16x32_bf16 v[0:3], v[184:187], v[216:219], v[0:3]
	s_setprio 0
	s_barrier
	s_add_i32 s86, s86, 2
	s_add_u32 s84, s84, 0x100
	s_addc_u32 s85, s85, 0
	s_cmp_gt_u32 s86, 41
	s_mov_b64 s[52:53], s[54:55]
	s_cbranch_scc0 .LBB0_264
	s_and_b64 vcc, exec, s[10:11]
	s_cbranch_vccz .LBB0_267
	s_barrier

.LBB0_386:
	s_ashr_i32 s49, s48, 31
	s_lshl_b64 s[52:53], s[48:49], 19
	s_add_u32 s52, s80, s52
	s_addc_u32 s53, s81, s53
	s_and_b64 s[54:55], s[4:5], exec
	s_cselect_b32 s49, s53, s59
	s_cselect_b32 s82, s52, s58
	s_ashr_i32 s47, s46, 31
	s_lshl_b64 s[54:55], s[46:47], 19
	s_add_u32 s54, s64, s54
	s_addc_u32 s55, s65, s55
	s_and_b64 s[62:63], s[4:5], exec
	s_cselect_b32 s47, s55, s61
	s_cselect_b32 s83, s54, s60
	s_add_u32 s58, s58, 0x40080
	s_addc_u32 s59, s59, 0
	s_add_u32 s84, s60, 0x100
	s_addc_u32 s85, s61, 0
	s_mov_b32 s86, -2
	ds_read_b128 v[152:155], v148
	ds_read_b128 v[156:159], v148 offset:1024
	ds_read_b128 v[160:163], v148 offset:2048
	ds_read_b128 v[164:167], v148 offset:3072
	ds_read_b128 v[168:171], v149
	ds_read_b128 v[172:175], v149 offset:1024
	ds_read_b128 v[176:179], v149 offset:2048
	ds_read_b128 v[184:187], v149 offset:3072
	s_add_u32 s18, s58, 0xfffc0080
	s_addc_u32 s19, s59, -1
	s_cmp_eq_u32 s86, 12
	s_cselect_b32 s63, s49, s19
	s_cselect_b32 s62, s82, s18
	s_cselect_b32 s61, s47, s85
	s_cselect_b32 s60, s83, s84
	v_lshl_add_u64 v[220:221], s[58:59], 0, v[138:139]
	s_add_i32 m0, s68, 0xc000
	ds_read_b128 v[188:191], v150
	ds_read_b128 v[192:195], v150 offset:1024
	ds_read_b128 v[196:199], v150 offset:2048
	ds_read_b128 v[200:203], v150 offset:3072
	ds_read_b128 v[204:207], v150 offset:4096
	ds_read_b128 v[208:211], v150 offset:5120
	ds_read_b128 v[212:215], v150 offset:6144
	ds_read_b128 v[216:219], v150 offset:7168
	global_load_lds_dwordx4 v[220:221], off
	v_lshl_add_u64 v[220:221], s[58:59], 0, v[140:141]
	s_add_i32 m0, s68, 0xe000
	s_nop 0
	global_load_lds_dwordx4 v[220:221], off
	s_waitcnt vmcnt(8)
	s_waitcnt lgkmcnt(0)
	s_barrier
	s_setprio 1
	s_waitcnt lgkmcnt(0)
	v_mfma_f32_16x16x32_bf16 v[124:127], v[152:155], v[188:191], 0
	v_mfma_f32_16x16x32_bf16 v[124:127], v[156:159], v[192:195], v[124:127]
	v_mfma_f32_16x16x32_bf16 v[120:123], v[160:163], v[188:191], 0
	v_mfma_f32_16x16x32_bf16 v[120:123], v[164:167], v[192:195], v[120:123]
	v_mfma_f32_16x16x32_bf16 v[116:119], v[152:155], v[196:199], 0
	v_mfma_f32_16x16x32_bf16 v[116:119], v[156:159], v[200:203], v[116:119]
	v_mfma_f32_16x16x32_bf16 v[112:115], v[160:163], v[196:199], 0
	v_mfma_f32_16x16x32_bf16 v[112:115], v[164:167], v[200:203], v[112:115]
	v_mfma_f32_16x16x32_bf16 v[108:111], v[152:155], v[204:207], 0
	v_mfma_f32_16x16x32_bf16 v[108:111], v[156:159], v[208:211], v[108:111]
	v_mfma_f32_16x16x32_bf16 v[104:107], v[160:163], v[204:207], 0
	v_mfma_f32_16x16x32_bf16 v[104:107], v[164:167], v[208:211], v[104:107]
	v_mfma_f32_16x16x32_bf16 v[100:103], v[152:155], v[212:215], 0
	v_mfma_f32_16x16x32_bf16 v[100:103], v[156:159], v[216:219], v[100:103]
	v_mfma_f32_16x16x32_bf16 v[96:99], v[160:163], v[212:215], 0
	v_mfma_f32_16x16x32_bf16 v[96:99], v[164:167], v[216:219], v[96:99]
	v_mfma_f32_16x16x32_bf16 v[68:71], v[168:171], v[188:191], 0
	v_mfma_f32_16x16x32_bf16 v[68:71], v[172:175], v[192:195], v[68:71]
	v_mfma_f32_16x16x32_bf16 v[64:67], v[176:179], v[188:191], 0
	v_mfma_f32_16x16x32_bf16 v[64:67], v[184:187], v[192:195], v[64:67]
	v_mfma_f32_16x16x32_bf16 v[52:55], v[168:171], v[196:199], 0
	v_mfma_f32_16x16x32_bf16 v[52:55], v[172:175], v[200:203], v[52:55]
	v_mfma_f32_16x16x32_bf16 v[48:51], v[176:179], v[196:199], 0
	v_mfma_f32_16x16x32_bf16 v[48:51], v[184:187], v[200:203], v[48:51]
	v_mfma_f32_16x16x32_bf16 v[44:47], v[168:171], v[204:207], 0
	v_mfma_f32_16x16x32_bf16 v[44:47], v[172:175], v[208:211], v[44:47]
	v_mfma_f32_16x16x32_bf16 v[40:43], v[176:179], v[204:207], 0
	v_mfma_f32_16x16x32_bf16 v[40:43], v[184:187], v[208:211], v[40:43]
	v_mfma_f32_16x16x32_bf16 v[36:39], v[168:171], v[212:215], 0
	v_mfma_f32_16x16x32_bf16 v[36:39], v[172:175], v[216:219], v[36:39]
	v_mfma_f32_16x16x32_bf16 v[32:35], v[176:179], v[212:215], 0
	v_mfma_f32_16x16x32_bf16 v[32:35], v[184:187], v[216:219], v[32:35]
	s_setprio 0
	s_barrier
	s_add_i32 s18, s76, s66
	v_lshl_add_u64 v[220:221], s[60:61], 0, v[132:133]
	s_mov_b32 m0, s18
	s_nop 0
	global_load_lds_dwordx4 v[220:221], off
	s_add_i32 m0, s18, 0x2000
	s_add_u32 s88, s60, 0x40000
	v_lshl_add_u64 v[222:223], s[60:61], 0, v[128:129]
	s_addc_u32 s89, s61, 0
	s_add_i32 s18, s77, s66
	global_load_lds_dwordx4 v[222:223], off
	v_lshl_add_u64 v[224:225], s[88:89], 0, v[132:133]
	s_mov_b32 m0, s18
	v_lshl_add_u64 v[226:227], s[62:63], 0, v[130:131]
	global_load_lds_dwordx4 v[224:225], off
	v_lshl_add_u64 v[224:225], s[88:89], 0, v[128:129]
	s_add_i32 m0, s18, 0x2000
	s_nop 0
	global_load_lds_dwordx4 v[224:225], off
	v_lshl_add_u64 v[224:225], s[62:63], 0, v[134:135]
	s_mov_b32 m0, s68
	s_nop 0
	global_load_lds_dwordx4 v[224:225], off
	s_mov_b32 m0, s69
	s_nop 0
	global_load_lds_dwordx4 v[226:227], off
	ds_read_b128 v[188:191], v150 offset:16384
	ds_read_b128 v[192:195], v150 offset:17408
	ds_read_b128 v[196:199], v150 offset:18432
	ds_read_b128 v[200:203], v150 offset:19456
	ds_read_b128 v[204:207], v150 offset:20480
	ds_read_b128 v[208:211], v150 offset:21504
	ds_read_b128 v[212:215], v150 offset:22528
	ds_read_b128 v[216:219], v150 offset:23552
	s_waitcnt vmcnt(8)
	s_waitcnt lgkmcnt(0)
	s_barrier
	s_setprio 1
	s_waitcnt lgkmcnt(0)
	v_mfma_f32_16x16x32_bf16 v[92:95], v[152:155], v[188:191], 0
	v_mfma_f32_16x16x32_bf16 v[92:95], v[156:159], v[192:195], v[92:95]
	v_mfma_f32_16x16x32_bf16 v[88:91], v[160:163], v[188:191], 0
	v_mfma_f32_16x16x32_bf16 v[88:91], v[164:167], v[192:195], v[88:91]
	v_mfma_f32_16x16x32_bf16 v[84:87], v[152:155], v[196:199], 0
	v_mfma_f32_16x16x32_bf16 v[84:87], v[156:159], v[200:203], v[84:87]
	v_mfma_f32_16x16x32_bf16 v[80:83], v[160:163], v[196:199], 0
	v_mfma_f32_16x16x32_bf16 v[80:83], v[164:167], v[200:203], v[80:83]
	v_mfma_f32_16x16x32_bf16 v[76:79], v[152:155], v[204:207], 0
	v_mfma_f32_16x16x32_bf16 v[76:79], v[156:159], v[208:211], v[76:79]
	v_mfma_f32_16x16x32_bf16 v[72:75], v[160:163], v[204:207], 0
	v_mfma_f32_16x16x32_bf16 v[72:75], v[164:167], v[208:211], v[72:75]
	v_mfma_f32_16x16x32_bf16 v[60:63], v[152:155], v[212:215], 0
	v_mfma_f32_16x16x32_bf16 v[60:63], v[156:159], v[216:219], v[60:63]
	v_mfma_f32_16x16x32_bf16 v[56:59], v[160:163], v[212:215], 0
	v_mfma_f32_16x16x32_bf16 v[56:59], v[164:167], v[216:219], v[56:59]
	v_mfma_f32_16x16x32_bf16 v[28:31], v[168:171], v[188:191], 0
	v_mfma_f32_16x16x32_bf16 v[28:31], v[172:175], v[192:195], v[28:31]
	v_mfma_f32_16x16x32_bf16 v[24:27], v[176:179], v[188:191], 0
	v_mfma_f32_16x16x32_bf16 v[24:27], v[184:187], v[192:195], v[24:27]
	v_mfma_f32_16x16x32_bf16 v[20:23], v[168:171], v[196:199], 0
	v_mfma_f32_16x16x32_bf16 v[20:23], v[172:175], v[200:203], v[20:23]
	v_mfma_f32_16x16x32_bf16 v[16:19], v[176:179], v[196:199], 0
	v_mfma_f32_16x16x32_bf16 v[16:19], v[184:187], v[200:203], v[16:19]
	v_mfma_f32_16x16x32_bf16 v[12:15], v[168:171], v[204:207], 0
	v_mfma_f32_16x16x32_bf16 v[12:15], v[172:175], v[208:211], v[12:15]
	v_mfma_f32_16x16x32_bf16 v[8:11], v[176:179], v[204:207], 0
	v_mfma_f32_16x16x32_bf16 v[8:11], v[184:187], v[208:211], v[8:11]
	v_mfma_f32_16x16x32_bf16 v[4:7], v[168:171], v[212:215], 0
	v_mfma_f32_16x16x32_bf16 v[4:7], v[172:175], v[216:219], v[4:7]
	v_mfma_f32_16x16x32_bf16 v[0:3], v[176:179], v[212:215], 0
	v_mfma_f32_16x16x32_bf16 v[0:3], v[184:187], v[216:219], v[0:3]
	s_setprio 0
	s_barrier
	s_branch .Lmid_gemm2
.LBB0_387:
	s_add_u32 s18, s58, 0xfffc0080
	s_addc_u32 s19, s59, -1
	s_cmp_eq_u32 s86, 12
	s_cselect_b32 s63, s49, s19
	s_cselect_b32 s62, s82, s18
	s_cselect_b32 s61, s47, s85
	s_cselect_b32 s60, s83, s84
	v_lshl_add_u64 v[220:221], s[58:59], 0, v[138:139]
	s_add_i32 m0, s68, 0xc000
	s_nop 0
	global_load_lds_dwordx4 v[220:221], off
	v_lshl_add_u64 v[220:221], s[58:59], 0, v[140:141]
	s_add_i32 m0, s68, 0xe000
	s_nop 0
	global_load_lds_dwordx4 v[220:221], off
	ds_read_b128 v[152:155], v148
	ds_read_b128 v[156:159], v148 offset:1024
	ds_read_b128 v[160:163], v148 offset:2048
	ds_read_b128 v[164:167], v148 offset:3072
	ds_read_b128 v[168:171], v149
	ds_read_b128 v[172:175], v149 offset:1024
	ds_read_b128 v[176:179], v149 offset:2048
	ds_read_b128 v[184:187], v149 offset:3072
	ds_read_b128 v[188:191], v150
	ds_read_b128 v[192:195], v150 offset:1024
	ds_read_b128 v[196:199], v150 offset:2048
	ds_read_b128 v[200:203], v150 offset:3072
	ds_read_b128 v[204:207], v150 offset:4096
	ds_read_b128 v[208:211], v150 offset:5120
	ds_read_b128 v[212:215], v150 offset:6144
	ds_read_b128 v[216:219], v150 offset:7168
	s_waitcnt vmcnt(8)
	s_waitcnt lgkmcnt(0)
	s_barrier
	s_setprio 1
	s_waitcnt lgkmcnt(0)
	v_mfma_f32_16x16x32_bf16 v[124:127], v[152:155], v[188:191], v[124:127]
	v_mfma_f32_16x16x32_bf16 v[124:127], v[156:159], v[192:195], v[124:127]
	v_mfma_f32_16x16x32_bf16 v[120:123], v[160:163], v[188:191], v[120:123]
	v_mfma_f32_16x16x32_bf16 v[120:123], v[164:167], v[192:195], v[120:123]
	v_mfma_f32_16x16x32_bf16 v[116:119], v[152:155], v[196:199], v[116:119]
	v_mfma_f32_16x16x32_bf16 v[116:119], v[156:159], v[200:203], v[116:119]
	v_mfma_f32_16x16x32_bf16 v[112:115], v[160:163], v[196:199], v[112:115]
	v_mfma_f32_16x16x32_bf16 v[112:115], v[164:167], v[200:203], v[112:115]
	v_mfma_f32_16x16x32_bf16 v[108:111], v[152:155], v[204:207], v[108:111]
	v_mfma_f32_16x16x32_bf16 v[108:111], v[156:159], v[208:211], v[108:111]
	v_mfma_f32_16x16x32_bf16 v[104:107], v[160:163], v[204:207], v[104:107]
	v_mfma_f32_16x16x32_bf16 v[104:107], v[164:167], v[208:211], v[104:107]
	v_mfma_f32_16x16x32_bf16 v[100:103], v[152:155], v[212:215], v[100:103]
	v_mfma_f32_16x16x32_bf16 v[100:103], v[156:159], v[216:219], v[100:103]
	v_mfma_f32_16x16x32_bf16 v[96:99], v[160:163], v[212:215], v[96:99]
	v_mfma_f32_16x16x32_bf16 v[96:99], v[164:167], v[216:219], v[96:99]
	v_mfma_f32_16x16x32_bf16 v[68:71], v[168:171], v[188:191], v[68:71]
	v_mfma_f32_16x16x32_bf16 v[68:71], v[172:175], v[192:195], v[68:71]
	v_mfma_f32_16x16x32_bf16 v[64:67], v[176:179], v[188:191], v[64:67]
	v_mfma_f32_16x16x32_bf16 v[64:67], v[184:187], v[192:195], v[64:67]
	v_mfma_f32_16x16x32_bf16 v[52:55], v[168:171], v[196:199], v[52:55]
	v_mfma_f32_16x16x32_bf16 v[52:55], v[172:175], v[200:203], v[52:55]
	v_mfma_f32_16x16x32_bf16 v[48:51], v[176:179], v[196:199], v[48:51]
	v_mfma_f32_16x16x32_bf16 v[48:51], v[184:187], v[200:203], v[48:51]
	v_mfma_f32_16x16x32_bf16 v[44:47], v[168:171], v[204:207], v[44:47]
	v_mfma_f32_16x16x32_bf16 v[44:47], v[172:175], v[208:211], v[44:47]
	v_mfma_f32_16x16x32_bf16 v[40:43], v[176:179], v[204:207], v[40:43]
	v_mfma_f32_16x16x32_bf16 v[40:43], v[184:187], v[208:211], v[40:43]
	v_mfma_f32_16x16x32_bf16 v[36:39], v[168:171], v[212:215], v[36:39]
	v_mfma_f32_16x16x32_bf16 v[36:39], v[172:175], v[216:219], v[36:39]
	v_mfma_f32_16x16x32_bf16 v[32:35], v[176:179], v[212:215], v[32:35]
	v_mfma_f32_16x16x32_bf16 v[32:35], v[184:187], v[216:219], v[32:35]
	s_setprio 0
	s_barrier
	s_add_i32 s18, s76, s66
	v_lshl_add_u64 v[220:221], s[60:61], 0, v[132:133]
	s_mov_b32 m0, s18
	s_nop 0
	global_load_lds_dwordx4 v[220:221], off
	s_add_i32 m0, s18, 0x2000
	s_add_u32 s88, s60, 0x40000
	v_lshl_add_u64 v[222:223], s[60:61], 0, v[128:129]
	s_addc_u32 s89, s61, 0
	s_add_i32 s18, s77, s66
	global_load_lds_dwordx4 v[222:223], off
	v_lshl_add_u64 v[224:225], s[88:89], 0, v[132:133]
	s_mov_b32 m0, s18
	v_lshl_add_u64 v[226:227], s[62:63], 0, v[130:131]
	global_load_lds_dwordx4 v[224:225], off
	v_lshl_add_u64 v[224:225], s[88:89], 0, v[128:129]
	s_add_i32 m0, s18, 0x2000
	s_nop 0
	global_load_lds_dwordx4 v[224:225], off
	v_lshl_add_u64 v[224:225], s[62:63], 0, v[134:135]
	s_mov_b32 m0, s68
	s_nop 0
	global_load_lds_dwordx4 v[224:225], off
	s_mov_b32 m0, s69
	s_nop 0
	global_load_lds_dwordx4 v[226:227], off
	ds_read_b128 v[188:191], v150 offset:16384
	ds_read_b128 v[192:195], v150 offset:17408
	ds_read_b128 v[196:199], v150 offset:18432
	ds_read_b128 v[200:203], v150 offset:19456
	ds_read_b128 v[204:207], v150 offset:20480
	ds_read_b128 v[208:211], v150 offset:21504
	ds_read_b128 v[212:215], v150 offset:22528
	ds_read_b128 v[216:219], v150 offset:23552
	s_waitcnt vmcnt(8)
	s_waitcnt lgkmcnt(0)
	s_barrier
	s_setprio 1
	s_waitcnt lgkmcnt(0)
	v_mfma_f32_16x16x32_bf16 v[92:95], v[152:155], v[188:191], v[92:95]
	v_mfma_f32_16x16x32_bf16 v[92:95], v[156:159], v[192:195], v[92:95]
	v_mfma_f32_16x16x32_bf16 v[88:91], v[160:163], v[188:191], v[88:91]
	v_mfma_f32_16x16x32_bf16 v[88:91], v[164:167], v[192:195], v[88:91]
	v_mfma_f32_16x16x32_bf16 v[84:87], v[152:155], v[196:199], v[84:87]
	v_mfma_f32_16x16x32_bf16 v[84:87], v[156:159], v[200:203], v[84:87]
	v_mfma_f32_16x16x32_bf16 v[80:83], v[160:163], v[196:199], v[80:83]
	v_mfma_f32_16x16x32_bf16 v[80:83], v[164:167], v[200:203], v[80:83]
	v_mfma_f32_16x16x32_bf16 v[76:79], v[152:155], v[204:207], v[76:79]
	v_mfma_f32_16x16x32_bf16 v[76:79], v[156:159], v[208:211], v[76:79]
	v_mfma_f32_16x16x32_bf16 v[72:75], v[160:163], v[204:207], v[72:75]
	v_mfma_f32_16x16x32_bf16 v[72:75], v[164:167], v[208:211], v[72:75]
	v_mfma_f32_16x16x32_bf16 v[60:63], v[152:155], v[212:215], v[60:63]
	v_mfma_f32_16x16x32_bf16 v[60:63], v[156:159], v[216:219], v[60:63]
	v_mfma_f32_16x16x32_bf16 v[56:59], v[160:163], v[212:215], v[56:59]
	v_mfma_f32_16x16x32_bf16 v[56:59], v[164:167], v[216:219], v[56:59]
	v_mfma_f32_16x16x32_bf16 v[28:31], v[168:171], v[188:191], v[28:31]
	v_mfma_f32_16x16x32_bf16 v[28:31], v[172:175], v[192:195], v[28:31]
	v_mfma_f32_16x16x32_bf16 v[24:27], v[176:179], v[188:191], v[24:27]
	v_mfma_f32_16x16x32_bf16 v[24:27], v[184:187], v[192:195], v[24:27]
	v_mfma_f32_16x16x32_bf16 v[20:23], v[168:171], v[196:199], v[20:23]
	v_mfma_f32_16x16x32_bf16 v[20:23], v[172:175], v[200:203], v[20:23]
	v_mfma_f32_16x16x32_bf16 v[16:19], v[176:179], v[196:199], v[16:19]
	v_mfma_f32_16x16x32_bf16 v[16:19], v[184:187], v[200:203], v[16:19]
	v_mfma_f32_16x16x32_bf16 v[12:15], v[168:171], v[204:207], v[12:15]
	v_mfma_f32_16x16x32_bf16 v[12:15], v[172:175], v[208:211], v[12:15]
	v_mfma_f32_16x16x32_bf16 v[8:11], v[176:179], v[204:207], v[8:11]
	v_mfma_f32_16x16x32_bf16 v[8:11], v[184:187], v[208:211], v[8:11]
	v_mfma_f32_16x16x32_bf16 v[4:7], v[168:171], v[212:215], v[4:7]
	v_mfma_f32_16x16x32_bf16 v[4:7], v[172:175], v[216:219], v[4:7]
	v_mfma_f32_16x16x32_bf16 v[0:3], v[176:179], v[212:215], v[0:3]
	v_mfma_f32_16x16x32_bf16 v[0:3], v[184:187], v[216:219], v[0:3]
	s_setprio 0
	s_barrier
.Lmid_gemm2:
	s_add_i32 s18, 0, 0x18000
	s_add_i32 s19, 0, 0x1c000
	v_add_u32_e32 v164, s18, v147
	v_add_u32_e32 v181, s19, v147
	s_add_u32 s62, s62, 0x40000
	s_addc_u32 s63, s63, 0
	s_mov_b32 m0, s70
	v_lshl_add_u64 v[228:229], s[62:63], 0, v[134:135]
	global_load_lds_dwordx4 v[228:229], off
	v_lshl_add_u64 v[228:229], s[62:63], 0, v[130:131]
	s_mov_b32 m0, s71
	s_nop 0
	global_load_lds_dwordx4 v[228:229], off
	ds_read_b128 v[152:155], v164
	ds_read_b128 v[156:159], v164 offset:1024
	ds_read_b128 v[160:163], v164 offset:2048
	ds_read_b128 v[164:167], v164 offset:3072
	ds_read_b128 v[168:171], v181
	ds_read_b128 v[172:175], v181 offset:1024
	ds_read_b128 v[176:179], v181 offset:2048
	ds_read_b128 v[184:187], v181 offset:3072
	ds_read_b128 v[188:191], v150 offset:32768
	ds_read_b128 v[192:195], v150 offset:33792
	ds_read_b128 v[196:199], v150 offset:34816
	ds_read_b128 v[200:203], v150 offset:35840
	ds_read_b128 v[204:207], v150 offset:36864
	ds_read_b128 v[208:211], v150 offset:37888
	ds_read_b128 v[212:215], v150 offset:38912
	ds_read_b128 v[216:219], v150 offset:39936
	s_waitcnt vmcnt(8)
	s_waitcnt lgkmcnt(0)
	s_barrier
	s_setprio 1
	s_waitcnt lgkmcnt(0)
	v_mfma_f32_16x16x32_bf16 v[124:127], v[152:155], v[188:191], v[124:127]
	v_mfma_f32_16x16x32_bf16 v[124:127], v[156:159], v[192:195], v[124:127]
	v_mfma_f32_16x16x32_bf16 v[120:123], v[160:163], v[188:191], v[120:123]
	v_mfma_f32_16x16x32_bf16 v[120:123], v[164:167], v[192:195], v[120:123]
	v_mfma_f32_16x16x32_bf16 v[116:119], v[152:155], v[196:199], v[116:119]
	v_mfma_f32_16x16x32_bf16 v[116:119], v[156:159], v[200:203], v[116:119]
	v_mfma_f32_16x16x32_bf16 v[112:115], v[160:163], v[196:199], v[112:115]
	v_mfma_f32_16x16x32_bf16 v[112:115], v[164:167], v[200:203], v[112:115]
	v_mfma_f32_16x16x32_bf16 v[108:111], v[152:155], v[204:207], v[108:111]
	v_mfma_f32_16x16x32_bf16 v[108:111], v[156:159], v[208:211], v[108:111]
	v_mfma_f32_16x16x32_bf16 v[104:107], v[160:163], v[204:207], v[104:107]
	v_mfma_f32_16x16x32_bf16 v[104:107], v[164:167], v[208:211], v[104:107]
	v_mfma_f32_16x16x32_bf16 v[100:103], v[152:155], v[212:215], v[100:103]
	v_mfma_f32_16x16x32_bf16 v[100:103], v[156:159], v[216:219], v[100:103]
	v_mfma_f32_16x16x32_bf16 v[96:99], v[160:163], v[212:215], v[96:99]
	v_mfma_f32_16x16x32_bf16 v[96:99], v[164:167], v[216:219], v[96:99]
	v_mfma_f32_16x16x32_bf16 v[68:71], v[168:171], v[188:191], v[68:71]
	v_mfma_f32_16x16x32_bf16 v[68:71], v[172:175], v[192:195], v[68:71]
	v_mfma_f32_16x16x32_bf16 v[64:67], v[176:179], v[188:191], v[64:67]
	v_mfma_f32_16x16x32_bf16 v[64:67], v[184:187], v[192:195], v[64:67]
	v_mfma_f32_16x16x32_bf16 v[52:55], v[168:171], v[196:199], v[52:55]
	v_mfma_f32_16x16x32_bf16 v[52:55], v[172:175], v[200:203], v[52:55]
	v_mfma_f32_16x16x32_bf16 v[48:51], v[176:179], v[196:199], v[48:51]
	v_mfma_f32_16x16x32_bf16 v[48:51], v[184:187], v[200:203], v[48:51]
	v_mfma_f32_16x16x32_bf16 v[44:47], v[168:171], v[204:207], v[44:47]
	v_mfma_f32_16x16x32_bf16 v[44:47], v[172:175], v[208:211], v[44:47]
	v_mfma_f32_16x16x32_bf16 v[40:43], v[176:179], v[204:207], v[40:43]
	v_mfma_f32_16x16x32_bf16 v[40:43], v[184:187], v[208:211], v[40:43]
	v_mfma_f32_16x16x32_bf16 v[36:39], v[168:171], v[212:215], v[36:39]
	v_mfma_f32_16x16x32_bf16 v[36:39], v[172:175], v[216:219], v[36:39]
	v_mfma_f32_16x16x32_bf16 v[32:35], v[176:179], v[212:215], v[32:35]
	v_mfma_f32_16x16x32_bf16 v[32:35], v[184:187], v[216:219], v[32:35]
	s_setprio 0
	s_barrier
	s_add_i32 s18, s18, s66
	v_lshl_add_u64 v[220:221], v[220:221], 0, s[6:7]
	s_mov_b32 m0, s18
	s_nop 0
	global_load_lds_dwordx4 v[220:221], off
	s_add_i32 m0, s18, 0x2000
	s_add_u32 s60, s60, 0x40080
	v_lshl_add_u64 v[220:221], v[222:223], 0, s[6:7]
	s_addc_u32 s61, s61, 0
	s_add_i32 s18, s19, s66
	global_load_lds_dwordx4 v[220:221], off
	v_lshl_add_u64 v[220:221], s[60:61], 0, v[132:133]
	s_mov_b32 m0, s18
	s_nop 0
	global_load_lds_dwordx4 v[220:221], off
	v_lshl_add_u64 v[220:221], s[60:61], 0, v[128:129]
	s_add_i32 m0, s18, 0x2000
	s_nop 0
	global_load_lds_dwordx4 v[220:221], off
	v_lshl_add_u64 v[220:221], v[224:225], 0, s[6:7]
	s_mov_b32 m0, s74
	s_nop 0
	global_load_lds_dwordx4 v[220:221], off
	v_lshl_add_u64 v[220:221], v[226:227], 0, s[6:7]
	s_mov_b32 m0, s75
	s_nop 0
	global_load_lds_dwordx4 v[220:221], off
	ds_read_b128 v[188:191], v150 offset:49152
	ds_read_b128 v[192:195], v150 offset:50176
	ds_read_b128 v[196:199], v150 offset:51200
	ds_read_b128 v[200:203], v150 offset:52224
	ds_read_b128 v[204:207], v150 offset:53248
	ds_read_b128 v[208:211], v150 offset:54272
	ds_read_b128 v[212:215], v150 offset:55296
	ds_read_b128 v[216:219], v150 offset:56320
	s_waitcnt vmcnt(8)
	s_waitcnt lgkmcnt(0)
	s_barrier
	s_setprio 1
	s_waitcnt lgkmcnt(0)
	v_mfma_f32_16x16x32_bf16 v[92:95], v[152:155], v[188:191], v[92:95]
	v_mfma_f32_16x16x32_bf16 v[92:95], v[156:159], v[192:195], v[92:95]
	v_mfma_f32_16x16x32_bf16 v[88:91], v[160:163], v[188:191], v[88:91]
	v_mfma_f32_16x16x32_bf16 v[88:91], v[164:167], v[192:195], v[88:91]
	v_mfma_f32_16x16x32_bf16 v[84:87], v[152:155], v[196:199], v[84:87]
	v_mfma_f32_16x16x32_bf16 v[84:87], v[156:159], v[200:203], v[84:87]
	v_mfma_f32_16x16x32_bf16 v[80:83], v[160:163], v[196:199], v[80:83]
	v_mfma_f32_16x16x32_bf16 v[80:83], v[164:167], v[200:203], v[80:83]
	v_mfma_f32_16x16x32_bf16 v[76:79], v[152:155], v[204:207], v[76:79]
	v_mfma_f32_16x16x32_bf16 v[76:79], v[156:159], v[208:211], v[76:79]
	v_mfma_f32_16x16x32_bf16 v[72:75], v[160:163], v[204:207], v[72:75]
	v_mfma_f32_16x16x32_bf16 v[72:75], v[164:167], v[208:211], v[72:75]
	v_mfma_f32_16x16x32_bf16 v[60:63], v[152:155], v[212:215], v[60:63]
	v_mfma_f32_16x16x32_bf16 v[60:63], v[156:159], v[216:219], v[60:63]
	v_mfma_f32_16x16x32_bf16 v[56:59], v[160:163], v[212:215], v[56:59]
	v_mfma_f32_16x16x32_bf16 v[56:59], v[164:167], v[216:219], v[56:59]
	v_mfma_f32_16x16x32_bf16 v[28:31], v[168:171], v[188:191], v[28:31]
	v_mfma_f32_16x16x32_bf16 v[28:31], v[172:175], v[192:195], v[28:31]
	v_mfma_f32_16x16x32_bf16 v[24:27], v[176:179], v[188:191], v[24:27]
	v_mfma_f32_16x16x32_bf16 v[24:27], v[184:187], v[192:195], v[24:27]
	v_mfma_f32_16x16x32_bf16 v[20:23], v[168:171], v[196:199], v[20:23]
	v_mfma_f32_16x16x32_bf16 v[20:23], v[172:175], v[200:203], v[20:23]
	v_mfma_f32_16x16x32_bf16 v[16:19], v[176:179], v[196:199], v[16:19]
	v_mfma_f32_16x16x32_bf16 v[16:19], v[184:187], v[200:203], v[16:19]
	v_mfma_f32_16x16x32_bf16 v[12:15], v[168:171], v[204:207], v[12:15]
	v_mfma_f32_16x16x32_bf16 v[12:15], v[172:175], v[208:211], v[12:15]
	v_mfma_f32_16x16x32_bf16 v[8:11], v[176:179], v[204:207], v[8:11]
	v_mfma_f32_16x16x32_bf16 v[8:11], v[184:187], v[208:211], v[8:11]
	v_mfma_f32_16x16x32_bf16 v[4:7], v[168:171], v[212:215], v[4:7]
	v_mfma_f32_16x16x32_bf16 v[4:7], v[172:175], v[216:219], v[4:7]
	v_mfma_f32_16x16x32_bf16 v[0:3], v[176:179], v[212:215], v[0:3]
	v_mfma_f32_16x16x32_bf16 v[0:3], v[184:187], v[216:219], v[0:3]
	s_setprio 0
	s_barrier
	s_add_i32 s86, s86, 2
	s_add_u32 s58, s58, 0x100
	s_addc_u32 s59, s59, 0
	s_add_u32 s84, s84, 0x100
	s_addc_u32 s85, s85, 0
	s_cmp_gt_u32 s86, 13
	s_cbranch_scc0 .LBB0_387
	s_and_b64 vcc, exec, s[8:9]
	s_cbranch_vccz .LBB0_390
	s_barrier

.LBB0_600:
	s_ashr_i32 s49, s48, 31
	s_lshl_b64 s[18:19], s[48:49], 19
	s_add_u32 s52, s38, s18
	s_addc_u32 s53, s39, s19
	s_and_b64 s[18:19], s[4:5], exec
	s_cselect_b32 s49, s53, s59
	s_cselect_b32 s84, s52, s58
	s_ashr_i32 s47, s46, 31
	s_lshl_b64 s[18:19], s[46:47], 19
	s_add_u32 s54, s64, s18
	s_addc_u32 s55, s65, s19
	s_and_b64 s[18:19], s[4:5], exec
	s_cselect_b32 s47, s55, s61
	s_cselect_b32 s85, s54, s60
	s_add_u32 s58, s58, 0x40080
	s_addc_u32 s59, s59, 0
	s_add_u32 s86, s60, 0x100
	s_addc_u32 s87, s61, 0
	s_mov_b32 s88, -2
	ds_read_b128 v[152:155], v149
	ds_read_b128 v[156:159], v149 offset:1024
	ds_read_b128 v[160:163], v149 offset:2048
	ds_read_b128 v[164:167], v149 offset:3072
	ds_read_b128 v[168:171], v150
	ds_read_b128 v[172:175], v150 offset:1024
	ds_read_b128 v[176:179], v150 offset:2048
	ds_read_b128 v[184:187], v150 offset:3072
	s_add_u32 s18, s58, 0xfffc0080
	s_addc_u32 s19, s59, -1
	s_cmp_eq_u32 s88, 12
	s_cselect_b32 s63, s49, s19
	s_cselect_b32 s62, s84, s18
	s_cselect_b32 s61, s47, s87
	s_cselect_b32 s60, s85, s86
	v_lshl_add_u64 v[144:145], s[58:59], 0, v[136:137]
	s_add_i32 m0, s57, 0xc000
	ds_read_b128 v[188:191], v151
	ds_read_b128 v[192:195], v151 offset:1024
	ds_read_b128 v[196:199], v151 offset:2048
	ds_read_b128 v[200:203], v151 offset:3072
	ds_read_b128 v[204:207], v151 offset:4096
	ds_read_b128 v[208:211], v151 offset:5120
	ds_read_b128 v[212:215], v151 offset:6144
	ds_read_b128 v[216:219], v151 offset:7168
	global_load_lds_dwordx4 v[144:145], off
	v_lshl_add_u64 v[144:145], s[58:59], 0, v[138:139]
	s_add_i32 m0, s57, 0xe000
	s_nop 0
	global_load_lds_dwordx4 v[144:145], off
	s_waitcnt vmcnt(8)
	s_waitcnt lgkmcnt(0)
	s_barrier
	s_setprio 1
	s_waitcnt lgkmcnt(0)
	v_mfma_f32_16x16x32_bf16 v[124:127], v[152:155], v[188:191], 0
	v_mfma_f32_16x16x32_bf16 v[124:127], v[156:159], v[192:195], v[124:127]
	v_mfma_f32_16x16x32_bf16 v[120:123], v[160:163], v[188:191], 0
	v_mfma_f32_16x16x32_bf16 v[120:123], v[164:167], v[192:195], v[120:123]
	v_mfma_f32_16x16x32_bf16 v[116:119], v[152:155], v[196:199], 0
	v_mfma_f32_16x16x32_bf16 v[116:119], v[156:159], v[200:203], v[116:119]
	v_mfma_f32_16x16x32_bf16 v[108:111], v[160:163], v[196:199], 0
	v_mfma_f32_16x16x32_bf16 v[108:111], v[164:167], v[200:203], v[108:111]
	v_mfma_f32_16x16x32_bf16 v[100:103], v[152:155], v[204:207], 0
	v_mfma_f32_16x16x32_bf16 v[100:103], v[156:159], v[208:211], v[100:103]
	v_mfma_f32_16x16x32_bf16 v[92:95], v[160:163], v[204:207], 0
	v_mfma_f32_16x16x32_bf16 v[92:95], v[164:167], v[208:211], v[92:95]
	v_mfma_f32_16x16x32_bf16 v[84:87], v[152:155], v[212:215], 0
	v_mfma_f32_16x16x32_bf16 v[84:87], v[156:159], v[216:219], v[84:87]
	v_mfma_f32_16x16x32_bf16 v[76:79], v[160:163], v[212:215], 0
	v_mfma_f32_16x16x32_bf16 v[76:79], v[164:167], v[216:219], v[76:79]
	v_mfma_f32_16x16x32_bf16 v[112:115], v[168:171], v[188:191], 0
	v_mfma_f32_16x16x32_bf16 v[112:115], v[172:175], v[192:195], v[112:115]
	v_mfma_f32_16x16x32_bf16 v[104:107], v[176:179], v[188:191], 0
	v_mfma_f32_16x16x32_bf16 v[104:107], v[184:187], v[192:195], v[104:107]
	v_mfma_f32_16x16x32_bf16 v[96:99], v[168:171], v[196:199], 0
	v_mfma_f32_16x16x32_bf16 v[96:99], v[172:175], v[200:203], v[96:99]
	v_mfma_f32_16x16x32_bf16 v[88:91], v[176:179], v[196:199], 0
	v_mfma_f32_16x16x32_bf16 v[88:91], v[184:187], v[200:203], v[88:91]
	v_mfma_f32_16x16x32_bf16 v[80:83], v[168:171], v[204:207], 0
	v_mfma_f32_16x16x32_bf16 v[80:83], v[172:175], v[208:211], v[80:83]
	v_mfma_f32_16x16x32_bf16 v[72:75], v[176:179], v[204:207], 0
	v_mfma_f32_16x16x32_bf16 v[72:75], v[184:187], v[208:211], v[72:75]
	v_mfma_f32_16x16x32_bf16 v[68:71], v[168:171], v[212:215], 0
	v_mfma_f32_16x16x32_bf16 v[68:71], v[172:175], v[216:219], v[68:71]
	v_mfma_f32_16x16x32_bf16 v[64:67], v[176:179], v[212:215], 0
	v_mfma_f32_16x16x32_bf16 v[64:67], v[184:187], v[216:219], v[64:67]
	s_setprio 0
	s_barrier
	s_add_i32 s18, s73, s66
	v_lshl_add_u64 v[144:145], s[60:61], 0, v[130:131]
	s_mov_b32 m0, s18
	s_nop 0
	global_load_lds_dwordx4 v[144:145], off
	s_add_i32 m0, s18, 0x2000
	s_add_u32 s18, s60, 0x40000
	v_lshl_add_u64 v[220:221], s[60:61], 0, v[134:135]
	s_addc_u32 s19, s61, 0
	s_add_i32 s79, s74, s66
	global_load_lds_dwordx4 v[220:221], off
	v_lshl_add_u64 v[222:223], s[18:19], 0, v[130:131]
	s_mov_b32 m0, s79
	v_lshl_add_u64 v[224:225], s[62:63], 0, v[132:133]
	global_load_lds_dwordx4 v[222:223], off
	v_lshl_add_u64 v[222:223], s[18:19], 0, v[134:135]
	s_add_i32 m0, s79, 0x2000
	s_nop 0
	global_load_lds_dwordx4 v[222:223], off
	v_lshl_add_u64 v[222:223], s[62:63], 0, v[128:129]
	s_mov_b32 m0, s57
	s_nop 0
	global_load_lds_dwordx4 v[222:223], off
	s_mov_b32 m0, s67
	s_nop 0
	global_load_lds_dwordx4 v[224:225], off
	ds_read_b128 v[188:191], v151 offset:16384
	ds_read_b128 v[192:195], v151 offset:17408
	ds_read_b128 v[196:199], v151 offset:18432
	ds_read_b128 v[200:203], v151 offset:19456
	ds_read_b128 v[204:207], v151 offset:20480
	ds_read_b128 v[208:211], v151 offset:21504
	ds_read_b128 v[212:215], v151 offset:22528
	ds_read_b128 v[216:219], v151 offset:23552
	s_waitcnt vmcnt(8)
	s_waitcnt lgkmcnt(0)
	s_barrier
	s_setprio 1
	s_waitcnt lgkmcnt(0)
	v_mfma_f32_16x16x32_bf16 v[60:63], v[152:155], v[188:191], 0
	v_mfma_f32_16x16x32_bf16 v[60:63], v[156:159], v[192:195], v[60:63]
	v_mfma_f32_16x16x32_bf16 v[56:59], v[160:163], v[188:191], 0
	v_mfma_f32_16x16x32_bf16 v[56:59], v[164:167], v[192:195], v[56:59]
	v_mfma_f32_16x16x32_bf16 v[52:55], v[152:155], v[196:199], 0
	v_mfma_f32_16x16x32_bf16 v[52:55], v[156:159], v[200:203], v[52:55]
	v_mfma_f32_16x16x32_bf16 v[44:47], v[160:163], v[196:199], 0
	v_mfma_f32_16x16x32_bf16 v[44:47], v[164:167], v[200:203], v[44:47]
	v_mfma_f32_16x16x32_bf16 v[36:39], v[152:155], v[204:207], 0
	v_mfma_f32_16x16x32_bf16 v[36:39], v[156:159], v[208:211], v[36:39]
	v_mfma_f32_16x16x32_bf16 v[28:31], v[160:163], v[204:207], 0
	v_mfma_f32_16x16x32_bf16 v[28:31], v[164:167], v[208:211], v[28:31]
	v_mfma_f32_16x16x32_bf16 v[20:23], v[152:155], v[212:215], 0
	v_mfma_f32_16x16x32_bf16 v[20:23], v[156:159], v[216:219], v[20:23]
	v_mfma_f32_16x16x32_bf16 v[12:15], v[160:163], v[212:215], 0
	v_mfma_f32_16x16x32_bf16 v[12:15], v[164:167], v[216:219], v[12:15]
	v_mfma_f32_16x16x32_bf16 v[48:51], v[168:171], v[188:191], 0
	v_mfma_f32_16x16x32_bf16 v[48:51], v[172:175], v[192:195], v[48:51]
	v_mfma_f32_16x16x32_bf16 v[40:43], v[176:179], v[188:191], 0
	v_mfma_f32_16x16x32_bf16 v[40:43], v[184:187], v[192:195], v[40:43]
	v_mfma_f32_16x16x32_bf16 v[32:35], v[168:171], v[196:199], 0
	v_mfma_f32_16x16x32_bf16 v[32:35], v[172:175], v[200:203], v[32:35]
	v_mfma_f32_16x16x32_bf16 v[24:27], v[176:179], v[196:199], 0
	v_mfma_f32_16x16x32_bf16 v[24:27], v[184:187], v[200:203], v[24:27]
	v_mfma_f32_16x16x32_bf16 v[16:19], v[168:171], v[204:207], 0
	v_mfma_f32_16x16x32_bf16 v[16:19], v[172:175], v[208:211], v[16:19]
	v_mfma_f32_16x16x32_bf16 v[8:11], v[176:179], v[204:207], 0
	v_mfma_f32_16x16x32_bf16 v[8:11], v[184:187], v[208:211], v[8:11]
	v_mfma_f32_16x16x32_bf16 v[4:7], v[168:171], v[212:215], 0
	v_mfma_f32_16x16x32_bf16 v[4:7], v[172:175], v[216:219], v[4:7]
	v_mfma_f32_16x16x32_bf16 v[0:3], v[176:179], v[212:215], 0
	v_mfma_f32_16x16x32_bf16 v[0:3], v[184:187], v[216:219], v[0:3]
	s_setprio 0
	s_barrier
	s_branch .Lmid_gemm3
.LBB0_601:
	s_add_u32 s18, s58, 0xfffc0080
	s_addc_u32 s19, s59, -1
	s_cmp_eq_u32 s88, 12
	s_cselect_b32 s63, s49, s19
	s_cselect_b32 s62, s84, s18
	s_cselect_b32 s61, s47, s87
	s_cselect_b32 s60, s85, s86
	v_lshl_add_u64 v[144:145], s[58:59], 0, v[136:137]
	s_add_i32 m0, s57, 0xc000
	s_nop 0
	global_load_lds_dwordx4 v[144:145], off
	v_lshl_add_u64 v[144:145], s[58:59], 0, v[138:139]
	s_add_i32 m0, s57, 0xe000
	s_nop 0
	global_load_lds_dwordx4 v[144:145], off
	ds_read_b128 v[152:155], v149
	ds_read_b128 v[156:159], v149 offset:1024
	ds_read_b128 v[160:163], v149 offset:2048
	ds_read_b128 v[164:167], v149 offset:3072
	ds_read_b128 v[168:171], v150
	ds_read_b128 v[172:175], v150 offset:1024
	ds_read_b128 v[176:179], v150 offset:2048
	ds_read_b128 v[184:187], v150 offset:3072
	ds_read_b128 v[188:191], v151
	ds_read_b128 v[192:195], v151 offset:1024
	ds_read_b128 v[196:199], v151 offset:2048
	ds_read_b128 v[200:203], v151 offset:3072
	ds_read_b128 v[204:207], v151 offset:4096
	ds_read_b128 v[208:211], v151 offset:5120
	ds_read_b128 v[212:215], v151 offset:6144
	ds_read_b128 v[216:219], v151 offset:7168
	s_waitcnt vmcnt(8)
	s_waitcnt lgkmcnt(0)
	s_barrier
	s_setprio 1
	s_waitcnt lgkmcnt(0)
	v_mfma_f32_16x16x32_bf16 v[124:127], v[152:155], v[188:191], v[124:127]
	v_mfma_f32_16x16x32_bf16 v[124:127], v[156:159], v[192:195], v[124:127]
	v_mfma_f32_16x16x32_bf16 v[120:123], v[160:163], v[188:191], v[120:123]
	v_mfma_f32_16x16x32_bf16 v[120:123], v[164:167], v[192:195], v[120:123]
	v_mfma_f32_16x16x32_bf16 v[116:119], v[152:155], v[196:199], v[116:119]
	v_mfma_f32_16x16x32_bf16 v[116:119], v[156:159], v[200:203], v[116:119]
	v_mfma_f32_16x16x32_bf16 v[108:111], v[160:163], v[196:199], v[108:111]
	v_mfma_f32_16x16x32_bf16 v[108:111], v[164:167], v[200:203], v[108:111]
	v_mfma_f32_16x16x32_bf16 v[100:103], v[152:155], v[204:207], v[100:103]
	v_mfma_f32_16x16x32_bf16 v[100:103], v[156:159], v[208:211], v[100:103]
	v_mfma_f32_16x16x32_bf16 v[92:95], v[160:163], v[204:207], v[92:95]
	v_mfma_f32_16x16x32_bf16 v[92:95], v[164:167], v[208:211], v[92:95]
	v_mfma_f32_16x16x32_bf16 v[84:87], v[152:155], v[212:215], v[84:87]
	v_mfma_f32_16x16x32_bf16 v[84:87], v[156:159], v[216:219], v[84:87]
	v_mfma_f32_16x16x32_bf16 v[76:79], v[160:163], v[212:215], v[76:79]
	v_mfma_f32_16x16x32_bf16 v[76:79], v[164:167], v[216:219], v[76:79]
	v_mfma_f32_16x16x32_bf16 v[112:115], v[168:171], v[188:191], v[112:115]
	v_mfma_f32_16x16x32_bf16 v[112:115], v[172:175], v[192:195], v[112:115]
	v_mfma_f32_16x16x32_bf16 v[104:107], v[176:179], v[188:191], v[104:107]
	v_mfma_f32_16x16x32_bf16 v[104:107], v[184:187], v[192:195], v[104:107]
	v_mfma_f32_16x16x32_bf16 v[96:99], v[168:171], v[196:199], v[96:99]
	v_mfma_f32_16x16x32_bf16 v[96:99], v[172:175], v[200:203], v[96:99]
	v_mfma_f32_16x16x32_bf16 v[88:91], v[176:179], v[196:199], v[88:91]
	v_mfma_f32_16x16x32_bf16 v[88:91], v[184:187], v[200:203], v[88:91]
	v_mfma_f32_16x16x32_bf16 v[80:83], v[168:171], v[204:207], v[80:83]
	v_mfma_f32_16x16x32_bf16 v[80:83], v[172:175], v[208:211], v[80:83]
	v_mfma_f32_16x16x32_bf16 v[72:75], v[176:179], v[204:207], v[72:75]
	v_mfma_f32_16x16x32_bf16 v[72:75], v[184:187], v[208:211], v[72:75]
	v_mfma_f32_16x16x32_bf16 v[68:71], v[168:171], v[212:215], v[68:71]
	v_mfma_f32_16x16x32_bf16 v[68:71], v[172:175], v[216:219], v[68:71]
	v_mfma_f32_16x16x32_bf16 v[64:67], v[176:179], v[212:215], v[64:67]
	v_mfma_f32_16x16x32_bf16 v[64:67], v[184:187], v[216:219], v[64:67]
	s_setprio 0
	s_barrier
	s_add_i32 s18, s73, s66
	v_lshl_add_u64 v[144:145], s[60:61], 0, v[130:131]
	s_mov_b32 m0, s18
	s_nop 0
	global_load_lds_dwordx4 v[144:145], off
	s_add_i32 m0, s18, 0x2000
	s_add_u32 s18, s60, 0x40000
	v_lshl_add_u64 v[220:221], s[60:61], 0, v[134:135]
	s_addc_u32 s19, s61, 0
	s_add_i32 s79, s74, s66
	global_load_lds_dwordx4 v[220:221], off
	v_lshl_add_u64 v[222:223], s[18:19], 0, v[130:131]
	s_mov_b32 m0, s79
	v_lshl_add_u64 v[224:225], s[62:63], 0, v[132:133]
	global_load_lds_dwordx4 v[222:223], off
	v_lshl_add_u64 v[222:223], s[18:19], 0, v[134:135]
	s_add_i32 m0, s79, 0x2000
	s_nop 0
	global_load_lds_dwordx4 v[222:223], off
	v_lshl_add_u64 v[222:223], s[62:63], 0, v[128:129]
	s_mov_b32 m0, s57
	s_nop 0
	global_load_lds_dwordx4 v[222:223], off
	s_mov_b32 m0, s67
	s_nop 0
	global_load_lds_dwordx4 v[224:225], off
	ds_read_b128 v[188:191], v151 offset:16384
	ds_read_b128 v[192:195], v151 offset:17408
	ds_read_b128 v[196:199], v151 offset:18432
	ds_read_b128 v[200:203], v151 offset:19456
	ds_read_b128 v[204:207], v151 offset:20480
	ds_read_b128 v[208:211], v151 offset:21504
	ds_read_b128 v[212:215], v151 offset:22528
	ds_read_b128 v[216:219], v151 offset:23552
	s_waitcnt vmcnt(8)
	s_waitcnt lgkmcnt(0)
	s_barrier
	s_setprio 1
	s_waitcnt lgkmcnt(0)
	v_mfma_f32_16x16x32_bf16 v[60:63], v[152:155], v[188:191], v[60:63]
	v_mfma_f32_16x16x32_bf16 v[60:63], v[156:159], v[192:195], v[60:63]
	v_mfma_f32_16x16x32_bf16 v[56:59], v[160:163], v[188:191], v[56:59]
	v_mfma_f32_16x16x32_bf16 v[56:59], v[164:167], v[192:195], v[56:59]
	v_mfma_f32_16x16x32_bf16 v[52:55], v[152:155], v[196:199], v[52:55]
	v_mfma_f32_16x16x32_bf16 v[52:55], v[156:159], v[200:203], v[52:55]
	v_mfma_f32_16x16x32_bf16 v[44:47], v[160:163], v[196:199], v[44:47]
	v_mfma_f32_16x16x32_bf16 v[44:47], v[164:167], v[200:203], v[44:47]
	v_mfma_f32_16x16x32_bf16 v[36:39], v[152:155], v[204:207], v[36:39]
	v_mfma_f32_16x16x32_bf16 v[36:39], v[156:159], v[208:211], v[36:39]
	v_mfma_f32_16x16x32_bf16 v[28:31], v[160:163], v[204:207], v[28:31]
	v_mfma_f32_16x16x32_bf16 v[28:31], v[164:167], v[208:211], v[28:31]
	v_mfma_f32_16x16x32_bf16 v[20:23], v[152:155], v[212:215], v[20:23]
	v_mfma_f32_16x16x32_bf16 v[20:23], v[156:159], v[216:219], v[20:23]
	v_mfma_f32_16x16x32_bf16 v[12:15], v[160:163], v[212:215], v[12:15]
	v_mfma_f32_16x16x32_bf16 v[12:15], v[164:167], v[216:219], v[12:15]
	v_mfma_f32_16x16x32_bf16 v[48:51], v[168:171], v[188:191], v[48:51]
	v_mfma_f32_16x16x32_bf16 v[48:51], v[172:175], v[192:195], v[48:51]
	v_mfma_f32_16x16x32_bf16 v[40:43], v[176:179], v[188:191], v[40:43]
	v_mfma_f32_16x16x32_bf16 v[40:43], v[184:187], v[192:195], v[40:43]
	v_mfma_f32_16x16x32_bf16 v[32:35], v[168:171], v[196:199], v[32:35]
	v_mfma_f32_16x16x32_bf16 v[32:35], v[172:175], v[200:203], v[32:35]
	v_mfma_f32_16x16x32_bf16 v[24:27], v[176:179], v[196:199], v[24:27]
	v_mfma_f32_16x16x32_bf16 v[24:27], v[184:187], v[200:203], v[24:27]
	v_mfma_f32_16x16x32_bf16 v[16:19], v[168:171], v[204:207], v[16:19]
	v_mfma_f32_16x16x32_bf16 v[16:19], v[172:175], v[208:211], v[16:19]
	v_mfma_f32_16x16x32_bf16 v[8:11], v[176:179], v[204:207], v[8:11]
	v_mfma_f32_16x16x32_bf16 v[8:11], v[184:187], v[208:211], v[8:11]
	v_mfma_f32_16x16x32_bf16 v[4:7], v[168:171], v[212:215], v[4:7]
	v_mfma_f32_16x16x32_bf16 v[4:7], v[172:175], v[216:219], v[4:7]
	v_mfma_f32_16x16x32_bf16 v[0:3], v[176:179], v[212:215], v[0:3]
	v_mfma_f32_16x16x32_bf16 v[0:3], v[184:187], v[216:219], v[0:3]
	s_setprio 0
	s_barrier
.Lmid_gemm3:
	s_add_i32 s79, 0, 0x18000
	s_add_i32 s89, 0, 0x1c000
	v_add_u32_e32 v164, s79, v147
	v_add_u32_e32 v181, s89, v147
	s_add_u32 s18, s62, 0x40000
	s_addc_u32 s19, s63, 0
	s_mov_b32 m0, s68
	v_lshl_add_u64 v[226:227], s[18:19], 0, v[128:129]
	global_load_lds_dwordx4 v[226:227], off
	v_lshl_add_u64 v[226:227], s[18:19], 0, v[132:133]
	s_mov_b32 m0, s69
	s_nop 0
	global_load_lds_dwordx4 v[226:227], off
	ds_read_b128 v[152:155], v164
	ds_read_b128 v[156:159], v164 offset:1024
	ds_read_b128 v[160:163], v164 offset:2048
	ds_read_b128 v[164:167], v164 offset:3072
	ds_read_b128 v[168:171], v181
	ds_read_b128 v[172:175], v181 offset:1024
	ds_read_b128 v[176:179], v181 offset:2048
	ds_read_b128 v[184:187], v181 offset:3072
	ds_read_b128 v[188:191], v151 offset:32768
	ds_read_b128 v[192:195], v151 offset:33792
	ds_read_b128 v[196:199], v151 offset:34816
	ds_read_b128 v[200:203], v151 offset:35840
	ds_read_b128 v[204:207], v151 offset:36864
	ds_read_b128 v[208:211], v151 offset:37888
	ds_read_b128 v[212:215], v151 offset:38912
	ds_read_b128 v[216:219], v151 offset:39936
	s_waitcnt vmcnt(8)
	s_waitcnt lgkmcnt(0)
	s_barrier
	s_setprio 1
	s_waitcnt lgkmcnt(0)
	v_mfma_f32_16x16x32_bf16 v[124:127], v[152:155], v[188:191], v[124:127]
	v_mfma_f32_16x16x32_bf16 v[124:127], v[156:159], v[192:195], v[124:127]
	v_mfma_f32_16x16x32_bf16 v[120:123], v[160:163], v[188:191], v[120:123]
	v_mfma_f32_16x16x32_bf16 v[120:123], v[164:167], v[192:195], v[120:123]
	v_mfma_f32_16x16x32_bf16 v[116:119], v[152:155], v[196:199], v[116:119]
	v_mfma_f32_16x16x32_bf16 v[116:119], v[156:159], v[200:203], v[116:119]
	v_mfma_f32_16x16x32_bf16 v[108:111], v[160:163], v[196:199], v[108:111]
	v_mfma_f32_16x16x32_bf16 v[108:111], v[164:167], v[200:203], v[108:111]
	v_mfma_f32_16x16x32_bf16 v[100:103], v[152:155], v[204:207], v[100:103]
	v_mfma_f32_16x16x32_bf16 v[100:103], v[156:159], v[208:211], v[100:103]
	v_mfma_f32_16x16x32_bf16 v[92:95], v[160:163], v[204:207], v[92:95]
	v_mfma_f32_16x16x32_bf16 v[92:95], v[164:167], v[208:211], v[92:95]
	v_mfma_f32_16x16x32_bf16 v[84:87], v[152:155], v[212:215], v[84:87]
	v_mfma_f32_16x16x32_bf16 v[84:87], v[156:159], v[216:219], v[84:87]
	v_mfma_f32_16x16x32_bf16 v[76:79], v[160:163], v[212:215], v[76:79]
	v_mfma_f32_16x16x32_bf16 v[76:79], v[164:167], v[216:219], v[76:79]
	v_mfma_f32_16x16x32_bf16 v[112:115], v[168:171], v[188:191], v[112:115]
	v_mfma_f32_16x16x32_bf16 v[112:115], v[172:175], v[192:195], v[112:115]
	v_mfma_f32_16x16x32_bf16 v[104:107], v[176:179], v[188:191], v[104:107]
	v_mfma_f32_16x16x32_bf16 v[104:107], v[184:187], v[192:195], v[104:107]
	v_mfma_f32_16x16x32_bf16 v[96:99], v[168:171], v[196:199], v[96:99]
	v_mfma_f32_16x16x32_bf16 v[96:99], v[172:175], v[200:203], v[96:99]
	v_mfma_f32_16x16x32_bf16 v[88:91], v[176:179], v[196:199], v[88:91]
	v_mfma_f32_16x16x32_bf16 v[88:91], v[184:187], v[200:203], v[88:91]
	v_mfma_f32_16x16x32_bf16 v[80:83], v[168:171], v[204:207], v[80:83]
	v_mfma_f32_16x16x32_bf16 v[80:83], v[172:175], v[208:211], v[80:83]
	v_mfma_f32_16x16x32_bf16 v[72:75], v[176:179], v[204:207], v[72:75]
	v_mfma_f32_16x16x32_bf16 v[72:75], v[184:187], v[208:211], v[72:75]
	v_mfma_f32_16x16x32_bf16 v[68:71], v[168:171], v[212:215], v[68:71]
	v_mfma_f32_16x16x32_bf16 v[68:71], v[172:175], v[216:219], v[68:71]
	v_mfma_f32_16x16x32_bf16 v[64:67], v[176:179], v[212:215], v[64:67]
	v_mfma_f32_16x16x32_bf16 v[64:67], v[184:187], v[216:219], v[64:67]
	s_setprio 0
	s_barrier
	s_add_i32 s18, s79, s66
	v_lshl_add_u64 v[144:145], v[144:145], 0, s[10:11]
	s_mov_b32 m0, s18
	s_nop 0
	global_load_lds_dwordx4 v[144:145], off
	s_add_i32 m0, s18, 0x2000
	s_add_u32 s18, s60, 0x40080
	v_lshl_add_u64 v[144:145], v[220:221], 0, s[10:11]
	s_addc_u32 s19, s61, 0
	s_add_i32 s60, s89, s66
	global_load_lds_dwordx4 v[144:145], off
	v_lshl_add_u64 v[144:145], s[18:19], 0, v[130:131]
	s_mov_b32 m0, s60
	s_nop 0
	global_load_lds_dwordx4 v[144:145], off
	v_lshl_add_u64 v[144:145], s[18:19], 0, v[134:135]
	s_add_i32 m0, s60, 0x2000
	s_nop 0
	global_load_lds_dwordx4 v[144:145], off
	v_lshl_add_u64 v[144:145], v[222:223], 0, s[10:11]
	s_mov_b32 m0, s71
	s_nop 0
	global_load_lds_dwordx4 v[144:145], off
	v_lshl_add_u64 v[144:145], v[224:225], 0, s[10:11]
	s_mov_b32 m0, s72
	s_nop 0
	global_load_lds_dwordx4 v[144:145], off
	ds_read_b128 v[188:191], v151 offset:49152
	ds_read_b128 v[192:195], v151 offset:50176
	ds_read_b128 v[196:199], v151 offset:51200
	ds_read_b128 v[200:203], v151 offset:52224
	ds_read_b128 v[204:207], v151 offset:53248
	ds_read_b128 v[208:211], v151 offset:54272
	ds_read_b128 v[212:215], v151 offset:55296
	ds_read_b128 v[216:219], v151 offset:56320
	s_waitcnt vmcnt(8)
	s_waitcnt lgkmcnt(0)
	s_barrier
	s_setprio 1
	s_waitcnt lgkmcnt(0)
	v_mfma_f32_16x16x32_bf16 v[60:63], v[152:155], v[188:191], v[60:63]
	v_mfma_f32_16x16x32_bf16 v[60:63], v[156:159], v[192:195], v[60:63]
	v_mfma_f32_16x16x32_bf16 v[56:59], v[160:163], v[188:191], v[56:59]
	v_mfma_f32_16x16x32_bf16 v[56:59], v[164:167], v[192:195], v[56:59]
	v_mfma_f32_16x16x32_bf16 v[52:55], v[152:155], v[196:199], v[52:55]
	v_mfma_f32_16x16x32_bf16 v[52:55], v[156:159], v[200:203], v[52:55]
	v_mfma_f32_16x16x32_bf16 v[44:47], v[160:163], v[196:199], v[44:47]
	v_mfma_f32_16x16x32_bf16 v[44:47], v[164:167], v[200:203], v[44:47]
	v_mfma_f32_16x16x32_bf16 v[36:39], v[152:155], v[204:207], v[36:39]
	v_mfma_f32_16x16x32_bf16 v[36:39], v[156:159], v[208:211], v[36:39]
	v_mfma_f32_16x16x32_bf16 v[28:31], v[160:163], v[204:207], v[28:31]
	v_mfma_f32_16x16x32_bf16 v[28:31], v[164:167], v[208:211], v[28:31]
	v_mfma_f32_16x16x32_bf16 v[20:23], v[152:155], v[212:215], v[20:23]
	v_mfma_f32_16x16x32_bf16 v[20:23], v[156:159], v[216:219], v[20:23]
	v_mfma_f32_16x16x32_bf16 v[12:15], v[160:163], v[212:215], v[12:15]
	v_mfma_f32_16x16x32_bf16 v[12:15], v[164:167], v[216:219], v[12:15]
	v_mfma_f32_16x16x32_bf16 v[48:51], v[168:171], v[188:191], v[48:51]
	v_mfma_f32_16x16x32_bf16 v[48:51], v[172:175], v[192:195], v[48:51]
	v_mfma_f32_16x16x32_bf16 v[40:43], v[176:179], v[188:191], v[40:43]
	v_mfma_f32_16x16x32_bf16 v[40:43], v[184:187], v[192:195], v[40:43]
	v_mfma_f32_16x16x32_bf16 v[32:35], v[168:171], v[196:199], v[32:35]
	v_mfma_f32_16x16x32_bf16 v[32:35], v[172:175], v[200:203], v[32:35]
	v_mfma_f32_16x16x32_bf16 v[24:27], v[176:179], v[196:199], v[24:27]
	v_mfma_f32_16x16x32_bf16 v[24:27], v[184:187], v[200:203], v[24:27]
	v_mfma_f32_16x16x32_bf16 v[16:19], v[168:171], v[204:207], v[16:19]
	v_mfma_f32_16x16x32_bf16 v[16:19], v[172:175], v[208:211], v[16:19]
	v_mfma_f32_16x16x32_bf16 v[8:11], v[176:179], v[204:207], v[8:11]
	v_mfma_f32_16x16x32_bf16 v[8:11], v[184:187], v[208:211], v[8:11]
	v_mfma_f32_16x16x32_bf16 v[4:7], v[168:171], v[212:215], v[4:7]
	v_mfma_f32_16x16x32_bf16 v[4:7], v[172:175], v[216:219], v[4:7]
	v_mfma_f32_16x16x32_bf16 v[0:3], v[176:179], v[212:215], v[0:3]
	v_mfma_f32_16x16x32_bf16 v[0:3], v[184:187], v[216:219], v[0:3]
	s_setprio 0
	s_barrier
	s_add_i32 s88, s88, 2
	s_add_u32 s58, s58, 0x100
	s_addc_u32 s59, s59, 0
	s_add_u32 s86, s86, 0x100
	s_addc_u32 s87, s87, 0
	s_cmp_gt_u32 s88, 13
	s_cbranch_scc0 .LBB0_601
	s_and_b64 vcc, exec, s[12:13]
	s_cbranch_vccz .LBB0_604
	s_barrier

.LBB0_723:
	s_ashr_i32 s31, s30, 31
	s_lshl_b64 s[36:37], s[30:31], 19
	s_add_u32 s36, s80, s36
	s_addc_u32 s37, s81, s37
	s_and_b64 s[44:45], s[10:11], exec
	s_cselect_b32 s31, s37, s49
	s_cselect_b32 s70, s36, s48
	s_ashr_i32 s19, s18, 31
	s_lshl_b64 s[44:45], s[18:19], 19
	s_add_u32 s44, s56, s44
	s_addc_u32 s45, s57, s45
	s_and_b64 s[54:55], s[10:11], exec
	s_cselect_b32 s19, s45, s53
	s_cselect_b32 s71, s44, s52
	s_add_u32 s48, s48, 0x40080
	s_addc_u32 s49, s49, 0
	s_add_u32 s72, s52, 0x100
	s_addc_u32 s73, s53, 0
	s_mov_b32 s74, -2
	ds_read_b128 v[140:143], v147
	ds_read_b128 v[150:153], v147 offset:1024
	ds_read_b128 v[154:157], v147 offset:2048
	ds_read_b128 v[158:161], v147 offset:3072
	ds_read_b128 v[162:165], v148
	ds_read_b128 v[166:169], v148 offset:1024
	ds_read_b128 v[170:173], v148 offset:2048
	ds_read_b128 v[174:177], v148 offset:3072
	s_add_u32 s52, s48, 0xfffc0080
	s_addc_u32 s53, s49, -1
	s_cmp_eq_u32 s74, 12
	s_cselect_b32 s55, s31, s53
	s_cselect_b32 s54, s70, s52
	s_cselect_b32 s53, s19, s73
	s_cselect_b32 s52, s71, s72
	v_lshl_add_u64 v[178:179], s[48:49], 0, v[132:133]
	s_add_i32 m0, s47, 0xc000
	ds_read_b128 v[184:187], v149
	ds_read_b128 v[188:191], v149 offset:1024
	ds_read_b128 v[192:195], v149 offset:2048
	ds_read_b128 v[196:199], v149 offset:3072
	ds_read_b128 v[200:203], v149 offset:4096
	ds_read_b128 v[204:207], v149 offset:5120
	ds_read_b128 v[208:211], v149 offset:6144
	ds_read_b128 v[212:215], v149 offset:7168
	global_load_lds_dwordx4 v[178:179], off
	v_lshl_add_u64 v[178:179], s[48:49], 0, v[134:135]
	s_add_i32 m0, s47, 0xe000
	s_nop 0
	global_load_lds_dwordx4 v[178:179], off
	s_waitcnt vmcnt(8)
	s_waitcnt lgkmcnt(0)
	s_barrier
	s_setprio 1
	s_waitcnt lgkmcnt(0)
	v_mfma_f32_16x16x32_bf16 v[124:127], v[140:143], v[184:187], 0
	v_mfma_f32_16x16x32_bf16 v[124:127], v[150:153], v[188:191], v[124:127]
	v_mfma_f32_16x16x32_bf16 v[120:123], v[154:157], v[184:187], 0
	v_mfma_f32_16x16x32_bf16 v[120:123], v[158:161], v[188:191], v[120:123]
	v_mfma_f32_16x16x32_bf16 v[108:111], v[140:143], v[192:195], 0
	v_mfma_f32_16x16x32_bf16 v[108:111], v[150:153], v[196:199], v[108:111]
	v_mfma_f32_16x16x32_bf16 v[104:107], v[154:157], v[192:195], 0
	v_mfma_f32_16x16x32_bf16 v[104:107], v[158:161], v[196:199], v[104:107]
	v_mfma_f32_16x16x32_bf16 v[92:95], v[140:143], v[200:203], 0
	v_mfma_f32_16x16x32_bf16 v[92:95], v[150:153], v[204:207], v[92:95]
	v_mfma_f32_16x16x32_bf16 v[88:91], v[154:157], v[200:203], 0
	v_mfma_f32_16x16x32_bf16 v[88:91], v[158:161], v[204:207], v[88:91]
	v_mfma_f32_16x16x32_bf16 v[76:79], v[140:143], v[208:211], 0
	v_mfma_f32_16x16x32_bf16 v[76:79], v[150:153], v[212:215], v[76:79]
	v_mfma_f32_16x16x32_bf16 v[72:75], v[154:157], v[208:211], 0
	v_mfma_f32_16x16x32_bf16 v[72:75], v[158:161], v[212:215], v[72:75]
	v_mfma_f32_16x16x32_bf16 v[116:119], v[162:165], v[184:187], 0
	v_mfma_f32_16x16x32_bf16 v[116:119], v[166:169], v[188:191], v[116:119]
	v_mfma_f32_16x16x32_bf16 v[112:115], v[170:173], v[184:187], 0
	v_mfma_f32_16x16x32_bf16 v[112:115], v[174:177], v[188:191], v[112:115]
	v_mfma_f32_16x16x32_bf16 v[100:103], v[162:165], v[192:195], 0
	v_mfma_f32_16x16x32_bf16 v[100:103], v[166:169], v[196:199], v[100:103]
	v_mfma_f32_16x16x32_bf16 v[96:99], v[170:173], v[192:195], 0
	v_mfma_f32_16x16x32_bf16 v[96:99], v[174:177], v[196:199], v[96:99]
	v_mfma_f32_16x16x32_bf16 v[84:87], v[162:165], v[200:203], 0
	v_mfma_f32_16x16x32_bf16 v[84:87], v[166:169], v[204:207], v[84:87]
	v_mfma_f32_16x16x32_bf16 v[80:83], v[170:173], v[200:203], 0
	v_mfma_f32_16x16x32_bf16 v[80:83], v[174:177], v[204:207], v[80:83]
	v_mfma_f32_16x16x32_bf16 v[68:71], v[162:165], v[208:211], 0
	v_mfma_f32_16x16x32_bf16 v[68:71], v[166:169], v[212:215], v[68:71]
	v_mfma_f32_16x16x32_bf16 v[64:67], v[170:173], v[208:211], 0
	v_mfma_f32_16x16x32_bf16 v[64:67], v[174:177], v[212:215], v[64:67]
	s_setprio 0
	s_barrier
	s_add_i32 s75, s66, s58
	v_lshl_add_u64 v[178:179], s[52:53], 0, v[130:131]
	s_mov_b32 m0, s75
	s_nop 0
	global_load_lds_dwordx4 v[178:179], off
	s_add_i32 m0, s75, 0x2000
	s_add_u32 s76, s52, 0x40000
	v_lshl_add_u64 v[216:217], s[52:53], 0, v[128:129]
	s_addc_u32 s77, s53, 0
	s_add_i32 s75, s67, s58
	global_load_lds_dwordx4 v[216:217], off
	v_lshl_add_u64 v[218:219], s[76:77], 0, v[130:131]
	s_mov_b32 m0, s75
	v_lshl_add_u64 v[220:221], s[54:55], 0, v[128:129]
	global_load_lds_dwordx4 v[218:219], off
	v_lshl_add_u64 v[218:219], s[76:77], 0, v[128:129]
	s_add_i32 m0, s75, 0x2000
	s_nop 0
	global_load_lds_dwordx4 v[218:219], off
	v_lshl_add_u64 v[218:219], s[54:55], 0, v[130:131]
	s_mov_b32 m0, s47
	s_nop 0
	global_load_lds_dwordx4 v[218:219], off
	s_mov_b32 m0, s60
	s_nop 0
	global_load_lds_dwordx4 v[220:221], off
	ds_read_b128 v[184:187], v149 offset:16384
	ds_read_b128 v[188:191], v149 offset:17408
	ds_read_b128 v[192:195], v149 offset:18432
	ds_read_b128 v[196:199], v149 offset:19456
	ds_read_b128 v[200:203], v149 offset:20480
	ds_read_b128 v[204:207], v149 offset:21504
	ds_read_b128 v[208:211], v149 offset:22528
	ds_read_b128 v[212:215], v149 offset:23552
	s_waitcnt vmcnt(8)
	s_waitcnt lgkmcnt(0)
	s_barrier
	s_setprio 1
	s_waitcnt lgkmcnt(0)
	v_mfma_f32_16x16x32_bf16 v[60:63], v[140:143], v[184:187], 0
	v_mfma_f32_16x16x32_bf16 v[60:63], v[150:153], v[188:191], v[60:63]
	v_mfma_f32_16x16x32_bf16 v[56:59], v[154:157], v[184:187], 0
	v_mfma_f32_16x16x32_bf16 v[56:59], v[158:161], v[188:191], v[56:59]
	v_mfma_f32_16x16x32_bf16 v[44:47], v[140:143], v[192:195], 0
	v_mfma_f32_16x16x32_bf16 v[44:47], v[150:153], v[196:199], v[44:47]
	v_mfma_f32_16x16x32_bf16 v[40:43], v[154:157], v[192:195], 0
	v_mfma_f32_16x16x32_bf16 v[40:43], v[158:161], v[196:199], v[40:43]
	v_mfma_f32_16x16x32_bf16 v[28:31], v[140:143], v[200:203], 0
	v_mfma_f32_16x16x32_bf16 v[28:31], v[150:153], v[204:207], v[28:31]
	v_mfma_f32_16x16x32_bf16 v[24:27], v[154:157], v[200:203], 0
	v_mfma_f32_16x16x32_bf16 v[24:27], v[158:161], v[204:207], v[24:27]
	v_mfma_f32_16x16x32_bf16 v[12:15], v[140:143], v[208:211], 0
	v_mfma_f32_16x16x32_bf16 v[12:15], v[150:153], v[212:215], v[12:15]
	v_mfma_f32_16x16x32_bf16 v[8:11], v[154:157], v[208:211], 0
	v_mfma_f32_16x16x32_bf16 v[8:11], v[158:161], v[212:215], v[8:11]
	v_mfma_f32_16x16x32_bf16 v[52:55], v[162:165], v[184:187], 0
	v_mfma_f32_16x16x32_bf16 v[52:55], v[166:169], v[188:191], v[52:55]
	v_mfma_f32_16x16x32_bf16 v[48:51], v[170:173], v[184:187], 0
	v_mfma_f32_16x16x32_bf16 v[48:51], v[174:177], v[188:191], v[48:51]
	v_mfma_f32_16x16x32_bf16 v[36:39], v[162:165], v[192:195], 0
	v_mfma_f32_16x16x32_bf16 v[36:39], v[166:169], v[196:199], v[36:39]
	v_mfma_f32_16x16x32_bf16 v[32:35], v[170:173], v[192:195], 0
	v_mfma_f32_16x16x32_bf16 v[32:35], v[174:177], v[196:199], v[32:35]
	v_mfma_f32_16x16x32_bf16 v[20:23], v[162:165], v[200:203], 0
	v_mfma_f32_16x16x32_bf16 v[20:23], v[166:169], v[204:207], v[20:23]
	v_mfma_f32_16x16x32_bf16 v[16:19], v[170:173], v[200:203], 0
	v_mfma_f32_16x16x32_bf16 v[16:19], v[174:177], v[204:207], v[16:19]
	v_mfma_f32_16x16x32_bf16 v[4:7], v[162:165], v[208:211], 0
	v_mfma_f32_16x16x32_bf16 v[4:7], v[166:169], v[212:215], v[4:7]
	v_mfma_f32_16x16x32_bf16 v[0:3], v[170:173], v[208:211], 0
	v_mfma_f32_16x16x32_bf16 v[0:3], v[174:177], v[212:215], v[0:3]
	s_setprio 0
	s_barrier
	s_branch .Lmid_gemm4
.LBB0_724:
	s_add_u32 s52, s48, 0xfffc0080
	s_addc_u32 s53, s49, -1
	s_cmp_eq_u32 s74, 12
	s_cselect_b32 s55, s31, s53
	s_cselect_b32 s54, s70, s52
	s_cselect_b32 s53, s19, s73
	s_cselect_b32 s52, s71, s72
	v_lshl_add_u64 v[178:179], s[48:49], 0, v[132:133]
	s_add_i32 m0, s47, 0xc000
	s_nop 0
	global_load_lds_dwordx4 v[178:179], off
	v_lshl_add_u64 v[178:179], s[48:49], 0, v[134:135]
	s_add_i32 m0, s47, 0xe000
	s_nop 0
	global_load_lds_dwordx4 v[178:179], off
	ds_read_b128 v[140:143], v147
	ds_read_b128 v[150:153], v147 offset:1024
	ds_read_b128 v[154:157], v147 offset:2048
	ds_read_b128 v[158:161], v147 offset:3072
	ds_read_b128 v[162:165], v148
	ds_read_b128 v[166:169], v148 offset:1024
	ds_read_b128 v[170:173], v148 offset:2048
	ds_read_b128 v[174:177], v148 offset:3072
	ds_read_b128 v[184:187], v149
	ds_read_b128 v[188:191], v149 offset:1024
	ds_read_b128 v[192:195], v149 offset:2048
	ds_read_b128 v[196:199], v149 offset:3072
	ds_read_b128 v[200:203], v149 offset:4096
	ds_read_b128 v[204:207], v149 offset:5120
	ds_read_b128 v[208:211], v149 offset:6144
	ds_read_b128 v[212:215], v149 offset:7168
	s_waitcnt vmcnt(8)
	s_waitcnt lgkmcnt(0)
	s_barrier
	s_setprio 1
	s_waitcnt lgkmcnt(0)
	v_mfma_f32_16x16x32_bf16 v[124:127], v[140:143], v[184:187], v[124:127]
	v_mfma_f32_16x16x32_bf16 v[124:127], v[150:153], v[188:191], v[124:127]
	v_mfma_f32_16x16x32_bf16 v[120:123], v[154:157], v[184:187], v[120:123]
	v_mfma_f32_16x16x32_bf16 v[120:123], v[158:161], v[188:191], v[120:123]
	v_mfma_f32_16x16x32_bf16 v[108:111], v[140:143], v[192:195], v[108:111]
	v_mfma_f32_16x16x32_bf16 v[108:111], v[150:153], v[196:199], v[108:111]
	v_mfma_f32_16x16x32_bf16 v[104:107], v[154:157], v[192:195], v[104:107]
	v_mfma_f32_16x16x32_bf16 v[104:107], v[158:161], v[196:199], v[104:107]
	v_mfma_f32_16x16x32_bf16 v[92:95], v[140:143], v[200:203], v[92:95]
	v_mfma_f32_16x16x32_bf16 v[92:95], v[150:153], v[204:207], v[92:95]
	v_mfma_f32_16x16x32_bf16 v[88:91], v[154:157], v[200:203], v[88:91]
	v_mfma_f32_16x16x32_bf16 v[88:91], v[158:161], v[204:207], v[88:91]
	v_mfma_f32_16x16x32_bf16 v[76:79], v[140:143], v[208:211], v[76:79]
	v_mfma_f32_16x16x32_bf16 v[76:79], v[150:153], v[212:215], v[76:79]
	v_mfma_f32_16x16x32_bf16 v[72:75], v[154:157], v[208:211], v[72:75]
	v_mfma_f32_16x16x32_bf16 v[72:75], v[158:161], v[212:215], v[72:75]
	v_mfma_f32_16x16x32_bf16 v[116:119], v[162:165], v[184:187], v[116:119]
	v_mfma_f32_16x16x32_bf16 v[116:119], v[166:169], v[188:191], v[116:119]
	v_mfma_f32_16x16x32_bf16 v[112:115], v[170:173], v[184:187], v[112:115]
	v_mfma_f32_16x16x32_bf16 v[112:115], v[174:177], v[188:191], v[112:115]
	v_mfma_f32_16x16x32_bf16 v[100:103], v[162:165], v[192:195], v[100:103]
	v_mfma_f32_16x16x32_bf16 v[100:103], v[166:169], v[196:199], v[100:103]
	v_mfma_f32_16x16x32_bf16 v[96:99], v[170:173], v[192:195], v[96:99]
	v_mfma_f32_16x16x32_bf16 v[96:99], v[174:177], v[196:199], v[96:99]
	v_mfma_f32_16x16x32_bf16 v[84:87], v[162:165], v[200:203], v[84:87]
	v_mfma_f32_16x16x32_bf16 v[84:87], v[166:169], v[204:207], v[84:87]
	v_mfma_f32_16x16x32_bf16 v[80:83], v[170:173], v[200:203], v[80:83]
	v_mfma_f32_16x16x32_bf16 v[80:83], v[174:177], v[204:207], v[80:83]
	v_mfma_f32_16x16x32_bf16 v[68:71], v[162:165], v[208:211], v[68:71]
	v_mfma_f32_16x16x32_bf16 v[68:71], v[166:169], v[212:215], v[68:71]
	v_mfma_f32_16x16x32_bf16 v[64:67], v[170:173], v[208:211], v[64:67]
	v_mfma_f32_16x16x32_bf16 v[64:67], v[174:177], v[212:215], v[64:67]
	s_setprio 0
	s_barrier
	s_add_i32 s75, s66, s58
	v_lshl_add_u64 v[178:179], s[52:53], 0, v[130:131]
	s_mov_b32 m0, s75
	s_nop 0
	global_load_lds_dwordx4 v[178:179], off
	s_add_i32 m0, s75, 0x2000
	s_add_u32 s76, s52, 0x40000
	v_lshl_add_u64 v[216:217], s[52:53], 0, v[128:129]
	s_addc_u32 s77, s53, 0
	s_add_i32 s75, s67, s58
	global_load_lds_dwordx4 v[216:217], off
	v_lshl_add_u64 v[218:219], s[76:77], 0, v[130:131]
	s_mov_b32 m0, s75
	v_lshl_add_u64 v[220:221], s[54:55], 0, v[128:129]
	global_load_lds_dwordx4 v[218:219], off
	v_lshl_add_u64 v[218:219], s[76:77], 0, v[128:129]
	s_add_i32 m0, s75, 0x2000
	s_nop 0
	global_load_lds_dwordx4 v[218:219], off
	v_lshl_add_u64 v[218:219], s[54:55], 0, v[130:131]
	s_mov_b32 m0, s47
	s_nop 0
	global_load_lds_dwordx4 v[218:219], off
	s_mov_b32 m0, s60
	s_nop 0
	global_load_lds_dwordx4 v[220:221], off
	ds_read_b128 v[184:187], v149 offset:16384
	ds_read_b128 v[188:191], v149 offset:17408
	ds_read_b128 v[192:195], v149 offset:18432
	ds_read_b128 v[196:199], v149 offset:19456
	ds_read_b128 v[200:203], v149 offset:20480
	ds_read_b128 v[204:207], v149 offset:21504
	ds_read_b128 v[208:211], v149 offset:22528
	ds_read_b128 v[212:215], v149 offset:23552
	s_waitcnt vmcnt(8)
	s_waitcnt lgkmcnt(0)
	s_barrier
	s_setprio 1
	s_waitcnt lgkmcnt(0)
	v_mfma_f32_16x16x32_bf16 v[60:63], v[140:143], v[184:187], v[60:63]
	v_mfma_f32_16x16x32_bf16 v[60:63], v[150:153], v[188:191], v[60:63]
	v_mfma_f32_16x16x32_bf16 v[56:59], v[154:157], v[184:187], v[56:59]
	v_mfma_f32_16x16x32_bf16 v[56:59], v[158:161], v[188:191], v[56:59]
	v_mfma_f32_16x16x32_bf16 v[44:47], v[140:143], v[192:195], v[44:47]
	v_mfma_f32_16x16x32_bf16 v[44:47], v[150:153], v[196:199], v[44:47]
	v_mfma_f32_16x16x32_bf16 v[40:43], v[154:157], v[192:195], v[40:43]
	v_mfma_f32_16x16x32_bf16 v[40:43], v[158:161], v[196:199], v[40:43]
	v_mfma_f32_16x16x32_bf16 v[28:31], v[140:143], v[200:203], v[28:31]
	v_mfma_f32_16x16x32_bf16 v[28:31], v[150:153], v[204:207], v[28:31]
	v_mfma_f32_16x16x32_bf16 v[24:27], v[154:157], v[200:203], v[24:27]
	v_mfma_f32_16x16x32_bf16 v[24:27], v[158:161], v[204:207], v[24:27]
	v_mfma_f32_16x16x32_bf16 v[12:15], v[140:143], v[208:211], v[12:15]
	v_mfma_f32_16x16x32_bf16 v[12:15], v[150:153], v[212:215], v[12:15]
	v_mfma_f32_16x16x32_bf16 v[8:11], v[154:157], v[208:211], v[8:11]
	v_mfma_f32_16x16x32_bf16 v[8:11], v[158:161], v[212:215], v[8:11]
	v_mfma_f32_16x16x32_bf16 v[52:55], v[162:165], v[184:187], v[52:55]
	v_mfma_f32_16x16x32_bf16 v[52:55], v[166:169], v[188:191], v[52:55]
	v_mfma_f32_16x16x32_bf16 v[48:51], v[170:173], v[184:187], v[48:51]
	v_mfma_f32_16x16x32_bf16 v[48:51], v[174:177], v[188:191], v[48:51]
	v_mfma_f32_16x16x32_bf16 v[36:39], v[162:165], v[192:195], v[36:39]
	v_mfma_f32_16x16x32_bf16 v[36:39], v[166:169], v[196:199], v[36:39]
	v_mfma_f32_16x16x32_bf16 v[32:35], v[170:173], v[192:195], v[32:35]
	v_mfma_f32_16x16x32_bf16 v[32:35], v[174:177], v[196:199], v[32:35]
	v_mfma_f32_16x16x32_bf16 v[20:23], v[162:165], v[200:203], v[20:23]
	v_mfma_f32_16x16x32_bf16 v[20:23], v[166:169], v[204:207], v[20:23]
	v_mfma_f32_16x16x32_bf16 v[16:19], v[170:173], v[200:203], v[16:19]
	v_mfma_f32_16x16x32_bf16 v[16:19], v[174:177], v[204:207], v[16:19]
	v_mfma_f32_16x16x32_bf16 v[4:7], v[162:165], v[208:211], v[4:7]
	v_mfma_f32_16x16x32_bf16 v[4:7], v[166:169], v[212:215], v[4:7]
	v_mfma_f32_16x16x32_bf16 v[0:3], v[170:173], v[208:211], v[0:3]
	v_mfma_f32_16x16x32_bf16 v[0:3], v[174:177], v[212:215], v[0:3]
	s_setprio 0
	s_barrier
.Lmid_gemm4:
	s_add_i32 s75, 0, 0x18000
	s_add_i32 s76, 0, 0x1c000
	v_add_u32_e32 v158, s75, v145
	v_add_u32_e32 v174, s76, v145
	s_add_u32 s54, s54, 0x40000
	s_addc_u32 s55, s55, 0
	s_mov_b32 m0, s61
	v_lshl_add_u64 v[222:223], s[54:55], 0, v[130:131]
	global_load_lds_dwordx4 v[222:223], off
	v_lshl_add_u64 v[222:223], s[54:55], 0, v[128:129]
	s_mov_b32 m0, s62
	s_nop 0
	global_load_lds_dwordx4 v[222:223], off
	ds_read_b128 v[140:143], v158
	ds_read_b128 v[150:153], v158 offset:1024
	ds_read_b128 v[154:157], v158 offset:2048
	ds_read_b128 v[158:161], v158 offset:3072
	ds_read_b128 v[162:165], v174
	ds_read_b128 v[166:169], v174 offset:1024
	ds_read_b128 v[170:173], v174 offset:2048
	ds_read_b128 v[174:177], v174 offset:3072
	ds_read_b128 v[184:187], v149 offset:32768
	ds_read_b128 v[188:191], v149 offset:33792
	ds_read_b128 v[192:195], v149 offset:34816
	ds_read_b128 v[196:199], v149 offset:35840
	ds_read_b128 v[200:203], v149 offset:36864
	ds_read_b128 v[204:207], v149 offset:37888
	ds_read_b128 v[208:211], v149 offset:38912
	ds_read_b128 v[212:215], v149 offset:39936
	s_waitcnt vmcnt(8)
	s_waitcnt lgkmcnt(0)
	s_barrier
	s_setprio 1
	s_waitcnt lgkmcnt(0)
	v_mfma_f32_16x16x32_bf16 v[124:127], v[140:143], v[184:187], v[124:127]
	v_mfma_f32_16x16x32_bf16 v[124:127], v[150:153], v[188:191], v[124:127]
	v_mfma_f32_16x16x32_bf16 v[120:123], v[154:157], v[184:187], v[120:123]
	v_mfma_f32_16x16x32_bf16 v[120:123], v[158:161], v[188:191], v[120:123]
	v_mfma_f32_16x16x32_bf16 v[108:111], v[140:143], v[192:195], v[108:111]
	v_mfma_f32_16x16x32_bf16 v[108:111], v[150:153], v[196:199], v[108:111]
	v_mfma_f32_16x16x32_bf16 v[104:107], v[154:157], v[192:195], v[104:107]
	v_mfma_f32_16x16x32_bf16 v[104:107], v[158:161], v[196:199], v[104:107]
	v_mfma_f32_16x16x32_bf16 v[92:95], v[140:143], v[200:203], v[92:95]
	v_mfma_f32_16x16x32_bf16 v[92:95], v[150:153], v[204:207], v[92:95]
	v_mfma_f32_16x16x32_bf16 v[88:91], v[154:157], v[200:203], v[88:91]
	v_mfma_f32_16x16x32_bf16 v[88:91], v[158:161], v[204:207], v[88:91]
	v_mfma_f32_16x16x32_bf16 v[76:79], v[140:143], v[208:211], v[76:79]
	v_mfma_f32_16x16x32_bf16 v[76:79], v[150:153], v[212:215], v[76:79]
	v_mfma_f32_16x16x32_bf16 v[72:75], v[154:157], v[208:211], v[72:75]
	v_mfma_f32_16x16x32_bf16 v[72:75], v[158:161], v[212:215], v[72:75]
	v_mfma_f32_16x16x32_bf16 v[116:119], v[162:165], v[184:187], v[116:119]
	v_mfma_f32_16x16x32_bf16 v[116:119], v[166:169], v[188:191], v[116:119]
	v_mfma_f32_16x16x32_bf16 v[112:115], v[170:173], v[184:187], v[112:115]
	v_mfma_f32_16x16x32_bf16 v[112:115], v[174:177], v[188:191], v[112:115]
	v_mfma_f32_16x16x32_bf16 v[100:103], v[162:165], v[192:195], v[100:103]
	v_mfma_f32_16x16x32_bf16 v[100:103], v[166:169], v[196:199], v[100:103]
	v_mfma_f32_16x16x32_bf16 v[96:99], v[170:173], v[192:195], v[96:99]
	v_mfma_f32_16x16x32_bf16 v[96:99], v[174:177], v[196:199], v[96:99]
	v_mfma_f32_16x16x32_bf16 v[84:87], v[162:165], v[200:203], v[84:87]
	v_mfma_f32_16x16x32_bf16 v[84:87], v[166:169], v[204:207], v[84:87]
	v_mfma_f32_16x16x32_bf16 v[80:83], v[170:173], v[200:203], v[80:83]
	v_mfma_f32_16x16x32_bf16 v[80:83], v[174:177], v[204:207], v[80:83]
	v_mfma_f32_16x16x32_bf16 v[68:71], v[162:165], v[208:211], v[68:71]
	v_mfma_f32_16x16x32_bf16 v[68:71], v[166:169], v[212:215], v[68:71]
	v_mfma_f32_16x16x32_bf16 v[64:67], v[170:173], v[208:211], v[64:67]
	v_mfma_f32_16x16x32_bf16 v[64:67], v[174:177], v[212:215], v[64:67]
	s_setprio 0
	s_barrier
	s_add_i32 s54, s75, s58
	v_lshl_add_u64 v[178:179], v[178:179], 0, s[12:13]
	s_mov_b32 m0, s54
	s_nop 0
	global_load_lds_dwordx4 v[178:179], off
	s_add_i32 m0, s54, 0x2000
	s_add_u32 s52, s52, 0x40080
	v_lshl_add_u64 v[178:179], v[216:217], 0, s[12:13]
	s_addc_u32 s53, s53, 0
	s_add_i32 s54, s76, s58
	global_load_lds_dwordx4 v[178:179], off
	v_lshl_add_u64 v[178:179], s[52:53], 0, v[130:131]
	s_mov_b32 m0, s54
	s_nop 0
	global_load_lds_dwordx4 v[178:179], off
	v_lshl_add_u64 v[178:179], s[52:53], 0, v[128:129]
	s_add_i32 m0, s54, 0x2000
	s_nop 0
	global_load_lds_dwordx4 v[178:179], off
	v_lshl_add_u64 v[178:179], v[218:219], 0, s[12:13]
	s_mov_b32 m0, s64
	s_nop 0
	global_load_lds_dwordx4 v[178:179], off
	v_lshl_add_u64 v[178:179], v[220:221], 0, s[12:13]
	s_mov_b32 m0, s65
	s_nop 0
	global_load_lds_dwordx4 v[178:179], off
	ds_read_b128 v[184:187], v149 offset:49152
	ds_read_b128 v[188:191], v149 offset:50176
	ds_read_b128 v[192:195], v149 offset:51200
	ds_read_b128 v[196:199], v149 offset:52224
	ds_read_b128 v[200:203], v149 offset:53248
	ds_read_b128 v[204:207], v149 offset:54272
	ds_read_b128 v[208:211], v149 offset:55296
	ds_read_b128 v[212:215], v149 offset:56320
	s_waitcnt vmcnt(8)
	s_waitcnt lgkmcnt(0)
	s_barrier
	s_setprio 1
	s_waitcnt lgkmcnt(0)
	v_mfma_f32_16x16x32_bf16 v[60:63], v[140:143], v[184:187], v[60:63]
	v_mfma_f32_16x16x32_bf16 v[60:63], v[150:153], v[188:191], v[60:63]
	v_mfma_f32_16x16x32_bf16 v[56:59], v[154:157], v[184:187], v[56:59]
	v_mfma_f32_16x16x32_bf16 v[56:59], v[158:161], v[188:191], v[56:59]
	v_mfma_f32_16x16x32_bf16 v[44:47], v[140:143], v[192:195], v[44:47]
	v_mfma_f32_16x16x32_bf16 v[44:47], v[150:153], v[196:199], v[44:47]
	v_mfma_f32_16x16x32_bf16 v[40:43], v[154:157], v[192:195], v[40:43]
	v_mfma_f32_16x16x32_bf16 v[40:43], v[158:161], v[196:199], v[40:43]
	v_mfma_f32_16x16x32_bf16 v[28:31], v[140:143], v[200:203], v[28:31]
	v_mfma_f32_16x16x32_bf16 v[28:31], v[150:153], v[204:207], v[28:31]
	v_mfma_f32_16x16x32_bf16 v[24:27], v[154:157], v[200:203], v[24:27]
	v_mfma_f32_16x16x32_bf16 v[24:27], v[158:161], v[204:207], v[24:27]
	v_mfma_f32_16x16x32_bf16 v[12:15], v[140:143], v[208:211], v[12:15]
	v_mfma_f32_16x16x32_bf16 v[12:15], v[150:153], v[212:215], v[12:15]
	v_mfma_f32_16x16x32_bf16 v[8:11], v[154:157], v[208:211], v[8:11]
	v_mfma_f32_16x16x32_bf16 v[8:11], v[158:161], v[212:215], v[8:11]
	v_mfma_f32_16x16x32_bf16 v[52:55], v[162:165], v[184:187], v[52:55]
	v_mfma_f32_16x16x32_bf16 v[52:55], v[166:169], v[188:191], v[52:55]
	v_mfma_f32_16x16x32_bf16 v[48:51], v[170:173], v[184:187], v[48:51]
	v_mfma_f32_16x16x32_bf16 v[48:51], v[174:177], v[188:191], v[48:51]
	v_mfma_f32_16x16x32_bf16 v[36:39], v[162:165], v[192:195], v[36:39]
	v_mfma_f32_16x16x32_bf16 v[36:39], v[166:169], v[196:199], v[36:39]
	v_mfma_f32_16x16x32_bf16 v[32:35], v[170:173], v[192:195], v[32:35]
	v_mfma_f32_16x16x32_bf16 v[32:35], v[174:177], v[196:199], v[32:35]
	v_mfma_f32_16x16x32_bf16 v[20:23], v[162:165], v[200:203], v[20:23]
	v_mfma_f32_16x16x32_bf16 v[20:23], v[166:169], v[204:207], v[20:23]
	v_mfma_f32_16x16x32_bf16 v[16:19], v[170:173], v[200:203], v[16:19]
	v_mfma_f32_16x16x32_bf16 v[16:19], v[174:177], v[204:207], v[16:19]
	v_mfma_f32_16x16x32_bf16 v[4:7], v[162:165], v[208:211], v[4:7]
	v_mfma_f32_16x16x32_bf16 v[4:7], v[166:169], v[212:215], v[4:7]
	v_mfma_f32_16x16x32_bf16 v[0:3], v[170:173], v[208:211], v[0:3]
	v_mfma_f32_16x16x32_bf16 v[0:3], v[174:177], v[212:215], v[0:3]
	s_setprio 0
	s_barrier
	s_add_i32 s74, s74, 2
	s_add_u32 s48, s48, 0x100
	s_addc_u32 s49, s49, 0
	s_add_u32 s72, s72, 0x100
	s_addc_u32 s73, s73, 0
	s_cmp_gt_u32 s74, 13
	s_cbranch_scc0 .LBB0_724
	s_and_b64 vcc, exec, s[16:17]
	s_cbranch_vccz .LBB0_727
	s_barrier

.LBB0_803:
	s_add_u32 s84, s54, 0x100
	s_addc_u32 s85, s55, 0
	s_mov_b32 s86, -2
	ds_read_b128 v[152:155], v149
	ds_read_b128 v[156:159], v149 offset:1024
	ds_read_b128 v[160:163], v149 offset:2048
	ds_read_b128 v[164:167], v149 offset:3072
	ds_read_b128 v[168:171], v150
	ds_read_b128 v[172:175], v150 offset:1024
	ds_read_b128 v[176:179], v150 offset:2048
	ds_read_b128 v[184:187], v150 offset:3072
	s_add_u32 s54, s52, 0x100
	s_addc_u32 s55, s53, 0
	s_cmp_eq_u32 s86, 40
	s_cselect_b32 s59, s13, s55
	s_cselect_b32 s58, s12, s54
	s_cselect_b32 s57, s49, s85
	s_cselect_b32 s56, s48, s84
	v_lshl_add_u64 v[144:145], s[52:53], 0, v[136:137]
	s_add_i32 m0, s63, 0xc000
	ds_read_b128 v[188:191], v151
	ds_read_b128 v[192:195], v151 offset:1024
	ds_read_b128 v[196:199], v151 offset:2048
	ds_read_b128 v[200:203], v151 offset:3072
	ds_read_b128 v[204:207], v151 offset:4096
	ds_read_b128 v[208:211], v151 offset:5120
	ds_read_b128 v[212:215], v151 offset:6144
	ds_read_b128 v[216:219], v151 offset:7168
	global_load_lds_dwordx4 v[144:145], off
	v_lshl_add_u64 v[144:145], s[52:53], 0, v[138:139]
	s_add_i32 m0, s63, 0xe000
	s_nop 0
	global_load_lds_dwordx4 v[144:145], off
	s_waitcnt vmcnt(8)
	s_waitcnt lgkmcnt(0)
	s_barrier
	s_setprio 1
	s_waitcnt lgkmcnt(0)
	v_mfma_f32_16x16x32_bf16 v[124:127], v[152:155], v[188:191], 0
	v_mfma_f32_16x16x32_bf16 v[124:127], v[156:159], v[192:195], v[124:127]
	v_mfma_f32_16x16x32_bf16 v[120:123], v[160:163], v[188:191], 0
	v_mfma_f32_16x16x32_bf16 v[120:123], v[164:167], v[192:195], v[120:123]
	v_mfma_f32_16x16x32_bf16 v[116:119], v[152:155], v[196:199], 0
	v_mfma_f32_16x16x32_bf16 v[116:119], v[156:159], v[200:203], v[116:119]
	v_mfma_f32_16x16x32_bf16 v[108:111], v[160:163], v[196:199], 0
	v_mfma_f32_16x16x32_bf16 v[108:111], v[164:167], v[200:203], v[108:111]
	v_mfma_f32_16x16x32_bf16 v[100:103], v[152:155], v[204:207], 0
	v_mfma_f32_16x16x32_bf16 v[100:103], v[156:159], v[208:211], v[100:103]
	v_mfma_f32_16x16x32_bf16 v[92:95], v[160:163], v[204:207], 0
	v_mfma_f32_16x16x32_bf16 v[92:95], v[164:167], v[208:211], v[92:95]
	v_mfma_f32_16x16x32_bf16 v[84:87], v[152:155], v[212:215], 0
	v_mfma_f32_16x16x32_bf16 v[84:87], v[156:159], v[216:219], v[84:87]
	v_mfma_f32_16x16x32_bf16 v[76:79], v[160:163], v[212:215], 0
	v_mfma_f32_16x16x32_bf16 v[76:79], v[164:167], v[216:219], v[76:79]
	v_mfma_f32_16x16x32_bf16 v[112:115], v[168:171], v[188:191], 0
	v_mfma_f32_16x16x32_bf16 v[112:115], v[172:175], v[192:195], v[112:115]
	v_mfma_f32_16x16x32_bf16 v[104:107], v[176:179], v[188:191], 0
	v_mfma_f32_16x16x32_bf16 v[104:107], v[184:187], v[192:195], v[104:107]
	v_mfma_f32_16x16x32_bf16 v[96:99], v[168:171], v[196:199], 0
	v_mfma_f32_16x16x32_bf16 v[96:99], v[172:175], v[200:203], v[96:99]
	v_mfma_f32_16x16x32_bf16 v[88:91], v[176:179], v[196:199], 0
	v_mfma_f32_16x16x32_bf16 v[88:91], v[184:187], v[200:203], v[88:91]
	v_mfma_f32_16x16x32_bf16 v[80:83], v[168:171], v[204:207], 0
	v_mfma_f32_16x16x32_bf16 v[80:83], v[172:175], v[208:211], v[80:83]
	v_mfma_f32_16x16x32_bf16 v[72:75], v[176:179], v[204:207], 0
	v_mfma_f32_16x16x32_bf16 v[72:75], v[184:187], v[208:211], v[72:75]
	v_mfma_f32_16x16x32_bf16 v[68:71], v[168:171], v[212:215], 0
	v_mfma_f32_16x16x32_bf16 v[68:71], v[172:175], v[216:219], v[68:71]
	v_mfma_f32_16x16x32_bf16 v[64:67], v[176:179], v[212:215], 0
	v_mfma_f32_16x16x32_bf16 v[64:67], v[184:187], v[216:219], v[64:67]
	s_setprio 0
	s_barrier
	s_add_i32 s52, s70, s62
	v_lshl_add_u64 v[144:145], s[56:57], 0, v[130:131]
	s_mov_b32 m0, s52
	s_nop 0
	global_load_lds_dwordx4 v[144:145], off
	s_add_i32 m0, s52, 0x2000
	s_add_u32 s52, s56, 0xb0000
	v_lshl_add_u64 v[220:221], s[56:57], 0, v[134:135]
	s_addc_u32 s53, s57, 0
	s_add_i32 s79, s71, s62
	global_load_lds_dwordx4 v[220:221], off
	v_lshl_add_u64 v[222:223], s[52:53], 0, v[130:131]
	s_mov_b32 m0, s79
	v_lshl_add_u64 v[224:225], s[58:59], 0, v[132:133]
	global_load_lds_dwordx4 v[222:223], off
	v_lshl_add_u64 v[222:223], s[52:53], 0, v[134:135]
	s_add_i32 m0, s79, 0x2000
	s_nop 0
	global_load_lds_dwordx4 v[222:223], off
	v_lshl_add_u64 v[222:223], s[58:59], 0, v[128:129]
	s_mov_b32 m0, s63
	s_nop 0
	global_load_lds_dwordx4 v[222:223], off
	s_mov_b32 m0, s64
	s_nop 0
	global_load_lds_dwordx4 v[224:225], off
	ds_read_b128 v[188:191], v151 offset:16384
	ds_read_b128 v[192:195], v151 offset:17408
	ds_read_b128 v[196:199], v151 offset:18432
	ds_read_b128 v[200:203], v151 offset:19456
	ds_read_b128 v[204:207], v151 offset:20480
	ds_read_b128 v[208:211], v151 offset:21504
	ds_read_b128 v[212:215], v151 offset:22528
	ds_read_b128 v[216:219], v151 offset:23552
	s_waitcnt vmcnt(8)
	s_waitcnt lgkmcnt(0)
	s_barrier
	s_setprio 1
	s_waitcnt lgkmcnt(0)
	v_mfma_f32_16x16x32_bf16 v[60:63], v[152:155], v[188:191], 0
	v_mfma_f32_16x16x32_bf16 v[60:63], v[156:159], v[192:195], v[60:63]
	v_mfma_f32_16x16x32_bf16 v[56:59], v[160:163], v[188:191], 0
	v_mfma_f32_16x16x32_bf16 v[56:59], v[164:167], v[192:195], v[56:59]
	v_mfma_f32_16x16x32_bf16 v[52:55], v[152:155], v[196:199], 0
	v_mfma_f32_16x16x32_bf16 v[52:55], v[156:159], v[200:203], v[52:55]
	v_mfma_f32_16x16x32_bf16 v[44:47], v[160:163], v[196:199], 0
	v_mfma_f32_16x16x32_bf16 v[44:47], v[164:167], v[200:203], v[44:47]
	v_mfma_f32_16x16x32_bf16 v[36:39], v[152:155], v[204:207], 0
	v_mfma_f32_16x16x32_bf16 v[36:39], v[156:159], v[208:211], v[36:39]
	v_mfma_f32_16x16x32_bf16 v[28:31], v[160:163], v[204:207], 0
	v_mfma_f32_16x16x32_bf16 v[28:31], v[164:167], v[208:211], v[28:31]
	v_mfma_f32_16x16x32_bf16 v[20:23], v[152:155], v[212:215], 0
	v_mfma_f32_16x16x32_bf16 v[20:23], v[156:159], v[216:219], v[20:23]
	v_mfma_f32_16x16x32_bf16 v[12:15], v[160:163], v[212:215], 0
	v_mfma_f32_16x16x32_bf16 v[12:15], v[164:167], v[216:219], v[12:15]
	v_mfma_f32_16x16x32_bf16 v[48:51], v[168:171], v[188:191], 0
	v_mfma_f32_16x16x32_bf16 v[48:51], v[172:175], v[192:195], v[48:51]
	v_mfma_f32_16x16x32_bf16 v[40:43], v[176:179], v[188:191], 0
	v_mfma_f32_16x16x32_bf16 v[40:43], v[184:187], v[192:195], v[40:43]
	v_mfma_f32_16x16x32_bf16 v[32:35], v[168:171], v[196:199], 0
	v_mfma_f32_16x16x32_bf16 v[32:35], v[172:175], v[200:203], v[32:35]
	v_mfma_f32_16x16x32_bf16 v[24:27], v[176:179], v[196:199], 0
	v_mfma_f32_16x16x32_bf16 v[24:27], v[184:187], v[200:203], v[24:27]
	v_mfma_f32_16x16x32_bf16 v[16:19], v[168:171], v[204:207], 0
	v_mfma_f32_16x16x32_bf16 v[16:19], v[172:175], v[208:211], v[16:19]
	v_mfma_f32_16x16x32_bf16 v[8:11], v[176:179], v[204:207], 0
	v_mfma_f32_16x16x32_bf16 v[8:11], v[184:187], v[208:211], v[8:11]
	v_mfma_f32_16x16x32_bf16 v[4:7], v[168:171], v[212:215], 0
	v_mfma_f32_16x16x32_bf16 v[4:7], v[172:175], v[216:219], v[4:7]
	v_mfma_f32_16x16x32_bf16 v[0:3], v[176:179], v[212:215], 0
	v_mfma_f32_16x16x32_bf16 v[0:3], v[184:187], v[216:219], v[0:3]
	s_setprio 0
	s_barrier
	s_branch .Lmid_gemm5
.LBB0_804:
	s_add_u32 s54, s52, 0x100
	s_addc_u32 s55, s53, 0
	s_cmp_eq_u32 s86, 40
	s_cselect_b32 s59, s13, s55
	s_cselect_b32 s58, s12, s54
	s_cselect_b32 s57, s49, s85
	s_cselect_b32 s56, s48, s84
	v_lshl_add_u64 v[144:145], s[52:53], 0, v[136:137]
	s_add_i32 m0, s63, 0xc000
	s_nop 0
	global_load_lds_dwordx4 v[144:145], off
	v_lshl_add_u64 v[144:145], s[52:53], 0, v[138:139]
	s_add_i32 m0, s63, 0xe000
	s_nop 0
	global_load_lds_dwordx4 v[144:145], off
	ds_read_b128 v[152:155], v149
	ds_read_b128 v[156:159], v149 offset:1024
	ds_read_b128 v[160:163], v149 offset:2048
	ds_read_b128 v[164:167], v149 offset:3072
	ds_read_b128 v[168:171], v150
	ds_read_b128 v[172:175], v150 offset:1024
	ds_read_b128 v[176:179], v150 offset:2048
	ds_read_b128 v[184:187], v150 offset:3072
	ds_read_b128 v[188:191], v151
	ds_read_b128 v[192:195], v151 offset:1024
	ds_read_b128 v[196:199], v151 offset:2048
	ds_read_b128 v[200:203], v151 offset:3072
	ds_read_b128 v[204:207], v151 offset:4096
	ds_read_b128 v[208:211], v151 offset:5120
	ds_read_b128 v[212:215], v151 offset:6144
	ds_read_b128 v[216:219], v151 offset:7168
	s_waitcnt vmcnt(8)
	s_waitcnt lgkmcnt(0)
	s_barrier
	s_setprio 1
	s_waitcnt lgkmcnt(0)
	v_mfma_f32_16x16x32_bf16 v[124:127], v[152:155], v[188:191], v[124:127]
	v_mfma_f32_16x16x32_bf16 v[124:127], v[156:159], v[192:195], v[124:127]
	v_mfma_f32_16x16x32_bf16 v[120:123], v[160:163], v[188:191], v[120:123]
	v_mfma_f32_16x16x32_bf16 v[120:123], v[164:167], v[192:195], v[120:123]
	v_mfma_f32_16x16x32_bf16 v[116:119], v[152:155], v[196:199], v[116:119]
	v_mfma_f32_16x16x32_bf16 v[116:119], v[156:159], v[200:203], v[116:119]
	v_mfma_f32_16x16x32_bf16 v[108:111], v[160:163], v[196:199], v[108:111]
	v_mfma_f32_16x16x32_bf16 v[108:111], v[164:167], v[200:203], v[108:111]
	v_mfma_f32_16x16x32_bf16 v[100:103], v[152:155], v[204:207], v[100:103]
	v_mfma_f32_16x16x32_bf16 v[100:103], v[156:159], v[208:211], v[100:103]
	v_mfma_f32_16x16x32_bf16 v[92:95], v[160:163], v[204:207], v[92:95]
	v_mfma_f32_16x16x32_bf16 v[92:95], v[164:167], v[208:211], v[92:95]
	v_mfma_f32_16x16x32_bf16 v[84:87], v[152:155], v[212:215], v[84:87]
	v_mfma_f32_16x16x32_bf16 v[84:87], v[156:159], v[216:219], v[84:87]
	v_mfma_f32_16x16x32_bf16 v[76:79], v[160:163], v[212:215], v[76:79]
	v_mfma_f32_16x16x32_bf16 v[76:79], v[164:167], v[216:219], v[76:79]
	v_mfma_f32_16x16x32_bf16 v[112:115], v[168:171], v[188:191], v[112:115]
	v_mfma_f32_16x16x32_bf16 v[112:115], v[172:175], v[192:195], v[112:115]
	v_mfma_f32_16x16x32_bf16 v[104:107], v[176:179], v[188:191], v[104:107]
	v_mfma_f32_16x16x32_bf16 v[104:107], v[184:187], v[192:195], v[104:107]
	v_mfma_f32_16x16x32_bf16 v[96:99], v[168:171], v[196:199], v[96:99]
	v_mfma_f32_16x16x32_bf16 v[96:99], v[172:175], v[200:203], v[96:99]
	v_mfma_f32_16x16x32_bf16 v[88:91], v[176:179], v[196:199], v[88:91]
	v_mfma_f32_16x16x32_bf16 v[88:91], v[184:187], v[200:203], v[88:91]
	v_mfma_f32_16x16x32_bf16 v[80:83], v[168:171], v[204:207], v[80:83]
	v_mfma_f32_16x16x32_bf16 v[80:83], v[172:175], v[208:211], v[80:83]
	v_mfma_f32_16x16x32_bf16 v[72:75], v[176:179], v[204:207], v[72:75]
	v_mfma_f32_16x16x32_bf16 v[72:75], v[184:187], v[208:211], v[72:75]
	v_mfma_f32_16x16x32_bf16 v[68:71], v[168:171], v[212:215], v[68:71]
	v_mfma_f32_16x16x32_bf16 v[68:71], v[172:175], v[216:219], v[68:71]
	v_mfma_f32_16x16x32_bf16 v[64:67], v[176:179], v[212:215], v[64:67]
	v_mfma_f32_16x16x32_bf16 v[64:67], v[184:187], v[216:219], v[64:67]
	s_setprio 0
	s_barrier
	s_add_i32 s52, s70, s62
	v_lshl_add_u64 v[144:145], s[56:57], 0, v[130:131]
	s_mov_b32 m0, s52
	s_nop 0
	global_load_lds_dwordx4 v[144:145], off
	s_add_i32 m0, s52, 0x2000
	s_add_u32 s52, s56, 0xb0000
	v_lshl_add_u64 v[220:221], s[56:57], 0, v[134:135]
	s_addc_u32 s53, s57, 0
	s_add_i32 s79, s71, s62
	global_load_lds_dwordx4 v[220:221], off
	v_lshl_add_u64 v[222:223], s[52:53], 0, v[130:131]
	s_mov_b32 m0, s79
	v_lshl_add_u64 v[224:225], s[58:59], 0, v[132:133]
	global_load_lds_dwordx4 v[222:223], off
	v_lshl_add_u64 v[222:223], s[52:53], 0, v[134:135]
	s_add_i32 m0, s79, 0x2000
	s_nop 0
	global_load_lds_dwordx4 v[222:223], off
	v_lshl_add_u64 v[222:223], s[58:59], 0, v[128:129]
	s_mov_b32 m0, s63
	s_nop 0
	global_load_lds_dwordx4 v[222:223], off
	s_mov_b32 m0, s64
	s_nop 0
	global_load_lds_dwordx4 v[224:225], off
	ds_read_b128 v[188:191], v151 offset:16384
	ds_read_b128 v[192:195], v151 offset:17408
	ds_read_b128 v[196:199], v151 offset:18432
	ds_read_b128 v[200:203], v151 offset:19456
	ds_read_b128 v[204:207], v151 offset:20480
	ds_read_b128 v[208:211], v151 offset:21504
	ds_read_b128 v[212:215], v151 offset:22528
	ds_read_b128 v[216:219], v151 offset:23552
	s_waitcnt vmcnt(8)
	s_waitcnt lgkmcnt(0)
	s_barrier
	s_setprio 1
	s_waitcnt lgkmcnt(0)
	v_mfma_f32_16x16x32_bf16 v[60:63], v[152:155], v[188:191], v[60:63]
	v_mfma_f32_16x16x32_bf16 v[60:63], v[156:159], v[192:195], v[60:63]
	v_mfma_f32_16x16x32_bf16 v[56:59], v[160:163], v[188:191], v[56:59]
	v_mfma_f32_16x16x32_bf16 v[56:59], v[164:167], v[192:195], v[56:59]
	v_mfma_f32_16x16x32_bf16 v[52:55], v[152:155], v[196:199], v[52:55]
	v_mfma_f32_16x16x32_bf16 v[52:55], v[156:159], v[200:203], v[52:55]
	v_mfma_f32_16x16x32_bf16 v[44:47], v[160:163], v[196:199], v[44:47]
	v_mfma_f32_16x16x32_bf16 v[44:47], v[164:167], v[200:203], v[44:47]
	v_mfma_f32_16x16x32_bf16 v[36:39], v[152:155], v[204:207], v[36:39]
	v_mfma_f32_16x16x32_bf16 v[36:39], v[156:159], v[208:211], v[36:39]
	v_mfma_f32_16x16x32_bf16 v[28:31], v[160:163], v[204:207], v[28:31]
	v_mfma_f32_16x16x32_bf16 v[28:31], v[164:167], v[208:211], v[28:31]
	v_mfma_f32_16x16x32_bf16 v[20:23], v[152:155], v[212:215], v[20:23]
	v_mfma_f32_16x16x32_bf16 v[20:23], v[156:159], v[216:219], v[20:23]
	v_mfma_f32_16x16x32_bf16 v[12:15], v[160:163], v[212:215], v[12:15]
	v_mfma_f32_16x16x32_bf16 v[12:15], v[164:167], v[216:219], v[12:15]
	v_mfma_f32_16x16x32_bf16 v[48:51], v[168:171], v[188:191], v[48:51]
	v_mfma_f32_16x16x32_bf16 v[48:51], v[172:175], v[192:195], v[48:51]
	v_mfma_f32_16x16x32_bf16 v[40:43], v[176:179], v[188:191], v[40:43]
	v_mfma_f32_16x16x32_bf16 v[40:43], v[184:187], v[192:195], v[40:43]
	v_mfma_f32_16x16x32_bf16 v[32:35], v[168:171], v[196:199], v[32:35]
	v_mfma_f32_16x16x32_bf16 v[32:35], v[172:175], v[200:203], v[32:35]
	v_mfma_f32_16x16x32_bf16 v[24:27], v[176:179], v[196:199], v[24:27]
	v_mfma_f32_16x16x32_bf16 v[24:27], v[184:187], v[200:203], v[24:27]
	v_mfma_f32_16x16x32_bf16 v[16:19], v[168:171], v[204:207], v[16:19]
	v_mfma_f32_16x16x32_bf16 v[16:19], v[172:175], v[208:211], v[16:19]
	v_mfma_f32_16x16x32_bf16 v[8:11], v[176:179], v[204:207], v[8:11]
	v_mfma_f32_16x16x32_bf16 v[8:11], v[184:187], v[208:211], v[8:11]
	v_mfma_f32_16x16x32_bf16 v[4:7], v[168:171], v[212:215], v[4:7]
	v_mfma_f32_16x16x32_bf16 v[4:7], v[172:175], v[216:219], v[4:7]
	v_mfma_f32_16x16x32_bf16 v[0:3], v[176:179], v[212:215], v[0:3]
	v_mfma_f32_16x16x32_bf16 v[0:3], v[184:187], v[216:219], v[0:3]
	s_setprio 0
	s_barrier
.Lmid_gemm5:
	s_add_i32 s79, 0, 0x18000
	s_add_i32 s87, 0, 0x1c000
	v_add_u32_e32 v164, s79, v147
	v_add_u32_e32 v181, s87, v147
	s_add_u32 s52, s58, 0xb0000
	s_addc_u32 s53, s59, 0
	s_mov_b32 m0, s65
	v_lshl_add_u64 v[226:227], s[52:53], 0, v[128:129]
	global_load_lds_dwordx4 v[226:227], off
	v_lshl_add_u64 v[226:227], s[52:53], 0, v[132:133]
	s_mov_b32 m0, s66
	s_nop 0
	global_load_lds_dwordx4 v[226:227], off
	ds_read_b128 v[152:155], v164
	ds_read_b128 v[156:159], v164 offset:1024
	ds_read_b128 v[160:163], v164 offset:2048
	ds_read_b128 v[164:167], v164 offset:3072
	ds_read_b128 v[168:171], v181
	ds_read_b128 v[172:175], v181 offset:1024
	ds_read_b128 v[176:179], v181 offset:2048
	ds_read_b128 v[184:187], v181 offset:3072
	ds_read_b128 v[188:191], v151 offset:32768
	ds_read_b128 v[192:195], v151 offset:33792
	ds_read_b128 v[196:199], v151 offset:34816
	ds_read_b128 v[200:203], v151 offset:35840
	ds_read_b128 v[204:207], v151 offset:36864
	ds_read_b128 v[208:211], v151 offset:37888
	ds_read_b128 v[212:215], v151 offset:38912
	ds_read_b128 v[216:219], v151 offset:39936
	s_waitcnt vmcnt(8)
	s_waitcnt lgkmcnt(0)
	s_barrier
	s_setprio 1
	s_waitcnt lgkmcnt(0)
	v_mfma_f32_16x16x32_bf16 v[124:127], v[152:155], v[188:191], v[124:127]
	v_mfma_f32_16x16x32_bf16 v[124:127], v[156:159], v[192:195], v[124:127]
	v_mfma_f32_16x16x32_bf16 v[120:123], v[160:163], v[188:191], v[120:123]
	v_mfma_f32_16x16x32_bf16 v[120:123], v[164:167], v[192:195], v[120:123]
	v_mfma_f32_16x16x32_bf16 v[116:119], v[152:155], v[196:199], v[116:119]
	v_mfma_f32_16x16x32_bf16 v[116:119], v[156:159], v[200:203], v[116:119]
	v_mfma_f32_16x16x32_bf16 v[108:111], v[160:163], v[196:199], v[108:111]
	v_mfma_f32_16x16x32_bf16 v[108:111], v[164:167], v[200:203], v[108:111]
	v_mfma_f32_16x16x32_bf16 v[100:103], v[152:155], v[204:207], v[100:103]
	v_mfma_f32_16x16x32_bf16 v[100:103], v[156:159], v[208:211], v[100:103]
	v_mfma_f32_16x16x32_bf16 v[92:95], v[160:163], v[204:207], v[92:95]
	v_mfma_f32_16x16x32_bf16 v[92:95], v[164:167], v[208:211], v[92:95]
	v_mfma_f32_16x16x32_bf16 v[84:87], v[152:155], v[212:215], v[84:87]
	v_mfma_f32_16x16x32_bf16 v[84:87], v[156:159], v[216:219], v[84:87]
	v_mfma_f32_16x16x32_bf16 v[76:79], v[160:163], v[212:215], v[76:79]
	v_mfma_f32_16x16x32_bf16 v[76:79], v[164:167], v[216:219], v[76:79]
	v_mfma_f32_16x16x32_bf16 v[112:115], v[168:171], v[188:191], v[112:115]
	v_mfma_f32_16x16x32_bf16 v[112:115], v[172:175], v[192:195], v[112:115]
	v_mfma_f32_16x16x32_bf16 v[104:107], v[176:179], v[188:191], v[104:107]
	v_mfma_f32_16x16x32_bf16 v[104:107], v[184:187], v[192:195], v[104:107]
	v_mfma_f32_16x16x32_bf16 v[96:99], v[168:171], v[196:199], v[96:99]
	v_mfma_f32_16x16x32_bf16 v[96:99], v[172:175], v[200:203], v[96:99]
	v_mfma_f32_16x16x32_bf16 v[88:91], v[176:179], v[196:199], v[88:91]
	v_mfma_f32_16x16x32_bf16 v[88:91], v[184:187], v[200:203], v[88:91]
	v_mfma_f32_16x16x32_bf16 v[80:83], v[168:171], v[204:207], v[80:83]
	v_mfma_f32_16x16x32_bf16 v[80:83], v[172:175], v[208:211], v[80:83]
	v_mfma_f32_16x16x32_bf16 v[72:75], v[176:179], v[204:207], v[72:75]
	v_mfma_f32_16x16x32_bf16 v[72:75], v[184:187], v[208:211], v[72:75]
	v_mfma_f32_16x16x32_bf16 v[68:71], v[168:171], v[212:215], v[68:71]
	v_mfma_f32_16x16x32_bf16 v[68:71], v[172:175], v[216:219], v[68:71]
	v_mfma_f32_16x16x32_bf16 v[64:67], v[176:179], v[212:215], v[64:67]
	v_mfma_f32_16x16x32_bf16 v[64:67], v[184:187], v[216:219], v[64:67]
	s_setprio 0
	s_barrier
	s_add_i32 s52, s79, s62
	v_lshl_add_u64 v[144:145], v[144:145], 0, s[16:17]
	s_mov_b32 m0, s52
	s_nop 0
	global_load_lds_dwordx4 v[144:145], off
	s_add_i32 m0, s52, 0x2000
	s_add_u32 s52, s56, 0xb0080
	v_lshl_add_u64 v[144:145], v[220:221], 0, s[16:17]
	s_addc_u32 s53, s57, 0
	s_add_i32 s56, s87, s62
	global_load_lds_dwordx4 v[144:145], off
	v_lshl_add_u64 v[144:145], s[52:53], 0, v[130:131]
	s_mov_b32 m0, s56
	s_nop 0
	global_load_lds_dwordx4 v[144:145], off
	v_lshl_add_u64 v[144:145], s[52:53], 0, v[134:135]
	s_add_i32 m0, s56, 0x2000
	s_nop 0
	global_load_lds_dwordx4 v[144:145], off
	v_lshl_add_u64 v[144:145], v[222:223], 0, s[16:17]
	s_mov_b32 m0, s68
	s_nop 0
	global_load_lds_dwordx4 v[144:145], off
	v_lshl_add_u64 v[144:145], v[224:225], 0, s[16:17]
	s_mov_b32 m0, s69
	s_nop 0
	global_load_lds_dwordx4 v[144:145], off
	ds_read_b128 v[188:191], v151 offset:49152
	ds_read_b128 v[192:195], v151 offset:50176
	ds_read_b128 v[196:199], v151 offset:51200
	ds_read_b128 v[200:203], v151 offset:52224
	ds_read_b128 v[204:207], v151 offset:53248
	ds_read_b128 v[208:211], v151 offset:54272
	ds_read_b128 v[212:215], v151 offset:55296
	ds_read_b128 v[216:219], v151 offset:56320
	s_waitcnt vmcnt(8)
	s_waitcnt lgkmcnt(0)
	s_barrier
	s_setprio 1
	s_waitcnt lgkmcnt(0)
	v_mfma_f32_16x16x32_bf16 v[60:63], v[152:155], v[188:191], v[60:63]
	v_mfma_f32_16x16x32_bf16 v[60:63], v[156:159], v[192:195], v[60:63]
	v_mfma_f32_16x16x32_bf16 v[56:59], v[160:163], v[188:191], v[56:59]
	v_mfma_f32_16x16x32_bf16 v[56:59], v[164:167], v[192:195], v[56:59]
	v_mfma_f32_16x16x32_bf16 v[52:55], v[152:155], v[196:199], v[52:55]
	v_mfma_f32_16x16x32_bf16 v[52:55], v[156:159], v[200:203], v[52:55]
	v_mfma_f32_16x16x32_bf16 v[44:47], v[160:163], v[196:199], v[44:47]
	v_mfma_f32_16x16x32_bf16 v[44:47], v[164:167], v[200:203], v[44:47]
	v_mfma_f32_16x16x32_bf16 v[36:39], v[152:155], v[204:207], v[36:39]
	v_mfma_f32_16x16x32_bf16 v[36:39], v[156:159], v[208:211], v[36:39]
	v_mfma_f32_16x16x32_bf16 v[28:31], v[160:163], v[204:207], v[28:31]
	v_mfma_f32_16x16x32_bf16 v[28:31], v[164:167], v[208:211], v[28:31]
	v_mfma_f32_16x16x32_bf16 v[20:23], v[152:155], v[212:215], v[20:23]
	v_mfma_f32_16x16x32_bf16 v[20:23], v[156:159], v[216:219], v[20:23]
	v_mfma_f32_16x16x32_bf16 v[12:15], v[160:163], v[212:215], v[12:15]
	v_mfma_f32_16x16x32_bf16 v[12:15], v[164:167], v[216:219], v[12:15]
	v_mfma_f32_16x16x32_bf16 v[48:51], v[168:171], v[188:191], v[48:51]
	v_mfma_f32_16x16x32_bf16 v[48:51], v[172:175], v[192:195], v[48:51]
	v_mfma_f32_16x16x32_bf16 v[40:43], v[176:179], v[188:191], v[40:43]
	v_mfma_f32_16x16x32_bf16 v[40:43], v[184:187], v[192:195], v[40:43]
	v_mfma_f32_16x16x32_bf16 v[32:35], v[168:171], v[196:199], v[32:35]
	v_mfma_f32_16x16x32_bf16 v[32:35], v[172:175], v[200:203], v[32:35]
	v_mfma_f32_16x16x32_bf16 v[24:27], v[176:179], v[196:199], v[24:27]
	v_mfma_f32_16x16x32_bf16 v[24:27], v[184:187], v[200:203], v[24:27]
	v_mfma_f32_16x16x32_bf16 v[16:19], v[168:171], v[204:207], v[16:19]
	v_mfma_f32_16x16x32_bf16 v[16:19], v[172:175], v[208:211], v[16:19]
	v_mfma_f32_16x16x32_bf16 v[8:11], v[176:179], v[204:207], v[8:11]
	v_mfma_f32_16x16x32_bf16 v[8:11], v[184:187], v[208:211], v[8:11]
	v_mfma_f32_16x16x32_bf16 v[4:7], v[168:171], v[212:215], v[4:7]
	v_mfma_f32_16x16x32_bf16 v[4:7], v[172:175], v[216:219], v[4:7]
	v_mfma_f32_16x16x32_bf16 v[0:3], v[176:179], v[212:215], v[0:3]
	v_mfma_f32_16x16x32_bf16 v[0:3], v[184:187], v[216:219], v[0:3]
	s_setprio 0
	s_barrier
	s_add_i32 s86, s86, 2
	s_add_u32 s84, s84, 0x100
	s_addc_u32 s85, s85, 0
	s_cmp_gt_u32 s86, 41
	s_mov_b64 s[52:53], s[54:55]
	s_cbranch_scc0 .LBB0_804
	s_and_b64 vcc, exec, s[18:19]
	s_cbranch_vccz .LBB0_807
	s_barrier

.LBB0_934:
	s_ashr_i32 s53, s52, 31
	s_lshl_b64 s[54:55], s[52:53], 19
	s_add_u32 s54, s80, s54
	s_addc_u32 s55, s81, s55
	s_and_b64 s[56:57], s[10:11], exec
	s_cselect_b32 s53, s55, s61
	s_cselect_b32 s83, s54, s60
	s_ashr_i32 s49, s48, 31
	s_lshl_b64 s[56:57], s[48:49], 19
	s_add_u32 s56, s66, s56
	s_addc_u32 s57, s67, s57
	s_and_b64 s[64:65], s[10:11], exec
	s_cselect_b32 s49, s57, s63
	s_cselect_b32 s84, s56, s62
	s_add_u32 s60, s60, 0x40080
	s_addc_u32 s61, s61, 0
	s_add_u32 s85, s62, 0x100
	s_addc_u32 s86, s63, 0
	s_mov_b32 s87, -2
	ds_read_b128 v[152:155], v148
	ds_read_b128 v[156:159], v148 offset:1024
	ds_read_b128 v[160:163], v148 offset:2048
	ds_read_b128 v[164:167], v148 offset:3072
	ds_read_b128 v[168:171], v149
	ds_read_b128 v[172:175], v149 offset:1024
	ds_read_b128 v[176:179], v149 offset:2048
	ds_read_b128 v[184:187], v149 offset:3072
	s_add_u32 s62, s60, 0xfffc0080
	s_addc_u32 s63, s61, -1
	s_cmp_eq_u32 s87, 12
	s_cselect_b32 s65, s53, s63
	s_cselect_b32 s64, s83, s62
	s_cselect_b32 s63, s49, s86
	s_cselect_b32 s62, s84, s85
	v_lshl_add_u64 v[220:221], s[60:61], 0, v[138:139]
	s_add_i32 m0, s69, 0xc000
	ds_read_b128 v[188:191], v150
	ds_read_b128 v[192:195], v150 offset:1024
	ds_read_b128 v[196:199], v150 offset:2048
	ds_read_b128 v[200:203], v150 offset:3072
	ds_read_b128 v[204:207], v150 offset:4096
	ds_read_b128 v[208:211], v150 offset:5120
	ds_read_b128 v[212:215], v150 offset:6144
	ds_read_b128 v[216:219], v150 offset:7168
	global_load_lds_dwordx4 v[220:221], off
	v_lshl_add_u64 v[220:221], s[60:61], 0, v[140:141]
	s_add_i32 m0, s69, 0xe000
	s_nop 0
	global_load_lds_dwordx4 v[220:221], off
	s_waitcnt vmcnt(8)
	s_waitcnt lgkmcnt(0)
	s_barrier
	s_setprio 1
	s_waitcnt lgkmcnt(0)
	v_mfma_f32_16x16x32_bf16 v[124:127], v[152:155], v[188:191], 0
	v_mfma_f32_16x16x32_bf16 v[124:127], v[156:159], v[192:195], v[124:127]
	v_mfma_f32_16x16x32_bf16 v[120:123], v[160:163], v[188:191], 0
	v_mfma_f32_16x16x32_bf16 v[120:123], v[164:167], v[192:195], v[120:123]
	v_mfma_f32_16x16x32_bf16 v[116:119], v[152:155], v[196:199], 0
	v_mfma_f32_16x16x32_bf16 v[116:119], v[156:159], v[200:203], v[116:119]
	v_mfma_f32_16x16x32_bf16 v[112:115], v[160:163], v[196:199], 0
	v_mfma_f32_16x16x32_bf16 v[112:115], v[164:167], v[200:203], v[112:115]
	v_mfma_f32_16x16x32_bf16 v[108:111], v[152:155], v[204:207], 0
	v_mfma_f32_16x16x32_bf16 v[108:111], v[156:159], v[208:211], v[108:111]
	v_mfma_f32_16x16x32_bf16 v[104:107], v[160:163], v[204:207], 0
	v_mfma_f32_16x16x32_bf16 v[104:107], v[164:167], v[208:211], v[104:107]
	v_mfma_f32_16x16x32_bf16 v[100:103], v[152:155], v[212:215], 0
	v_mfma_f32_16x16x32_bf16 v[100:103], v[156:159], v[216:219], v[100:103]
	v_mfma_f32_16x16x32_bf16 v[96:99], v[160:163], v[212:215], 0
	v_mfma_f32_16x16x32_bf16 v[96:99], v[164:167], v[216:219], v[96:99]
	v_mfma_f32_16x16x32_bf16 v[76:79], v[168:171], v[188:191], 0
	v_mfma_f32_16x16x32_bf16 v[76:79], v[172:175], v[192:195], v[76:79]
	v_mfma_f32_16x16x32_bf16 v[68:71], v[176:179], v[188:191], 0
	v_mfma_f32_16x16x32_bf16 v[68:71], v[184:187], v[192:195], v[68:71]
	v_mfma_f32_16x16x32_bf16 v[60:63], v[168:171], v[196:199], 0
	v_mfma_f32_16x16x32_bf16 v[60:63], v[172:175], v[200:203], v[60:63]
	v_mfma_f32_16x16x32_bf16 v[52:55], v[176:179], v[196:199], 0
	v_mfma_f32_16x16x32_bf16 v[52:55], v[184:187], v[200:203], v[52:55]
	v_mfma_f32_16x16x32_bf16 v[44:47], v[168:171], v[204:207], 0
	v_mfma_f32_16x16x32_bf16 v[44:47], v[172:175], v[208:211], v[44:47]
	v_mfma_f32_16x16x32_bf16 v[40:43], v[176:179], v[204:207], 0
	v_mfma_f32_16x16x32_bf16 v[40:43], v[184:187], v[208:211], v[40:43]
	v_mfma_f32_16x16x32_bf16 v[36:39], v[168:171], v[212:215], 0
	v_mfma_f32_16x16x32_bf16 v[36:39], v[172:175], v[216:219], v[36:39]
	v_mfma_f32_16x16x32_bf16 v[32:35], v[176:179], v[212:215], 0
	v_mfma_f32_16x16x32_bf16 v[32:35], v[184:187], v[216:219], v[32:35]
	s_setprio 0
	s_barrier
	s_add_i32 s79, s77, s68
	v_lshl_add_u64 v[220:221], s[62:63], 0, v[130:131]
	s_mov_b32 m0, s79
	s_nop 0
	global_load_lds_dwordx4 v[220:221], off
	s_add_i32 m0, s79, 0x2000
	s_add_u32 s88, s62, 0x40000
	v_lshl_add_u64 v[222:223], s[62:63], 0, v[134:135]
	s_addc_u32 s89, s63, 0
	s_add_i32 s79, s82, s68
	global_load_lds_dwordx4 v[222:223], off
	v_lshl_add_u64 v[224:225], s[88:89], 0, v[130:131]
	s_mov_b32 m0, s79
	v_lshl_add_u64 v[226:227], s[64:65], 0, v[132:133]
	global_load_lds_dwordx4 v[224:225], off
	v_lshl_add_u64 v[224:225], s[88:89], 0, v[134:135]
	s_add_i32 m0, s79, 0x2000
	s_nop 0
	global_load_lds_dwordx4 v[224:225], off
	v_lshl_add_u64 v[224:225], s[64:65], 0, v[128:129]
	s_mov_b32 m0, s69
	s_nop 0
	global_load_lds_dwordx4 v[224:225], off
	s_mov_b32 m0, s70
	s_nop 0
	global_load_lds_dwordx4 v[226:227], off
	ds_read_b128 v[188:191], v150 offset:16384
	ds_read_b128 v[192:195], v150 offset:17408
	ds_read_b128 v[196:199], v150 offset:18432
	ds_read_b128 v[200:203], v150 offset:19456
	ds_read_b128 v[204:207], v150 offset:20480
	ds_read_b128 v[208:211], v150 offset:21504
	ds_read_b128 v[212:215], v150 offset:22528
	ds_read_b128 v[216:219], v150 offset:23552
	s_waitcnt vmcnt(8)
	s_waitcnt lgkmcnt(0)
	s_barrier
	s_setprio 1
	s_waitcnt lgkmcnt(0)
	v_mfma_f32_16x16x32_bf16 v[92:95], v[152:155], v[188:191], 0
	v_mfma_f32_16x16x32_bf16 v[92:95], v[156:159], v[192:195], v[92:95]
	v_mfma_f32_16x16x32_bf16 v[88:91], v[160:163], v[188:191], 0
	v_mfma_f32_16x16x32_bf16 v[88:91], v[164:167], v[192:195], v[88:91]
	v_mfma_f32_16x16x32_bf16 v[84:87], v[152:155], v[196:199], 0
	v_mfma_f32_16x16x32_bf16 v[84:87], v[156:159], v[200:203], v[84:87]
	v_mfma_f32_16x16x32_bf16 v[80:83], v[160:163], v[196:199], 0
	v_mfma_f32_16x16x32_bf16 v[80:83], v[164:167], v[200:203], v[80:83]
	v_mfma_f32_16x16x32_bf16 v[72:75], v[152:155], v[204:207], 0
	v_mfma_f32_16x16x32_bf16 v[72:75], v[156:159], v[208:211], v[72:75]
	v_mfma_f32_16x16x32_bf16 v[64:67], v[160:163], v[204:207], 0
	v_mfma_f32_16x16x32_bf16 v[64:67], v[164:167], v[208:211], v[64:67]
	v_mfma_f32_16x16x32_bf16 v[56:59], v[152:155], v[212:215], 0
	v_mfma_f32_16x16x32_bf16 v[56:59], v[156:159], v[216:219], v[56:59]
	v_mfma_f32_16x16x32_bf16 v[48:51], v[160:163], v[212:215], 0
	v_mfma_f32_16x16x32_bf16 v[48:51], v[164:167], v[216:219], v[48:51]
	v_mfma_f32_16x16x32_bf16 v[28:31], v[168:171], v[188:191], 0
	v_mfma_f32_16x16x32_bf16 v[28:31], v[172:175], v[192:195], v[28:31]
	v_mfma_f32_16x16x32_bf16 v[24:27], v[176:179], v[188:191], 0
	v_mfma_f32_16x16x32_bf16 v[24:27], v[184:187], v[192:195], v[24:27]
	v_mfma_f32_16x16x32_bf16 v[20:23], v[168:171], v[196:199], 0
	v_mfma_f32_16x16x32_bf16 v[20:23], v[172:175], v[200:203], v[20:23]
	v_mfma_f32_16x16x32_bf16 v[16:19], v[176:179], v[196:199], 0
	v_mfma_f32_16x16x32_bf16 v[16:19], v[184:187], v[200:203], v[16:19]
	v_mfma_f32_16x16x32_bf16 v[12:15], v[168:171], v[204:207], 0
	v_mfma_f32_16x16x32_bf16 v[12:15], v[172:175], v[208:211], v[12:15]
	v_mfma_f32_16x16x32_bf16 v[8:11], v[176:179], v[204:207], 0
	v_mfma_f32_16x16x32_bf16 v[8:11], v[184:187], v[208:211], v[8:11]
	v_mfma_f32_16x16x32_bf16 v[4:7], v[168:171], v[212:215], 0
	v_mfma_f32_16x16x32_bf16 v[4:7], v[172:175], v[216:219], v[4:7]
	v_mfma_f32_16x16x32_bf16 v[0:3], v[176:179], v[212:215], 0
	v_mfma_f32_16x16x32_bf16 v[0:3], v[184:187], v[216:219], v[0:3]
	s_setprio 0
	s_barrier
	s_branch .Lmid_gemm6
.LBB0_935:
	s_add_u32 s62, s60, 0xfffc0080
	s_addc_u32 s63, s61, -1
	s_cmp_eq_u32 s87, 12
	s_cselect_b32 s65, s53, s63
	s_cselect_b32 s64, s83, s62
	s_cselect_b32 s63, s49, s86
	s_cselect_b32 s62, s84, s85
	v_lshl_add_u64 v[220:221], s[60:61], 0, v[138:139]
	s_add_i32 m0, s69, 0xc000
	s_nop 0
	global_load_lds_dwordx4 v[220:221], off
	v_lshl_add_u64 v[220:221], s[60:61], 0, v[140:141]
	s_add_i32 m0, s69, 0xe000
	s_nop 0
	global_load_lds_dwordx4 v[220:221], off
	ds_read_b128 v[152:155], v148
	ds_read_b128 v[156:159], v148 offset:1024
	ds_read_b128 v[160:163], v148 offset:2048
	ds_read_b128 v[164:167], v148 offset:3072
	ds_read_b128 v[168:171], v149
	ds_read_b128 v[172:175], v149 offset:1024
	ds_read_b128 v[176:179], v149 offset:2048
	ds_read_b128 v[184:187], v149 offset:3072
	ds_read_b128 v[188:191], v150
	ds_read_b128 v[192:195], v150 offset:1024
	ds_read_b128 v[196:199], v150 offset:2048
	ds_read_b128 v[200:203], v150 offset:3072
	ds_read_b128 v[204:207], v150 offset:4096
	ds_read_b128 v[208:211], v150 offset:5120
	ds_read_b128 v[212:215], v150 offset:6144
	ds_read_b128 v[216:219], v150 offset:7168
	s_waitcnt vmcnt(8)
	s_waitcnt lgkmcnt(0)
	s_barrier
	s_setprio 1
	s_waitcnt lgkmcnt(0)
	v_mfma_f32_16x16x32_bf16 v[124:127], v[152:155], v[188:191], v[124:127]
	v_mfma_f32_16x16x32_bf16 v[124:127], v[156:159], v[192:195], v[124:127]
	v_mfma_f32_16x16x32_bf16 v[120:123], v[160:163], v[188:191], v[120:123]
	v_mfma_f32_16x16x32_bf16 v[120:123], v[164:167], v[192:195], v[120:123]
	v_mfma_f32_16x16x32_bf16 v[116:119], v[152:155], v[196:199], v[116:119]
	v_mfma_f32_16x16x32_bf16 v[116:119], v[156:159], v[200:203], v[116:119]
	v_mfma_f32_16x16x32_bf16 v[112:115], v[160:163], v[196:199], v[112:115]
	v_mfma_f32_16x16x32_bf16 v[112:115], v[164:167], v[200:203], v[112:115]
	v_mfma_f32_16x16x32_bf16 v[108:111], v[152:155], v[204:207], v[108:111]
	v_mfma_f32_16x16x32_bf16 v[108:111], v[156:159], v[208:211], v[108:111]
	v_mfma_f32_16x16x32_bf16 v[104:107], v[160:163], v[204:207], v[104:107]
	v_mfma_f32_16x16x32_bf16 v[104:107], v[164:167], v[208:211], v[104:107]
	v_mfma_f32_16x16x32_bf16 v[100:103], v[152:155], v[212:215], v[100:103]
	v_mfma_f32_16x16x32_bf16 v[100:103], v[156:159], v[216:219], v[100:103]
	v_mfma_f32_16x16x32_bf16 v[96:99], v[160:163], v[212:215], v[96:99]
	v_mfma_f32_16x16x32_bf16 v[96:99], v[164:167], v[216:219], v[96:99]
	v_mfma_f32_16x16x32_bf16 v[76:79], v[168:171], v[188:191], v[76:79]
	v_mfma_f32_16x16x32_bf16 v[76:79], v[172:175], v[192:195], v[76:79]
	v_mfma_f32_16x16x32_bf16 v[68:71], v[176:179], v[188:191], v[68:71]
	v_mfma_f32_16x16x32_bf16 v[68:71], v[184:187], v[192:195], v[68:71]
	v_mfma_f32_16x16x32_bf16 v[60:63], v[168:171], v[196:199], v[60:63]
	v_mfma_f32_16x16x32_bf16 v[60:63], v[172:175], v[200:203], v[60:63]
	v_mfma_f32_16x16x32_bf16 v[52:55], v[176:179], v[196:199], v[52:55]
	v_mfma_f32_16x16x32_bf16 v[52:55], v[184:187], v[200:203], v[52:55]
	v_mfma_f32_16x16x32_bf16 v[44:47], v[168:171], v[204:207], v[44:47]
	v_mfma_f32_16x16x32_bf16 v[44:47], v[172:175], v[208:211], v[44:47]
	v_mfma_f32_16x16x32_bf16 v[40:43], v[176:179], v[204:207], v[40:43]
	v_mfma_f32_16x16x32_bf16 v[40:43], v[184:187], v[208:211], v[40:43]
	v_mfma_f32_16x16x32_bf16 v[36:39], v[168:171], v[212:215], v[36:39]
	v_mfma_f32_16x16x32_bf16 v[36:39], v[172:175], v[216:219], v[36:39]
	v_mfma_f32_16x16x32_bf16 v[32:35], v[176:179], v[212:215], v[32:35]
	v_mfma_f32_16x16x32_bf16 v[32:35], v[184:187], v[216:219], v[32:35]
	s_setprio 0
	s_barrier
	s_add_i32 s79, s77, s68
	v_lshl_add_u64 v[220:221], s[62:63], 0, v[130:131]
	s_mov_b32 m0, s79
	s_nop 0
	global_load_lds_dwordx4 v[220:221], off
	s_add_i32 m0, s79, 0x2000
	s_add_u32 s88, s62, 0x40000
	v_lshl_add_u64 v[222:223], s[62:63], 0, v[134:135]
	s_addc_u32 s89, s63, 0
	s_add_i32 s79, s82, s68
	global_load_lds_dwordx4 v[222:223], off
	v_lshl_add_u64 v[224:225], s[88:89], 0, v[130:131]
	s_mov_b32 m0, s79
	v_lshl_add_u64 v[226:227], s[64:65], 0, v[132:133]
	global_load_lds_dwordx4 v[224:225], off
	v_lshl_add_u64 v[224:225], s[88:89], 0, v[134:135]
	s_add_i32 m0, s79, 0x2000
	s_nop 0
	global_load_lds_dwordx4 v[224:225], off
	v_lshl_add_u64 v[224:225], s[64:65], 0, v[128:129]
	s_mov_b32 m0, s69
	s_nop 0
	global_load_lds_dwordx4 v[224:225], off
	s_mov_b32 m0, s70
	s_nop 0
	global_load_lds_dwordx4 v[226:227], off
	ds_read_b128 v[188:191], v150 offset:16384
	ds_read_b128 v[192:195], v150 offset:17408
	ds_read_b128 v[196:199], v150 offset:18432
	ds_read_b128 v[200:203], v150 offset:19456
	ds_read_b128 v[204:207], v150 offset:20480
	ds_read_b128 v[208:211], v150 offset:21504
	ds_read_b128 v[212:215], v150 offset:22528
	ds_read_b128 v[216:219], v150 offset:23552
	s_waitcnt vmcnt(8)
	s_waitcnt lgkmcnt(0)
	s_barrier
	s_setprio 1
	s_waitcnt lgkmcnt(0)
	v_mfma_f32_16x16x32_bf16 v[92:95], v[152:155], v[188:191], v[92:95]
	v_mfma_f32_16x16x32_bf16 v[92:95], v[156:159], v[192:195], v[92:95]
	v_mfma_f32_16x16x32_bf16 v[88:91], v[160:163], v[188:191], v[88:91]
	v_mfma_f32_16x16x32_bf16 v[88:91], v[164:167], v[192:195], v[88:91]
	v_mfma_f32_16x16x32_bf16 v[84:87], v[152:155], v[196:199], v[84:87]
	v_mfma_f32_16x16x32_bf16 v[84:87], v[156:159], v[200:203], v[84:87]
	v_mfma_f32_16x16x32_bf16 v[80:83], v[160:163], v[196:199], v[80:83]
	v_mfma_f32_16x16x32_bf16 v[80:83], v[164:167], v[200:203], v[80:83]
	v_mfma_f32_16x16x32_bf16 v[72:75], v[152:155], v[204:207], v[72:75]
	v_mfma_f32_16x16x32_bf16 v[72:75], v[156:159], v[208:211], v[72:75]
	v_mfma_f32_16x16x32_bf16 v[64:67], v[160:163], v[204:207], v[64:67]
	v_mfma_f32_16x16x32_bf16 v[64:67], v[164:167], v[208:211], v[64:67]
	v_mfma_f32_16x16x32_bf16 v[56:59], v[152:155], v[212:215], v[56:59]
	v_mfma_f32_16x16x32_bf16 v[56:59], v[156:159], v[216:219], v[56:59]
	v_mfma_f32_16x16x32_bf16 v[48:51], v[160:163], v[212:215], v[48:51]
	v_mfma_f32_16x16x32_bf16 v[48:51], v[164:167], v[216:219], v[48:51]
	v_mfma_f32_16x16x32_bf16 v[28:31], v[168:171], v[188:191], v[28:31]
	v_mfma_f32_16x16x32_bf16 v[28:31], v[172:175], v[192:195], v[28:31]
	v_mfma_f32_16x16x32_bf16 v[24:27], v[176:179], v[188:191], v[24:27]
	v_mfma_f32_16x16x32_bf16 v[24:27], v[184:187], v[192:195], v[24:27]
	v_mfma_f32_16x16x32_bf16 v[20:23], v[168:171], v[196:199], v[20:23]
	v_mfma_f32_16x16x32_bf16 v[20:23], v[172:175], v[200:203], v[20:23]
	v_mfma_f32_16x16x32_bf16 v[16:19], v[176:179], v[196:199], v[16:19]
	v_mfma_f32_16x16x32_bf16 v[16:19], v[184:187], v[200:203], v[16:19]
	v_mfma_f32_16x16x32_bf16 v[12:15], v[168:171], v[204:207], v[12:15]
	v_mfma_f32_16x16x32_bf16 v[12:15], v[172:175], v[208:211], v[12:15]
	v_mfma_f32_16x16x32_bf16 v[8:11], v[176:179], v[204:207], v[8:11]
	v_mfma_f32_16x16x32_bf16 v[8:11], v[184:187], v[208:211], v[8:11]
	v_mfma_f32_16x16x32_bf16 v[4:7], v[168:171], v[212:215], v[4:7]
	v_mfma_f32_16x16x32_bf16 v[4:7], v[172:175], v[216:219], v[4:7]
	v_mfma_f32_16x16x32_bf16 v[0:3], v[176:179], v[212:215], v[0:3]
	v_mfma_f32_16x16x32_bf16 v[0:3], v[184:187], v[216:219], v[0:3]
	s_setprio 0
	s_barrier
.Lmid_gemm6:
	s_add_i32 s79, 0, 0x18000
	v_add_u32_e32 v151, s79, v147
	s_add_i32 s88, 0, 0x1c000
	ds_read_b128 v[152:155], v151
	ds_read_b128 v[156:159], v151 offset:1024
	ds_read_b128 v[160:163], v151 offset:2048
	ds_read_b128 v[164:167], v151 offset:3072
	v_add_u32_e32 v151, s88, v147
	ds_read_b128 v[168:171], v151
	ds_read_b128 v[172:175], v151 offset:1024
	ds_read_b128 v[176:179], v151 offset:2048
	ds_read_b128 v[184:187], v151 offset:3072
	s_add_u32 s64, s64, 0x40000
	s_addc_u32 s65, s65, 0
	s_mov_b32 m0, s71
	v_lshl_add_u64 v[228:229], s[64:65], 0, v[128:129]
	ds_read_b128 v[188:191], v150 offset:32768
	ds_read_b128 v[192:195], v150 offset:33792
	ds_read_b128 v[196:199], v150 offset:34816
	ds_read_b128 v[200:203], v150 offset:35840
	ds_read_b128 v[204:207], v150 offset:36864
	ds_read_b128 v[208:211], v150 offset:37888
	ds_read_b128 v[212:215], v150 offset:38912
	ds_read_b128 v[216:219], v150 offset:39936
	global_load_lds_dwordx4 v[228:229], off
	v_lshl_add_u64 v[228:229], s[64:65], 0, v[132:133]
	s_mov_b32 m0, s72
	s_nop 0
	global_load_lds_dwordx4 v[228:229], off
	s_waitcnt vmcnt(8)
	s_waitcnt lgkmcnt(0)
	s_barrier
	s_setprio 1
	s_waitcnt lgkmcnt(0)
	v_mfma_f32_16x16x32_bf16 v[124:127], v[152:155], v[188:191], v[124:127]
	v_mfma_f32_16x16x32_bf16 v[124:127], v[156:159], v[192:195], v[124:127]
	v_mfma_f32_16x16x32_bf16 v[120:123], v[160:163], v[188:191], v[120:123]
	v_mfma_f32_16x16x32_bf16 v[120:123], v[164:167], v[192:195], v[120:123]
	v_mfma_f32_16x16x32_bf16 v[116:119], v[152:155], v[196:199], v[116:119]
	v_mfma_f32_16x16x32_bf16 v[116:119], v[156:159], v[200:203], v[116:119]
	v_mfma_f32_16x16x32_bf16 v[112:115], v[160:163], v[196:199], v[112:115]
	v_mfma_f32_16x16x32_bf16 v[112:115], v[164:167], v[200:203], v[112:115]
	v_mfma_f32_16x16x32_bf16 v[108:111], v[152:155], v[204:207], v[108:111]
	v_mfma_f32_16x16x32_bf16 v[108:111], v[156:159], v[208:211], v[108:111]
	v_mfma_f32_16x16x32_bf16 v[104:107], v[160:163], v[204:207], v[104:107]
	v_mfma_f32_16x16x32_bf16 v[104:107], v[164:167], v[208:211], v[104:107]
	v_mfma_f32_16x16x32_bf16 v[100:103], v[152:155], v[212:215], v[100:103]
	v_mfma_f32_16x16x32_bf16 v[100:103], v[156:159], v[216:219], v[100:103]
	v_mfma_f32_16x16x32_bf16 v[96:99], v[160:163], v[212:215], v[96:99]
	v_mfma_f32_16x16x32_bf16 v[96:99], v[164:167], v[216:219], v[96:99]
	v_mfma_f32_16x16x32_bf16 v[76:79], v[168:171], v[188:191], v[76:79]
	v_mfma_f32_16x16x32_bf16 v[76:79], v[172:175], v[192:195], v[76:79]
	v_mfma_f32_16x16x32_bf16 v[68:71], v[176:179], v[188:191], v[68:71]
	v_mfma_f32_16x16x32_bf16 v[68:71], v[184:187], v[192:195], v[68:71]
	v_mfma_f32_16x16x32_bf16 v[60:63], v[168:171], v[196:199], v[60:63]
	v_mfma_f32_16x16x32_bf16 v[60:63], v[172:175], v[200:203], v[60:63]
	v_mfma_f32_16x16x32_bf16 v[52:55], v[176:179], v[196:199], v[52:55]
	v_mfma_f32_16x16x32_bf16 v[52:55], v[184:187], v[200:203], v[52:55]
	v_mfma_f32_16x16x32_bf16 v[44:47], v[168:171], v[204:207], v[44:47]
	v_mfma_f32_16x16x32_bf16 v[44:47], v[172:175], v[208:211], v[44:47]
	v_mfma_f32_16x16x32_bf16 v[40:43], v[176:179], v[204:207], v[40:43]
	v_mfma_f32_16x16x32_bf16 v[40:43], v[184:187], v[208:211], v[40:43]
	v_mfma_f32_16x16x32_bf16 v[36:39], v[168:171], v[212:215], v[36:39]
	v_mfma_f32_16x16x32_bf16 v[36:39], v[172:175], v[216:219], v[36:39]
	v_mfma_f32_16x16x32_bf16 v[32:35], v[176:179], v[212:215], v[32:35]
	v_mfma_f32_16x16x32_bf16 v[32:35], v[184:187], v[216:219], v[32:35]
	s_setprio 0
	s_barrier
	s_add_i32 s64, s79, s68
	v_lshl_add_u64 v[220:221], v[220:221], 0, s[12:13]
	s_mov_b32 m0, s64
	s_nop 0
	global_load_lds_dwordx4 v[220:221], off
	s_add_i32 m0, s64, 0x2000
	s_add_u32 s62, s62, 0x40080
	v_lshl_add_u64 v[220:221], v[222:223], 0, s[12:13]
	s_addc_u32 s63, s63, 0
	s_add_i32 s64, s88, s68
	global_load_lds_dwordx4 v[220:221], off
	v_lshl_add_u64 v[220:221], s[62:63], 0, v[130:131]
	s_mov_b32 m0, s64
	s_nop 0
	global_load_lds_dwordx4 v[220:221], off
	v_lshl_add_u64 v[220:221], s[62:63], 0, v[134:135]
	s_add_i32 m0, s64, 0x2000
	s_nop 0
	global_load_lds_dwordx4 v[220:221], off
	v_lshl_add_u64 v[220:221], v[224:225], 0, s[12:13]
	s_mov_b32 m0, s75
	s_nop 0
	global_load_lds_dwordx4 v[220:221], off
	v_lshl_add_u64 v[220:221], v[226:227], 0, s[12:13]
	s_mov_b32 m0, s76
	s_nop 0
	global_load_lds_dwordx4 v[220:221], off
	ds_read_b128 v[188:191], v150 offset:49152
	ds_read_b128 v[192:195], v150 offset:50176
	ds_read_b128 v[196:199], v150 offset:51200
	ds_read_b128 v[200:203], v150 offset:52224
	ds_read_b128 v[204:207], v150 offset:53248
	ds_read_b128 v[208:211], v150 offset:54272
	ds_read_b128 v[212:215], v150 offset:55296
	ds_read_b128 v[216:219], v150 offset:56320
	s_waitcnt vmcnt(8)
	s_waitcnt lgkmcnt(0)
	s_barrier
	s_setprio 1
	s_waitcnt lgkmcnt(0)
	v_mfma_f32_16x16x32_bf16 v[92:95], v[152:155], v[188:191], v[92:95]
	v_mfma_f32_16x16x32_bf16 v[92:95], v[156:159], v[192:195], v[92:95]
	v_mfma_f32_16x16x32_bf16 v[88:91], v[160:163], v[188:191], v[88:91]
	v_mfma_f32_16x16x32_bf16 v[88:91], v[164:167], v[192:195], v[88:91]
	v_mfma_f32_16x16x32_bf16 v[84:87], v[152:155], v[196:199], v[84:87]
	v_mfma_f32_16x16x32_bf16 v[84:87], v[156:159], v[200:203], v[84:87]
	v_mfma_f32_16x16x32_bf16 v[80:83], v[160:163], v[196:199], v[80:83]
	v_mfma_f32_16x16x32_bf16 v[80:83], v[164:167], v[200:203], v[80:83]
	v_mfma_f32_16x16x32_bf16 v[72:75], v[152:155], v[204:207], v[72:75]
	v_mfma_f32_16x16x32_bf16 v[72:75], v[156:159], v[208:211], v[72:75]
	v_mfma_f32_16x16x32_bf16 v[64:67], v[160:163], v[204:207], v[64:67]
	v_mfma_f32_16x16x32_bf16 v[64:67], v[164:167], v[208:211], v[64:67]
	v_mfma_f32_16x16x32_bf16 v[56:59], v[152:155], v[212:215], v[56:59]
	v_mfma_f32_16x16x32_bf16 v[56:59], v[156:159], v[216:219], v[56:59]
	v_mfma_f32_16x16x32_bf16 v[48:51], v[160:163], v[212:215], v[48:51]
	v_mfma_f32_16x16x32_bf16 v[48:51], v[164:167], v[216:219], v[48:51]
	v_mfma_f32_16x16x32_bf16 v[28:31], v[168:171], v[188:191], v[28:31]
	v_mfma_f32_16x16x32_bf16 v[28:31], v[172:175], v[192:195], v[28:31]
	v_mfma_f32_16x16x32_bf16 v[24:27], v[176:179], v[188:191], v[24:27]
	v_mfma_f32_16x16x32_bf16 v[24:27], v[184:187], v[192:195], v[24:27]
	v_mfma_f32_16x16x32_bf16 v[20:23], v[168:171], v[196:199], v[20:23]
	v_mfma_f32_16x16x32_bf16 v[20:23], v[172:175], v[200:203], v[20:23]
	v_mfma_f32_16x16x32_bf16 v[16:19], v[176:179], v[196:199], v[16:19]
	v_mfma_f32_16x16x32_bf16 v[16:19], v[184:187], v[200:203], v[16:19]
	v_mfma_f32_16x16x32_bf16 v[12:15], v[168:171], v[204:207], v[12:15]
	v_mfma_f32_16x16x32_bf16 v[12:15], v[172:175], v[208:211], v[12:15]
	v_mfma_f32_16x16x32_bf16 v[8:11], v[176:179], v[204:207], v[8:11]
	v_mfma_f32_16x16x32_bf16 v[8:11], v[184:187], v[208:211], v[8:11]
	v_mfma_f32_16x16x32_bf16 v[4:7], v[168:171], v[212:215], v[4:7]
	v_mfma_f32_16x16x32_bf16 v[4:7], v[172:175], v[216:219], v[4:7]
	v_mfma_f32_16x16x32_bf16 v[0:3], v[176:179], v[212:215], v[0:3]
	v_mfma_f32_16x16x32_bf16 v[0:3], v[184:187], v[216:219], v[0:3]
	s_setprio 0
	s_barrier
	s_add_i32 s87, s87, 2
	s_add_u32 s60, s60, 0x100
	s_addc_u32 s61, s61, 0
	s_add_u32 s85, s85, 0x100
	s_addc_u32 s86, s86, 0
	s_cmp_gt_u32 s87, 13
	s_cbranch_scc0 .LBB0_935
	s_and_b64 vcc, exec, s[16:17]
	s_cbranch_vccz .LBB0_938
	s_barrier

.LBB0_950:
	s_ashr_i32 s37, s36, 31
	s_lshl_b64 s[44:45], s[36:37], 19
	s_add_u32 s44, s80, s44
	s_addc_u32 s45, s81, s45
	s_and_b64 s[46:47], s[10:11], exec
	s_cselect_b32 s37, s45, s53
	s_cselect_b32 s72, s44, s52
	s_ashr_i32 s19, s18, 31
	s_lshl_b64 s[46:47], s[18:19], 19
	s_add_u32 s46, s58, s46
	s_addc_u32 s47, s59, s47
	s_and_b64 s[56:57], s[10:11], exec
	s_cselect_b32 s19, s47, s55
	s_cselect_b32 s73, s46, s54
	s_add_u32 s52, s52, 0x40080
	s_addc_u32 s53, s53, 0
	s_add_u32 s74, s54, 0x100
	s_addc_u32 s75, s55, 0
	s_mov_b32 s76, -2
	ds_read_b128 v[140:143], v147
	ds_read_b128 v[150:153], v147 offset:1024
	ds_read_b128 v[154:157], v147 offset:2048
	ds_read_b128 v[158:161], v147 offset:3072
	ds_read_b128 v[162:165], v148
	ds_read_b128 v[166:169], v148 offset:1024
	ds_read_b128 v[170:173], v148 offset:2048
	ds_read_b128 v[174:177], v148 offset:3072
	s_add_u32 s54, s52, 0xfffc0080
	s_addc_u32 s55, s53, -1
	s_cmp_eq_u32 s76, 12
	s_cselect_b32 s57, s37, s55
	s_cselect_b32 s56, s72, s54
	s_cselect_b32 s55, s19, s75
	s_cselect_b32 s54, s73, s74
	v_lshl_add_u64 v[178:179], s[52:53], 0, v[132:133]
	s_add_i32 m0, s49, 0xc000
	ds_read_b128 v[184:187], v149
	ds_read_b128 v[188:191], v149 offset:1024
	ds_read_b128 v[192:195], v149 offset:2048
	ds_read_b128 v[196:199], v149 offset:3072
	ds_read_b128 v[200:203], v149 offset:4096
	ds_read_b128 v[204:207], v149 offset:5120
	ds_read_b128 v[208:211], v149 offset:6144
	ds_read_b128 v[212:215], v149 offset:7168
	global_load_lds_dwordx4 v[178:179], off
	v_lshl_add_u64 v[178:179], s[52:53], 0, v[134:135]
	s_add_i32 m0, s49, 0xe000
	s_nop 0
	global_load_lds_dwordx4 v[178:179], off
	s_waitcnt vmcnt(8)
	s_waitcnt lgkmcnt(0)
	s_barrier
	s_setprio 1
	s_waitcnt lgkmcnt(0)
	v_mfma_f32_16x16x32_bf16 v[124:127], v[140:143], v[184:187], 0
	v_mfma_f32_16x16x32_bf16 v[124:127], v[150:153], v[188:191], v[124:127]
	v_mfma_f32_16x16x32_bf16 v[120:123], v[154:157], v[184:187], 0
	v_mfma_f32_16x16x32_bf16 v[120:123], v[158:161], v[188:191], v[120:123]
	v_mfma_f32_16x16x32_bf16 v[108:111], v[140:143], v[192:195], 0
	v_mfma_f32_16x16x32_bf16 v[108:111], v[150:153], v[196:199], v[108:111]
	v_mfma_f32_16x16x32_bf16 v[104:107], v[154:157], v[192:195], 0
	v_mfma_f32_16x16x32_bf16 v[104:107], v[158:161], v[196:199], v[104:107]
	v_mfma_f32_16x16x32_bf16 v[92:95], v[140:143], v[200:203], 0
	v_mfma_f32_16x16x32_bf16 v[92:95], v[150:153], v[204:207], v[92:95]
	v_mfma_f32_16x16x32_bf16 v[88:91], v[154:157], v[200:203], 0
	v_mfma_f32_16x16x32_bf16 v[88:91], v[158:161], v[204:207], v[88:91]
	v_mfma_f32_16x16x32_bf16 v[76:79], v[140:143], v[208:211], 0
	v_mfma_f32_16x16x32_bf16 v[76:79], v[150:153], v[212:215], v[76:79]
	v_mfma_f32_16x16x32_bf16 v[72:75], v[154:157], v[208:211], 0
	v_mfma_f32_16x16x32_bf16 v[72:75], v[158:161], v[212:215], v[72:75]
	v_mfma_f32_16x16x32_bf16 v[116:119], v[162:165], v[184:187], 0
	v_mfma_f32_16x16x32_bf16 v[116:119], v[166:169], v[188:191], v[116:119]
	v_mfma_f32_16x16x32_bf16 v[112:115], v[170:173], v[184:187], 0
	v_mfma_f32_16x16x32_bf16 v[112:115], v[174:177], v[188:191], v[112:115]
	v_mfma_f32_16x16x32_bf16 v[100:103], v[162:165], v[192:195], 0
	v_mfma_f32_16x16x32_bf16 v[100:103], v[166:169], v[196:199], v[100:103]
	v_mfma_f32_16x16x32_bf16 v[96:99], v[170:173], v[192:195], 0
	v_mfma_f32_16x16x32_bf16 v[96:99], v[174:177], v[196:199], v[96:99]
	v_mfma_f32_16x16x32_bf16 v[84:87], v[162:165], v[200:203], 0
	v_mfma_f32_16x16x32_bf16 v[84:87], v[166:169], v[204:207], v[84:87]
	v_mfma_f32_16x16x32_bf16 v[80:83], v[170:173], v[200:203], 0
	v_mfma_f32_16x16x32_bf16 v[80:83], v[174:177], v[204:207], v[80:83]
	v_mfma_f32_16x16x32_bf16 v[68:71], v[162:165], v[208:211], 0
	v_mfma_f32_16x16x32_bf16 v[68:71], v[166:169], v[212:215], v[68:71]
	v_mfma_f32_16x16x32_bf16 v[64:67], v[170:173], v[208:211], 0
	v_mfma_f32_16x16x32_bf16 v[64:67], v[174:177], v[212:215], v[64:67]
	s_setprio 0
	s_barrier
	s_add_i32 s77, s68, s60
	v_lshl_add_u64 v[178:179], s[54:55], 0, v[130:131]
	s_mov_b32 m0, s77
	s_nop 0
	global_load_lds_dwordx4 v[178:179], off
	s_add_i32 m0, s77, 0x2000
	s_add_u32 s82, s54, 0x40000
	v_lshl_add_u64 v[216:217], s[54:55], 0, v[128:129]
	s_addc_u32 s83, s55, 0
	s_add_i32 s77, s69, s60
	global_load_lds_dwordx4 v[216:217], off
	v_lshl_add_u64 v[218:219], s[82:83], 0, v[130:131]
	s_mov_b32 m0, s77
	v_lshl_add_u64 v[220:221], s[56:57], 0, v[128:129]
	global_load_lds_dwordx4 v[218:219], off
	v_lshl_add_u64 v[218:219], s[82:83], 0, v[128:129]
	s_add_i32 m0, s77, 0x2000
	s_nop 0
	global_load_lds_dwordx4 v[218:219], off
	v_lshl_add_u64 v[218:219], s[56:57], 0, v[130:131]
	s_mov_b32 m0, s49
	s_nop 0
	global_load_lds_dwordx4 v[218:219], off
	s_mov_b32 m0, s62
	s_nop 0
	global_load_lds_dwordx4 v[220:221], off
	ds_read_b128 v[184:187], v149 offset:16384
	ds_read_b128 v[188:191], v149 offset:17408
	ds_read_b128 v[192:195], v149 offset:18432
	ds_read_b128 v[196:199], v149 offset:19456
	ds_read_b128 v[200:203], v149 offset:20480
	ds_read_b128 v[204:207], v149 offset:21504
	ds_read_b128 v[208:211], v149 offset:22528
	ds_read_b128 v[212:215], v149 offset:23552
	s_waitcnt vmcnt(8)
	s_waitcnt lgkmcnt(0)
	s_barrier
	s_setprio 1
	s_waitcnt lgkmcnt(0)
	v_mfma_f32_16x16x32_bf16 v[60:63], v[140:143], v[184:187], 0
	v_mfma_f32_16x16x32_bf16 v[60:63], v[150:153], v[188:191], v[60:63]
	v_mfma_f32_16x16x32_bf16 v[56:59], v[154:157], v[184:187], 0
	v_mfma_f32_16x16x32_bf16 v[56:59], v[158:161], v[188:191], v[56:59]
	v_mfma_f32_16x16x32_bf16 v[44:47], v[140:143], v[192:195], 0
	v_mfma_f32_16x16x32_bf16 v[44:47], v[150:153], v[196:199], v[44:47]
	v_mfma_f32_16x16x32_bf16 v[40:43], v[154:157], v[192:195], 0
	v_mfma_f32_16x16x32_bf16 v[40:43], v[158:161], v[196:199], v[40:43]
	v_mfma_f32_16x16x32_bf16 v[28:31], v[140:143], v[200:203], 0
	v_mfma_f32_16x16x32_bf16 v[28:31], v[150:153], v[204:207], v[28:31]
	v_mfma_f32_16x16x32_bf16 v[24:27], v[154:157], v[200:203], 0
	v_mfma_f32_16x16x32_bf16 v[24:27], v[158:161], v[204:207], v[24:27]
	v_mfma_f32_16x16x32_bf16 v[12:15], v[140:143], v[208:211], 0
	v_mfma_f32_16x16x32_bf16 v[12:15], v[150:153], v[212:215], v[12:15]
	v_mfma_f32_16x16x32_bf16 v[8:11], v[154:157], v[208:211], 0
	v_mfma_f32_16x16x32_bf16 v[8:11], v[158:161], v[212:215], v[8:11]
	v_mfma_f32_16x16x32_bf16 v[52:55], v[162:165], v[184:187], 0
	v_mfma_f32_16x16x32_bf16 v[52:55], v[166:169], v[188:191], v[52:55]
	v_mfma_f32_16x16x32_bf16 v[48:51], v[170:173], v[184:187], 0
	v_mfma_f32_16x16x32_bf16 v[48:51], v[174:177], v[188:191], v[48:51]
	v_mfma_f32_16x16x32_bf16 v[36:39], v[162:165], v[192:195], 0
	v_mfma_f32_16x16x32_bf16 v[36:39], v[166:169], v[196:199], v[36:39]
	v_mfma_f32_16x16x32_bf16 v[32:35], v[170:173], v[192:195], 0
	v_mfma_f32_16x16x32_bf16 v[32:35], v[174:177], v[196:199], v[32:35]
	v_mfma_f32_16x16x32_bf16 v[20:23], v[162:165], v[200:203], 0
	v_mfma_f32_16x16x32_bf16 v[20:23], v[166:169], v[204:207], v[20:23]
	v_mfma_f32_16x16x32_bf16 v[16:19], v[170:173], v[200:203], 0
	v_mfma_f32_16x16x32_bf16 v[16:19], v[174:177], v[204:207], v[16:19]
	v_mfma_f32_16x16x32_bf16 v[4:7], v[162:165], v[208:211], 0
	v_mfma_f32_16x16x32_bf16 v[4:7], v[166:169], v[212:215], v[4:7]
	v_mfma_f32_16x16x32_bf16 v[0:3], v[170:173], v[208:211], 0
	v_mfma_f32_16x16x32_bf16 v[0:3], v[174:177], v[212:215], v[0:3]
	s_setprio 0
	s_barrier
	s_branch .Lmid_gemm7
.LBB0_951:
	s_add_u32 s54, s52, 0xfffc0080
	s_addc_u32 s55, s53, -1
	s_cmp_eq_u32 s76, 12
	s_cselect_b32 s57, s37, s55
	s_cselect_b32 s56, s72, s54
	s_cselect_b32 s55, s19, s75
	s_cselect_b32 s54, s73, s74
	v_lshl_add_u64 v[178:179], s[52:53], 0, v[132:133]
	s_add_i32 m0, s49, 0xc000
	s_nop 0
	global_load_lds_dwordx4 v[178:179], off
	v_lshl_add_u64 v[178:179], s[52:53], 0, v[134:135]
	s_add_i32 m0, s49, 0xe000
	s_nop 0
	global_load_lds_dwordx4 v[178:179], off
	ds_read_b128 v[140:143], v147
	ds_read_b128 v[150:153], v147 offset:1024
	ds_read_b128 v[154:157], v147 offset:2048
	ds_read_b128 v[158:161], v147 offset:3072
	ds_read_b128 v[162:165], v148
	ds_read_b128 v[166:169], v148 offset:1024
	ds_read_b128 v[170:173], v148 offset:2048
	ds_read_b128 v[174:177], v148 offset:3072
	ds_read_b128 v[184:187], v149
	ds_read_b128 v[188:191], v149 offset:1024
	ds_read_b128 v[192:195], v149 offset:2048
	ds_read_b128 v[196:199], v149 offset:3072
	ds_read_b128 v[200:203], v149 offset:4096
	ds_read_b128 v[204:207], v149 offset:5120
	ds_read_b128 v[208:211], v149 offset:6144
	ds_read_b128 v[212:215], v149 offset:7168
	s_waitcnt vmcnt(8)
	s_waitcnt lgkmcnt(0)
	s_barrier
	s_setprio 1
	s_waitcnt lgkmcnt(0)
	v_mfma_f32_16x16x32_bf16 v[124:127], v[140:143], v[184:187], v[124:127]
	v_mfma_f32_16x16x32_bf16 v[124:127], v[150:153], v[188:191], v[124:127]
	v_mfma_f32_16x16x32_bf16 v[120:123], v[154:157], v[184:187], v[120:123]
	v_mfma_f32_16x16x32_bf16 v[120:123], v[158:161], v[188:191], v[120:123]
	v_mfma_f32_16x16x32_bf16 v[108:111], v[140:143], v[192:195], v[108:111]
	v_mfma_f32_16x16x32_bf16 v[108:111], v[150:153], v[196:199], v[108:111]
	v_mfma_f32_16x16x32_bf16 v[104:107], v[154:157], v[192:195], v[104:107]
	v_mfma_f32_16x16x32_bf16 v[104:107], v[158:161], v[196:199], v[104:107]
	v_mfma_f32_16x16x32_bf16 v[92:95], v[140:143], v[200:203], v[92:95]
	v_mfma_f32_16x16x32_bf16 v[92:95], v[150:153], v[204:207], v[92:95]
	v_mfma_f32_16x16x32_bf16 v[88:91], v[154:157], v[200:203], v[88:91]
	v_mfma_f32_16x16x32_bf16 v[88:91], v[158:161], v[204:207], v[88:91]
	v_mfma_f32_16x16x32_bf16 v[76:79], v[140:143], v[208:211], v[76:79]
	v_mfma_f32_16x16x32_bf16 v[76:79], v[150:153], v[212:215], v[76:79]
	v_mfma_f32_16x16x32_bf16 v[72:75], v[154:157], v[208:211], v[72:75]
	v_mfma_f32_16x16x32_bf16 v[72:75], v[158:161], v[212:215], v[72:75]
	v_mfma_f32_16x16x32_bf16 v[116:119], v[162:165], v[184:187], v[116:119]
	v_mfma_f32_16x16x32_bf16 v[116:119], v[166:169], v[188:191], v[116:119]
	v_mfma_f32_16x16x32_bf16 v[112:115], v[170:173], v[184:187], v[112:115]
	v_mfma_f32_16x16x32_bf16 v[112:115], v[174:177], v[188:191], v[112:115]
	v_mfma_f32_16x16x32_bf16 v[100:103], v[162:165], v[192:195], v[100:103]
	v_mfma_f32_16x16x32_bf16 v[100:103], v[166:169], v[196:199], v[100:103]
	v_mfma_f32_16x16x32_bf16 v[96:99], v[170:173], v[192:195], v[96:99]
	v_mfma_f32_16x16x32_bf16 v[96:99], v[174:177], v[196:199], v[96:99]
	v_mfma_f32_16x16x32_bf16 v[84:87], v[162:165], v[200:203], v[84:87]
	v_mfma_f32_16x16x32_bf16 v[84:87], v[166:169], v[204:207], v[84:87]
	v_mfma_f32_16x16x32_bf16 v[80:83], v[170:173], v[200:203], v[80:83]
	v_mfma_f32_16x16x32_bf16 v[80:83], v[174:177], v[204:207], v[80:83]
	v_mfma_f32_16x16x32_bf16 v[68:71], v[162:165], v[208:211], v[68:71]
	v_mfma_f32_16x16x32_bf16 v[68:71], v[166:169], v[212:215], v[68:71]
	v_mfma_f32_16x16x32_bf16 v[64:67], v[170:173], v[208:211], v[64:67]
	v_mfma_f32_16x16x32_bf16 v[64:67], v[174:177], v[212:215], v[64:67]
	s_setprio 0
	s_barrier
	s_add_i32 s77, s68, s60
	v_lshl_add_u64 v[178:179], s[54:55], 0, v[130:131]
	s_mov_b32 m0, s77
	s_nop 0
	global_load_lds_dwordx4 v[178:179], off
	s_add_i32 m0, s77, 0x2000
	s_add_u32 s82, s54, 0x40000
	v_lshl_add_u64 v[216:217], s[54:55], 0, v[128:129]
	s_addc_u32 s83, s55, 0
	s_add_i32 s77, s69, s60
	global_load_lds_dwordx4 v[216:217], off
	v_lshl_add_u64 v[218:219], s[82:83], 0, v[130:131]
	s_mov_b32 m0, s77
	v_lshl_add_u64 v[220:221], s[56:57], 0, v[128:129]
	global_load_lds_dwordx4 v[218:219], off
	v_lshl_add_u64 v[218:219], s[82:83], 0, v[128:129]
	s_add_i32 m0, s77, 0x2000
	s_nop 0
	global_load_lds_dwordx4 v[218:219], off
	v_lshl_add_u64 v[218:219], s[56:57], 0, v[130:131]
	s_mov_b32 m0, s49
	s_nop 0
	global_load_lds_dwordx4 v[218:219], off
	s_mov_b32 m0, s62
	s_nop 0
	global_load_lds_dwordx4 v[220:221], off
	ds_read_b128 v[184:187], v149 offset:16384
	ds_read_b128 v[188:191], v149 offset:17408
	ds_read_b128 v[192:195], v149 offset:18432
	ds_read_b128 v[196:199], v149 offset:19456
	ds_read_b128 v[200:203], v149 offset:20480
	ds_read_b128 v[204:207], v149 offset:21504
	ds_read_b128 v[208:211], v149 offset:22528
	ds_read_b128 v[212:215], v149 offset:23552
	s_waitcnt vmcnt(8)
	s_waitcnt lgkmcnt(0)
	s_barrier
	s_setprio 1
	s_waitcnt lgkmcnt(0)
	v_mfma_f32_16x16x32_bf16 v[60:63], v[140:143], v[184:187], v[60:63]
	v_mfma_f32_16x16x32_bf16 v[60:63], v[150:153], v[188:191], v[60:63]
	v_mfma_f32_16x16x32_bf16 v[56:59], v[154:157], v[184:187], v[56:59]
	v_mfma_f32_16x16x32_bf16 v[56:59], v[158:161], v[188:191], v[56:59]
	v_mfma_f32_16x16x32_bf16 v[44:47], v[140:143], v[192:195], v[44:47]
	v_mfma_f32_16x16x32_bf16 v[44:47], v[150:153], v[196:199], v[44:47]
	v_mfma_f32_16x16x32_bf16 v[40:43], v[154:157], v[192:195], v[40:43]
	v_mfma_f32_16x16x32_bf16 v[40:43], v[158:161], v[196:199], v[40:43]
	v_mfma_f32_16x16x32_bf16 v[28:31], v[140:143], v[200:203], v[28:31]
	v_mfma_f32_16x16x32_bf16 v[28:31], v[150:153], v[204:207], v[28:31]
	v_mfma_f32_16x16x32_bf16 v[24:27], v[154:157], v[200:203], v[24:27]
	v_mfma_f32_16x16x32_bf16 v[24:27], v[158:161], v[204:207], v[24:27]
	v_mfma_f32_16x16x32_bf16 v[12:15], v[140:143], v[208:211], v[12:15]
	v_mfma_f32_16x16x32_bf16 v[12:15], v[150:153], v[212:215], v[12:15]
	v_mfma_f32_16x16x32_bf16 v[8:11], v[154:157], v[208:211], v[8:11]
	v_mfma_f32_16x16x32_bf16 v[8:11], v[158:161], v[212:215], v[8:11]
	v_mfma_f32_16x16x32_bf16 v[52:55], v[162:165], v[184:187], v[52:55]
	v_mfma_f32_16x16x32_bf16 v[52:55], v[166:169], v[188:191], v[52:55]
	v_mfma_f32_16x16x32_bf16 v[48:51], v[170:173], v[184:187], v[48:51]
	v_mfma_f32_16x16x32_bf16 v[48:51], v[174:177], v[188:191], v[48:51]
	v_mfma_f32_16x16x32_bf16 v[36:39], v[162:165], v[192:195], v[36:39]
	v_mfma_f32_16x16x32_bf16 v[36:39], v[166:169], v[196:199], v[36:39]
	v_mfma_f32_16x16x32_bf16 v[32:35], v[170:173], v[192:195], v[32:35]
	v_mfma_f32_16x16x32_bf16 v[32:35], v[174:177], v[196:199], v[32:35]
	v_mfma_f32_16x16x32_bf16 v[20:23], v[162:165], v[200:203], v[20:23]
	v_mfma_f32_16x16x32_bf16 v[20:23], v[166:169], v[204:207], v[20:23]
	v_mfma_f32_16x16x32_bf16 v[16:19], v[170:173], v[200:203], v[16:19]
	v_mfma_f32_16x16x32_bf16 v[16:19], v[174:177], v[204:207], v[16:19]
	v_mfma_f32_16x16x32_bf16 v[4:7], v[162:165], v[208:211], v[4:7]
	v_mfma_f32_16x16x32_bf16 v[4:7], v[166:169], v[212:215], v[4:7]
	v_mfma_f32_16x16x32_bf16 v[0:3], v[170:173], v[208:211], v[0:3]
	v_mfma_f32_16x16x32_bf16 v[0:3], v[174:177], v[212:215], v[0:3]
	s_setprio 0
	s_barrier
.Lmid_gemm7:
	s_add_i32 s77, 0, 0x18000
	s_add_i32 s79, 0, 0x1c000
	v_add_u32_e32 v158, s77, v145
	v_add_u32_e32 v174, s79, v145
	s_add_u32 s56, s56, 0x40000
	s_addc_u32 s57, s57, 0
	s_mov_b32 m0, s63
	v_lshl_add_u64 v[222:223], s[56:57], 0, v[130:131]
	global_load_lds_dwordx4 v[222:223], off
	v_lshl_add_u64 v[222:223], s[56:57], 0, v[128:129]
	s_mov_b32 m0, s64
	s_nop 0
	global_load_lds_dwordx4 v[222:223], off
	ds_read_b128 v[140:143], v158
	ds_read_b128 v[150:153], v158 offset:1024
	ds_read_b128 v[154:157], v158 offset:2048
	ds_read_b128 v[158:161], v158 offset:3072
	ds_read_b128 v[162:165], v174
	ds_read_b128 v[166:169], v174 offset:1024
	ds_read_b128 v[170:173], v174 offset:2048
	ds_read_b128 v[174:177], v174 offset:3072
	ds_read_b128 v[184:187], v149 offset:32768
	ds_read_b128 v[188:191], v149 offset:33792
	ds_read_b128 v[192:195], v149 offset:34816
	ds_read_b128 v[196:199], v149 offset:35840
	ds_read_b128 v[200:203], v149 offset:36864
	ds_read_b128 v[204:207], v149 offset:37888
	ds_read_b128 v[208:211], v149 offset:38912
	ds_read_b128 v[212:215], v149 offset:39936
	s_waitcnt vmcnt(8)
	s_waitcnt lgkmcnt(0)
	s_barrier
	s_setprio 1
	s_waitcnt lgkmcnt(0)
	v_mfma_f32_16x16x32_bf16 v[124:127], v[140:143], v[184:187], v[124:127]
	v_mfma_f32_16x16x32_bf16 v[124:127], v[150:153], v[188:191], v[124:127]
	v_mfma_f32_16x16x32_bf16 v[120:123], v[154:157], v[184:187], v[120:123]
	v_mfma_f32_16x16x32_bf16 v[120:123], v[158:161], v[188:191], v[120:123]
	v_mfma_f32_16x16x32_bf16 v[108:111], v[140:143], v[192:195], v[108:111]
	v_mfma_f32_16x16x32_bf16 v[108:111], v[150:153], v[196:199], v[108:111]
	v_mfma_f32_16x16x32_bf16 v[104:107], v[154:157], v[192:195], v[104:107]
	v_mfma_f32_16x16x32_bf16 v[104:107], v[158:161], v[196:199], v[104:107]
	v_mfma_f32_16x16x32_bf16 v[92:95], v[140:143], v[200:203], v[92:95]
	v_mfma_f32_16x16x32_bf16 v[92:95], v[150:153], v[204:207], v[92:95]
	v_mfma_f32_16x16x32_bf16 v[88:91], v[154:157], v[200:203], v[88:91]
	v_mfma_f32_16x16x32_bf16 v[88:91], v[158:161], v[204:207], v[88:91]
	v_mfma_f32_16x16x32_bf16 v[76:79], v[140:143], v[208:211], v[76:79]
	v_mfma_f32_16x16x32_bf16 v[76:79], v[150:153], v[212:215], v[76:79]
	v_mfma_f32_16x16x32_bf16 v[72:75], v[154:157], v[208:211], v[72:75]
	v_mfma_f32_16x16x32_bf16 v[72:75], v[158:161], v[212:215], v[72:75]
	v_mfma_f32_16x16x32_bf16 v[116:119], v[162:165], v[184:187], v[116:119]
	v_mfma_f32_16x16x32_bf16 v[116:119], v[166:169], v[188:191], v[116:119]
	v_mfma_f32_16x16x32_bf16 v[112:115], v[170:173], v[184:187], v[112:115]
	v_mfma_f32_16x16x32_bf16 v[112:115], v[174:177], v[188:191], v[112:115]
	v_mfma_f32_16x16x32_bf16 v[100:103], v[162:165], v[192:195], v[100:103]
	v_mfma_f32_16x16x32_bf16 v[100:103], v[166:169], v[196:199], v[100:103]
	v_mfma_f32_16x16x32_bf16 v[96:99], v[170:173], v[192:195], v[96:99]
	v_mfma_f32_16x16x32_bf16 v[96:99], v[174:177], v[196:199], v[96:99]
	v_mfma_f32_16x16x32_bf16 v[84:87], v[162:165], v[200:203], v[84:87]
	v_mfma_f32_16x16x32_bf16 v[84:87], v[166:169], v[204:207], v[84:87]
	v_mfma_f32_16x16x32_bf16 v[80:83], v[170:173], v[200:203], v[80:83]
	v_mfma_f32_16x16x32_bf16 v[80:83], v[174:177], v[204:207], v[80:83]
	v_mfma_f32_16x16x32_bf16 v[68:71], v[162:165], v[208:211], v[68:71]
	v_mfma_f32_16x16x32_bf16 v[68:71], v[166:169], v[212:215], v[68:71]
	v_mfma_f32_16x16x32_bf16 v[64:67], v[170:173], v[208:211], v[64:67]
	v_mfma_f32_16x16x32_bf16 v[64:67], v[174:177], v[212:215], v[64:67]
	s_setprio 0
	s_barrier
	s_add_i32 s56, s77, s60
	v_lshl_add_u64 v[178:179], v[178:179], 0, s[12:13]
	s_mov_b32 m0, s56
	s_nop 0
	global_load_lds_dwordx4 v[178:179], off
	s_add_i32 m0, s56, 0x2000
	s_add_u32 s54, s54, 0x40080
	v_lshl_add_u64 v[178:179], v[216:217], 0, s[12:13]
	s_addc_u32 s55, s55, 0
	s_add_i32 s56, s79, s60
	global_load_lds_dwordx4 v[178:179], off
	v_lshl_add_u64 v[178:179], s[54:55], 0, v[130:131]
	s_mov_b32 m0, s56
	s_nop 0
	global_load_lds_dwordx4 v[178:179], off
	v_lshl_add_u64 v[178:179], s[54:55], 0, v[128:129]
	s_add_i32 m0, s56, 0x2000
	s_nop 0
	global_load_lds_dwordx4 v[178:179], off
	v_lshl_add_u64 v[178:179], v[218:219], 0, s[12:13]
	s_mov_b32 m0, s66
	s_nop 0
	global_load_lds_dwordx4 v[178:179], off
	v_lshl_add_u64 v[178:179], v[220:221], 0, s[12:13]
	s_mov_b32 m0, s67
	s_nop 0
	global_load_lds_dwordx4 v[178:179], off
	ds_read_b128 v[184:187], v149 offset:49152
	ds_read_b128 v[188:191], v149 offset:50176
	ds_read_b128 v[192:195], v149 offset:51200
	ds_read_b128 v[196:199], v149 offset:52224
	ds_read_b128 v[200:203], v149 offset:53248
	ds_read_b128 v[204:207], v149 offset:54272
	ds_read_b128 v[208:211], v149 offset:55296
	ds_read_b128 v[212:215], v149 offset:56320
	s_waitcnt vmcnt(8)
	s_waitcnt lgkmcnt(0)
	s_barrier
	s_setprio 1
	s_waitcnt lgkmcnt(0)
	v_mfma_f32_16x16x32_bf16 v[60:63], v[140:143], v[184:187], v[60:63]
	v_mfma_f32_16x16x32_bf16 v[60:63], v[150:153], v[188:191], v[60:63]
	v_mfma_f32_16x16x32_bf16 v[56:59], v[154:157], v[184:187], v[56:59]
	v_mfma_f32_16x16x32_bf16 v[56:59], v[158:161], v[188:191], v[56:59]
	v_mfma_f32_16x16x32_bf16 v[44:47], v[140:143], v[192:195], v[44:47]
	v_mfma_f32_16x16x32_bf16 v[44:47], v[150:153], v[196:199], v[44:47]
	v_mfma_f32_16x16x32_bf16 v[40:43], v[154:157], v[192:195], v[40:43]
	v_mfma_f32_16x16x32_bf16 v[40:43], v[158:161], v[196:199], v[40:43]
	v_mfma_f32_16x16x32_bf16 v[28:31], v[140:143], v[200:203], v[28:31]
	v_mfma_f32_16x16x32_bf16 v[28:31], v[150:153], v[204:207], v[28:31]
	v_mfma_f32_16x16x32_bf16 v[24:27], v[154:157], v[200:203], v[24:27]
	v_mfma_f32_16x16x32_bf16 v[24:27], v[158:161], v[204:207], v[24:27]
	v_mfma_f32_16x16x32_bf16 v[12:15], v[140:143], v[208:211], v[12:15]
	v_mfma_f32_16x16x32_bf16 v[12:15], v[150:153], v[212:215], v[12:15]
	v_mfma_f32_16x16x32_bf16 v[8:11], v[154:157], v[208:211], v[8:11]
	v_mfma_f32_16x16x32_bf16 v[8:11], v[158:161], v[212:215], v[8:11]
	v_mfma_f32_16x16x32_bf16 v[52:55], v[162:165], v[184:187], v[52:55]
	v_mfma_f32_16x16x32_bf16 v[52:55], v[166:169], v[188:191], v[52:55]
	v_mfma_f32_16x16x32_bf16 v[48:51], v[170:173], v[184:187], v[48:51]
	v_mfma_f32_16x16x32_bf16 v[48:51], v[174:177], v[188:191], v[48:51]
	v_mfma_f32_16x16x32_bf16 v[36:39], v[162:165], v[192:195], v[36:39]
	v_mfma_f32_16x16x32_bf16 v[36:39], v[166:169], v[196:199], v[36:39]
	v_mfma_f32_16x16x32_bf16 v[32:35], v[170:173], v[192:195], v[32:35]
	v_mfma_f32_16x16x32_bf16 v[32:35], v[174:177], v[196:199], v[32:35]
	v_mfma_f32_16x16x32_bf16 v[20:23], v[162:165], v[200:203], v[20:23]
	v_mfma_f32_16x16x32_bf16 v[20:23], v[166:169], v[204:207], v[20:23]
	v_mfma_f32_16x16x32_bf16 v[16:19], v[170:173], v[200:203], v[16:19]
	v_mfma_f32_16x16x32_bf16 v[16:19], v[174:177], v[204:207], v[16:19]
	v_mfma_f32_16x16x32_bf16 v[4:7], v[162:165], v[208:211], v[4:7]
	v_mfma_f32_16x16x32_bf16 v[4:7], v[166:169], v[212:215], v[4:7]
	v_mfma_f32_16x16x32_bf16 v[0:3], v[170:173], v[208:211], v[0:3]
	v_mfma_f32_16x16x32_bf16 v[0:3], v[174:177], v[212:215], v[0:3]
	s_setprio 0
	s_barrier
	s_add_i32 s76, s76, 2
	s_add_u32 s52, s52, 0x100
	s_addc_u32 s53, s53, 0
	s_add_u32 s74, s74, 0x100
	s_addc_u32 s75, s75, 0
	s_cmp_gt_u32 s76, 13
	s_cbranch_scc0 .LBB0_951
	s_and_b64 vcc, exec, s[16:17]
	s_cbranch_vccz .LBB0_954
	s_barrier

.LBB0_1030:
	s_add_u32 s86, s56, 0x100
	s_addc_u32 s87, s57, 0
	s_mov_b32 s88, -2
	ds_read_b128 v[152:155], v149
	ds_read_b128 v[156:159], v149 offset:1024
	ds_read_b128 v[160:163], v149 offset:2048
	ds_read_b128 v[164:167], v149 offset:3072
	ds_read_b128 v[168:171], v150
	ds_read_b128 v[172:175], v150 offset:1024
	ds_read_b128 v[176:179], v150 offset:2048
	ds_read_b128 v[184:187], v150 offset:3072
	s_add_u32 s56, s54, 0x100
	s_addc_u32 s57, s55, 0
	s_cmp_eq_u32 s88, 40
	s_cselect_b32 s61, s13, s57
	s_cselect_b32 s60, s12, s56
	s_cselect_b32 s59, s53, s87
	s_cselect_b32 s58, s52, s86
	v_lshl_add_u64 v[144:145], s[54:55], 0, v[136:137]
	s_add_i32 m0, s65, 0xc000
	ds_read_b128 v[188:191], v151
	ds_read_b128 v[192:195], v151 offset:1024
	ds_read_b128 v[196:199], v151 offset:2048
	ds_read_b128 v[200:203], v151 offset:3072
	ds_read_b128 v[204:207], v151 offset:4096
	ds_read_b128 v[208:211], v151 offset:5120
	ds_read_b128 v[212:215], v151 offset:6144
	ds_read_b128 v[216:219], v151 offset:7168
	global_load_lds_dwordx4 v[144:145], off
	v_lshl_add_u64 v[144:145], s[54:55], 0, v[138:139]
	s_add_i32 m0, s65, 0xe000
	s_nop 0
	global_load_lds_dwordx4 v[144:145], off
	s_waitcnt vmcnt(8)
	s_waitcnt lgkmcnt(0)
	s_barrier
	s_setprio 1
	s_waitcnt lgkmcnt(0)
	v_mfma_f32_16x16x32_bf16 v[124:127], v[152:155], v[188:191], 0
	v_mfma_f32_16x16x32_bf16 v[124:127], v[156:159], v[192:195], v[124:127]
	v_mfma_f32_16x16x32_bf16 v[120:123], v[160:163], v[188:191], 0
	v_mfma_f32_16x16x32_bf16 v[120:123], v[164:167], v[192:195], v[120:123]
	v_mfma_f32_16x16x32_bf16 v[116:119], v[152:155], v[196:199], 0
	v_mfma_f32_16x16x32_bf16 v[116:119], v[156:159], v[200:203], v[116:119]
	v_mfma_f32_16x16x32_bf16 v[108:111], v[160:163], v[196:199], 0
	v_mfma_f32_16x16x32_bf16 v[108:111], v[164:167], v[200:203], v[108:111]
	v_mfma_f32_16x16x32_bf16 v[100:103], v[152:155], v[204:207], 0
	v_mfma_f32_16x16x32_bf16 v[100:103], v[156:159], v[208:211], v[100:103]
	v_mfma_f32_16x16x32_bf16 v[92:95], v[160:163], v[204:207], 0
	v_mfma_f32_16x16x32_bf16 v[92:95], v[164:167], v[208:211], v[92:95]
	v_mfma_f32_16x16x32_bf16 v[84:87], v[152:155], v[212:215], 0
	v_mfma_f32_16x16x32_bf16 v[84:87], v[156:159], v[216:219], v[84:87]
	v_mfma_f32_16x16x32_bf16 v[76:79], v[160:163], v[212:215], 0
	v_mfma_f32_16x16x32_bf16 v[76:79], v[164:167], v[216:219], v[76:79]
	v_mfma_f32_16x16x32_bf16 v[112:115], v[168:171], v[188:191], 0
	v_mfma_f32_16x16x32_bf16 v[112:115], v[172:175], v[192:195], v[112:115]
	v_mfma_f32_16x16x32_bf16 v[104:107], v[176:179], v[188:191], 0
	v_mfma_f32_16x16x32_bf16 v[104:107], v[184:187], v[192:195], v[104:107]
	v_mfma_f32_16x16x32_bf16 v[96:99], v[168:171], v[196:199], 0
	v_mfma_f32_16x16x32_bf16 v[96:99], v[172:175], v[200:203], v[96:99]
	v_mfma_f32_16x16x32_bf16 v[88:91], v[176:179], v[196:199], 0
	v_mfma_f32_16x16x32_bf16 v[88:91], v[184:187], v[200:203], v[88:91]
	v_mfma_f32_16x16x32_bf16 v[80:83], v[168:171], v[204:207], 0
	v_mfma_f32_16x16x32_bf16 v[80:83], v[172:175], v[208:211], v[80:83]
	v_mfma_f32_16x16x32_bf16 v[72:75], v[176:179], v[204:207], 0
	v_mfma_f32_16x16x32_bf16 v[72:75], v[184:187], v[208:211], v[72:75]
	v_mfma_f32_16x16x32_bf16 v[68:71], v[168:171], v[212:215], 0
	v_mfma_f32_16x16x32_bf16 v[68:71], v[172:175], v[216:219], v[68:71]
	v_mfma_f32_16x16x32_bf16 v[64:67], v[176:179], v[212:215], 0
	v_mfma_f32_16x16x32_bf16 v[64:67], v[184:187], v[216:219], v[64:67]
	s_setprio 0
	s_barrier
	s_add_i32 s54, s72, s64
	v_lshl_add_u64 v[144:145], s[58:59], 0, v[130:131]
	s_mov_b32 m0, s54
	s_nop 0
	global_load_lds_dwordx4 v[144:145], off
	s_add_i32 m0, s54, 0x2000
	s_add_u32 s54, s58, 0xb0000
	v_lshl_add_u64 v[220:221], s[58:59], 0, v[134:135]
	s_addc_u32 s55, s59, 0
	s_add_i32 s79, s73, s64
	global_load_lds_dwordx4 v[220:221], off
	v_lshl_add_u64 v[222:223], s[54:55], 0, v[130:131]
	s_mov_b32 m0, s79
	v_lshl_add_u64 v[224:225], s[60:61], 0, v[132:133]
	global_load_lds_dwordx4 v[222:223], off
	v_lshl_add_u64 v[222:223], s[54:55], 0, v[134:135]
	s_add_i32 m0, s79, 0x2000
	s_nop 0
	global_load_lds_dwordx4 v[222:223], off
	v_lshl_add_u64 v[222:223], s[60:61], 0, v[128:129]
	s_mov_b32 m0, s65
	s_nop 0
	global_load_lds_dwordx4 v[222:223], off
	s_mov_b32 m0, s66
	s_nop 0
	global_load_lds_dwordx4 v[224:225], off
	ds_read_b128 v[188:191], v151 offset:16384
	ds_read_b128 v[192:195], v151 offset:17408
	ds_read_b128 v[196:199], v151 offset:18432
	ds_read_b128 v[200:203], v151 offset:19456
	ds_read_b128 v[204:207], v151 offset:20480
	ds_read_b128 v[208:211], v151 offset:21504
	ds_read_b128 v[212:215], v151 offset:22528
	ds_read_b128 v[216:219], v151 offset:23552
	s_waitcnt vmcnt(8)
	s_waitcnt lgkmcnt(0)
	s_barrier
	s_setprio 1
	s_waitcnt lgkmcnt(0)
	v_mfma_f32_16x16x32_bf16 v[60:63], v[152:155], v[188:191], 0
	v_mfma_f32_16x16x32_bf16 v[60:63], v[156:159], v[192:195], v[60:63]
	v_mfma_f32_16x16x32_bf16 v[56:59], v[160:163], v[188:191], 0
	v_mfma_f32_16x16x32_bf16 v[56:59], v[164:167], v[192:195], v[56:59]
	v_mfma_f32_16x16x32_bf16 v[52:55], v[152:155], v[196:199], 0
	v_mfma_f32_16x16x32_bf16 v[52:55], v[156:159], v[200:203], v[52:55]
	v_mfma_f32_16x16x32_bf16 v[44:47], v[160:163], v[196:199], 0
	v_mfma_f32_16x16x32_bf16 v[44:47], v[164:167], v[200:203], v[44:47]
	v_mfma_f32_16x16x32_bf16 v[36:39], v[152:155], v[204:207], 0
	v_mfma_f32_16x16x32_bf16 v[36:39], v[156:159], v[208:211], v[36:39]
	v_mfma_f32_16x16x32_bf16 v[28:31], v[160:163], v[204:207], 0
	v_mfma_f32_16x16x32_bf16 v[28:31], v[164:167], v[208:211], v[28:31]
	v_mfma_f32_16x16x32_bf16 v[20:23], v[152:155], v[212:215], 0
	v_mfma_f32_16x16x32_bf16 v[20:23], v[156:159], v[216:219], v[20:23]
	v_mfma_f32_16x16x32_bf16 v[12:15], v[160:163], v[212:215], 0
	v_mfma_f32_16x16x32_bf16 v[12:15], v[164:167], v[216:219], v[12:15]
	v_mfma_f32_16x16x32_bf16 v[48:51], v[168:171], v[188:191], 0
	v_mfma_f32_16x16x32_bf16 v[48:51], v[172:175], v[192:195], v[48:51]
	v_mfma_f32_16x16x32_bf16 v[40:43], v[176:179], v[188:191], 0
	v_mfma_f32_16x16x32_bf16 v[40:43], v[184:187], v[192:195], v[40:43]
	v_mfma_f32_16x16x32_bf16 v[32:35], v[168:171], v[196:199], 0
	v_mfma_f32_16x16x32_bf16 v[32:35], v[172:175], v[200:203], v[32:35]
	v_mfma_f32_16x16x32_bf16 v[24:27], v[176:179], v[196:199], 0
	v_mfma_f32_16x16x32_bf16 v[24:27], v[184:187], v[200:203], v[24:27]
	v_mfma_f32_16x16x32_bf16 v[16:19], v[168:171], v[204:207], 0
	v_mfma_f32_16x16x32_bf16 v[16:19], v[172:175], v[208:211], v[16:19]
	v_mfma_f32_16x16x32_bf16 v[8:11], v[176:179], v[204:207], 0
	v_mfma_f32_16x16x32_bf16 v[8:11], v[184:187], v[208:211], v[8:11]
	v_mfma_f32_16x16x32_bf16 v[4:7], v[168:171], v[212:215], 0
	v_mfma_f32_16x16x32_bf16 v[4:7], v[172:175], v[216:219], v[4:7]
	v_mfma_f32_16x16x32_bf16 v[0:3], v[176:179], v[212:215], 0
	v_mfma_f32_16x16x32_bf16 v[0:3], v[184:187], v[216:219], v[0:3]
	s_setprio 0
	s_barrier
	s_branch .Lmid_gemm8
.LBB0_1031:
	s_add_u32 s56, s54, 0x100
	s_addc_u32 s57, s55, 0
	s_cmp_eq_u32 s88, 40
	s_cselect_b32 s61, s13, s57
	s_cselect_b32 s60, s12, s56
	s_cselect_b32 s59, s53, s87
	s_cselect_b32 s58, s52, s86
	v_lshl_add_u64 v[144:145], s[54:55], 0, v[136:137]
	s_add_i32 m0, s65, 0xc000
	s_nop 0
	global_load_lds_dwordx4 v[144:145], off
	v_lshl_add_u64 v[144:145], s[54:55], 0, v[138:139]
	s_add_i32 m0, s65, 0xe000
	s_nop 0
	global_load_lds_dwordx4 v[144:145], off
	ds_read_b128 v[152:155], v149
	ds_read_b128 v[156:159], v149 offset:1024
	ds_read_b128 v[160:163], v149 offset:2048
	ds_read_b128 v[164:167], v149 offset:3072
	ds_read_b128 v[168:171], v150
	ds_read_b128 v[172:175], v150 offset:1024
	ds_read_b128 v[176:179], v150 offset:2048
	ds_read_b128 v[184:187], v150 offset:3072
	ds_read_b128 v[188:191], v151
	ds_read_b128 v[192:195], v151 offset:1024
	ds_read_b128 v[196:199], v151 offset:2048
	ds_read_b128 v[200:203], v151 offset:3072
	ds_read_b128 v[204:207], v151 offset:4096
	ds_read_b128 v[208:211], v151 offset:5120
	ds_read_b128 v[212:215], v151 offset:6144
	ds_read_b128 v[216:219], v151 offset:7168
	s_waitcnt vmcnt(8)
	s_waitcnt lgkmcnt(0)
	s_barrier
	s_setprio 1
	s_waitcnt lgkmcnt(0)
	v_mfma_f32_16x16x32_bf16 v[124:127], v[152:155], v[188:191], v[124:127]
	v_mfma_f32_16x16x32_bf16 v[124:127], v[156:159], v[192:195], v[124:127]
	v_mfma_f32_16x16x32_bf16 v[120:123], v[160:163], v[188:191], v[120:123]
	v_mfma_f32_16x16x32_bf16 v[120:123], v[164:167], v[192:195], v[120:123]
	v_mfma_f32_16x16x32_bf16 v[116:119], v[152:155], v[196:199], v[116:119]
	v_mfma_f32_16x16x32_bf16 v[116:119], v[156:159], v[200:203], v[116:119]
	v_mfma_f32_16x16x32_bf16 v[108:111], v[160:163], v[196:199], v[108:111]
	v_mfma_f32_16x16x32_bf16 v[108:111], v[164:167], v[200:203], v[108:111]
	v_mfma_f32_16x16x32_bf16 v[100:103], v[152:155], v[204:207], v[100:103]
	v_mfma_f32_16x16x32_bf16 v[100:103], v[156:159], v[208:211], v[100:103]
	v_mfma_f32_16x16x32_bf16 v[92:95], v[160:163], v[204:207], v[92:95]
	v_mfma_f32_16x16x32_bf16 v[92:95], v[164:167], v[208:211], v[92:95]
	v_mfma_f32_16x16x32_bf16 v[84:87], v[152:155], v[212:215], v[84:87]
	v_mfma_f32_16x16x32_bf16 v[84:87], v[156:159], v[216:219], v[84:87]
	v_mfma_f32_16x16x32_bf16 v[76:79], v[160:163], v[212:215], v[76:79]
	v_mfma_f32_16x16x32_bf16 v[76:79], v[164:167], v[216:219], v[76:79]
	v_mfma_f32_16x16x32_bf16 v[112:115], v[168:171], v[188:191], v[112:115]
	v_mfma_f32_16x16x32_bf16 v[112:115], v[172:175], v[192:195], v[112:115]
	v_mfma_f32_16x16x32_bf16 v[104:107], v[176:179], v[188:191], v[104:107]
	v_mfma_f32_16x16x32_bf16 v[104:107], v[184:187], v[192:195], v[104:107]
	v_mfma_f32_16x16x32_bf16 v[96:99], v[168:171], v[196:199], v[96:99]
	v_mfma_f32_16x16x32_bf16 v[96:99], v[172:175], v[200:203], v[96:99]
	v_mfma_f32_16x16x32_bf16 v[88:91], v[176:179], v[196:199], v[88:91]
	v_mfma_f32_16x16x32_bf16 v[88:91], v[184:187], v[200:203], v[88:91]
	v_mfma_f32_16x16x32_bf16 v[80:83], v[168:171], v[204:207], v[80:83]
	v_mfma_f32_16x16x32_bf16 v[80:83], v[172:175], v[208:211], v[80:83]
	v_mfma_f32_16x16x32_bf16 v[72:75], v[176:179], v[204:207], v[72:75]
	v_mfma_f32_16x16x32_bf16 v[72:75], v[184:187], v[208:211], v[72:75]
	v_mfma_f32_16x16x32_bf16 v[68:71], v[168:171], v[212:215], v[68:71]
	v_mfma_f32_16x16x32_bf16 v[68:71], v[172:175], v[216:219], v[68:71]
	v_mfma_f32_16x16x32_bf16 v[64:67], v[176:179], v[212:215], v[64:67]
	v_mfma_f32_16x16x32_bf16 v[64:67], v[184:187], v[216:219], v[64:67]
	s_setprio 0
	s_barrier
	s_add_i32 s54, s72, s64
	v_lshl_add_u64 v[144:145], s[58:59], 0, v[130:131]
	s_mov_b32 m0, s54
	s_nop 0
	global_load_lds_dwordx4 v[144:145], off
	s_add_i32 m0, s54, 0x2000
	s_add_u32 s54, s58, 0xb0000
	v_lshl_add_u64 v[220:221], s[58:59], 0, v[134:135]
	s_addc_u32 s55, s59, 0
	s_add_i32 s79, s73, s64
	global_load_lds_dwordx4 v[220:221], off
	v_lshl_add_u64 v[222:223], s[54:55], 0, v[130:131]
	s_mov_b32 m0, s79
	v_lshl_add_u64 v[224:225], s[60:61], 0, v[132:133]
	global_load_lds_dwordx4 v[222:223], off
	v_lshl_add_u64 v[222:223], s[54:55], 0, v[134:135]
	s_add_i32 m0, s79, 0x2000
	s_nop 0
	global_load_lds_dwordx4 v[222:223], off
	v_lshl_add_u64 v[222:223], s[60:61], 0, v[128:129]
	s_mov_b32 m0, s65
	s_nop 0
	global_load_lds_dwordx4 v[222:223], off
	s_mov_b32 m0, s66
	s_nop 0
	global_load_lds_dwordx4 v[224:225], off
	ds_read_b128 v[188:191], v151 offset:16384
	ds_read_b128 v[192:195], v151 offset:17408
	ds_read_b128 v[196:199], v151 offset:18432
	ds_read_b128 v[200:203], v151 offset:19456
	ds_read_b128 v[204:207], v151 offset:20480
	ds_read_b128 v[208:211], v151 offset:21504
	ds_read_b128 v[212:215], v151 offset:22528
	ds_read_b128 v[216:219], v151 offset:23552
	s_waitcnt vmcnt(8)
	s_waitcnt lgkmcnt(0)
	s_barrier
	s_setprio 1
	s_waitcnt lgkmcnt(0)
	v_mfma_f32_16x16x32_bf16 v[60:63], v[152:155], v[188:191], v[60:63]
	v_mfma_f32_16x16x32_bf16 v[60:63], v[156:159], v[192:195], v[60:63]
	v_mfma_f32_16x16x32_bf16 v[56:59], v[160:163], v[188:191], v[56:59]
	v_mfma_f32_16x16x32_bf16 v[56:59], v[164:167], v[192:195], v[56:59]
	v_mfma_f32_16x16x32_bf16 v[52:55], v[152:155], v[196:199], v[52:55]
	v_mfma_f32_16x16x32_bf16 v[52:55], v[156:159], v[200:203], v[52:55]
	v_mfma_f32_16x16x32_bf16 v[44:47], v[160:163], v[196:199], v[44:47]
	v_mfma_f32_16x16x32_bf16 v[44:47], v[164:167], v[200:203], v[44:47]
	v_mfma_f32_16x16x32_bf16 v[36:39], v[152:155], v[204:207], v[36:39]
	v_mfma_f32_16x16x32_bf16 v[36:39], v[156:159], v[208:211], v[36:39]
	v_mfma_f32_16x16x32_bf16 v[28:31], v[160:163], v[204:207], v[28:31]
	v_mfma_f32_16x16x32_bf16 v[28:31], v[164:167], v[208:211], v[28:31]
	v_mfma_f32_16x16x32_bf16 v[20:23], v[152:155], v[212:215], v[20:23]
	v_mfma_f32_16x16x32_bf16 v[20:23], v[156:159], v[216:219], v[20:23]
	v_mfma_f32_16x16x32_bf16 v[12:15], v[160:163], v[212:215], v[12:15]
	v_mfma_f32_16x16x32_bf16 v[12:15], v[164:167], v[216:219], v[12:15]
	v_mfma_f32_16x16x32_bf16 v[48:51], v[168:171], v[188:191], v[48:51]
	v_mfma_f32_16x16x32_bf16 v[48:51], v[172:175], v[192:195], v[48:51]
	v_mfma_f32_16x16x32_bf16 v[40:43], v[176:179], v[188:191], v[40:43]
	v_mfma_f32_16x16x32_bf16 v[40:43], v[184:187], v[192:195], v[40:43]
	v_mfma_f32_16x16x32_bf16 v[32:35], v[168:171], v[196:199], v[32:35]
	v_mfma_f32_16x16x32_bf16 v[32:35], v[172:175], v[200:203], v[32:35]
	v_mfma_f32_16x16x32_bf16 v[24:27], v[176:179], v[196:199], v[24:27]
	v_mfma_f32_16x16x32_bf16 v[24:27], v[184:187], v[200:203], v[24:27]
	v_mfma_f32_16x16x32_bf16 v[16:19], v[168:171], v[204:207], v[16:19]
	v_mfma_f32_16x16x32_bf16 v[16:19], v[172:175], v[208:211], v[16:19]
	v_mfma_f32_16x16x32_bf16 v[8:11], v[176:179], v[204:207], v[8:11]
	v_mfma_f32_16x16x32_bf16 v[8:11], v[184:187], v[208:211], v[8:11]
	v_mfma_f32_16x16x32_bf16 v[4:7], v[168:171], v[212:215], v[4:7]
	v_mfma_f32_16x16x32_bf16 v[4:7], v[172:175], v[216:219], v[4:7]
	v_mfma_f32_16x16x32_bf16 v[0:3], v[176:179], v[212:215], v[0:3]
	v_mfma_f32_16x16x32_bf16 v[0:3], v[184:187], v[216:219], v[0:3]
	s_setprio 0
	s_barrier
.Lmid_gemm8:
	s_add_i32 s79, 0, 0x18000
	s_add_i32 s89, 0, 0x1c000
	v_add_u32_e32 v164, s79, v147
	v_add_u32_e32 v181, s89, v147
	s_add_u32 s54, s60, 0xb0000
	s_addc_u32 s55, s61, 0
	s_mov_b32 m0, s67
	v_lshl_add_u64 v[226:227], s[54:55], 0, v[128:129]
	global_load_lds_dwordx4 v[226:227], off
	v_lshl_add_u64 v[226:227], s[54:55], 0, v[132:133]
	s_mov_b32 m0, s68
	s_nop 0
	global_load_lds_dwordx4 v[226:227], off
	ds_read_b128 v[152:155], v164
	ds_read_b128 v[156:159], v164 offset:1024
	ds_read_b128 v[160:163], v164 offset:2048
	ds_read_b128 v[164:167], v164 offset:3072
	ds_read_b128 v[168:171], v181
	ds_read_b128 v[172:175], v181 offset:1024
	ds_read_b128 v[176:179], v181 offset:2048
	ds_read_b128 v[184:187], v181 offset:3072
	ds_read_b128 v[188:191], v151 offset:32768
	ds_read_b128 v[192:195], v151 offset:33792
	ds_read_b128 v[196:199], v151 offset:34816
	ds_read_b128 v[200:203], v151 offset:35840
	ds_read_b128 v[204:207], v151 offset:36864
	ds_read_b128 v[208:211], v151 offset:37888
	ds_read_b128 v[212:215], v151 offset:38912
	ds_read_b128 v[216:219], v151 offset:39936
	s_waitcnt vmcnt(8)
	s_waitcnt lgkmcnt(0)
	s_barrier
	s_setprio 1
	s_waitcnt lgkmcnt(0)
	v_mfma_f32_16x16x32_bf16 v[124:127], v[152:155], v[188:191], v[124:127]
	v_mfma_f32_16x16x32_bf16 v[124:127], v[156:159], v[192:195], v[124:127]
	v_mfma_f32_16x16x32_bf16 v[120:123], v[160:163], v[188:191], v[120:123]
	v_mfma_f32_16x16x32_bf16 v[120:123], v[164:167], v[192:195], v[120:123]
	v_mfma_f32_16x16x32_bf16 v[116:119], v[152:155], v[196:199], v[116:119]
	v_mfma_f32_16x16x32_bf16 v[116:119], v[156:159], v[200:203], v[116:119]
	v_mfma_f32_16x16x32_bf16 v[108:111], v[160:163], v[196:199], v[108:111]
	v_mfma_f32_16x16x32_bf16 v[108:111], v[164:167], v[200:203], v[108:111]
	v_mfma_f32_16x16x32_bf16 v[100:103], v[152:155], v[204:207], v[100:103]
	v_mfma_f32_16x16x32_bf16 v[100:103], v[156:159], v[208:211], v[100:103]
	v_mfma_f32_16x16x32_bf16 v[92:95], v[160:163], v[204:207], v[92:95]
	v_mfma_f32_16x16x32_bf16 v[92:95], v[164:167], v[208:211], v[92:95]
	v_mfma_f32_16x16x32_bf16 v[84:87], v[152:155], v[212:215], v[84:87]
	v_mfma_f32_16x16x32_bf16 v[84:87], v[156:159], v[216:219], v[84:87]
	v_mfma_f32_16x16x32_bf16 v[76:79], v[160:163], v[212:215], v[76:79]
	v_mfma_f32_16x16x32_bf16 v[76:79], v[164:167], v[216:219], v[76:79]
	v_mfma_f32_16x16x32_bf16 v[112:115], v[168:171], v[188:191], v[112:115]
	v_mfma_f32_16x16x32_bf16 v[112:115], v[172:175], v[192:195], v[112:115]
	v_mfma_f32_16x16x32_bf16 v[104:107], v[176:179], v[188:191], v[104:107]
	v_mfma_f32_16x16x32_bf16 v[104:107], v[184:187], v[192:195], v[104:107]
	v_mfma_f32_16x16x32_bf16 v[96:99], v[168:171], v[196:199], v[96:99]
	v_mfma_f32_16x16x32_bf16 v[96:99], v[172:175], v[200:203], v[96:99]
	v_mfma_f32_16x16x32_bf16 v[88:91], v[176:179], v[196:199], v[88:91]
	v_mfma_f32_16x16x32_bf16 v[88:91], v[184:187], v[200:203], v[88:91]
	v_mfma_f32_16x16x32_bf16 v[80:83], v[168:171], v[204:207], v[80:83]
	v_mfma_f32_16x16x32_bf16 v[80:83], v[172:175], v[208:211], v[80:83]
	v_mfma_f32_16x16x32_bf16 v[72:75], v[176:179], v[204:207], v[72:75]
	v_mfma_f32_16x16x32_bf16 v[72:75], v[184:187], v[208:211], v[72:75]
	v_mfma_f32_16x16x32_bf16 v[68:71], v[168:171], v[212:215], v[68:71]
	v_mfma_f32_16x16x32_bf16 v[68:71], v[172:175], v[216:219], v[68:71]
	v_mfma_f32_16x16x32_bf16 v[64:67], v[176:179], v[212:215], v[64:67]
	v_mfma_f32_16x16x32_bf16 v[64:67], v[184:187], v[216:219], v[64:67]
	s_setprio 0
	s_barrier
	s_add_i32 s54, s79, s64
	v_lshl_add_u64 v[144:145], v[144:145], 0, s[16:17]
	s_mov_b32 m0, s54
	s_nop 0
	global_load_lds_dwordx4 v[144:145], off
	s_add_i32 m0, s54, 0x2000
	s_add_u32 s54, s58, 0xb0080
	v_lshl_add_u64 v[144:145], v[220:221], 0, s[16:17]
	s_addc_u32 s55, s59, 0
	s_add_i32 s58, s89, s64
	global_load_lds_dwordx4 v[144:145], off
	v_lshl_add_u64 v[144:145], s[54:55], 0, v[130:131]
	s_mov_b32 m0, s58
	s_nop 0
	global_load_lds_dwordx4 v[144:145], off
	v_lshl_add_u64 v[144:145], s[54:55], 0, v[134:135]
	s_add_i32 m0, s58, 0x2000
	s_nop 0
	global_load_lds_dwordx4 v[144:145], off
	v_lshl_add_u64 v[144:145], v[222:223], 0, s[16:17]
	s_mov_b32 m0, s70
	s_nop 0
	global_load_lds_dwordx4 v[144:145], off
	v_lshl_add_u64 v[144:145], v[224:225], 0, s[16:17]
	s_mov_b32 m0, s71
	s_nop 0
	global_load_lds_dwordx4 v[144:145], off
	ds_read_b128 v[188:191], v151 offset:49152
	ds_read_b128 v[192:195], v151 offset:50176
	ds_read_b128 v[196:199], v151 offset:51200
	ds_read_b128 v[200:203], v151 offset:52224
	ds_read_b128 v[204:207], v151 offset:53248
	ds_read_b128 v[208:211], v151 offset:54272
	ds_read_b128 v[212:215], v151 offset:55296
	ds_read_b128 v[216:219], v151 offset:56320
	s_waitcnt vmcnt(8)
	s_waitcnt lgkmcnt(0)
	s_barrier
	s_setprio 1
	s_waitcnt lgkmcnt(0)
	v_mfma_f32_16x16x32_bf16 v[60:63], v[152:155], v[188:191], v[60:63]
	v_mfma_f32_16x16x32_bf16 v[60:63], v[156:159], v[192:195], v[60:63]
	v_mfma_f32_16x16x32_bf16 v[56:59], v[160:163], v[188:191], v[56:59]
	v_mfma_f32_16x16x32_bf16 v[56:59], v[164:167], v[192:195], v[56:59]
	v_mfma_f32_16x16x32_bf16 v[52:55], v[152:155], v[196:199], v[52:55]
	v_mfma_f32_16x16x32_bf16 v[52:55], v[156:159], v[200:203], v[52:55]
	v_mfma_f32_16x16x32_bf16 v[44:47], v[160:163], v[196:199], v[44:47]
	v_mfma_f32_16x16x32_bf16 v[44:47], v[164:167], v[200:203], v[44:47]
	v_mfma_f32_16x16x32_bf16 v[36:39], v[152:155], v[204:207], v[36:39]
	v_mfma_f32_16x16x32_bf16 v[36:39], v[156:159], v[208:211], v[36:39]
	v_mfma_f32_16x16x32_bf16 v[28:31], v[160:163], v[204:207], v[28:31]
	v_mfma_f32_16x16x32_bf16 v[28:31], v[164:167], v[208:211], v[28:31]
	v_mfma_f32_16x16x32_bf16 v[20:23], v[152:155], v[212:215], v[20:23]
	v_mfma_f32_16x16x32_bf16 v[20:23], v[156:159], v[216:219], v[20:23]
	v_mfma_f32_16x16x32_bf16 v[12:15], v[160:163], v[212:215], v[12:15]
	v_mfma_f32_16x16x32_bf16 v[12:15], v[164:167], v[216:219], v[12:15]
	v_mfma_f32_16x16x32_bf16 v[48:51], v[168:171], v[188:191], v[48:51]
	v_mfma_f32_16x16x32_bf16 v[48:51], v[172:175], v[192:195], v[48:51]
	v_mfma_f32_16x16x32_bf16 v[40:43], v[176:179], v[188:191], v[40:43]
	v_mfma_f32_16x16x32_bf16 v[40:43], v[184:187], v[192:195], v[40:43]
	v_mfma_f32_16x16x32_bf16 v[32:35], v[168:171], v[196:199], v[32:35]
	v_mfma_f32_16x16x32_bf16 v[32:35], v[172:175], v[200:203], v[32:35]
	v_mfma_f32_16x16x32_bf16 v[24:27], v[176:179], v[196:199], v[24:27]
	v_mfma_f32_16x16x32_bf16 v[24:27], v[184:187], v[200:203], v[24:27]
	v_mfma_f32_16x16x32_bf16 v[16:19], v[168:171], v[204:207], v[16:19]
	v_mfma_f32_16x16x32_bf16 v[16:19], v[172:175], v[208:211], v[16:19]
	v_mfma_f32_16x16x32_bf16 v[8:11], v[176:179], v[204:207], v[8:11]
	v_mfma_f32_16x16x32_bf16 v[8:11], v[184:187], v[208:211], v[8:11]
	v_mfma_f32_16x16x32_bf16 v[4:7], v[168:171], v[212:215], v[4:7]
	v_mfma_f32_16x16x32_bf16 v[4:7], v[172:175], v[216:219], v[4:7]
	v_mfma_f32_16x16x32_bf16 v[0:3], v[176:179], v[212:215], v[0:3]
	v_mfma_f32_16x16x32_bf16 v[0:3], v[184:187], v[216:219], v[0:3]
	s_setprio 0
	s_barrier
	s_add_i32 s88, s88, 2
	s_add_u32 s86, s86, 0x100
	s_addc_u32 s87, s87, 0
	s_cmp_gt_u32 s88, 41
	s_mov_b64 s[54:55], s[56:57]
	s_cbranch_scc0 .LBB0_1031
	s_and_b64 vcc, exec, s[18:19]
	s_cbranch_vccz .LBB0_1034
	s_barrier

.LBB0_1161:
	s_ashr_i32 s53, s52, 31
	s_lshl_b64 s[54:55], s[52:53], 19
	s_add_u32 s54, s80, s54
	s_addc_u32 s55, s81, s55
	s_and_b64 s[56:57], s[10:11], exec
	s_cselect_b32 s53, s55, s61
	s_cselect_b32 s83, s54, s60
	s_ashr_i32 s49, s48, 31
	s_lshl_b64 s[56:57], s[48:49], 19
	s_add_u32 s56, s66, s56
	s_addc_u32 s57, s67, s57
	s_and_b64 s[64:65], s[10:11], exec
	s_cselect_b32 s49, s57, s63
	s_cselect_b32 s84, s56, s62
	s_add_u32 s60, s60, 0x40080
	s_addc_u32 s61, s61, 0
	s_add_u32 s85, s62, 0x100
	s_addc_u32 s86, s63, 0
	s_mov_b32 s87, -2
	ds_read_b128 v[152:155], v148
	ds_read_b128 v[156:159], v148 offset:1024
	ds_read_b128 v[160:163], v148 offset:2048
	ds_read_b128 v[164:167], v148 offset:3072
	ds_read_b128 v[168:171], v149
	ds_read_b128 v[172:175], v149 offset:1024
	ds_read_b128 v[176:179], v149 offset:2048
	ds_read_b128 v[184:187], v149 offset:3072
	s_add_u32 s62, s60, 0xfffc0080
	s_addc_u32 s63, s61, -1
	s_cmp_eq_u32 s87, 12
	s_cselect_b32 s65, s53, s63
	s_cselect_b32 s64, s83, s62
	s_cselect_b32 s63, s49, s86
	s_cselect_b32 s62, s84, s85
	v_lshl_add_u64 v[220:221], s[60:61], 0, v[138:139]
	s_add_i32 m0, s69, 0xc000
	ds_read_b128 v[188:191], v150
	ds_read_b128 v[192:195], v150 offset:1024
	ds_read_b128 v[196:199], v150 offset:2048
	ds_read_b128 v[200:203], v150 offset:3072
	ds_read_b128 v[204:207], v150 offset:4096
	ds_read_b128 v[208:211], v150 offset:5120
	ds_read_b128 v[212:215], v150 offset:6144
	ds_read_b128 v[216:219], v150 offset:7168
	global_load_lds_dwordx4 v[220:221], off
	v_lshl_add_u64 v[220:221], s[60:61], 0, v[140:141]
	s_add_i32 m0, s69, 0xe000
	s_nop 0
	global_load_lds_dwordx4 v[220:221], off
	s_waitcnt vmcnt(8)
	s_waitcnt lgkmcnt(0)
	s_barrier
	s_setprio 1
	s_waitcnt lgkmcnt(0)
	v_mfma_f32_16x16x32_bf16 v[124:127], v[152:155], v[188:191], 0
	v_mfma_f32_16x16x32_bf16 v[124:127], v[156:159], v[192:195], v[124:127]
	v_mfma_f32_16x16x32_bf16 v[120:123], v[160:163], v[188:191], 0
	v_mfma_f32_16x16x32_bf16 v[120:123], v[164:167], v[192:195], v[120:123]
	v_mfma_f32_16x16x32_bf16 v[116:119], v[152:155], v[196:199], 0
	v_mfma_f32_16x16x32_bf16 v[116:119], v[156:159], v[200:203], v[116:119]
	v_mfma_f32_16x16x32_bf16 v[112:115], v[160:163], v[196:199], 0
	v_mfma_f32_16x16x32_bf16 v[112:115], v[164:167], v[200:203], v[112:115]
	v_mfma_f32_16x16x32_bf16 v[108:111], v[152:155], v[204:207], 0
	v_mfma_f32_16x16x32_bf16 v[108:111], v[156:159], v[208:211], v[108:111]
	v_mfma_f32_16x16x32_bf16 v[104:107], v[160:163], v[204:207], 0
	v_mfma_f32_16x16x32_bf16 v[104:107], v[164:167], v[208:211], v[104:107]
	v_mfma_f32_16x16x32_bf16 v[100:103], v[152:155], v[212:215], 0
	v_mfma_f32_16x16x32_bf16 v[100:103], v[156:159], v[216:219], v[100:103]
	v_mfma_f32_16x16x32_bf16 v[96:99], v[160:163], v[212:215], 0
	v_mfma_f32_16x16x32_bf16 v[96:99], v[164:167], v[216:219], v[96:99]
	v_mfma_f32_16x16x32_bf16 v[68:71], v[168:171], v[188:191], 0
	v_mfma_f32_16x16x32_bf16 v[68:71], v[172:175], v[192:195], v[68:71]
	v_mfma_f32_16x16x32_bf16 v[64:67], v[176:179], v[188:191], 0
	v_mfma_f32_16x16x32_bf16 v[64:67], v[184:187], v[192:195], v[64:67]
	v_mfma_f32_16x16x32_bf16 v[52:55], v[168:171], v[196:199], 0
	v_mfma_f32_16x16x32_bf16 v[52:55], v[172:175], v[200:203], v[52:55]
	v_mfma_f32_16x16x32_bf16 v[48:51], v[176:179], v[196:199], 0
	v_mfma_f32_16x16x32_bf16 v[48:51], v[184:187], v[200:203], v[48:51]
	v_mfma_f32_16x16x32_bf16 v[44:47], v[168:171], v[204:207], 0
	v_mfma_f32_16x16x32_bf16 v[44:47], v[172:175], v[208:211], v[44:47]
	v_mfma_f32_16x16x32_bf16 v[40:43], v[176:179], v[204:207], 0
	v_mfma_f32_16x16x32_bf16 v[40:43], v[184:187], v[208:211], v[40:43]
	v_mfma_f32_16x16x32_bf16 v[36:39], v[168:171], v[212:215], 0
	v_mfma_f32_16x16x32_bf16 v[36:39], v[172:175], v[216:219], v[36:39]
	v_mfma_f32_16x16x32_bf16 v[32:35], v[176:179], v[212:215], 0
	v_mfma_f32_16x16x32_bf16 v[32:35], v[184:187], v[216:219], v[32:35]
	s_setprio 0
	s_barrier
	s_add_i32 s79, s77, s68
	v_lshl_add_u64 v[220:221], s[62:63], 0, v[130:131]
	s_mov_b32 m0, s79
	s_nop 0
	global_load_lds_dwordx4 v[220:221], off
	s_add_i32 m0, s79, 0x2000
	s_add_u32 s88, s62, 0x40000
	v_lshl_add_u64 v[222:223], s[62:63], 0, v[134:135]
	s_addc_u32 s89, s63, 0
	s_add_i32 s79, s82, s68
	global_load_lds_dwordx4 v[222:223], off
	v_lshl_add_u64 v[224:225], s[88:89], 0, v[130:131]
	s_mov_b32 m0, s79
	v_lshl_add_u64 v[226:227], s[64:65], 0, v[132:133]
	global_load_lds_dwordx4 v[224:225], off
	v_lshl_add_u64 v[224:225], s[88:89], 0, v[134:135]
	s_add_i32 m0, s79, 0x2000
	s_nop 0
	global_load_lds_dwordx4 v[224:225], off
	v_lshl_add_u64 v[224:225], s[64:65], 0, v[128:129]
	s_mov_b32 m0, s69
	s_nop 0
	global_load_lds_dwordx4 v[224:225], off
	s_mov_b32 m0, s70
	s_nop 0
	global_load_lds_dwordx4 v[226:227], off
	ds_read_b128 v[188:191], v150 offset:16384
	ds_read_b128 v[192:195], v150 offset:17408
	ds_read_b128 v[196:199], v150 offset:18432
	ds_read_b128 v[200:203], v150 offset:19456
	ds_read_b128 v[204:207], v150 offset:20480
	ds_read_b128 v[208:211], v150 offset:21504
	ds_read_b128 v[212:215], v150 offset:22528
	ds_read_b128 v[216:219], v150 offset:23552
	s_waitcnt vmcnt(8)
	s_waitcnt lgkmcnt(0)
	s_barrier
	s_setprio 1
	s_waitcnt lgkmcnt(0)
	v_mfma_f32_16x16x32_bf16 v[92:95], v[152:155], v[188:191], 0
	v_mfma_f32_16x16x32_bf16 v[92:95], v[156:159], v[192:195], v[92:95]
	v_mfma_f32_16x16x32_bf16 v[88:91], v[160:163], v[188:191], 0
	v_mfma_f32_16x16x32_bf16 v[88:91], v[164:167], v[192:195], v[88:91]
	v_mfma_f32_16x16x32_bf16 v[84:87], v[152:155], v[196:199], 0
	v_mfma_f32_16x16x32_bf16 v[84:87], v[156:159], v[200:203], v[84:87]
	v_mfma_f32_16x16x32_bf16 v[80:83], v[160:163], v[196:199], 0
	v_mfma_f32_16x16x32_bf16 v[80:83], v[164:167], v[200:203], v[80:83]
	v_mfma_f32_16x16x32_bf16 v[76:79], v[152:155], v[204:207], 0
	v_mfma_f32_16x16x32_bf16 v[76:79], v[156:159], v[208:211], v[76:79]
	v_mfma_f32_16x16x32_bf16 v[72:75], v[160:163], v[204:207], 0
	v_mfma_f32_16x16x32_bf16 v[72:75], v[164:167], v[208:211], v[72:75]
	v_mfma_f32_16x16x32_bf16 v[60:63], v[152:155], v[212:215], 0
	v_mfma_f32_16x16x32_bf16 v[60:63], v[156:159], v[216:219], v[60:63]
	v_mfma_f32_16x16x32_bf16 v[56:59], v[160:163], v[212:215], 0
	v_mfma_f32_16x16x32_bf16 v[56:59], v[164:167], v[216:219], v[56:59]
	v_mfma_f32_16x16x32_bf16 v[28:31], v[168:171], v[188:191], 0
	v_mfma_f32_16x16x32_bf16 v[28:31], v[172:175], v[192:195], v[28:31]
	v_mfma_f32_16x16x32_bf16 v[24:27], v[176:179], v[188:191], 0
	v_mfma_f32_16x16x32_bf16 v[24:27], v[184:187], v[192:195], v[24:27]
	v_mfma_f32_16x16x32_bf16 v[20:23], v[168:171], v[196:199], 0
	v_mfma_f32_16x16x32_bf16 v[20:23], v[172:175], v[200:203], v[20:23]
	v_mfma_f32_16x16x32_bf16 v[16:19], v[176:179], v[196:199], 0
	v_mfma_f32_16x16x32_bf16 v[16:19], v[184:187], v[200:203], v[16:19]
	v_mfma_f32_16x16x32_bf16 v[12:15], v[168:171], v[204:207], 0
	v_mfma_f32_16x16x32_bf16 v[12:15], v[172:175], v[208:211], v[12:15]
	v_mfma_f32_16x16x32_bf16 v[8:11], v[176:179], v[204:207], 0
	v_mfma_f32_16x16x32_bf16 v[8:11], v[184:187], v[208:211], v[8:11]
	v_mfma_f32_16x16x32_bf16 v[4:7], v[168:171], v[212:215], 0
	v_mfma_f32_16x16x32_bf16 v[4:7], v[172:175], v[216:219], v[4:7]
	v_mfma_f32_16x16x32_bf16 v[0:3], v[176:179], v[212:215], 0
	v_mfma_f32_16x16x32_bf16 v[0:3], v[184:187], v[216:219], v[0:3]
	s_setprio 0
	s_barrier
	s_branch .Lmid_gemm9
.LBB0_1162:
	s_add_u32 s62, s60, 0xfffc0080
	s_addc_u32 s63, s61, -1
	s_cmp_eq_u32 s87, 12
	s_cselect_b32 s65, s53, s63
	s_cselect_b32 s64, s83, s62
	s_cselect_b32 s63, s49, s86
	s_cselect_b32 s62, s84, s85
	v_lshl_add_u64 v[220:221], s[60:61], 0, v[138:139]
	s_add_i32 m0, s69, 0xc000
	s_nop 0
	global_load_lds_dwordx4 v[220:221], off
	v_lshl_add_u64 v[220:221], s[60:61], 0, v[140:141]
	s_add_i32 m0, s69, 0xe000
	s_nop 0
	global_load_lds_dwordx4 v[220:221], off
	ds_read_b128 v[152:155], v148
	ds_read_b128 v[156:159], v148 offset:1024
	ds_read_b128 v[160:163], v148 offset:2048
	ds_read_b128 v[164:167], v148 offset:3072
	ds_read_b128 v[168:171], v149
	ds_read_b128 v[172:175], v149 offset:1024
	ds_read_b128 v[176:179], v149 offset:2048
	ds_read_b128 v[184:187], v149 offset:3072
	ds_read_b128 v[188:191], v150
	ds_read_b128 v[192:195], v150 offset:1024
	ds_read_b128 v[196:199], v150 offset:2048
	ds_read_b128 v[200:203], v150 offset:3072
	ds_read_b128 v[204:207], v150 offset:4096
	ds_read_b128 v[208:211], v150 offset:5120
	ds_read_b128 v[212:215], v150 offset:6144
	ds_read_b128 v[216:219], v150 offset:7168
	s_waitcnt vmcnt(8)
	s_waitcnt lgkmcnt(0)
	s_barrier
	s_setprio 1
	s_waitcnt lgkmcnt(0)
	v_mfma_f32_16x16x32_bf16 v[124:127], v[152:155], v[188:191], v[124:127]
	v_mfma_f32_16x16x32_bf16 v[124:127], v[156:159], v[192:195], v[124:127]
	v_mfma_f32_16x16x32_bf16 v[120:123], v[160:163], v[188:191], v[120:123]
	v_mfma_f32_16x16x32_bf16 v[120:123], v[164:167], v[192:195], v[120:123]
	v_mfma_f32_16x16x32_bf16 v[116:119], v[152:155], v[196:199], v[116:119]
	v_mfma_f32_16x16x32_bf16 v[116:119], v[156:159], v[200:203], v[116:119]
	v_mfma_f32_16x16x32_bf16 v[112:115], v[160:163], v[196:199], v[112:115]
	v_mfma_f32_16x16x32_bf16 v[112:115], v[164:167], v[200:203], v[112:115]
	v_mfma_f32_16x16x32_bf16 v[108:111], v[152:155], v[204:207], v[108:111]
	v_mfma_f32_16x16x32_bf16 v[108:111], v[156:159], v[208:211], v[108:111]
	v_mfma_f32_16x16x32_bf16 v[104:107], v[160:163], v[204:207], v[104:107]
	v_mfma_f32_16x16x32_bf16 v[104:107], v[164:167], v[208:211], v[104:107]
	v_mfma_f32_16x16x32_bf16 v[100:103], v[152:155], v[212:215], v[100:103]
	v_mfma_f32_16x16x32_bf16 v[100:103], v[156:159], v[216:219], v[100:103]
	v_mfma_f32_16x16x32_bf16 v[96:99], v[160:163], v[212:215], v[96:99]
	v_mfma_f32_16x16x32_bf16 v[96:99], v[164:167], v[216:219], v[96:99]
	v_mfma_f32_16x16x32_bf16 v[68:71], v[168:171], v[188:191], v[68:71]
	v_mfma_f32_16x16x32_bf16 v[68:71], v[172:175], v[192:195], v[68:71]
	v_mfma_f32_16x16x32_bf16 v[64:67], v[176:179], v[188:191], v[64:67]
	v_mfma_f32_16x16x32_bf16 v[64:67], v[184:187], v[192:195], v[64:67]
	v_mfma_f32_16x16x32_bf16 v[52:55], v[168:171], v[196:199], v[52:55]
	v_mfma_f32_16x16x32_bf16 v[52:55], v[172:175], v[200:203], v[52:55]
	v_mfma_f32_16x16x32_bf16 v[48:51], v[176:179], v[196:199], v[48:51]
	v_mfma_f32_16x16x32_bf16 v[48:51], v[184:187], v[200:203], v[48:51]
	v_mfma_f32_16x16x32_bf16 v[44:47], v[168:171], v[204:207], v[44:47]
	v_mfma_f32_16x16x32_bf16 v[44:47], v[172:175], v[208:211], v[44:47]
	v_mfma_f32_16x16x32_bf16 v[40:43], v[176:179], v[204:207], v[40:43]
	v_mfma_f32_16x16x32_bf16 v[40:43], v[184:187], v[208:211], v[40:43]
	v_mfma_f32_16x16x32_bf16 v[36:39], v[168:171], v[212:215], v[36:39]
	v_mfma_f32_16x16x32_bf16 v[36:39], v[172:175], v[216:219], v[36:39]
	v_mfma_f32_16x16x32_bf16 v[32:35], v[176:179], v[212:215], v[32:35]
	v_mfma_f32_16x16x32_bf16 v[32:35], v[184:187], v[216:219], v[32:35]
	s_setprio 0
	s_barrier
	s_add_i32 s79, s77, s68
	v_lshl_add_u64 v[220:221], s[62:63], 0, v[130:131]
	s_mov_b32 m0, s79
	s_nop 0
	global_load_lds_dwordx4 v[220:221], off
	s_add_i32 m0, s79, 0x2000
	s_add_u32 s88, s62, 0x40000
	v_lshl_add_u64 v[222:223], s[62:63], 0, v[134:135]
	s_addc_u32 s89, s63, 0
	s_add_i32 s79, s82, s68
	global_load_lds_dwordx4 v[222:223], off
	v_lshl_add_u64 v[224:225], s[88:89], 0, v[130:131]
	s_mov_b32 m0, s79
	v_lshl_add_u64 v[226:227], s[64:65], 0, v[132:133]
	global_load_lds_dwordx4 v[224:225], off
	v_lshl_add_u64 v[224:225], s[88:89], 0, v[134:135]
	s_add_i32 m0, s79, 0x2000
	s_nop 0
	global_load_lds_dwordx4 v[224:225], off
	v_lshl_add_u64 v[224:225], s[64:65], 0, v[128:129]
	s_mov_b32 m0, s69
	s_nop 0
	global_load_lds_dwordx4 v[224:225], off
	s_mov_b32 m0, s70
	s_nop 0
	global_load_lds_dwordx4 v[226:227], off
	ds_read_b128 v[188:191], v150 offset:16384
	ds_read_b128 v[192:195], v150 offset:17408
	ds_read_b128 v[196:199], v150 offset:18432
	ds_read_b128 v[200:203], v150 offset:19456
	ds_read_b128 v[204:207], v150 offset:20480
	ds_read_b128 v[208:211], v150 offset:21504
	ds_read_b128 v[212:215], v150 offset:22528
	ds_read_b128 v[216:219], v150 offset:23552
	s_waitcnt vmcnt(8)
	s_waitcnt lgkmcnt(0)
	s_barrier
	s_setprio 1
	s_waitcnt lgkmcnt(0)
	v_mfma_f32_16x16x32_bf16 v[92:95], v[152:155], v[188:191], v[92:95]
	v_mfma_f32_16x16x32_bf16 v[92:95], v[156:159], v[192:195], v[92:95]
	v_mfma_f32_16x16x32_bf16 v[88:91], v[160:163], v[188:191], v[88:91]
	v_mfma_f32_16x16x32_bf16 v[88:91], v[164:167], v[192:195], v[88:91]
	v_mfma_f32_16x16x32_bf16 v[84:87], v[152:155], v[196:199], v[84:87]
	v_mfma_f32_16x16x32_bf16 v[84:87], v[156:159], v[200:203], v[84:87]
	v_mfma_f32_16x16x32_bf16 v[80:83], v[160:163], v[196:199], v[80:83]
	v_mfma_f32_16x16x32_bf16 v[80:83], v[164:167], v[200:203], v[80:83]
	v_mfma_f32_16x16x32_bf16 v[76:79], v[152:155], v[204:207], v[76:79]
	v_mfma_f32_16x16x32_bf16 v[76:79], v[156:159], v[208:211], v[76:79]
	v_mfma_f32_16x16x32_bf16 v[72:75], v[160:163], v[204:207], v[72:75]
	v_mfma_f32_16x16x32_bf16 v[72:75], v[164:167], v[208:211], v[72:75]
	v_mfma_f32_16x16x32_bf16 v[60:63], v[152:155], v[212:215], v[60:63]
	v_mfma_f32_16x16x32_bf16 v[60:63], v[156:159], v[216:219], v[60:63]
	v_mfma_f32_16x16x32_bf16 v[56:59], v[160:163], v[212:215], v[56:59]
	v_mfma_f32_16x16x32_bf16 v[56:59], v[164:167], v[216:219], v[56:59]
	v_mfma_f32_16x16x32_bf16 v[28:31], v[168:171], v[188:191], v[28:31]
	v_mfma_f32_16x16x32_bf16 v[28:31], v[172:175], v[192:195], v[28:31]
	v_mfma_f32_16x16x32_bf16 v[24:27], v[176:179], v[188:191], v[24:27]
	v_mfma_f32_16x16x32_bf16 v[24:27], v[184:187], v[192:195], v[24:27]
	v_mfma_f32_16x16x32_bf16 v[20:23], v[168:171], v[196:199], v[20:23]
	v_mfma_f32_16x16x32_bf16 v[20:23], v[172:175], v[200:203], v[20:23]
	v_mfma_f32_16x16x32_bf16 v[16:19], v[176:179], v[196:199], v[16:19]
	v_mfma_f32_16x16x32_bf16 v[16:19], v[184:187], v[200:203], v[16:19]
	v_mfma_f32_16x16x32_bf16 v[12:15], v[168:171], v[204:207], v[12:15]
	v_mfma_f32_16x16x32_bf16 v[12:15], v[172:175], v[208:211], v[12:15]
	v_mfma_f32_16x16x32_bf16 v[8:11], v[176:179], v[204:207], v[8:11]
	v_mfma_f32_16x16x32_bf16 v[8:11], v[184:187], v[208:211], v[8:11]
	v_mfma_f32_16x16x32_bf16 v[4:7], v[168:171], v[212:215], v[4:7]
	v_mfma_f32_16x16x32_bf16 v[4:7], v[172:175], v[216:219], v[4:7]
	v_mfma_f32_16x16x32_bf16 v[0:3], v[176:179], v[212:215], v[0:3]
	v_mfma_f32_16x16x32_bf16 v[0:3], v[184:187], v[216:219], v[0:3]
	s_setprio 0
	s_barrier
.Lmid_gemm9:
	s_add_i32 s79, 0, 0x18000
	s_add_i32 s88, 0, 0x1c000
	v_add_u32_e32 v164, s79, v147
	v_add_u32_e32 v181, s88, v147
	s_add_u32 s64, s64, 0x40000
	s_addc_u32 s65, s65, 0
	s_mov_b32 m0, s71
	v_lshl_add_u64 v[228:229], s[64:65], 0, v[128:129]
	global_load_lds_dwordx4 v[228:229], off
	v_lshl_add_u64 v[228:229], s[64:65], 0, v[132:133]
	s_mov_b32 m0, s72
	s_nop 0
	global_load_lds_dwordx4 v[228:229], off
	ds_read_b128 v[152:155], v164
	ds_read_b128 v[156:159], v164 offset:1024
	ds_read_b128 v[160:163], v164 offset:2048
	ds_read_b128 v[164:167], v164 offset:3072
	ds_read_b128 v[168:171], v181
	ds_read_b128 v[172:175], v181 offset:1024
	ds_read_b128 v[176:179], v181 offset:2048
	ds_read_b128 v[184:187], v181 offset:3072
	ds_read_b128 v[188:191], v150 offset:32768
	ds_read_b128 v[192:195], v150 offset:33792
	ds_read_b128 v[196:199], v150 offset:34816
	ds_read_b128 v[200:203], v150 offset:35840
	ds_read_b128 v[204:207], v150 offset:36864
	ds_read_b128 v[208:211], v150 offset:37888
	ds_read_b128 v[212:215], v150 offset:38912
	ds_read_b128 v[216:219], v150 offset:39936
	s_waitcnt vmcnt(8)
	s_waitcnt lgkmcnt(0)
	s_barrier
	s_setprio 1
	s_waitcnt lgkmcnt(0)
	v_mfma_f32_16x16x32_bf16 v[124:127], v[152:155], v[188:191], v[124:127]
	v_mfma_f32_16x16x32_bf16 v[124:127], v[156:159], v[192:195], v[124:127]
	v_mfma_f32_16x16x32_bf16 v[120:123], v[160:163], v[188:191], v[120:123]
	v_mfma_f32_16x16x32_bf16 v[120:123], v[164:167], v[192:195], v[120:123]
	v_mfma_f32_16x16x32_bf16 v[116:119], v[152:155], v[196:199], v[116:119]
	v_mfma_f32_16x16x32_bf16 v[116:119], v[156:159], v[200:203], v[116:119]
	v_mfma_f32_16x16x32_bf16 v[112:115], v[160:163], v[196:199], v[112:115]
	v_mfma_f32_16x16x32_bf16 v[112:115], v[164:167], v[200:203], v[112:115]
	v_mfma_f32_16x16x32_bf16 v[108:111], v[152:155], v[204:207], v[108:111]
	v_mfma_f32_16x16x32_bf16 v[108:111], v[156:159], v[208:211], v[108:111]
	v_mfma_f32_16x16x32_bf16 v[104:107], v[160:163], v[204:207], v[104:107]
	v_mfma_f32_16x16x32_bf16 v[104:107], v[164:167], v[208:211], v[104:107]
	v_mfma_f32_16x16x32_bf16 v[100:103], v[152:155], v[212:215], v[100:103]
	v_mfma_f32_16x16x32_bf16 v[100:103], v[156:159], v[216:219], v[100:103]
	v_mfma_f32_16x16x32_bf16 v[96:99], v[160:163], v[212:215], v[96:99]
	v_mfma_f32_16x16x32_bf16 v[96:99], v[164:167], v[216:219], v[96:99]
	v_mfma_f32_16x16x32_bf16 v[68:71], v[168:171], v[188:191], v[68:71]
	v_mfma_f32_16x16x32_bf16 v[68:71], v[172:175], v[192:195], v[68:71]
	v_mfma_f32_16x16x32_bf16 v[64:67], v[176:179], v[188:191], v[64:67]
	v_mfma_f32_16x16x32_bf16 v[64:67], v[184:187], v[192:195], v[64:67]
	v_mfma_f32_16x16x32_bf16 v[52:55], v[168:171], v[196:199], v[52:55]
	v_mfma_f32_16x16x32_bf16 v[52:55], v[172:175], v[200:203], v[52:55]
	v_mfma_f32_16x16x32_bf16 v[48:51], v[176:179], v[196:199], v[48:51]
	v_mfma_f32_16x16x32_bf16 v[48:51], v[184:187], v[200:203], v[48:51]
	v_mfma_f32_16x16x32_bf16 v[44:47], v[168:171], v[204:207], v[44:47]
	v_mfma_f32_16x16x32_bf16 v[44:47], v[172:175], v[208:211], v[44:47]
	v_mfma_f32_16x16x32_bf16 v[40:43], v[176:179], v[204:207], v[40:43]
	v_mfma_f32_16x16x32_bf16 v[40:43], v[184:187], v[208:211], v[40:43]
	v_mfma_f32_16x16x32_bf16 v[36:39], v[168:171], v[212:215], v[36:39]
	v_mfma_f32_16x16x32_bf16 v[36:39], v[172:175], v[216:219], v[36:39]
	v_mfma_f32_16x16x32_bf16 v[32:35], v[176:179], v[212:215], v[32:35]
	v_mfma_f32_16x16x32_bf16 v[32:35], v[184:187], v[216:219], v[32:35]
	s_setprio 0
	s_barrier
	s_add_i32 s64, s79, s68
	v_lshl_add_u64 v[220:221], v[220:221], 0, s[12:13]
	s_mov_b32 m0, s64
	s_nop 0
	global_load_lds_dwordx4 v[220:221], off
	s_add_i32 m0, s64, 0x2000
	s_add_u32 s62, s62, 0x40080
	v_lshl_add_u64 v[220:221], v[222:223], 0, s[12:13]
	s_addc_u32 s63, s63, 0
	s_add_i32 s64, s88, s68
	global_load_lds_dwordx4 v[220:221], off
	v_lshl_add_u64 v[220:221], s[62:63], 0, v[130:131]
	s_mov_b32 m0, s64
	s_nop 0
	global_load_lds_dwordx4 v[220:221], off
	v_lshl_add_u64 v[220:221], s[62:63], 0, v[134:135]
	s_add_i32 m0, s64, 0x2000
	s_nop 0
	global_load_lds_dwordx4 v[220:221], off
	v_lshl_add_u64 v[220:221], v[224:225], 0, s[12:13]
	s_mov_b32 m0, s75
	s_nop 0
	global_load_lds_dwordx4 v[220:221], off
	v_lshl_add_u64 v[220:221], v[226:227], 0, s[12:13]
	s_mov_b32 m0, s76
	s_nop 0
	global_load_lds_dwordx4 v[220:221], off
	ds_read_b128 v[188:191], v150 offset:49152
	ds_read_b128 v[192:195], v150 offset:50176
	ds_read_b128 v[196:199], v150 offset:51200
	ds_read_b128 v[200:203], v150 offset:52224
	ds_read_b128 v[204:207], v150 offset:53248
	ds_read_b128 v[208:211], v150 offset:54272
	ds_read_b128 v[212:215], v150 offset:55296
	ds_read_b128 v[216:219], v150 offset:56320
	s_waitcnt vmcnt(8)
	s_waitcnt lgkmcnt(0)
	s_barrier
	s_setprio 1
	s_waitcnt lgkmcnt(0)
	v_mfma_f32_16x16x32_bf16 v[92:95], v[152:155], v[188:191], v[92:95]
	v_mfma_f32_16x16x32_bf16 v[92:95], v[156:159], v[192:195], v[92:95]
	v_mfma_f32_16x16x32_bf16 v[88:91], v[160:163], v[188:191], v[88:91]
	v_mfma_f32_16x16x32_bf16 v[88:91], v[164:167], v[192:195], v[88:91]
	v_mfma_f32_16x16x32_bf16 v[84:87], v[152:155], v[196:199], v[84:87]
	v_mfma_f32_16x16x32_bf16 v[84:87], v[156:159], v[200:203], v[84:87]
	v_mfma_f32_16x16x32_bf16 v[80:83], v[160:163], v[196:199], v[80:83]
	v_mfma_f32_16x16x32_bf16 v[80:83], v[164:167], v[200:203], v[80:83]
	v_mfma_f32_16x16x32_bf16 v[76:79], v[152:155], v[204:207], v[76:79]
	v_mfma_f32_16x16x32_bf16 v[76:79], v[156:159], v[208:211], v[76:79]
	v_mfma_f32_16x16x32_bf16 v[72:75], v[160:163], v[204:207], v[72:75]
	v_mfma_f32_16x16x32_bf16 v[72:75], v[164:167], v[208:211], v[72:75]
	v_mfma_f32_16x16x32_bf16 v[60:63], v[152:155], v[212:215], v[60:63]
	v_mfma_f32_16x16x32_bf16 v[60:63], v[156:159], v[216:219], v[60:63]
	v_mfma_f32_16x16x32_bf16 v[56:59], v[160:163], v[212:215], v[56:59]
	v_mfma_f32_16x16x32_bf16 v[56:59], v[164:167], v[216:219], v[56:59]
	v_mfma_f32_16x16x32_bf16 v[28:31], v[168:171], v[188:191], v[28:31]
	v_mfma_f32_16x16x32_bf16 v[28:31], v[172:175], v[192:195], v[28:31]
	v_mfma_f32_16x16x32_bf16 v[24:27], v[176:179], v[188:191], v[24:27]
	v_mfma_f32_16x16x32_bf16 v[24:27], v[184:187], v[192:195], v[24:27]
	v_mfma_f32_16x16x32_bf16 v[20:23], v[168:171], v[196:199], v[20:23]
	v_mfma_f32_16x16x32_bf16 v[20:23], v[172:175], v[200:203], v[20:23]
	v_mfma_f32_16x16x32_bf16 v[16:19], v[176:179], v[196:199], v[16:19]
	v_mfma_f32_16x16x32_bf16 v[16:19], v[184:187], v[200:203], v[16:19]
	v_mfma_f32_16x16x32_bf16 v[12:15], v[168:171], v[204:207], v[12:15]
	v_mfma_f32_16x16x32_bf16 v[12:15], v[172:175], v[208:211], v[12:15]
	v_mfma_f32_16x16x32_bf16 v[8:11], v[176:179], v[204:207], v[8:11]
	v_mfma_f32_16x16x32_bf16 v[8:11], v[184:187], v[208:211], v[8:11]
	v_mfma_f32_16x16x32_bf16 v[4:7], v[168:171], v[212:215], v[4:7]
	v_mfma_f32_16x16x32_bf16 v[4:7], v[172:175], v[216:219], v[4:7]
	v_mfma_f32_16x16x32_bf16 v[0:3], v[176:179], v[212:215], v[0:3]
	v_mfma_f32_16x16x32_bf16 v[0:3], v[184:187], v[216:219], v[0:3]
	s_setprio 0
	s_barrier
	s_add_i32 s87, s87, 2
	s_add_u32 s60, s60, 0x100
	s_addc_u32 s61, s61, 0
	s_add_u32 s85, s85, 0x100
	s_addc_u32 s86, s86, 0
	s_cmp_gt_u32 s87, 13
	s_cbranch_scc0 .LBB0_1162
	s_and_b64 vcc, exec, s[16:17]
	s_cbranch_vccz .LBB0_1165
	s_barrier

.LBB0_1310:
	s_ashr_i32 s49, s48, 31
	s_lshl_b64 s[50:51], s[48:49], 19
	s_add_u32 s50, s38, s50
	s_addc_u32 s51, s39, s51
	s_and_b64 s[52:53], s[10:11], exec
	s_cselect_b32 s49, s51, s57
	s_cselect_b32 s82, s50, s56
	s_ashr_i32 s47, s46, 31
	s_lshl_b64 s[52:53], s[46:47], 19
	s_add_u32 s52, s62, s52
	s_addc_u32 s53, s63, s53
	s_and_b64 s[60:61], s[10:11], exec
	s_cselect_b32 s47, s53, s59
	s_cselect_b32 s83, s52, s58
	s_add_u32 s56, s56, 0x40080
	s_addc_u32 s57, s57, 0
	s_add_u32 s84, s58, 0x100
	s_addc_u32 s85, s59, 0
	s_mov_b32 s86, -2
	ds_read_b128 v[152:155], v149
	ds_read_b128 v[156:159], v149 offset:1024
	ds_read_b128 v[160:163], v149 offset:2048
	ds_read_b128 v[164:167], v149 offset:3072
	ds_read_b128 v[168:171], v150
	ds_read_b128 v[172:175], v150 offset:1024
	ds_read_b128 v[176:179], v150 offset:2048
	ds_read_b128 v[184:187], v150 offset:3072
	s_add_u32 s58, s56, 0xfffc0080
	s_addc_u32 s59, s57, -1
	s_cmp_eq_u32 s86, 12
	s_cselect_b32 s61, s49, s59
	s_cselect_b32 s60, s82, s58
	s_cselect_b32 s59, s47, s85
	s_cselect_b32 s58, s83, s84
	v_lshl_add_u64 v[144:145], s[56:57], 0, v[136:137]
	s_add_i32 m0, s55, 0xc000
	ds_read_b128 v[188:191], v151
	ds_read_b128 v[192:195], v151 offset:1024
	ds_read_b128 v[196:199], v151 offset:2048
	ds_read_b128 v[200:203], v151 offset:3072
	ds_read_b128 v[204:207], v151 offset:4096
	ds_read_b128 v[208:211], v151 offset:5120
	ds_read_b128 v[212:215], v151 offset:6144
	ds_read_b128 v[216:219], v151 offset:7168
	global_load_lds_dwordx4 v[144:145], off
	v_lshl_add_u64 v[144:145], s[56:57], 0, v[138:139]
	s_add_i32 m0, s55, 0xe000
	s_nop 0
	global_load_lds_dwordx4 v[144:145], off
	s_waitcnt vmcnt(8)
	s_waitcnt lgkmcnt(0)
	s_barrier
	s_setprio 1
	s_waitcnt lgkmcnt(0)
	v_mfma_f32_16x16x32_bf16 v[124:127], v[152:155], v[188:191], 0
	v_mfma_f32_16x16x32_bf16 v[124:127], v[156:159], v[192:195], v[124:127]
	v_mfma_f32_16x16x32_bf16 v[120:123], v[160:163], v[188:191], 0
	v_mfma_f32_16x16x32_bf16 v[120:123], v[164:167], v[192:195], v[120:123]
	v_mfma_f32_16x16x32_bf16 v[116:119], v[152:155], v[196:199], 0
	v_mfma_f32_16x16x32_bf16 v[116:119], v[156:159], v[200:203], v[116:119]
	v_mfma_f32_16x16x32_bf16 v[108:111], v[160:163], v[196:199], 0
	v_mfma_f32_16x16x32_bf16 v[108:111], v[164:167], v[200:203], v[108:111]
	v_mfma_f32_16x16x32_bf16 v[100:103], v[152:155], v[204:207], 0
	v_mfma_f32_16x16x32_bf16 v[100:103], v[156:159], v[208:211], v[100:103]
	v_mfma_f32_16x16x32_bf16 v[92:95], v[160:163], v[204:207], 0
	v_mfma_f32_16x16x32_bf16 v[92:95], v[164:167], v[208:211], v[92:95]
	v_mfma_f32_16x16x32_bf16 v[84:87], v[152:155], v[212:215], 0
	v_mfma_f32_16x16x32_bf16 v[84:87], v[156:159], v[216:219], v[84:87]
	v_mfma_f32_16x16x32_bf16 v[76:79], v[160:163], v[212:215], 0
	v_mfma_f32_16x16x32_bf16 v[76:79], v[164:167], v[216:219], v[76:79]
	v_mfma_f32_16x16x32_bf16 v[112:115], v[168:171], v[188:191], 0
	v_mfma_f32_16x16x32_bf16 v[112:115], v[172:175], v[192:195], v[112:115]
	v_mfma_f32_16x16x32_bf16 v[104:107], v[176:179], v[188:191], 0
	v_mfma_f32_16x16x32_bf16 v[104:107], v[184:187], v[192:195], v[104:107]
	v_mfma_f32_16x16x32_bf16 v[96:99], v[168:171], v[196:199], 0
	v_mfma_f32_16x16x32_bf16 v[96:99], v[172:175], v[200:203], v[96:99]
	v_mfma_f32_16x16x32_bf16 v[88:91], v[176:179], v[196:199], 0
	v_mfma_f32_16x16x32_bf16 v[88:91], v[184:187], v[200:203], v[88:91]
	v_mfma_f32_16x16x32_bf16 v[80:83], v[168:171], v[204:207], 0
	v_mfma_f32_16x16x32_bf16 v[80:83], v[172:175], v[208:211], v[80:83]
	v_mfma_f32_16x16x32_bf16 v[72:75], v[176:179], v[204:207], 0
	v_mfma_f32_16x16x32_bf16 v[72:75], v[184:187], v[208:211], v[72:75]
	v_mfma_f32_16x16x32_bf16 v[68:71], v[168:171], v[212:215], 0
	v_mfma_f32_16x16x32_bf16 v[68:71], v[172:175], v[216:219], v[68:71]
	v_mfma_f32_16x16x32_bf16 v[64:67], v[176:179], v[212:215], 0
	v_mfma_f32_16x16x32_bf16 v[64:67], v[184:187], v[216:219], v[64:67]
	s_setprio 0
	s_barrier
	s_add_i32 s79, s71, s64
	v_lshl_add_u64 v[144:145], s[58:59], 0, v[130:131]
	s_mov_b32 m0, s79
	s_nop 0
	global_load_lds_dwordx4 v[144:145], off
	s_add_i32 m0, s79, 0x2000
	s_add_u32 s88, s58, 0x40000
	v_lshl_add_u64 v[220:221], s[58:59], 0, v[134:135]
	s_addc_u32 s89, s59, 0
	s_add_i32 s79, s72, s64
	global_load_lds_dwordx4 v[220:221], off
	v_lshl_add_u64 v[222:223], s[88:89], 0, v[130:131]
	s_mov_b32 m0, s79
	v_lshl_add_u64 v[224:225], s[60:61], 0, v[132:133]
	global_load_lds_dwordx4 v[222:223], off
	v_lshl_add_u64 v[222:223], s[88:89], 0, v[134:135]
	s_add_i32 m0, s79, 0x2000
	s_nop 0
	global_load_lds_dwordx4 v[222:223], off
	v_lshl_add_u64 v[222:223], s[60:61], 0, v[128:129]
	s_mov_b32 m0, s55
	s_nop 0
	global_load_lds_dwordx4 v[222:223], off
	s_mov_b32 m0, s65
	s_nop 0
	global_load_lds_dwordx4 v[224:225], off
	ds_read_b128 v[188:191], v151 offset:16384
	ds_read_b128 v[192:195], v151 offset:17408
	ds_read_b128 v[196:199], v151 offset:18432
	ds_read_b128 v[200:203], v151 offset:19456
	ds_read_b128 v[204:207], v151 offset:20480
	ds_read_b128 v[208:211], v151 offset:21504
	ds_read_b128 v[212:215], v151 offset:22528
	ds_read_b128 v[216:219], v151 offset:23552
	s_waitcnt vmcnt(8)
	s_waitcnt lgkmcnt(0)
	s_barrier
	s_setprio 1
	s_waitcnt lgkmcnt(0)
	v_mfma_f32_16x16x32_bf16 v[60:63], v[152:155], v[188:191], 0
	v_mfma_f32_16x16x32_bf16 v[60:63], v[156:159], v[192:195], v[60:63]
	v_mfma_f32_16x16x32_bf16 v[56:59], v[160:163], v[188:191], 0
	v_mfma_f32_16x16x32_bf16 v[56:59], v[164:167], v[192:195], v[56:59]
	v_mfma_f32_16x16x32_bf16 v[52:55], v[152:155], v[196:199], 0
	v_mfma_f32_16x16x32_bf16 v[52:55], v[156:159], v[200:203], v[52:55]
	v_mfma_f32_16x16x32_bf16 v[44:47], v[160:163], v[196:199], 0
	v_mfma_f32_16x16x32_bf16 v[44:47], v[164:167], v[200:203], v[44:47]
	v_mfma_f32_16x16x32_bf16 v[36:39], v[152:155], v[204:207], 0
	v_mfma_f32_16x16x32_bf16 v[36:39], v[156:159], v[208:211], v[36:39]
	v_mfma_f32_16x16x32_bf16 v[28:31], v[160:163], v[204:207], 0
	v_mfma_f32_16x16x32_bf16 v[28:31], v[164:167], v[208:211], v[28:31]
	v_mfma_f32_16x16x32_bf16 v[20:23], v[152:155], v[212:215], 0
	v_mfma_f32_16x16x32_bf16 v[20:23], v[156:159], v[216:219], v[20:23]
	v_mfma_f32_16x16x32_bf16 v[12:15], v[160:163], v[212:215], 0
	v_mfma_f32_16x16x32_bf16 v[12:15], v[164:167], v[216:219], v[12:15]
	v_mfma_f32_16x16x32_bf16 v[48:51], v[168:171], v[188:191], 0
	v_mfma_f32_16x16x32_bf16 v[48:51], v[172:175], v[192:195], v[48:51]
	v_mfma_f32_16x16x32_bf16 v[40:43], v[176:179], v[188:191], 0
	v_mfma_f32_16x16x32_bf16 v[40:43], v[184:187], v[192:195], v[40:43]
	v_mfma_f32_16x16x32_bf16 v[32:35], v[168:171], v[196:199], 0
	v_mfma_f32_16x16x32_bf16 v[32:35], v[172:175], v[200:203], v[32:35]
	v_mfma_f32_16x16x32_bf16 v[24:27], v[176:179], v[196:199], 0
	v_mfma_f32_16x16x32_bf16 v[24:27], v[184:187], v[200:203], v[24:27]
	v_mfma_f32_16x16x32_bf16 v[16:19], v[168:171], v[204:207], 0
	v_mfma_f32_16x16x32_bf16 v[16:19], v[172:175], v[208:211], v[16:19]
	v_mfma_f32_16x16x32_bf16 v[8:11], v[176:179], v[204:207], 0
	v_mfma_f32_16x16x32_bf16 v[8:11], v[184:187], v[208:211], v[8:11]
	v_mfma_f32_16x16x32_bf16 v[4:7], v[168:171], v[212:215], 0
	v_mfma_f32_16x16x32_bf16 v[4:7], v[172:175], v[216:219], v[4:7]
	v_mfma_f32_16x16x32_bf16 v[0:3], v[176:179], v[212:215], 0
	v_mfma_f32_16x16x32_bf16 v[0:3], v[184:187], v[216:219], v[0:3]
	s_setprio 0
	s_barrier
	s_branch .Lmid_gemm10
.LBB0_1311:
	s_add_u32 s58, s56, 0xfffc0080
	s_addc_u32 s59, s57, -1
	s_cmp_eq_u32 s86, 12
	s_cselect_b32 s61, s49, s59
	s_cselect_b32 s60, s82, s58
	s_cselect_b32 s59, s47, s85
	s_cselect_b32 s58, s83, s84
	v_lshl_add_u64 v[144:145], s[56:57], 0, v[136:137]
	s_add_i32 m0, s55, 0xc000
	s_nop 0
	global_load_lds_dwordx4 v[144:145], off
	v_lshl_add_u64 v[144:145], s[56:57], 0, v[138:139]
	s_add_i32 m0, s55, 0xe000
	s_nop 0
	global_load_lds_dwordx4 v[144:145], off
	ds_read_b128 v[152:155], v149
	ds_read_b128 v[156:159], v149 offset:1024
	ds_read_b128 v[160:163], v149 offset:2048
	ds_read_b128 v[164:167], v149 offset:3072
	ds_read_b128 v[168:171], v150
	ds_read_b128 v[172:175], v150 offset:1024
	ds_read_b128 v[176:179], v150 offset:2048
	ds_read_b128 v[184:187], v150 offset:3072
	ds_read_b128 v[188:191], v151
	ds_read_b128 v[192:195], v151 offset:1024
	ds_read_b128 v[196:199], v151 offset:2048
	ds_read_b128 v[200:203], v151 offset:3072
	ds_read_b128 v[204:207], v151 offset:4096
	ds_read_b128 v[208:211], v151 offset:5120
	ds_read_b128 v[212:215], v151 offset:6144
	ds_read_b128 v[216:219], v151 offset:7168
	s_waitcnt vmcnt(8)
	s_waitcnt lgkmcnt(0)
	s_barrier
	s_setprio 1
	s_waitcnt lgkmcnt(0)
	v_mfma_f32_16x16x32_bf16 v[124:127], v[152:155], v[188:191], v[124:127]
	v_mfma_f32_16x16x32_bf16 v[124:127], v[156:159], v[192:195], v[124:127]
	v_mfma_f32_16x16x32_bf16 v[120:123], v[160:163], v[188:191], v[120:123]
	v_mfma_f32_16x16x32_bf16 v[120:123], v[164:167], v[192:195], v[120:123]
	v_mfma_f32_16x16x32_bf16 v[116:119], v[152:155], v[196:199], v[116:119]
	v_mfma_f32_16x16x32_bf16 v[116:119], v[156:159], v[200:203], v[116:119]
	v_mfma_f32_16x16x32_bf16 v[108:111], v[160:163], v[196:199], v[108:111]
	v_mfma_f32_16x16x32_bf16 v[108:111], v[164:167], v[200:203], v[108:111]
	v_mfma_f32_16x16x32_bf16 v[100:103], v[152:155], v[204:207], v[100:103]
	v_mfma_f32_16x16x32_bf16 v[100:103], v[156:159], v[208:211], v[100:103]
	v_mfma_f32_16x16x32_bf16 v[92:95], v[160:163], v[204:207], v[92:95]
	v_mfma_f32_16x16x32_bf16 v[92:95], v[164:167], v[208:211], v[92:95]
	v_mfma_f32_16x16x32_bf16 v[84:87], v[152:155], v[212:215], v[84:87]
	v_mfma_f32_16x16x32_bf16 v[84:87], v[156:159], v[216:219], v[84:87]
	v_mfma_f32_16x16x32_bf16 v[76:79], v[160:163], v[212:215], v[76:79]
	v_mfma_f32_16x16x32_bf16 v[76:79], v[164:167], v[216:219], v[76:79]
	v_mfma_f32_16x16x32_bf16 v[112:115], v[168:171], v[188:191], v[112:115]
	v_mfma_f32_16x16x32_bf16 v[112:115], v[172:175], v[192:195], v[112:115]
	v_mfma_f32_16x16x32_bf16 v[104:107], v[176:179], v[188:191], v[104:107]
	v_mfma_f32_16x16x32_bf16 v[104:107], v[184:187], v[192:195], v[104:107]
	v_mfma_f32_16x16x32_bf16 v[96:99], v[168:171], v[196:199], v[96:99]
	v_mfma_f32_16x16x32_bf16 v[96:99], v[172:175], v[200:203], v[96:99]
	v_mfma_f32_16x16x32_bf16 v[88:91], v[176:179], v[196:199], v[88:91]
	v_mfma_f32_16x16x32_bf16 v[88:91], v[184:187], v[200:203], v[88:91]
	v_mfma_f32_16x16x32_bf16 v[80:83], v[168:171], v[204:207], v[80:83]
	v_mfma_f32_16x16x32_bf16 v[80:83], v[172:175], v[208:211], v[80:83]
	v_mfma_f32_16x16x32_bf16 v[72:75], v[176:179], v[204:207], v[72:75]
	v_mfma_f32_16x16x32_bf16 v[72:75], v[184:187], v[208:211], v[72:75]
	v_mfma_f32_16x16x32_bf16 v[68:71], v[168:171], v[212:215], v[68:71]
	v_mfma_f32_16x16x32_bf16 v[68:71], v[172:175], v[216:219], v[68:71]
	v_mfma_f32_16x16x32_bf16 v[64:67], v[176:179], v[212:215], v[64:67]
	v_mfma_f32_16x16x32_bf16 v[64:67], v[184:187], v[216:219], v[64:67]
	s_setprio 0
	s_barrier
	s_add_i32 s79, s71, s64
	v_lshl_add_u64 v[144:145], s[58:59], 0, v[130:131]
	s_mov_b32 m0, s79
	s_nop 0
	global_load_lds_dwordx4 v[144:145], off
	s_add_i32 m0, s79, 0x2000
	s_add_u32 s88, s58, 0x40000
	v_lshl_add_u64 v[220:221], s[58:59], 0, v[134:135]
	s_addc_u32 s89, s59, 0
	s_add_i32 s79, s72, s64
	global_load_lds_dwordx4 v[220:221], off
	v_lshl_add_u64 v[222:223], s[88:89], 0, v[130:131]
	s_mov_b32 m0, s79
	v_lshl_add_u64 v[224:225], s[60:61], 0, v[132:133]
	global_load_lds_dwordx4 v[222:223], off
	v_lshl_add_u64 v[222:223], s[88:89], 0, v[134:135]
	s_add_i32 m0, s79, 0x2000
	s_nop 0
	global_load_lds_dwordx4 v[222:223], off
	v_lshl_add_u64 v[222:223], s[60:61], 0, v[128:129]
	s_mov_b32 m0, s55
	s_nop 0
	global_load_lds_dwordx4 v[222:223], off
	s_mov_b32 m0, s65
	s_nop 0
	global_load_lds_dwordx4 v[224:225], off
	ds_read_b128 v[188:191], v151 offset:16384
	ds_read_b128 v[192:195], v151 offset:17408
	ds_read_b128 v[196:199], v151 offset:18432
	ds_read_b128 v[200:203], v151 offset:19456
	ds_read_b128 v[204:207], v151 offset:20480
	ds_read_b128 v[208:211], v151 offset:21504
	ds_read_b128 v[212:215], v151 offset:22528
	ds_read_b128 v[216:219], v151 offset:23552
	s_waitcnt vmcnt(8)
	s_waitcnt lgkmcnt(0)
	s_barrier
	s_setprio 1
	s_waitcnt lgkmcnt(0)
	v_mfma_f32_16x16x32_bf16 v[60:63], v[152:155], v[188:191], v[60:63]
	v_mfma_f32_16x16x32_bf16 v[60:63], v[156:159], v[192:195], v[60:63]
	v_mfma_f32_16x16x32_bf16 v[56:59], v[160:163], v[188:191], v[56:59]
	v_mfma_f32_16x16x32_bf16 v[56:59], v[164:167], v[192:195], v[56:59]
	v_mfma_f32_16x16x32_bf16 v[52:55], v[152:155], v[196:199], v[52:55]
	v_mfma_f32_16x16x32_bf16 v[52:55], v[156:159], v[200:203], v[52:55]
	v_mfma_f32_16x16x32_bf16 v[44:47], v[160:163], v[196:199], v[44:47]
	v_mfma_f32_16x16x32_bf16 v[44:47], v[164:167], v[200:203], v[44:47]
	v_mfma_f32_16x16x32_bf16 v[36:39], v[152:155], v[204:207], v[36:39]
	v_mfma_f32_16x16x32_bf16 v[36:39], v[156:159], v[208:211], v[36:39]
	v_mfma_f32_16x16x32_bf16 v[28:31], v[160:163], v[204:207], v[28:31]
	v_mfma_f32_16x16x32_bf16 v[28:31], v[164:167], v[208:211], v[28:31]
	v_mfma_f32_16x16x32_bf16 v[20:23], v[152:155], v[212:215], v[20:23]
	v_mfma_f32_16x16x32_bf16 v[20:23], v[156:159], v[216:219], v[20:23]
	v_mfma_f32_16x16x32_bf16 v[12:15], v[160:163], v[212:215], v[12:15]
	v_mfma_f32_16x16x32_bf16 v[12:15], v[164:167], v[216:219], v[12:15]
	v_mfma_f32_16x16x32_bf16 v[48:51], v[168:171], v[188:191], v[48:51]
	v_mfma_f32_16x16x32_bf16 v[48:51], v[172:175], v[192:195], v[48:51]
	v_mfma_f32_16x16x32_bf16 v[40:43], v[176:179], v[188:191], v[40:43]
	v_mfma_f32_16x16x32_bf16 v[40:43], v[184:187], v[192:195], v[40:43]
	v_mfma_f32_16x16x32_bf16 v[32:35], v[168:171], v[196:199], v[32:35]
	v_mfma_f32_16x16x32_bf16 v[32:35], v[172:175], v[200:203], v[32:35]
	v_mfma_f32_16x16x32_bf16 v[24:27], v[176:179], v[196:199], v[24:27]
	v_mfma_f32_16x16x32_bf16 v[24:27], v[184:187], v[200:203], v[24:27]
	v_mfma_f32_16x16x32_bf16 v[16:19], v[168:171], v[204:207], v[16:19]
	v_mfma_f32_16x16x32_bf16 v[16:19], v[172:175], v[208:211], v[16:19]
	v_mfma_f32_16x16x32_bf16 v[8:11], v[176:179], v[204:207], v[8:11]
	v_mfma_f32_16x16x32_bf16 v[8:11], v[184:187], v[208:211], v[8:11]
	v_mfma_f32_16x16x32_bf16 v[4:7], v[168:171], v[212:215], v[4:7]
	v_mfma_f32_16x16x32_bf16 v[4:7], v[172:175], v[216:219], v[4:7]
	v_mfma_f32_16x16x32_bf16 v[0:3], v[176:179], v[212:215], v[0:3]
	v_mfma_f32_16x16x32_bf16 v[0:3], v[184:187], v[216:219], v[0:3]
	s_setprio 0
	s_barrier
.Lmid_gemm10:
	s_add_i32 s79, 0, 0x18000
	s_add_i32 s87, 0, 0x1c000
	v_add_u32_e32 v164, s79, v147
	v_add_u32_e32 v181, s87, v147
	s_add_u32 s60, s60, 0x40000
	s_addc_u32 s61, s61, 0
	s_mov_b32 m0, s66
	v_lshl_add_u64 v[226:227], s[60:61], 0, v[128:129]
	global_load_lds_dwordx4 v[226:227], off
	v_lshl_add_u64 v[226:227], s[60:61], 0, v[132:133]
	s_mov_b32 m0, s67
	s_nop 0
	global_load_lds_dwordx4 v[226:227], off
	ds_read_b128 v[152:155], v164
	ds_read_b128 v[156:159], v164 offset:1024
	ds_read_b128 v[160:163], v164 offset:2048
	ds_read_b128 v[164:167], v164 offset:3072
	ds_read_b128 v[168:171], v181
	ds_read_b128 v[172:175], v181 offset:1024
	ds_read_b128 v[176:179], v181 offset:2048
	ds_read_b128 v[184:187], v181 offset:3072
	ds_read_b128 v[188:191], v151 offset:32768
	ds_read_b128 v[192:195], v151 offset:33792
	ds_read_b128 v[196:199], v151 offset:34816
	ds_read_b128 v[200:203], v151 offset:35840
	ds_read_b128 v[204:207], v151 offset:36864
	ds_read_b128 v[208:211], v151 offset:37888
	ds_read_b128 v[212:215], v151 offset:38912
	ds_read_b128 v[216:219], v151 offset:39936
	s_waitcnt vmcnt(8)
	s_waitcnt lgkmcnt(0)
	s_barrier
	s_setprio 1
	s_waitcnt lgkmcnt(0)
	v_mfma_f32_16x16x32_bf16 v[124:127], v[152:155], v[188:191], v[124:127]
	v_mfma_f32_16x16x32_bf16 v[124:127], v[156:159], v[192:195], v[124:127]
	v_mfma_f32_16x16x32_bf16 v[120:123], v[160:163], v[188:191], v[120:123]
	v_mfma_f32_16x16x32_bf16 v[120:123], v[164:167], v[192:195], v[120:123]
	v_mfma_f32_16x16x32_bf16 v[116:119], v[152:155], v[196:199], v[116:119]
	v_mfma_f32_16x16x32_bf16 v[116:119], v[156:159], v[200:203], v[116:119]
	v_mfma_f32_16x16x32_bf16 v[108:111], v[160:163], v[196:199], v[108:111]
	v_mfma_f32_16x16x32_bf16 v[108:111], v[164:167], v[200:203], v[108:111]
	v_mfma_f32_16x16x32_bf16 v[100:103], v[152:155], v[204:207], v[100:103]
	v_mfma_f32_16x16x32_bf16 v[100:103], v[156:159], v[208:211], v[100:103]
	v_mfma_f32_16x16x32_bf16 v[92:95], v[160:163], v[204:207], v[92:95]
	v_mfma_f32_16x16x32_bf16 v[92:95], v[164:167], v[208:211], v[92:95]
	v_mfma_f32_16x16x32_bf16 v[84:87], v[152:155], v[212:215], v[84:87]
	v_mfma_f32_16x16x32_bf16 v[84:87], v[156:159], v[216:219], v[84:87]
	v_mfma_f32_16x16x32_bf16 v[76:79], v[160:163], v[212:215], v[76:79]
	v_mfma_f32_16x16x32_bf16 v[76:79], v[164:167], v[216:219], v[76:79]
	v_mfma_f32_16x16x32_bf16 v[112:115], v[168:171], v[188:191], v[112:115]
	v_mfma_f32_16x16x32_bf16 v[112:115], v[172:175], v[192:195], v[112:115]
	v_mfma_f32_16x16x32_bf16 v[104:107], v[176:179], v[188:191], v[104:107]
	v_mfma_f32_16x16x32_bf16 v[104:107], v[184:187], v[192:195], v[104:107]
	v_mfma_f32_16x16x32_bf16 v[96:99], v[168:171], v[196:199], v[96:99]
	v_mfma_f32_16x16x32_bf16 v[96:99], v[172:175], v[200:203], v[96:99]
	v_mfma_f32_16x16x32_bf16 v[88:91], v[176:179], v[196:199], v[88:91]
	v_mfma_f32_16x16x32_bf16 v[88:91], v[184:187], v[200:203], v[88:91]
	v_mfma_f32_16x16x32_bf16 v[80:83], v[168:171], v[204:207], v[80:83]
	v_mfma_f32_16x16x32_bf16 v[80:83], v[172:175], v[208:211], v[80:83]
	v_mfma_f32_16x16x32_bf16 v[72:75], v[176:179], v[204:207], v[72:75]
	v_mfma_f32_16x16x32_bf16 v[72:75], v[184:187], v[208:211], v[72:75]
	v_mfma_f32_16x16x32_bf16 v[68:71], v[168:171], v[212:215], v[68:71]
	v_mfma_f32_16x16x32_bf16 v[68:71], v[172:175], v[216:219], v[68:71]
	v_mfma_f32_16x16x32_bf16 v[64:67], v[176:179], v[212:215], v[64:67]
	v_mfma_f32_16x16x32_bf16 v[64:67], v[184:187], v[216:219], v[64:67]
	s_setprio 0
	s_barrier
	s_add_i32 s60, s79, s64
	v_lshl_add_u64 v[144:145], v[144:145], 0, s[16:17]
	s_mov_b32 m0, s60
	s_nop 0
	global_load_lds_dwordx4 v[144:145], off
	s_add_i32 m0, s60, 0x2000
	s_add_u32 s58, s58, 0x40080
	v_lshl_add_u64 v[144:145], v[220:221], 0, s[16:17]
	s_addc_u32 s59, s59, 0
	s_add_i32 s60, s87, s64
	global_load_lds_dwordx4 v[144:145], off
	v_lshl_add_u64 v[144:145], s[58:59], 0, v[130:131]
	s_mov_b32 m0, s60
	s_nop 0
	global_load_lds_dwordx4 v[144:145], off
	v_lshl_add_u64 v[144:145], s[58:59], 0, v[134:135]
	s_add_i32 m0, s60, 0x2000
	s_nop 0
	global_load_lds_dwordx4 v[144:145], off
	v_lshl_add_u64 v[144:145], v[222:223], 0, s[16:17]
	s_mov_b32 m0, s69
	s_nop 0
	global_load_lds_dwordx4 v[144:145], off
	v_lshl_add_u64 v[144:145], v[224:225], 0, s[16:17]
	s_mov_b32 m0, s70
	s_nop 0
	global_load_lds_dwordx4 v[144:145], off
	ds_read_b128 v[188:191], v151 offset:49152
	ds_read_b128 v[192:195], v151 offset:50176
	ds_read_b128 v[196:199], v151 offset:51200
	ds_read_b128 v[200:203], v151 offset:52224
	ds_read_b128 v[204:207], v151 offset:53248
	ds_read_b128 v[208:211], v151 offset:54272
	ds_read_b128 v[212:215], v151 offset:55296
	ds_read_b128 v[216:219], v151 offset:56320
	s_waitcnt vmcnt(8)
	s_waitcnt lgkmcnt(0)
	s_barrier
	s_setprio 1
	s_waitcnt lgkmcnt(0)
	v_mfma_f32_16x16x32_bf16 v[60:63], v[152:155], v[188:191], v[60:63]
	v_mfma_f32_16x16x32_bf16 v[60:63], v[156:159], v[192:195], v[60:63]
	v_mfma_f32_16x16x32_bf16 v[56:59], v[160:163], v[188:191], v[56:59]
	v_mfma_f32_16x16x32_bf16 v[56:59], v[164:167], v[192:195], v[56:59]
	v_mfma_f32_16x16x32_bf16 v[52:55], v[152:155], v[196:199], v[52:55]
	v_mfma_f32_16x16x32_bf16 v[52:55], v[156:159], v[200:203], v[52:55]
	v_mfma_f32_16x16x32_bf16 v[44:47], v[160:163], v[196:199], v[44:47]
	v_mfma_f32_16x16x32_bf16 v[44:47], v[164:167], v[200:203], v[44:47]
	v_mfma_f32_16x16x32_bf16 v[36:39], v[152:155], v[204:207], v[36:39]
	v_mfma_f32_16x16x32_bf16 v[36:39], v[156:159], v[208:211], v[36:39]
	v_mfma_f32_16x16x32_bf16 v[28:31], v[160:163], v[204:207], v[28:31]
	v_mfma_f32_16x16x32_bf16 v[28:31], v[164:167], v[208:211], v[28:31]
	v_mfma_f32_16x16x32_bf16 v[20:23], v[152:155], v[212:215], v[20:23]
	v_mfma_f32_16x16x32_bf16 v[20:23], v[156:159], v[216:219], v[20:23]
	v_mfma_f32_16x16x32_bf16 v[12:15], v[160:163], v[212:215], v[12:15]
	v_mfma_f32_16x16x32_bf16 v[12:15], v[164:167], v[216:219], v[12:15]
	v_mfma_f32_16x16x32_bf16 v[48:51], v[168:171], v[188:191], v[48:51]
	v_mfma_f32_16x16x32_bf16 v[48:51], v[172:175], v[192:195], v[48:51]
	v_mfma_f32_16x16x32_bf16 v[40:43], v[176:179], v[188:191], v[40:43]
	v_mfma_f32_16x16x32_bf16 v[40:43], v[184:187], v[192:195], v[40:43]
	v_mfma_f32_16x16x32_bf16 v[32:35], v[168:171], v[196:199], v[32:35]
	v_mfma_f32_16x16x32_bf16 v[32:35], v[172:175], v[200:203], v[32:35]
	v_mfma_f32_16x16x32_bf16 v[24:27], v[176:179], v[196:199], v[24:27]
	v_mfma_f32_16x16x32_bf16 v[24:27], v[184:187], v[200:203], v[24:27]
	v_mfma_f32_16x16x32_bf16 v[16:19], v[168:171], v[204:207], v[16:19]
	v_mfma_f32_16x16x32_bf16 v[16:19], v[172:175], v[208:211], v[16:19]
	v_mfma_f32_16x16x32_bf16 v[8:11], v[176:179], v[204:207], v[8:11]
	v_mfma_f32_16x16x32_bf16 v[8:11], v[184:187], v[208:211], v[8:11]
	v_mfma_f32_16x16x32_bf16 v[4:7], v[168:171], v[212:215], v[4:7]
	v_mfma_f32_16x16x32_bf16 v[4:7], v[172:175], v[216:219], v[4:7]
	v_mfma_f32_16x16x32_bf16 v[0:3], v[176:179], v[212:215], v[0:3]
	v_mfma_f32_16x16x32_bf16 v[0:3], v[184:187], v[216:219], v[0:3]
	s_setprio 0
	s_barrier
	s_add_i32 s86, s86, 2
	s_add_u32 s56, s56, 0x100
	s_addc_u32 s57, s57, 0
	s_add_u32 s84, s84, 0x100
	s_addc_u32 s85, s85, 0
	s_cmp_gt_u32 s86, 13
	s_cbranch_scc0 .LBB0_1311
	s_and_b64 vcc, exec, s[18:19]
	s_cbranch_vccz .LBB0_1314
	s_barrier

.LBB0_1433:
	s_ashr_i32 s19, s18, 31
	s_lshl_b64 s[30:31], s[18:19], 19
	s_add_u32 s30, s80, s30
	s_addc_u32 s31, s81, s31
	s_and_b64 s[36:37], s[8:9], exec
	s_cselect_b32 s19, s31, s47
	s_cselect_b32 s66, s30, s46
	s_ashr_i32 s17, s16, 31
	s_lshl_b64 s[36:37], s[16:17], 19
	s_add_u32 s36, s52, s36
	s_addc_u32 s37, s53, s37
	s_and_b64 s[50:51], s[8:9], exec
	s_cselect_b32 s17, s37, s49
	s_cselect_b32 s67, s36, s48
	s_add_u32 s46, s46, 0x40080
	s_addc_u32 s47, s47, 0
	s_add_u32 s68, s48, 0x100
	s_addc_u32 s69, s49, 0
	s_mov_b32 s70, -2
	s_add_u32 s48, s46, 0xfffc0080
	s_addc_u32 s49, s47, -1
	s_cmp_eq_u32 s70, 12
	s_cselect_b32 s51, s19, s49
	s_cselect_b32 s50, s66, s48
	s_cselect_b32 s49, s17, s69
	s_cselect_b32 s48, s67, s68
	v_lshl_add_u64 v[178:179], s[46:47], 0, v[132:133]
	s_add_i32 m0, s45, 0xc000
	s_nop 0
	global_load_lds_dwordx4 v[178:179], off
	v_lshl_add_u64 v[178:179], s[46:47], 0, v[134:135]
	s_add_i32 m0, s45, 0xe000
	s_nop 0
	global_load_lds_dwordx4 v[178:179], off
	ds_read_b128 v[140:143], v147
	ds_read_b128 v[150:153], v147 offset:1024
	ds_read_b128 v[154:157], v147 offset:2048
	ds_read_b128 v[158:161], v147 offset:3072
	ds_read_b128 v[162:165], v148
	ds_read_b128 v[166:169], v148 offset:1024
	ds_read_b128 v[170:173], v148 offset:2048
	ds_read_b128 v[174:177], v148 offset:3072
	ds_read_b128 v[184:187], v149
	ds_read_b128 v[188:191], v149 offset:1024
	ds_read_b128 v[192:195], v149 offset:2048
	ds_read_b128 v[196:199], v149 offset:3072
	ds_read_b128 v[200:203], v149 offset:4096
	ds_read_b128 v[204:207], v149 offset:5120
	ds_read_b128 v[208:211], v149 offset:6144
	ds_read_b128 v[212:215], v149 offset:7168
	s_waitcnt vmcnt(8)
	s_waitcnt lgkmcnt(0)
	s_barrier
	s_setprio 1
	s_waitcnt lgkmcnt(0)
	v_mfma_f32_16x16x32_bf16 v[124:127], v[140:143], v[184:187], 0
	v_mfma_f32_16x16x32_bf16 v[124:127], v[150:153], v[188:191], v[124:127]
	v_mfma_f32_16x16x32_bf16 v[120:123], v[154:157], v[184:187], 0
	v_mfma_f32_16x16x32_bf16 v[120:123], v[158:161], v[188:191], v[120:123]
	v_mfma_f32_16x16x32_bf16 v[108:111], v[140:143], v[192:195], 0
	v_mfma_f32_16x16x32_bf16 v[108:111], v[150:153], v[196:199], v[108:111]
	v_mfma_f32_16x16x32_bf16 v[104:107], v[154:157], v[192:195], 0
	v_mfma_f32_16x16x32_bf16 v[104:107], v[158:161], v[196:199], v[104:107]
	v_mfma_f32_16x16x32_bf16 v[92:95], v[140:143], v[200:203], 0
	v_mfma_f32_16x16x32_bf16 v[92:95], v[150:153], v[204:207], v[92:95]
	v_mfma_f32_16x16x32_bf16 v[88:91], v[154:157], v[200:203], 0
	v_mfma_f32_16x16x32_bf16 v[88:91], v[158:161], v[204:207], v[88:91]
	v_mfma_f32_16x16x32_bf16 v[76:79], v[140:143], v[208:211], 0
	v_mfma_f32_16x16x32_bf16 v[76:79], v[150:153], v[212:215], v[76:79]
	v_mfma_f32_16x16x32_bf16 v[72:75], v[154:157], v[208:211], 0
	v_mfma_f32_16x16x32_bf16 v[72:75], v[158:161], v[212:215], v[72:75]
	v_mfma_f32_16x16x32_bf16 v[116:119], v[162:165], v[184:187], 0
	v_mfma_f32_16x16x32_bf16 v[116:119], v[166:169], v[188:191], v[116:119]
	v_mfma_f32_16x16x32_bf16 v[112:115], v[170:173], v[184:187], 0
	v_mfma_f32_16x16x32_bf16 v[112:115], v[174:177], v[188:191], v[112:115]
	v_mfma_f32_16x16x32_bf16 v[100:103], v[162:165], v[192:195], 0
	v_mfma_f32_16x16x32_bf16 v[100:103], v[166:169], v[196:199], v[100:103]
	v_mfma_f32_16x16x32_bf16 v[96:99], v[170:173], v[192:195], 0
	v_mfma_f32_16x16x32_bf16 v[96:99], v[174:177], v[196:199], v[96:99]
	v_mfma_f32_16x16x32_bf16 v[84:87], v[162:165], v[200:203], 0
	v_mfma_f32_16x16x32_bf16 v[84:87], v[166:169], v[204:207], v[84:87]
	v_mfma_f32_16x16x32_bf16 v[80:83], v[170:173], v[200:203], 0
	v_mfma_f32_16x16x32_bf16 v[80:83], v[174:177], v[204:207], v[80:83]
	v_mfma_f32_16x16x32_bf16 v[68:71], v[162:165], v[208:211], 0
	v_mfma_f32_16x16x32_bf16 v[68:71], v[166:169], v[212:215], v[68:71]
	v_mfma_f32_16x16x32_bf16 v[64:67], v[170:173], v[208:211], 0
	v_mfma_f32_16x16x32_bf16 v[64:67], v[174:177], v[212:215], v[64:67]
	s_setprio 0
	s_barrier
	s_add_i32 s71, s62, s54
	v_lshl_add_u64 v[178:179], s[48:49], 0, v[130:131]
	s_mov_b32 m0, s71
	s_nop 0
	global_load_lds_dwordx4 v[178:179], off
	s_add_i32 m0, s71, 0x2000
	s_add_u32 s72, s48, 0x40000
	v_lshl_add_u64 v[216:217], s[48:49], 0, v[128:129]
	s_addc_u32 s73, s49, 0
	s_add_i32 s71, s63, s54
	global_load_lds_dwordx4 v[216:217], off
	v_lshl_add_u64 v[218:219], s[72:73], 0, v[130:131]
	s_mov_b32 m0, s71
	v_lshl_add_u64 v[220:221], s[50:51], 0, v[128:129]
	global_load_lds_dwordx4 v[218:219], off
	v_lshl_add_u64 v[218:219], s[72:73], 0, v[128:129]
	s_add_i32 m0, s71, 0x2000
	s_nop 0
	global_load_lds_dwordx4 v[218:219], off
	v_lshl_add_u64 v[218:219], s[50:51], 0, v[130:131]
	s_mov_b32 m0, s45
	s_nop 0
	global_load_lds_dwordx4 v[218:219], off
	s_mov_b32 m0, s56
	s_nop 0
	global_load_lds_dwordx4 v[220:221], off
	ds_read_b128 v[184:187], v149 offset:16384
	ds_read_b128 v[188:191], v149 offset:17408
	ds_read_b128 v[192:195], v149 offset:18432
	ds_read_b128 v[196:199], v149 offset:19456
	ds_read_b128 v[200:203], v149 offset:20480
	ds_read_b128 v[204:207], v149 offset:21504
	ds_read_b128 v[208:211], v149 offset:22528
	ds_read_b128 v[212:215], v149 offset:23552
	s_waitcnt vmcnt(8)
	s_waitcnt lgkmcnt(0)
	s_barrier
	s_setprio 1
	s_waitcnt lgkmcnt(0)
	v_mfma_f32_16x16x32_bf16 v[60:63], v[140:143], v[184:187], 0
	v_mfma_f32_16x16x32_bf16 v[60:63], v[150:153], v[188:191], v[60:63]
	v_mfma_f32_16x16x32_bf16 v[56:59], v[154:157], v[184:187], 0
	v_mfma_f32_16x16x32_bf16 v[56:59], v[158:161], v[188:191], v[56:59]
	v_mfma_f32_16x16x32_bf16 v[44:47], v[140:143], v[192:195], 0
	v_mfma_f32_16x16x32_bf16 v[44:47], v[150:153], v[196:199], v[44:47]
	v_mfma_f32_16x16x32_bf16 v[40:43], v[154:157], v[192:195], 0
	v_mfma_f32_16x16x32_bf16 v[40:43], v[158:161], v[196:199], v[40:43]
	v_mfma_f32_16x16x32_bf16 v[28:31], v[140:143], v[200:203], 0
	v_mfma_f32_16x16x32_bf16 v[28:31], v[150:153], v[204:207], v[28:31]
	v_mfma_f32_16x16x32_bf16 v[24:27], v[154:157], v[200:203], 0
	v_mfma_f32_16x16x32_bf16 v[24:27], v[158:161], v[204:207], v[24:27]
	v_mfma_f32_16x16x32_bf16 v[12:15], v[140:143], v[208:211], 0
	v_mfma_f32_16x16x32_bf16 v[12:15], v[150:153], v[212:215], v[12:15]
	v_mfma_f32_16x16x32_bf16 v[8:11], v[154:157], v[208:211], 0
	v_mfma_f32_16x16x32_bf16 v[8:11], v[158:161], v[212:215], v[8:11]
	v_mfma_f32_16x16x32_bf16 v[52:55], v[162:165], v[184:187], 0
	v_mfma_f32_16x16x32_bf16 v[52:55], v[166:169], v[188:191], v[52:55]
	v_mfma_f32_16x16x32_bf16 v[48:51], v[170:173], v[184:187], 0
	v_mfma_f32_16x16x32_bf16 v[48:51], v[174:177], v[188:191], v[48:51]
	v_mfma_f32_16x16x32_bf16 v[36:39], v[162:165], v[192:195], 0
	v_mfma_f32_16x16x32_bf16 v[36:39], v[166:169], v[196:199], v[36:39]
	v_mfma_f32_16x16x32_bf16 v[32:35], v[170:173], v[192:195], 0
	v_mfma_f32_16x16x32_bf16 v[32:35], v[174:177], v[196:199], v[32:35]
	v_mfma_f32_16x16x32_bf16 v[20:23], v[162:165], v[200:203], 0
	v_mfma_f32_16x16x32_bf16 v[20:23], v[166:169], v[204:207], v[20:23]
	v_mfma_f32_16x16x32_bf16 v[16:19], v[170:173], v[200:203], 0
	v_mfma_f32_16x16x32_bf16 v[16:19], v[174:177], v[204:207], v[16:19]
	v_mfma_f32_16x16x32_bf16 v[4:7], v[162:165], v[208:211], 0
	v_mfma_f32_16x16x32_bf16 v[4:7], v[166:169], v[212:215], v[4:7]
	v_mfma_f32_16x16x32_bf16 v[0:3], v[170:173], v[208:211], 0
	v_mfma_f32_16x16x32_bf16 v[0:3], v[174:177], v[212:215], v[0:3]
	s_setprio 0
	s_barrier
	s_branch .Lmid_gemm11
.LBB0_1434:
	s_add_u32 s48, s46, 0xfffc0080
	s_addc_u32 s49, s47, -1
	s_cmp_eq_u32 s70, 12
	s_cselect_b32 s51, s19, s49
	s_cselect_b32 s50, s66, s48
	s_cselect_b32 s49, s17, s69
	s_cselect_b32 s48, s67, s68
	v_lshl_add_u64 v[178:179], s[46:47], 0, v[132:133]
	s_add_i32 m0, s45, 0xc000
	s_nop 0
	global_load_lds_dwordx4 v[178:179], off
	v_lshl_add_u64 v[178:179], s[46:47], 0, v[134:135]
	s_add_i32 m0, s45, 0xe000
	s_nop 0
	global_load_lds_dwordx4 v[178:179], off
	ds_read_b128 v[140:143], v147
	ds_read_b128 v[150:153], v147 offset:1024
	ds_read_b128 v[154:157], v147 offset:2048
	ds_read_b128 v[158:161], v147 offset:3072
	ds_read_b128 v[162:165], v148
	ds_read_b128 v[166:169], v148 offset:1024
	ds_read_b128 v[170:173], v148 offset:2048
	ds_read_b128 v[174:177], v148 offset:3072
	ds_read_b128 v[184:187], v149
	ds_read_b128 v[188:191], v149 offset:1024
	ds_read_b128 v[192:195], v149 offset:2048
	ds_read_b128 v[196:199], v149 offset:3072
	ds_read_b128 v[200:203], v149 offset:4096
	ds_read_b128 v[204:207], v149 offset:5120
	ds_read_b128 v[208:211], v149 offset:6144
	ds_read_b128 v[212:215], v149 offset:7168
	s_waitcnt vmcnt(8)
	s_waitcnt lgkmcnt(0)
	s_barrier
	s_setprio 1
	s_waitcnt lgkmcnt(0)
	v_mfma_f32_16x16x32_bf16 v[124:127], v[140:143], v[184:187], v[124:127]
	v_mfma_f32_16x16x32_bf16 v[124:127], v[150:153], v[188:191], v[124:127]
	v_mfma_f32_16x16x32_bf16 v[120:123], v[154:157], v[184:187], v[120:123]
	v_mfma_f32_16x16x32_bf16 v[120:123], v[158:161], v[188:191], v[120:123]
	v_mfma_f32_16x16x32_bf16 v[108:111], v[140:143], v[192:195], v[108:111]
	v_mfma_f32_16x16x32_bf16 v[108:111], v[150:153], v[196:199], v[108:111]
	v_mfma_f32_16x16x32_bf16 v[104:107], v[154:157], v[192:195], v[104:107]
	v_mfma_f32_16x16x32_bf16 v[104:107], v[158:161], v[196:199], v[104:107]
	v_mfma_f32_16x16x32_bf16 v[92:95], v[140:143], v[200:203], v[92:95]
	v_mfma_f32_16x16x32_bf16 v[92:95], v[150:153], v[204:207], v[92:95]
	v_mfma_f32_16x16x32_bf16 v[88:91], v[154:157], v[200:203], v[88:91]
	v_mfma_f32_16x16x32_bf16 v[88:91], v[158:161], v[204:207], v[88:91]
	v_mfma_f32_16x16x32_bf16 v[76:79], v[140:143], v[208:211], v[76:79]
	v_mfma_f32_16x16x32_bf16 v[76:79], v[150:153], v[212:215], v[76:79]
	v_mfma_f32_16x16x32_bf16 v[72:75], v[154:157], v[208:211], v[72:75]
	v_mfma_f32_16x16x32_bf16 v[72:75], v[158:161], v[212:215], v[72:75]
	v_mfma_f32_16x16x32_bf16 v[116:119], v[162:165], v[184:187], v[116:119]
	v_mfma_f32_16x16x32_bf16 v[116:119], v[166:169], v[188:191], v[116:119]
	v_mfma_f32_16x16x32_bf16 v[112:115], v[170:173], v[184:187], v[112:115]
	v_mfma_f32_16x16x32_bf16 v[112:115], v[174:177], v[188:191], v[112:115]
	v_mfma_f32_16x16x32_bf16 v[100:103], v[162:165], v[192:195], v[100:103]
	v_mfma_f32_16x16x32_bf16 v[100:103], v[166:169], v[196:199], v[100:103]
	v_mfma_f32_16x16x32_bf16 v[96:99], v[170:173], v[192:195], v[96:99]
	v_mfma_f32_16x16x32_bf16 v[96:99], v[174:177], v[196:199], v[96:99]
	v_mfma_f32_16x16x32_bf16 v[84:87], v[162:165], v[200:203], v[84:87]
	v_mfma_f32_16x16x32_bf16 v[84:87], v[166:169], v[204:207], v[84:87]
	v_mfma_f32_16x16x32_bf16 v[80:83], v[170:173], v[200:203], v[80:83]
	v_mfma_f32_16x16x32_bf16 v[80:83], v[174:177], v[204:207], v[80:83]
	v_mfma_f32_16x16x32_bf16 v[68:71], v[162:165], v[208:211], v[68:71]
	v_mfma_f32_16x16x32_bf16 v[68:71], v[166:169], v[212:215], v[68:71]
	v_mfma_f32_16x16x32_bf16 v[64:67], v[170:173], v[208:211], v[64:67]
	v_mfma_f32_16x16x32_bf16 v[64:67], v[174:177], v[212:215], v[64:67]
	s_setprio 0
	s_barrier
	s_add_i32 s71, s62, s54
	v_lshl_add_u64 v[178:179], s[48:49], 0, v[130:131]
	s_mov_b32 m0, s71
	s_nop 0
	global_load_lds_dwordx4 v[178:179], off
	s_add_i32 m0, s71, 0x2000
	s_add_u32 s72, s48, 0x40000
	v_lshl_add_u64 v[216:217], s[48:49], 0, v[128:129]
	s_addc_u32 s73, s49, 0
	s_add_i32 s71, s63, s54
	global_load_lds_dwordx4 v[216:217], off
	v_lshl_add_u64 v[218:219], s[72:73], 0, v[130:131]
	s_mov_b32 m0, s71
	v_lshl_add_u64 v[220:221], s[50:51], 0, v[128:129]
	global_load_lds_dwordx4 v[218:219], off
	v_lshl_add_u64 v[218:219], s[72:73], 0, v[128:129]
	s_add_i32 m0, s71, 0x2000
	s_nop 0
	global_load_lds_dwordx4 v[218:219], off
	v_lshl_add_u64 v[218:219], s[50:51], 0, v[130:131]
	s_mov_b32 m0, s45
	s_nop 0
	global_load_lds_dwordx4 v[218:219], off
	s_mov_b32 m0, s56
	s_nop 0
	global_load_lds_dwordx4 v[220:221], off
	ds_read_b128 v[184:187], v149 offset:16384
	ds_read_b128 v[188:191], v149 offset:17408
	ds_read_b128 v[192:195], v149 offset:18432
	ds_read_b128 v[196:199], v149 offset:19456
	ds_read_b128 v[200:203], v149 offset:20480
	ds_read_b128 v[204:207], v149 offset:21504
	ds_read_b128 v[208:211], v149 offset:22528
	ds_read_b128 v[212:215], v149 offset:23552
	s_waitcnt vmcnt(8)
	s_waitcnt lgkmcnt(0)
	s_barrier
	s_setprio 1
	s_waitcnt lgkmcnt(0)
	v_mfma_f32_16x16x32_bf16 v[60:63], v[140:143], v[184:187], v[60:63]
	v_mfma_f32_16x16x32_bf16 v[60:63], v[150:153], v[188:191], v[60:63]
	v_mfma_f32_16x16x32_bf16 v[56:59], v[154:157], v[184:187], v[56:59]
	v_mfma_f32_16x16x32_bf16 v[56:59], v[158:161], v[188:191], v[56:59]
	v_mfma_f32_16x16x32_bf16 v[44:47], v[140:143], v[192:195], v[44:47]
	v_mfma_f32_16x16x32_bf16 v[44:47], v[150:153], v[196:199], v[44:47]
	v_mfma_f32_16x16x32_bf16 v[40:43], v[154:157], v[192:195], v[40:43]
	v_mfma_f32_16x16x32_bf16 v[40:43], v[158:161], v[196:199], v[40:43]
	v_mfma_f32_16x16x32_bf16 v[28:31], v[140:143], v[200:203], v[28:31]
	v_mfma_f32_16x16x32_bf16 v[28:31], v[150:153], v[204:207], v[28:31]
	v_mfma_f32_16x16x32_bf16 v[24:27], v[154:157], v[200:203], v[24:27]
	v_mfma_f32_16x16x32_bf16 v[24:27], v[158:161], v[204:207], v[24:27]
	v_mfma_f32_16x16x32_bf16 v[12:15], v[140:143], v[208:211], v[12:15]
	v_mfma_f32_16x16x32_bf16 v[12:15], v[150:153], v[212:215], v[12:15]
	v_mfma_f32_16x16x32_bf16 v[8:11], v[154:157], v[208:211], v[8:11]
	v_mfma_f32_16x16x32_bf16 v[8:11], v[158:161], v[212:215], v[8:11]
	v_mfma_f32_16x16x32_bf16 v[52:55], v[162:165], v[184:187], v[52:55]
	v_mfma_f32_16x16x32_bf16 v[52:55], v[166:169], v[188:191], v[52:55]
	v_mfma_f32_16x16x32_bf16 v[48:51], v[170:173], v[184:187], v[48:51]
	v_mfma_f32_16x16x32_bf16 v[48:51], v[174:177], v[188:191], v[48:51]
	v_mfma_f32_16x16x32_bf16 v[36:39], v[162:165], v[192:195], v[36:39]
	v_mfma_f32_16x16x32_bf16 v[36:39], v[166:169], v[196:199], v[36:39]
	v_mfma_f32_16x16x32_bf16 v[32:35], v[170:173], v[192:195], v[32:35]
	v_mfma_f32_16x16x32_bf16 v[32:35], v[174:177], v[196:199], v[32:35]
	v_mfma_f32_16x16x32_bf16 v[20:23], v[162:165], v[200:203], v[20:23]
	v_mfma_f32_16x16x32_bf16 v[20:23], v[166:169], v[204:207], v[20:23]
	v_mfma_f32_16x16x32_bf16 v[16:19], v[170:173], v[200:203], v[16:19]
	v_mfma_f32_16x16x32_bf16 v[16:19], v[174:177], v[204:207], v[16:19]
	v_mfma_f32_16x16x32_bf16 v[4:7], v[162:165], v[208:211], v[4:7]
	v_mfma_f32_16x16x32_bf16 v[4:7], v[166:169], v[212:215], v[4:7]
	v_mfma_f32_16x16x32_bf16 v[0:3], v[170:173], v[208:211], v[0:3]
	v_mfma_f32_16x16x32_bf16 v[0:3], v[174:177], v[212:215], v[0:3]
	s_setprio 0
	s_barrier
.Lmid_gemm11:
	s_add_i32 s71, 0, 0x18000
	s_add_i32 s72, 0, 0x1c000
	v_add_u32_e32 v158, s71, v145
	v_add_u32_e32 v174, s72, v145
	s_add_u32 s50, s50, 0x40000
	s_addc_u32 s51, s51, 0
	s_mov_b32 m0, s57
	v_lshl_add_u64 v[222:223], s[50:51], 0, v[130:131]
	global_load_lds_dwordx4 v[222:223], off
	v_lshl_add_u64 v[222:223], s[50:51], 0, v[128:129]
	s_mov_b32 m0, s58
	s_nop 0
	global_load_lds_dwordx4 v[222:223], off
	ds_read_b128 v[140:143], v158
	ds_read_b128 v[150:153], v158 offset:1024
	ds_read_b128 v[154:157], v158 offset:2048
	ds_read_b128 v[158:161], v158 offset:3072
	ds_read_b128 v[162:165], v174
	ds_read_b128 v[166:169], v174 offset:1024
	ds_read_b128 v[170:173], v174 offset:2048
	ds_read_b128 v[174:177], v174 offset:3072
	ds_read_b128 v[184:187], v149 offset:32768
	ds_read_b128 v[188:191], v149 offset:33792
	ds_read_b128 v[192:195], v149 offset:34816
	ds_read_b128 v[196:199], v149 offset:35840
	ds_read_b128 v[200:203], v149 offset:36864
	ds_read_b128 v[204:207], v149 offset:37888
	ds_read_b128 v[208:211], v149 offset:38912
	ds_read_b128 v[212:215], v149 offset:39936
	s_waitcnt vmcnt(8)
	s_waitcnt lgkmcnt(0)
	s_barrier
	s_setprio 1
	s_waitcnt lgkmcnt(0)
	v_mfma_f32_16x16x32_bf16 v[124:127], v[140:143], v[184:187], v[124:127]
	v_mfma_f32_16x16x32_bf16 v[124:127], v[150:153], v[188:191], v[124:127]
	v_mfma_f32_16x16x32_bf16 v[120:123], v[154:157], v[184:187], v[120:123]
	v_mfma_f32_16x16x32_bf16 v[120:123], v[158:161], v[188:191], v[120:123]
	v_mfma_f32_16x16x32_bf16 v[108:111], v[140:143], v[192:195], v[108:111]
	v_mfma_f32_16x16x32_bf16 v[108:111], v[150:153], v[196:199], v[108:111]
	v_mfma_f32_16x16x32_bf16 v[104:107], v[154:157], v[192:195], v[104:107]
	v_mfma_f32_16x16x32_bf16 v[104:107], v[158:161], v[196:199], v[104:107]
	v_mfma_f32_16x16x32_bf16 v[92:95], v[140:143], v[200:203], v[92:95]
	v_mfma_f32_16x16x32_bf16 v[92:95], v[150:153], v[204:207], v[92:95]
	v_mfma_f32_16x16x32_bf16 v[88:91], v[154:157], v[200:203], v[88:91]
	v_mfma_f32_16x16x32_bf16 v[88:91], v[158:161], v[204:207], v[88:91]
	v_mfma_f32_16x16x32_bf16 v[76:79], v[140:143], v[208:211], v[76:79]
	v_mfma_f32_16x16x32_bf16 v[76:79], v[150:153], v[212:215], v[76:79]
	v_mfma_f32_16x16x32_bf16 v[72:75], v[154:157], v[208:211], v[72:75]
	v_mfma_f32_16x16x32_bf16 v[72:75], v[158:161], v[212:215], v[72:75]
	v_mfma_f32_16x16x32_bf16 v[116:119], v[162:165], v[184:187], v[116:119]
	v_mfma_f32_16x16x32_bf16 v[116:119], v[166:169], v[188:191], v[116:119]
	v_mfma_f32_16x16x32_bf16 v[112:115], v[170:173], v[184:187], v[112:115]
	v_mfma_f32_16x16x32_bf16 v[112:115], v[174:177], v[188:191], v[112:115]
	v_mfma_f32_16x16x32_bf16 v[100:103], v[162:165], v[192:195], v[100:103]
	v_mfma_f32_16x16x32_bf16 v[100:103], v[166:169], v[196:199], v[100:103]
	v_mfma_f32_16x16x32_bf16 v[96:99], v[170:173], v[192:195], v[96:99]
	v_mfma_f32_16x16x32_bf16 v[96:99], v[174:177], v[196:199], v[96:99]
	v_mfma_f32_16x16x32_bf16 v[84:87], v[162:165], v[200:203], v[84:87]
	v_mfma_f32_16x16x32_bf16 v[84:87], v[166:169], v[204:207], v[84:87]
	v_mfma_f32_16x16x32_bf16 v[80:83], v[170:173], v[200:203], v[80:83]
	v_mfma_f32_16x16x32_bf16 v[80:83], v[174:177], v[204:207], v[80:83]
	v_mfma_f32_16x16x32_bf16 v[68:71], v[162:165], v[208:211], v[68:71]
	v_mfma_f32_16x16x32_bf16 v[68:71], v[166:169], v[212:215], v[68:71]
	v_mfma_f32_16x16x32_bf16 v[64:67], v[170:173], v[208:211], v[64:67]
	v_mfma_f32_16x16x32_bf16 v[64:67], v[174:177], v[212:215], v[64:67]
	s_setprio 0
	s_barrier
	s_add_i32 s50, s71, s54
	v_lshl_add_u64 v[178:179], v[178:179], 0, s[10:11]
	s_mov_b32 m0, s50
	s_nop 0
	global_load_lds_dwordx4 v[178:179], off
	s_add_i32 m0, s50, 0x2000
	s_add_u32 s48, s48, 0x40080
	v_lshl_add_u64 v[178:179], v[216:217], 0, s[10:11]
	s_addc_u32 s49, s49, 0
	s_add_i32 s50, s72, s54
	global_load_lds_dwordx4 v[178:179], off
	v_lshl_add_u64 v[178:179], s[48:49], 0, v[130:131]
	s_mov_b32 m0, s50
	s_nop 0
	global_load_lds_dwordx4 v[178:179], off
	v_lshl_add_u64 v[178:179], s[48:49], 0, v[128:129]
	s_add_i32 m0, s50, 0x2000
	s_nop 0
	global_load_lds_dwordx4 v[178:179], off
	v_lshl_add_u64 v[178:179], v[218:219], 0, s[10:11]
	s_mov_b32 m0, s60
	s_nop 0
	global_load_lds_dwordx4 v[178:179], off
	v_lshl_add_u64 v[178:179], v[220:221], 0, s[10:11]
	s_mov_b32 m0, s61
	s_nop 0
	global_load_lds_dwordx4 v[178:179], off
	ds_read_b128 v[184:187], v149 offset:49152
	ds_read_b128 v[188:191], v149 offset:50176
	ds_read_b128 v[192:195], v149 offset:51200
	ds_read_b128 v[196:199], v149 offset:52224
	ds_read_b128 v[200:203], v149 offset:53248
	ds_read_b128 v[204:207], v149 offset:54272
	ds_read_b128 v[208:211], v149 offset:55296
	ds_read_b128 v[212:215], v149 offset:56320
	s_waitcnt vmcnt(8)
	s_waitcnt lgkmcnt(0)
	s_barrier
	s_setprio 1
	s_waitcnt lgkmcnt(0)
	v_mfma_f32_16x16x32_bf16 v[60:63], v[140:143], v[184:187], v[60:63]
	v_mfma_f32_16x16x32_bf16 v[60:63], v[150:153], v[188:191], v[60:63]
	v_mfma_f32_16x16x32_bf16 v[56:59], v[154:157], v[184:187], v[56:59]
	v_mfma_f32_16x16x32_bf16 v[56:59], v[158:161], v[188:191], v[56:59]
	v_mfma_f32_16x16x32_bf16 v[44:47], v[140:143], v[192:195], v[44:47]
	v_mfma_f32_16x16x32_bf16 v[44:47], v[150:153], v[196:199], v[44:47]
	v_mfma_f32_16x16x32_bf16 v[40:43], v[154:157], v[192:195], v[40:43]
	v_mfma_f32_16x16x32_bf16 v[40:43], v[158:161], v[196:199], v[40:43]
	v_mfma_f32_16x16x32_bf16 v[28:31], v[140:143], v[200:203], v[28:31]
	v_mfma_f32_16x16x32_bf16 v[28:31], v[150:153], v[204:207], v[28:31]
	v_mfma_f32_16x16x32_bf16 v[24:27], v[154:157], v[200:203], v[24:27]
	v_mfma_f32_16x16x32_bf16 v[24:27], v[158:161], v[204:207], v[24:27]
	v_mfma_f32_16x16x32_bf16 v[12:15], v[140:143], v[208:211], v[12:15]
	v_mfma_f32_16x16x32_bf16 v[12:15], v[150:153], v[212:215], v[12:15]
	v_mfma_f32_16x16x32_bf16 v[8:11], v[154:157], v[208:211], v[8:11]
	v_mfma_f32_16x16x32_bf16 v[8:11], v[158:161], v[212:215], v[8:11]
	v_mfma_f32_16x16x32_bf16 v[52:55], v[162:165], v[184:187], v[52:55]
	v_mfma_f32_16x16x32_bf16 v[52:55], v[166:169], v[188:191], v[52:55]
	v_mfma_f32_16x16x32_bf16 v[48:51], v[170:173], v[184:187], v[48:51]
	v_mfma_f32_16x16x32_bf16 v[48:51], v[174:177], v[188:191], v[48:51]
	v_mfma_f32_16x16x32_bf16 v[36:39], v[162:165], v[192:195], v[36:39]
	v_mfma_f32_16x16x32_bf16 v[36:39], v[166:169], v[196:199], v[36:39]
	v_mfma_f32_16x16x32_bf16 v[32:35], v[170:173], v[192:195], v[32:35]
	v_mfma_f32_16x16x32_bf16 v[32:35], v[174:177], v[196:199], v[32:35]
	v_mfma_f32_16x16x32_bf16 v[20:23], v[162:165], v[200:203], v[20:23]
	v_mfma_f32_16x16x32_bf16 v[20:23], v[166:169], v[204:207], v[20:23]
	v_mfma_f32_16x16x32_bf16 v[16:19], v[170:173], v[200:203], v[16:19]
	v_mfma_f32_16x16x32_bf16 v[16:19], v[174:177], v[204:207], v[16:19]
	v_mfma_f32_16x16x32_bf16 v[4:7], v[162:165], v[208:211], v[4:7]
	v_mfma_f32_16x16x32_bf16 v[4:7], v[166:169], v[212:215], v[4:7]
	v_mfma_f32_16x16x32_bf16 v[0:3], v[170:173], v[208:211], v[0:3]
	v_mfma_f32_16x16x32_bf16 v[0:3], v[174:177], v[212:215], v[0:3]
	s_setprio 0
	s_barrier
	s_add_i32 s70, s70, 2
	s_add_u32 s46, s46, 0x100
	s_addc_u32 s47, s47, 0
	s_add_u32 s68, s68, 0x100
	s_addc_u32 s69, s69, 0
	s_cmp_gt_u32 s70, 13
	s_cbranch_scc0 .LBB0_1434
	s_and_b64 vcc, exec, s[12:13]
	s_cbranch_vccz .LBB0_1437
	s_barrier

.LBB0_1513:
	s_add_u32 s74, s48, 0x100
	s_addc_u32 s75, s49, 0
	s_mov_b32 s76, -2
	ds_read_b128 v[152:155], v149
	ds_read_b128 v[156:159], v149 offset:1024
	ds_read_b128 v[160:163], v149 offset:2048
	ds_read_b128 v[164:167], v149 offset:3072
	ds_read_b128 v[168:171], v150
	ds_read_b128 v[172:175], v150 offset:1024
	ds_read_b128 v[176:179], v150 offset:2048
	ds_read_b128 v[184:187], v150 offset:3072
	s_add_u32 s48, s46, 0x100
	s_addc_u32 s49, s47, 0
	s_cmp_eq_u32 s76, 40
	s_cselect_b32 s53, s9, s49
	s_cselect_b32 s52, s8, s48
	s_cselect_b32 s51, s45, s75
	s_cselect_b32 s50, s44, s74
	v_lshl_add_u64 v[144:145], s[46:47], 0, v[136:137]
	s_add_i32 m0, s57, 0xc000
	ds_read_b128 v[188:191], v151
	ds_read_b128 v[192:195], v151 offset:1024
	ds_read_b128 v[196:199], v151 offset:2048
	ds_read_b128 v[200:203], v151 offset:3072
	ds_read_b128 v[204:207], v151 offset:4096
	ds_read_b128 v[208:211], v151 offset:5120
	ds_read_b128 v[212:215], v151 offset:6144
	ds_read_b128 v[216:219], v151 offset:7168
	global_load_lds_dwordx4 v[144:145], off
	v_lshl_add_u64 v[144:145], s[46:47], 0, v[138:139]
	s_add_i32 m0, s57, 0xe000
	s_nop 0
	global_load_lds_dwordx4 v[144:145], off
	s_waitcnt vmcnt(8)
	s_waitcnt lgkmcnt(0)
	s_barrier
	s_setprio 1
	s_waitcnt lgkmcnt(0)
	v_mfma_f32_16x16x32_bf16 v[124:127], v[152:155], v[188:191], 0
	v_mfma_f32_16x16x32_bf16 v[124:127], v[156:159], v[192:195], v[124:127]
	v_mfma_f32_16x16x32_bf16 v[120:123], v[160:163], v[188:191], 0
	v_mfma_f32_16x16x32_bf16 v[120:123], v[164:167], v[192:195], v[120:123]
	v_mfma_f32_16x16x32_bf16 v[116:119], v[152:155], v[196:199], 0
	v_mfma_f32_16x16x32_bf16 v[116:119], v[156:159], v[200:203], v[116:119]
	v_mfma_f32_16x16x32_bf16 v[108:111], v[160:163], v[196:199], 0
	v_mfma_f32_16x16x32_bf16 v[108:111], v[164:167], v[200:203], v[108:111]
	v_mfma_f32_16x16x32_bf16 v[100:103], v[152:155], v[204:207], 0
	v_mfma_f32_16x16x32_bf16 v[100:103], v[156:159], v[208:211], v[100:103]
	v_mfma_f32_16x16x32_bf16 v[92:95], v[160:163], v[204:207], 0
	v_mfma_f32_16x16x32_bf16 v[92:95], v[164:167], v[208:211], v[92:95]
	v_mfma_f32_16x16x32_bf16 v[84:87], v[152:155], v[212:215], 0
	v_mfma_f32_16x16x32_bf16 v[84:87], v[156:159], v[216:219], v[84:87]
	v_mfma_f32_16x16x32_bf16 v[76:79], v[160:163], v[212:215], 0
	v_mfma_f32_16x16x32_bf16 v[76:79], v[164:167], v[216:219], v[76:79]
	v_mfma_f32_16x16x32_bf16 v[112:115], v[168:171], v[188:191], 0
	v_mfma_f32_16x16x32_bf16 v[112:115], v[172:175], v[192:195], v[112:115]
	v_mfma_f32_16x16x32_bf16 v[104:107], v[176:179], v[188:191], 0
	v_mfma_f32_16x16x32_bf16 v[104:107], v[184:187], v[192:195], v[104:107]
	v_mfma_f32_16x16x32_bf16 v[96:99], v[168:171], v[196:199], 0
	v_mfma_f32_16x16x32_bf16 v[96:99], v[172:175], v[200:203], v[96:99]
	v_mfma_f32_16x16x32_bf16 v[88:91], v[176:179], v[196:199], 0
	v_mfma_f32_16x16x32_bf16 v[88:91], v[184:187], v[200:203], v[88:91]
	v_mfma_f32_16x16x32_bf16 v[80:83], v[168:171], v[204:207], 0
	v_mfma_f32_16x16x32_bf16 v[80:83], v[172:175], v[208:211], v[80:83]
	v_mfma_f32_16x16x32_bf16 v[72:75], v[176:179], v[204:207], 0
	v_mfma_f32_16x16x32_bf16 v[72:75], v[184:187], v[208:211], v[72:75]
	v_mfma_f32_16x16x32_bf16 v[68:71], v[168:171], v[212:215], 0
	v_mfma_f32_16x16x32_bf16 v[68:71], v[172:175], v[216:219], v[68:71]
	v_mfma_f32_16x16x32_bf16 v[64:67], v[176:179], v[212:215], 0
	v_mfma_f32_16x16x32_bf16 v[64:67], v[184:187], v[216:219], v[64:67]
	s_setprio 0
	s_barrier
	s_add_i32 s46, s64, s56
	v_lshl_add_u64 v[144:145], s[50:51], 0, v[130:131]
	s_mov_b32 m0, s46
	s_nop 0
	global_load_lds_dwordx4 v[144:145], off
	s_add_i32 m0, s46, 0x2000
	s_add_u32 s46, s50, 0xb0000
	v_lshl_add_u64 v[220:221], s[50:51], 0, v[134:135]
	s_addc_u32 s47, s51, 0
	s_add_i32 s77, s65, s56
	global_load_lds_dwordx4 v[220:221], off
	v_lshl_add_u64 v[222:223], s[46:47], 0, v[130:131]
	s_mov_b32 m0, s77
	v_lshl_add_u64 v[224:225], s[52:53], 0, v[132:133]
	global_load_lds_dwordx4 v[222:223], off
	v_lshl_add_u64 v[222:223], s[46:47], 0, v[134:135]
	s_add_i32 m0, s77, 0x2000
	s_nop 0
	global_load_lds_dwordx4 v[222:223], off
	v_lshl_add_u64 v[222:223], s[52:53], 0, v[128:129]
	s_mov_b32 m0, s57
	s_nop 0
	global_load_lds_dwordx4 v[222:223], off
	s_mov_b32 m0, s58
	s_nop 0
	global_load_lds_dwordx4 v[224:225], off
	ds_read_b128 v[188:191], v151 offset:16384
	ds_read_b128 v[192:195], v151 offset:17408
	ds_read_b128 v[196:199], v151 offset:18432
	ds_read_b128 v[200:203], v151 offset:19456
	ds_read_b128 v[204:207], v151 offset:20480
	ds_read_b128 v[208:211], v151 offset:21504
	ds_read_b128 v[212:215], v151 offset:22528
	ds_read_b128 v[216:219], v151 offset:23552
	s_waitcnt vmcnt(8)
	s_waitcnt lgkmcnt(0)
	s_barrier
	s_setprio 1
	s_waitcnt lgkmcnt(0)
	v_mfma_f32_16x16x32_bf16 v[60:63], v[152:155], v[188:191], 0
	v_mfma_f32_16x16x32_bf16 v[60:63], v[156:159], v[192:195], v[60:63]
	v_mfma_f32_16x16x32_bf16 v[56:59], v[160:163], v[188:191], 0
	v_mfma_f32_16x16x32_bf16 v[56:59], v[164:167], v[192:195], v[56:59]
	v_mfma_f32_16x16x32_bf16 v[52:55], v[152:155], v[196:199], 0
	v_mfma_f32_16x16x32_bf16 v[52:55], v[156:159], v[200:203], v[52:55]
	v_mfma_f32_16x16x32_bf16 v[44:47], v[160:163], v[196:199], 0
	v_mfma_f32_16x16x32_bf16 v[44:47], v[164:167], v[200:203], v[44:47]
	v_mfma_f32_16x16x32_bf16 v[36:39], v[152:155], v[204:207], 0
	v_mfma_f32_16x16x32_bf16 v[36:39], v[156:159], v[208:211], v[36:39]
	v_mfma_f32_16x16x32_bf16 v[28:31], v[160:163], v[204:207], 0
	v_mfma_f32_16x16x32_bf16 v[28:31], v[164:167], v[208:211], v[28:31]
	v_mfma_f32_16x16x32_bf16 v[20:23], v[152:155], v[212:215], 0
	v_mfma_f32_16x16x32_bf16 v[20:23], v[156:159], v[216:219], v[20:23]
	v_mfma_f32_16x16x32_bf16 v[12:15], v[160:163], v[212:215], 0
	v_mfma_f32_16x16x32_bf16 v[12:15], v[164:167], v[216:219], v[12:15]
	v_mfma_f32_16x16x32_bf16 v[48:51], v[168:171], v[188:191], 0
	v_mfma_f32_16x16x32_bf16 v[48:51], v[172:175], v[192:195], v[48:51]
	v_mfma_f32_16x16x32_bf16 v[40:43], v[176:179], v[188:191], 0
	v_mfma_f32_16x16x32_bf16 v[40:43], v[184:187], v[192:195], v[40:43]
	v_mfma_f32_16x16x32_bf16 v[32:35], v[168:171], v[196:199], 0
	v_mfma_f32_16x16x32_bf16 v[32:35], v[172:175], v[200:203], v[32:35]
	v_mfma_f32_16x16x32_bf16 v[24:27], v[176:179], v[196:199], 0
	v_mfma_f32_16x16x32_bf16 v[24:27], v[184:187], v[200:203], v[24:27]
	v_mfma_f32_16x16x32_bf16 v[16:19], v[168:171], v[204:207], 0
	v_mfma_f32_16x16x32_bf16 v[16:19], v[172:175], v[208:211], v[16:19]
	v_mfma_f32_16x16x32_bf16 v[8:11], v[176:179], v[204:207], 0
	v_mfma_f32_16x16x32_bf16 v[8:11], v[184:187], v[208:211], v[8:11]
	v_mfma_f32_16x16x32_bf16 v[4:7], v[168:171], v[212:215], 0
	v_mfma_f32_16x16x32_bf16 v[4:7], v[172:175], v[216:219], v[4:7]
	v_mfma_f32_16x16x32_bf16 v[0:3], v[176:179], v[212:215], 0
	v_mfma_f32_16x16x32_bf16 v[0:3], v[184:187], v[216:219], v[0:3]
	s_setprio 0
	s_barrier
	s_branch .Lmid_gemm12
.LBB0_1514:
	s_add_u32 s48, s46, 0x100
	s_addc_u32 s49, s47, 0
	s_cmp_eq_u32 s76, 40
	s_cselect_b32 s53, s9, s49
	s_cselect_b32 s52, s8, s48
	s_cselect_b32 s51, s45, s75
	s_cselect_b32 s50, s44, s74
	v_lshl_add_u64 v[144:145], s[46:47], 0, v[136:137]
	s_add_i32 m0, s57, 0xc000
	s_nop 0
	global_load_lds_dwordx4 v[144:145], off
	v_lshl_add_u64 v[144:145], s[46:47], 0, v[138:139]
	s_add_i32 m0, s57, 0xe000
	s_nop 0
	global_load_lds_dwordx4 v[144:145], off
	ds_read_b128 v[152:155], v149
	ds_read_b128 v[156:159], v149 offset:1024
	ds_read_b128 v[160:163], v149 offset:2048
	ds_read_b128 v[164:167], v149 offset:3072
	ds_read_b128 v[168:171], v150
	ds_read_b128 v[172:175], v150 offset:1024
	ds_read_b128 v[176:179], v150 offset:2048
	ds_read_b128 v[184:187], v150 offset:3072
	ds_read_b128 v[188:191], v151
	ds_read_b128 v[192:195], v151 offset:1024
	ds_read_b128 v[196:199], v151 offset:2048
	ds_read_b128 v[200:203], v151 offset:3072
	ds_read_b128 v[204:207], v151 offset:4096
	ds_read_b128 v[208:211], v151 offset:5120
	ds_read_b128 v[212:215], v151 offset:6144
	ds_read_b128 v[216:219], v151 offset:7168
	s_waitcnt vmcnt(8)
	s_waitcnt lgkmcnt(0)
	s_barrier
	s_setprio 1
	s_waitcnt lgkmcnt(0)
	v_mfma_f32_16x16x32_bf16 v[124:127], v[152:155], v[188:191], v[124:127]
	v_mfma_f32_16x16x32_bf16 v[124:127], v[156:159], v[192:195], v[124:127]
	v_mfma_f32_16x16x32_bf16 v[120:123], v[160:163], v[188:191], v[120:123]
	v_mfma_f32_16x16x32_bf16 v[120:123], v[164:167], v[192:195], v[120:123]
	v_mfma_f32_16x16x32_bf16 v[116:119], v[152:155], v[196:199], v[116:119]
	v_mfma_f32_16x16x32_bf16 v[116:119], v[156:159], v[200:203], v[116:119]
	v_mfma_f32_16x16x32_bf16 v[108:111], v[160:163], v[196:199], v[108:111]
	v_mfma_f32_16x16x32_bf16 v[108:111], v[164:167], v[200:203], v[108:111]
	v_mfma_f32_16x16x32_bf16 v[100:103], v[152:155], v[204:207], v[100:103]
	v_mfma_f32_16x16x32_bf16 v[100:103], v[156:159], v[208:211], v[100:103]
	v_mfma_f32_16x16x32_bf16 v[92:95], v[160:163], v[204:207], v[92:95]
	v_mfma_f32_16x16x32_bf16 v[92:95], v[164:167], v[208:211], v[92:95]
	v_mfma_f32_16x16x32_bf16 v[84:87], v[152:155], v[212:215], v[84:87]
	v_mfma_f32_16x16x32_bf16 v[84:87], v[156:159], v[216:219], v[84:87]
	v_mfma_f32_16x16x32_bf16 v[76:79], v[160:163], v[212:215], v[76:79]
	v_mfma_f32_16x16x32_bf16 v[76:79], v[164:167], v[216:219], v[76:79]
	v_mfma_f32_16x16x32_bf16 v[112:115], v[168:171], v[188:191], v[112:115]
	v_mfma_f32_16x16x32_bf16 v[112:115], v[172:175], v[192:195], v[112:115]
	v_mfma_f32_16x16x32_bf16 v[104:107], v[176:179], v[188:191], v[104:107]
	v_mfma_f32_16x16x32_bf16 v[104:107], v[184:187], v[192:195], v[104:107]
	v_mfma_f32_16x16x32_bf16 v[96:99], v[168:171], v[196:199], v[96:99]
	v_mfma_f32_16x16x32_bf16 v[96:99], v[172:175], v[200:203], v[96:99]
	v_mfma_f32_16x16x32_bf16 v[88:91], v[176:179], v[196:199], v[88:91]
	v_mfma_f32_16x16x32_bf16 v[88:91], v[184:187], v[200:203], v[88:91]
	v_mfma_f32_16x16x32_bf16 v[80:83], v[168:171], v[204:207], v[80:83]
	v_mfma_f32_16x16x32_bf16 v[80:83], v[172:175], v[208:211], v[80:83]
	v_mfma_f32_16x16x32_bf16 v[72:75], v[176:179], v[204:207], v[72:75]
	v_mfma_f32_16x16x32_bf16 v[72:75], v[184:187], v[208:211], v[72:75]
	v_mfma_f32_16x16x32_bf16 v[68:71], v[168:171], v[212:215], v[68:71]
	v_mfma_f32_16x16x32_bf16 v[68:71], v[172:175], v[216:219], v[68:71]
	v_mfma_f32_16x16x32_bf16 v[64:67], v[176:179], v[212:215], v[64:67]
	v_mfma_f32_16x16x32_bf16 v[64:67], v[184:187], v[216:219], v[64:67]
	s_setprio 0
	s_barrier
	s_add_i32 s46, s64, s56
	v_lshl_add_u64 v[144:145], s[50:51], 0, v[130:131]
	s_mov_b32 m0, s46
	s_nop 0
	global_load_lds_dwordx4 v[144:145], off
	s_add_i32 m0, s46, 0x2000
	s_add_u32 s46, s50, 0xb0000
	v_lshl_add_u64 v[220:221], s[50:51], 0, v[134:135]
	s_addc_u32 s47, s51, 0
	s_add_i32 s77, s65, s56
	global_load_lds_dwordx4 v[220:221], off
	v_lshl_add_u64 v[222:223], s[46:47], 0, v[130:131]
	s_mov_b32 m0, s77
	v_lshl_add_u64 v[224:225], s[52:53], 0, v[132:133]
	global_load_lds_dwordx4 v[222:223], off
	v_lshl_add_u64 v[222:223], s[46:47], 0, v[134:135]
	s_add_i32 m0, s77, 0x2000
	s_nop 0
	global_load_lds_dwordx4 v[222:223], off
	v_lshl_add_u64 v[222:223], s[52:53], 0, v[128:129]
	s_mov_b32 m0, s57
	s_nop 0
	global_load_lds_dwordx4 v[222:223], off
	s_mov_b32 m0, s58
	s_nop 0
	global_load_lds_dwordx4 v[224:225], off
	ds_read_b128 v[188:191], v151 offset:16384
	ds_read_b128 v[192:195], v151 offset:17408
	ds_read_b128 v[196:199], v151 offset:18432
	ds_read_b128 v[200:203], v151 offset:19456
	ds_read_b128 v[204:207], v151 offset:20480
	ds_read_b128 v[208:211], v151 offset:21504
	ds_read_b128 v[212:215], v151 offset:22528
	ds_read_b128 v[216:219], v151 offset:23552
	s_waitcnt vmcnt(8)
	s_waitcnt lgkmcnt(0)
	s_barrier
	s_setprio 1
	s_waitcnt lgkmcnt(0)
	v_mfma_f32_16x16x32_bf16 v[60:63], v[152:155], v[188:191], v[60:63]
	v_mfma_f32_16x16x32_bf16 v[60:63], v[156:159], v[192:195], v[60:63]
	v_mfma_f32_16x16x32_bf16 v[56:59], v[160:163], v[188:191], v[56:59]
	v_mfma_f32_16x16x32_bf16 v[56:59], v[164:167], v[192:195], v[56:59]
	v_mfma_f32_16x16x32_bf16 v[52:55], v[152:155], v[196:199], v[52:55]
	v_mfma_f32_16x16x32_bf16 v[52:55], v[156:159], v[200:203], v[52:55]
	v_mfma_f32_16x16x32_bf16 v[44:47], v[160:163], v[196:199], v[44:47]
	v_mfma_f32_16x16x32_bf16 v[44:47], v[164:167], v[200:203], v[44:47]
	v_mfma_f32_16x16x32_bf16 v[36:39], v[152:155], v[204:207], v[36:39]
	v_mfma_f32_16x16x32_bf16 v[36:39], v[156:159], v[208:211], v[36:39]
	v_mfma_f32_16x16x32_bf16 v[28:31], v[160:163], v[204:207], v[28:31]
	v_mfma_f32_16x16x32_bf16 v[28:31], v[164:167], v[208:211], v[28:31]
	v_mfma_f32_16x16x32_bf16 v[20:23], v[152:155], v[212:215], v[20:23]
	v_mfma_f32_16x16x32_bf16 v[20:23], v[156:159], v[216:219], v[20:23]
	v_mfma_f32_16x16x32_bf16 v[12:15], v[160:163], v[212:215], v[12:15]
	v_mfma_f32_16x16x32_bf16 v[12:15], v[164:167], v[216:219], v[12:15]
	v_mfma_f32_16x16x32_bf16 v[48:51], v[168:171], v[188:191], v[48:51]
	v_mfma_f32_16x16x32_bf16 v[48:51], v[172:175], v[192:195], v[48:51]
	v_mfma_f32_16x16x32_bf16 v[40:43], v[176:179], v[188:191], v[40:43]
	v_mfma_f32_16x16x32_bf16 v[40:43], v[184:187], v[192:195], v[40:43]
	v_mfma_f32_16x16x32_bf16 v[32:35], v[168:171], v[196:199], v[32:35]
	v_mfma_f32_16x16x32_bf16 v[32:35], v[172:175], v[200:203], v[32:35]
	v_mfma_f32_16x16x32_bf16 v[24:27], v[176:179], v[196:199], v[24:27]
	v_mfma_f32_16x16x32_bf16 v[24:27], v[184:187], v[200:203], v[24:27]
	v_mfma_f32_16x16x32_bf16 v[16:19], v[168:171], v[204:207], v[16:19]
	v_mfma_f32_16x16x32_bf16 v[16:19], v[172:175], v[208:211], v[16:19]
	v_mfma_f32_16x16x32_bf16 v[8:11], v[176:179], v[204:207], v[8:11]
	v_mfma_f32_16x16x32_bf16 v[8:11], v[184:187], v[208:211], v[8:11]
	v_mfma_f32_16x16x32_bf16 v[4:7], v[168:171], v[212:215], v[4:7]
	v_mfma_f32_16x16x32_bf16 v[4:7], v[172:175], v[216:219], v[4:7]
	v_mfma_f32_16x16x32_bf16 v[0:3], v[176:179], v[212:215], v[0:3]
	v_mfma_f32_16x16x32_bf16 v[0:3], v[184:187], v[216:219], v[0:3]
	s_setprio 0
	s_barrier
.Lmid_gemm12:
	s_add_i32 s77, 0, 0x18000
	s_add_i32 s79, 0, 0x1c000
	v_add_u32_e32 v164, s77, v147
	v_add_u32_e32 v181, s79, v147
	s_add_u32 s46, s52, 0xb0000
	s_addc_u32 s47, s53, 0
	s_mov_b32 m0, s59
	v_lshl_add_u64 v[226:227], s[46:47], 0, v[128:129]
	global_load_lds_dwordx4 v[226:227], off
	v_lshl_add_u64 v[226:227], s[46:47], 0, v[132:133]
	s_mov_b32 m0, s60
	s_nop 0
	global_load_lds_dwordx4 v[226:227], off
	ds_read_b128 v[152:155], v164
	ds_read_b128 v[156:159], v164 offset:1024
	ds_read_b128 v[160:163], v164 offset:2048
	ds_read_b128 v[164:167], v164 offset:3072
	ds_read_b128 v[168:171], v181
	ds_read_b128 v[172:175], v181 offset:1024
	ds_read_b128 v[176:179], v181 offset:2048
	ds_read_b128 v[184:187], v181 offset:3072
	ds_read_b128 v[188:191], v151 offset:32768
	ds_read_b128 v[192:195], v151 offset:33792
	ds_read_b128 v[196:199], v151 offset:34816
	ds_read_b128 v[200:203], v151 offset:35840
	ds_read_b128 v[204:207], v151 offset:36864
	ds_read_b128 v[208:211], v151 offset:37888
	ds_read_b128 v[212:215], v151 offset:38912
	ds_read_b128 v[216:219], v151 offset:39936
	s_waitcnt vmcnt(8)
	s_waitcnt lgkmcnt(0)
	s_barrier
	s_setprio 1
	s_waitcnt lgkmcnt(0)
	v_mfma_f32_16x16x32_bf16 v[124:127], v[152:155], v[188:191], v[124:127]
	v_mfma_f32_16x16x32_bf16 v[124:127], v[156:159], v[192:195], v[124:127]
	v_mfma_f32_16x16x32_bf16 v[120:123], v[160:163], v[188:191], v[120:123]
	v_mfma_f32_16x16x32_bf16 v[120:123], v[164:167], v[192:195], v[120:123]
	v_mfma_f32_16x16x32_bf16 v[116:119], v[152:155], v[196:199], v[116:119]
	v_mfma_f32_16x16x32_bf16 v[116:119], v[156:159], v[200:203], v[116:119]
	v_mfma_f32_16x16x32_bf16 v[108:111], v[160:163], v[196:199], v[108:111]
	v_mfma_f32_16x16x32_bf16 v[108:111], v[164:167], v[200:203], v[108:111]
	v_mfma_f32_16x16x32_bf16 v[100:103], v[152:155], v[204:207], v[100:103]
	v_mfma_f32_16x16x32_bf16 v[100:103], v[156:159], v[208:211], v[100:103]
	v_mfma_f32_16x16x32_bf16 v[92:95], v[160:163], v[204:207], v[92:95]
	v_mfma_f32_16x16x32_bf16 v[92:95], v[164:167], v[208:211], v[92:95]
	v_mfma_f32_16x16x32_bf16 v[84:87], v[152:155], v[212:215], v[84:87]
	v_mfma_f32_16x16x32_bf16 v[84:87], v[156:159], v[216:219], v[84:87]
	v_mfma_f32_16x16x32_bf16 v[76:79], v[160:163], v[212:215], v[76:79]
	v_mfma_f32_16x16x32_bf16 v[76:79], v[164:167], v[216:219], v[76:79]
	v_mfma_f32_16x16x32_bf16 v[112:115], v[168:171], v[188:191], v[112:115]
	v_mfma_f32_16x16x32_bf16 v[112:115], v[172:175], v[192:195], v[112:115]
	v_mfma_f32_16x16x32_bf16 v[104:107], v[176:179], v[188:191], v[104:107]
	v_mfma_f32_16x16x32_bf16 v[104:107], v[184:187], v[192:195], v[104:107]
	v_mfma_f32_16x16x32_bf16 v[96:99], v[168:171], v[196:199], v[96:99]
	v_mfma_f32_16x16x32_bf16 v[96:99], v[172:175], v[200:203], v[96:99]
	v_mfma_f32_16x16x32_bf16 v[88:91], v[176:179], v[196:199], v[88:91]
	v_mfma_f32_16x16x32_bf16 v[88:91], v[184:187], v[200:203], v[88:91]
	v_mfma_f32_16x16x32_bf16 v[80:83], v[168:171], v[204:207], v[80:83]
	v_mfma_f32_16x16x32_bf16 v[80:83], v[172:175], v[208:211], v[80:83]
	v_mfma_f32_16x16x32_bf16 v[72:75], v[176:179], v[204:207], v[72:75]
	v_mfma_f32_16x16x32_bf16 v[72:75], v[184:187], v[208:211], v[72:75]
	v_mfma_f32_16x16x32_bf16 v[68:71], v[168:171], v[212:215], v[68:71]
	v_mfma_f32_16x16x32_bf16 v[68:71], v[172:175], v[216:219], v[68:71]
	v_mfma_f32_16x16x32_bf16 v[64:67], v[176:179], v[212:215], v[64:67]
	v_mfma_f32_16x16x32_bf16 v[64:67], v[184:187], v[216:219], v[64:67]
	s_setprio 0
	s_barrier
	s_add_i32 s46, s77, s56
	v_lshl_add_u64 v[144:145], v[144:145], 0, s[10:11]
	s_mov_b32 m0, s46
	s_nop 0
	global_load_lds_dwordx4 v[144:145], off
	s_add_i32 m0, s46, 0x2000
	s_add_u32 s46, s50, 0xb0080
	v_lshl_add_u64 v[144:145], v[220:221], 0, s[10:11]
	s_addc_u32 s47, s51, 0
	s_add_i32 s50, s79, s56
	global_load_lds_dwordx4 v[144:145], off
	v_lshl_add_u64 v[144:145], s[46:47], 0, v[130:131]
	s_mov_b32 m0, s50
	s_nop 0
	global_load_lds_dwordx4 v[144:145], off
	v_lshl_add_u64 v[144:145], s[46:47], 0, v[134:135]
	s_add_i32 m0, s50, 0x2000
	s_nop 0
	global_load_lds_dwordx4 v[144:145], off
	v_lshl_add_u64 v[144:145], v[222:223], 0, s[10:11]
	s_mov_b32 m0, s62
	s_nop 0
	global_load_lds_dwordx4 v[144:145], off
	v_lshl_add_u64 v[144:145], v[224:225], 0, s[10:11]
	s_mov_b32 m0, s63
	s_nop 0
	global_load_lds_dwordx4 v[144:145], off
	ds_read_b128 v[188:191], v151 offset:49152
	ds_read_b128 v[192:195], v151 offset:50176
	ds_read_b128 v[196:199], v151 offset:51200
	ds_read_b128 v[200:203], v151 offset:52224
	ds_read_b128 v[204:207], v151 offset:53248
	ds_read_b128 v[208:211], v151 offset:54272
	ds_read_b128 v[212:215], v151 offset:55296
	ds_read_b128 v[216:219], v151 offset:56320
	s_waitcnt vmcnt(8)
	s_waitcnt lgkmcnt(0)
	s_barrier
	s_setprio 1
	s_waitcnt lgkmcnt(0)
	v_mfma_f32_16x16x32_bf16 v[60:63], v[152:155], v[188:191], v[60:63]
	v_mfma_f32_16x16x32_bf16 v[60:63], v[156:159], v[192:195], v[60:63]
	v_mfma_f32_16x16x32_bf16 v[56:59], v[160:163], v[188:191], v[56:59]
	v_mfma_f32_16x16x32_bf16 v[56:59], v[164:167], v[192:195], v[56:59]
	v_mfma_f32_16x16x32_bf16 v[52:55], v[152:155], v[196:199], v[52:55]
	v_mfma_f32_16x16x32_bf16 v[52:55], v[156:159], v[200:203], v[52:55]
	v_mfma_f32_16x16x32_bf16 v[44:47], v[160:163], v[196:199], v[44:47]
	v_mfma_f32_16x16x32_bf16 v[44:47], v[164:167], v[200:203], v[44:47]
	v_mfma_f32_16x16x32_bf16 v[36:39], v[152:155], v[204:207], v[36:39]
	v_mfma_f32_16x16x32_bf16 v[36:39], v[156:159], v[208:211], v[36:39]
	v_mfma_f32_16x16x32_bf16 v[28:31], v[160:163], v[204:207], v[28:31]
	v_mfma_f32_16x16x32_bf16 v[28:31], v[164:167], v[208:211], v[28:31]
	v_mfma_f32_16x16x32_bf16 v[20:23], v[152:155], v[212:215], v[20:23]
	v_mfma_f32_16x16x32_bf16 v[20:23], v[156:159], v[216:219], v[20:23]
	v_mfma_f32_16x16x32_bf16 v[12:15], v[160:163], v[212:215], v[12:15]
	v_mfma_f32_16x16x32_bf16 v[12:15], v[164:167], v[216:219], v[12:15]
	v_mfma_f32_16x16x32_bf16 v[48:51], v[168:171], v[188:191], v[48:51]
	v_mfma_f32_16x16x32_bf16 v[48:51], v[172:175], v[192:195], v[48:51]
	v_mfma_f32_16x16x32_bf16 v[40:43], v[176:179], v[188:191], v[40:43]
	v_mfma_f32_16x16x32_bf16 v[40:43], v[184:187], v[192:195], v[40:43]
	v_mfma_f32_16x16x32_bf16 v[32:35], v[168:171], v[196:199], v[32:35]
	v_mfma_f32_16x16x32_bf16 v[32:35], v[172:175], v[200:203], v[32:35]
	v_mfma_f32_16x16x32_bf16 v[24:27], v[176:179], v[196:199], v[24:27]
	v_mfma_f32_16x16x32_bf16 v[24:27], v[184:187], v[200:203], v[24:27]
	v_mfma_f32_16x16x32_bf16 v[16:19], v[168:171], v[204:207], v[16:19]
	v_mfma_f32_16x16x32_bf16 v[16:19], v[172:175], v[208:211], v[16:19]
	v_mfma_f32_16x16x32_bf16 v[8:11], v[176:179], v[204:207], v[8:11]
	v_mfma_f32_16x16x32_bf16 v[8:11], v[184:187], v[208:211], v[8:11]
	v_mfma_f32_16x16x32_bf16 v[4:7], v[168:171], v[212:215], v[4:7]
	v_mfma_f32_16x16x32_bf16 v[4:7], v[172:175], v[216:219], v[4:7]
	v_mfma_f32_16x16x32_bf16 v[0:3], v[176:179], v[212:215], v[0:3]
	v_mfma_f32_16x16x32_bf16 v[0:3], v[184:187], v[216:219], v[0:3]
	s_setprio 0
	s_barrier
	s_add_i32 s76, s76, 2
	s_add_u32 s74, s74, 0x100
	s_addc_u32 s75, s75, 0
	s_cmp_gt_u32 s76, 41
	s_mov_b64 s[46:47], s[48:49]
	s_cbranch_scc0 .LBB0_1514
	s_and_b64 vcc, exec, s[12:13]
	s_cbranch_vccz .LBB0_1517
	s_barrier
